# plus 16-byte global stores write-through (sc1) outside the score tiles, to shorten the barriers' L2 write-back
# baseline (speedup 1.0000x reference)
; template <class Epi>
; DEV void gemm256_tile(const bf16_t* __restrict__ A, int lda, const bf16_t* __restrict__ Bt, int ldb, int K, unsigned char* lds, const Epi& epi) {
;     ...
;         __syncthreads();
; #pragma unroll 4
;         for (int i = 0; i < 16; ++i) {
;             const int idx = tid + 512 * i, row = idx >> 5, cp = idx & 31, c = cp ^ (row & 31);
;             const uint4 d = *(const uint4*)(lds + row * 512 + (cp << 4));
;             *(uint4*)(epi.obase + (size_t)row * epi.old + c * 8) = epi.finish(row, c * 8, d);
;         }
; __global__ void __launch_bounds__(512) hymba_fwd(Params p) {
;     ...
;         for (int t = bid; t < 32 * 24; t += G) { int nt, mt; tile_map(t, 32, 24, mt, nt);
;             EpiBfS e{proj + (size_t)mt * 256 * NPJ + nt * 256, NPJ};
;             gemm256_tile(hbuf + (size_t)mt * 256 * LDB, LDB, Wt_in + (size_t)nt * 256 * LDB, LDB, D, lds, e);
;         }
.LBB0_176:
	v_add_u32_e32 v3, s19, v150
	v_ashrrev_i32_e32 v4, 5, v3
	v_add_u32_e32 v5, 0x200, v3
	v_add_u32_e32 v6, 0x400, v3
	v_add_u32_e32 v3, 0x600, v3
	v_xor_b32_e32 v7, v4, v150
	v_lshl_or_b32 v8, v4, 9, v2
	v_ashrrev_i32_e32 v9, 5, v5
	v_ashrrev_i32_e32 v10, 5, v6
	v_ashrrev_i32_e32 v3, 5, v3
	v_mad_i64_i32 v[20:21], s[20:21], v4, s17, v[26:27]
	v_lshlrev_b32_e32 v11, 4, v7
	ds_read_b128 v[4:7], v8
	v_xor_b32_e32 v8, v9, v150
	v_lshl_or_b32 v12, v9, 9, v2
	v_xor_b32_e32 v13, v10, v150
	v_lshl_or_b32 v14, v10, 9, v2
	v_xor_b32_e32 v15, v3, v150
	v_lshl_or_b32 v16, v3, 9, v2
	v_mad_i64_i32 v[22:23], s[20:21], v9, s17, v[26:27]
	v_mad_i64_i32 v[24:25], s[20:21], v10, s17, v[26:27]
	v_mad_i64_i32 v[28:29], s[20:21], v3, s17, v[26:27]
	v_and_b32_e32 v142, 0x1f0, v11
	v_lshlrev_b32_e32 v3, 4, v8
	ds_read_b128 v[8:11], v12
	v_lshlrev_b32_e32 v30, 4, v13
	v_lshlrev_b32_e32 v31, 4, v15
	ds_read_b128 v[12:15], v14
	ds_read_b128 v[16:19], v16
	v_lshl_add_u64 v[20:21], v[20:21], 0, v[142:143]
	v_and_b32_e32 v142, 0x1f0, v3
	s_addk_i32 s19, 0x800
	v_lshl_add_u64 v[22:23], v[22:23], 0, v[142:143]
	v_and_b32_e32 v142, 0x1f0, v30
	s_cmpk_lg_i32 s19, 0x2000
	v_lshl_add_u64 v[24:25], v[24:25], 0, v[142:143]
	v_and_b32_e32 v142, 0x1f0, v31
	s_waitcnt lgkmcnt(3)
	global_store_dwordx4 v[20:21], v[4:7], off sc1
	s_nop 1
	v_lshl_add_u64 v[4:5], v[28:29], 0, v[142:143]
	s_waitcnt lgkmcnt(2)
	global_store_dwordx4 v[22:23], v[8:11], off sc1
	s_waitcnt lgkmcnt(1)
	global_store_dwordx4 v[24:25], v[12:15], off sc1
	s_waitcnt lgkmcnt(0)
	global_store_dwordx4 v[4:5], v[16:19], off sc1
	s_cbranch_scc1 .LBB0_176
	s_add_i32 s18, s18, s33
	s_cmpk_gt_i32 s18, 0x2ff
	s_barrier
	s_cbranch_scc0 .LBB0_173

; #define GLDS_STAGE(st, kt_) do { \
;         _Pragma("unroll") for (int i_ = 0; i_ < FI; ++i_) { \
;             glds16(ap + (size_t)(32 * i_) * lda + (kt_) * 64, l3a + (st) + tid * 16 + i_ * 4096); \
;             glds16(bp + (size_t)(32 * i_) * ldb + (kt_) * 64, l3a + (st) + OPB + tid * 16 + i_ * 4096); } } while (0)
; #define GLDS_STAGE(st, kt_) do { \
;         _Pragma("unroll") for (int i_ = 0; i_ < 4; ++i_) { \
;             glds16(ap + (size_t)(64 * i_) * lda + (kt_) * 64, l3a + (st) + tid * 16 + i_ * 8192); \
;             glds16(bp + (size_t)(64 * i_) * ldb + (kt_) * 64, l3a + (st) + 32768 + tid * 16 + i_ * 8192); } } while (0)
; template <int WT, class Epi>
; DEV void gemm_tile(const bf16_t* __restrict__ A, int lda, const bf16_t* __restrict__ Bt, int ldb, int K, unsigned char* lds, const Epi& epi) {
;     ...
;     for (int kt = 0; kt < nk; ++kt) {
;         if (NSTG == 4 && kt + 2 < nk) { if (FI == 2) asm volatile("s_waitcnt vmcnt(8)" ::: "memory"); else asm volatile("s_waitcnt vmcnt(0)" ::: "memory"); }
;         else asm volatile("s_waitcnt vmcnt(0)" ::: "memory");
;         __syncthreads();
;         if (kt + NSTG - 1 < nk) GLDS_STAGE(nxt, kt + NSTG - 1);
; #pragma unroll
;         for (int kh = 0; kh < 2; ++kh) {
;             bf16x8 af[FI], bfr[FI];
;             const int ch = ((kh * 4 + fq) ^ sw) << 4;
; #pragma unroll
;             for (int i = 0; i < FI; ++i) { af[i] = *(const bf16x8*)(lds + cur + aoff + i * 2048 + ch); bfr[i] = *(const bf16x8*)(lds + cur + boff + i * 2048 + ch); }
; #pragma unroll
;             for (int mi = 0; mi < FI; ++mi)
; #pragma unroll
;                 for (int ni = 0; ni < FI; ++ni) acc[mi][ni] = __builtin_amdgcn_mfma_f32_16x16x32_bf16(bfr[ni], af[mi], acc[mi][ni], 0, 0, 0);
;         }
;         nxt = cur; cur += STB; if (cur == NSTG * STB) cur = 0;
.LBB0_184:
	v_add_u32_e32 v94, s11, v83
	s_add_i32 s11, s53, s9
	s_waitcnt vmcnt(0)
	s_barrier
	v_lshl_add_u64 v[90:91], v[78:79], 0, s[4:5]
	v_add_u32_e32 v106, 0x4000, v94
	v_readfirstlane_b32 s12, v94
	v_add_u32_e32 v114, s11, v82
	v_add_u32_e32 v115, s11, v85
	s_mov_b32 s11, m0
	s_mov_b32 m0, s12
	s_nop 0
	global_load_lds_dwordx4 v[90:91], off
	s_mov_b32 m0, s11
	v_lshl_add_u64 v[92:93], v[76:77], 0, s[4:5]
	v_readfirstlane_b32 s11, v106
	s_mov_b32 s38, m0
	s_mov_b32 m0, s11
	s_nop 0
	global_load_lds_dwordx4 v[92:93], off
	s_mov_b32 m0, s38
	v_lshl_add_u64 v[94:95], v[90:91], 0, s[30:31]
	s_add_i32 s13, s12, 0x1000
	s_mov_b32 s40, m0
	s_mov_b32 m0, s13
	s_nop 0
	global_load_lds_dwordx4 v[94:95], off
	s_mov_b32 m0, s40
	v_lshl_add_u64 v[96:97], v[92:93], 0, s[30:31]
	s_add_i32 s38, s11, 0x1000
	s_mov_b32 s13, m0
	s_mov_b32 m0, s38
	s_nop 0
	global_load_lds_dwordx4 v[96:97], off
	s_mov_b32 m0, s13
	v_lshl_add_u64 v[98:99], v[90:91], 0, s[34:35]
	s_add_i32 s26, s12, 0x2000
	s_mov_b32 s13, m0
	s_mov_b32 m0, s26
	s_nop 0
	global_load_lds_dwordx4 v[98:99], off
	s_mov_b32 m0, s13
	v_lshl_add_u64 v[100:101], v[92:93], 0, s[34:35]
	s_add_i32 s39, s11, 0x2000
	s_mov_b32 s13, m0
	s_mov_b32 m0, s39
	s_nop 0
	global_load_lds_dwordx4 v[100:101], off
	s_mov_b32 m0, s13
	v_lshl_add_u64 v[102:103], v[90:91], 0, s[36:37]
	s_addk_i32 s12, 0x3000
	s_mov_b32 s13, m0
	s_mov_b32 m0, s12
	s_nop 0
	global_load_lds_dwordx4 v[102:103], off
	s_mov_b32 m0, s13
	v_lshl_add_u64 v[104:105], v[92:93], 0, s[36:37]
	v_add_u32_e32 v110, v115, v84
	s_addk_i32 s11, 0x3000
	s_mov_b32 s12, m0
	s_mov_b32 m0, s11
	s_nop 0
	global_load_lds_dwordx4 v[104:105], off
	s_mov_b32 m0, s12
	v_add_u32_e32 v116, v114, v84
	ds_read_b128 v[90:93], v110 offset:16384
	ds_read_b128 v[94:97], v110 offset:18432
	ds_read_b128 v[98:101], v116
	ds_read_b128 v[102:105], v116 offset:2048
	ds_read_b128 v[106:109], v110 offset:20480
	ds_read_b128 v[110:113], v110 offset:22528
	s_waitcnt lgkmcnt(3)
	v_mfma_f32_16x16x32_bf16 v[62:65], v[90:93], v[98:101], v[62:65]
	v_add_u32_e32 v114, v114, v81
	v_add_u32_e32 v115, v115, v81
	s_add_i32 s12, s9, 0x8000
	v_mfma_f32_16x16x32_bf16 v[54:57], v[94:97], v[98:101], v[54:57]
	s_cmp_lg_u32 s12, 0x10000
	s_mov_b32 s11, s9
	s_cselect_b32 s9, s12, 0
	s_waitcnt lgkmcnt(1)
	v_mfma_f32_16x16x32_bf16 v[50:53], v[106:109], v[98:101], v[50:53]
	s_add_u32 s4, s4, 0x80
	s_addc_u32 s5, s5, 0
	s_cmpk_eq_i32 s4, 0xf80
	s_waitcnt lgkmcnt(0)
	v_mfma_f32_16x16x32_bf16 v[46:49], v[110:113], v[98:101], v[46:49]
	v_mfma_f32_16x16x32_bf16 v[38:41], v[90:93], v[102:105], v[38:41]
	v_mfma_f32_16x16x32_bf16 v[34:37], v[94:97], v[102:105], v[34:37]
	v_mfma_f32_16x16x32_bf16 v[30:33], v[106:109], v[102:105], v[30:33]
	v_mfma_f32_16x16x32_bf16 v[26:29], v[110:113], v[102:105], v[26:29]
	ds_read_b128 v[98:101], v116 offset:4096
	ds_read_b128 v[102:105], v116 offset:6144
	s_waitcnt lgkmcnt(1)
	v_mfma_f32_16x16x32_bf16 v[22:25], v[90:93], v[98:101], v[22:25]
	v_mfma_f32_16x16x32_bf16 v[18:21], v[94:97], v[98:101], v[18:21]
	v_mfma_f32_16x16x32_bf16 v[14:17], v[106:109], v[98:101], v[14:17]
	v_mfma_f32_16x16x32_bf16 v[10:13], v[110:113], v[98:101], v[10:13]
	s_waitcnt lgkmcnt(0)
	v_mfma_f32_16x16x32_bf16 v[6:9], v[90:93], v[102:105], v[6:9]
	v_mfma_f32_16x16x32_bf16 v[2:5], v[94:97], v[102:105], v[2:5]
	ds_read_b128 v[90:93], v115 offset:16384
	ds_read_b128 v[94:97], v115 offset:18432
	v_mfma_f32_16x16x32_bf16 v[58:61], v[106:109], v[102:105], v[58:61]
	v_mfma_f32_16x16x32_bf16 v[42:45], v[110:113], v[102:105], v[42:45]
	ds_read_b128 v[98:101], v114
	ds_read_b128 v[102:105], v114 offset:2048
	ds_read_b128 v[106:109], v115 offset:20480
	ds_read_b128 v[110:113], v115 offset:22528
	s_waitcnt lgkmcnt(3)
	v_mfma_f32_16x16x32_bf16 v[62:65], v[90:93], v[98:101], v[62:65]
	v_mfma_f32_16x16x32_bf16 v[54:57], v[94:97], v[98:101], v[54:57]
	s_waitcnt lgkmcnt(1)
	v_mfma_f32_16x16x32_bf16 v[50:53], v[106:109], v[98:101], v[50:53]
	s_waitcnt lgkmcnt(0)
	v_mfma_f32_16x16x32_bf16 v[46:49], v[110:113], v[98:101], v[46:49]
	v_mfma_f32_16x16x32_bf16 v[38:41], v[90:93], v[102:105], v[38:41]
	v_mfma_f32_16x16x32_bf16 v[34:37], v[94:97], v[102:105], v[34:37]
	v_mfma_f32_16x16x32_bf16 v[30:33], v[106:109], v[102:105], v[30:33]
	v_mfma_f32_16x16x32_bf16 v[26:29], v[110:113], v[102:105], v[26:29]
	ds_read_b128 v[98:101], v114 offset:4096
	ds_read_b128 v[102:105], v114 offset:6144
	s_waitcnt lgkmcnt(1)
	v_mfma_f32_16x16x32_bf16 v[22:25], v[90:93], v[98:101], v[22:25]
	v_mfma_f32_16x16x32_bf16 v[18:21], v[94:97], v[98:101], v[18:21]
	v_mfma_f32_16x16x32_bf16 v[14:17], v[106:109], v[98:101], v[14:17]
	v_mfma_f32_16x16x32_bf16 v[10:13], v[110:113], v[98:101], v[10:13]
	s_waitcnt lgkmcnt(0)
	v_mfma_f32_16x16x32_bf16 v[6:9], v[90:93], v[102:105], v[6:9]
	v_mfma_f32_16x16x32_bf16 v[2:5], v[94:97], v[102:105], v[2:5]
	v_mfma_f32_16x16x32_bf16 v[58:61], v[106:109], v[102:105], v[58:61]
	v_mfma_f32_16x16x32_bf16 v[42:45], v[110:113], v[102:105], v[42:45]
	s_cbranch_scc0 .LBB0_184
; DEV bf16_t f2bf(float f) { return (bf16_t)(cvt_pk_bf16(f, 0.f) & 0xffffu); }
; DEV void store_bf4(bf16_t* p, f32x4 v) { uint2 w; w.x = cvt_pk_bf16(v[0], v[1]); w.y = cvt_pk_bf16(v[2], v[3]); *(uint2*)p = w; }
;     DEV void operator()(int r, int c, f32x4 v) const { store_bf4(dst + (size_t)r * ld + c, v); }
; template <int WT, class Epi>
; DEV void gemm_tile(const bf16_t* __restrict__ A, int lda, const bf16_t* __restrict__ Bt, int ldb, int K, unsigned char* lds, const Epi& epi) {
;     ...
; #pragma unroll
;         for (int kh = 0; kh < 2; ++kh) {
;             bf16x8 af[FI], bfr[FI];
;             const int ch = ((kh * 4 + fq) ^ sw) << 4;
; #pragma unroll
;             for (int i = 0; i < FI; ++i) { af[i] = *(const bf16x8*)(lds + cur + aoff + i * 2048 + ch); bfr[i] = *(const bf16x8*)(lds + cur + boff + i * 2048 + ch); }
; #pragma unroll
;             for (int mi = 0; mi < FI; ++mi)
; #pragma unroll
;                 for (int ni = 0; ni < FI; ++ni) acc[mi][ni] = __builtin_amdgcn_mfma_f32_16x16x32_bf16(bfr[ni], af[mi], acc[mi][ni], 0, 0, 0);
;         }
;         nxt = cur; cur += STB; if (cur == NSTG * STB) cur = 0;
;     }
;     ...
;     __syncthreads();
;     DEV void operator()(int r, int c, f32x4 v) const {
;         const int row = m0 + r, col = n0 + c;
;         if (col < D) {
;             __builtin_nontemporal_store(v, (f32x4*)(out + O_MK + (size_t)row * D + col));
;             store_bf4(mkb + (size_t)row * LDB + col, v);
;         } else {
;             const int cc = col - D, b = row >> 8, m = row & 255;
;             __builtin_nontemporal_store(v, (f32x4*)(out + O_MV + (size_t)row * D + cc));
;             bf16_t* p = mvt + ((size_t)b * D + cc) * LDM + m;
;             p[0] = f2bf(v[0]); p[LDM] = f2bf(v[1]); p[2 * LDM] = f2bf(v[2]); p[3 * LDM] = f2bf(v[3]);
;         }
	v_add_u32_e32 v102, s53, v85
	v_add_u32_e32 v103, s53, v82
	v_add_u32_e32 v98, v102, v84
	v_add_u32_e32 v104, v103, v84
	s_waitcnt vmcnt(0)
	s_barrier
	ds_read_b128 v[76:79], v98 offset:49152
	ds_read_b128 v[90:93], v98 offset:51200
	ds_read_b128 v[82:85], v104 offset:32768
	ds_read_b128 v[94:97], v98 offset:53248
	ds_read_b128 v[98:101], v98 offset:55296
	s_waitcnt lgkmcnt(2)
	v_mfma_f32_16x16x32_bf16 v[62:65], v[76:79], v[82:85], v[62:65]
	v_add_u32_e32 v102, v102, v81
	v_add_u32_e32 v81, v103, v81
	s_lshl_b32 s11, s8, 7
	v_mfma_f32_16x16x32_bf16 v[54:57], v[90:93], v[82:85], v[54:57]
	s_lshl_b32 s4, s7, 7
	s_cmpk_gt_u32 s6, 0x7f
	s_cselect_b64 s[6:7], -1, 0
	s_waitcnt lgkmcnt(1)
	v_mfma_f32_16x16x32_bf16 v[50:53], v[94:97], v[82:85], v[50:53]
	ds_read_b128 v[106:109], v81 offset:34816
	s_and_b64 vcc, exec, s[6:7]
	ds_read_b128 v[110:113], v81 offset:38912
	s_waitcnt lgkmcnt(2)
	v_mfma_f32_16x16x32_bf16 v[46:49], v[98:101], v[82:85], v[46:49]
	ds_read_b128 v[82:85], v104 offset:34816
	s_waitcnt lgkmcnt(0)
	v_mfma_f32_16x16x32_bf16 v[38:41], v[76:79], v[82:85], v[38:41]
	v_mfma_f32_16x16x32_bf16 v[34:37], v[90:93], v[82:85], v[34:37]
	v_mfma_f32_16x16x32_bf16 v[30:33], v[94:97], v[82:85], v[30:33]
	v_mfma_f32_16x16x32_bf16 v[26:29], v[98:101], v[82:85], v[26:29]
	ds_read_b128 v[82:85], v104 offset:36864
	s_waitcnt lgkmcnt(0)
	v_mfma_f32_16x16x32_bf16 v[22:25], v[76:79], v[82:85], v[22:25]
	v_mfma_f32_16x16x32_bf16 v[18:21], v[90:93], v[82:85], v[18:21]
	v_mfma_f32_16x16x32_bf16 v[14:17], v[94:97], v[82:85], v[14:17]
	v_mfma_f32_16x16x32_bf16 v[10:13], v[98:101], v[82:85], v[10:13]
	ds_read_b128 v[82:85], v104 offset:38912
	s_waitcnt lgkmcnt(0)
	v_mfma_f32_16x16x32_bf16 v[6:9], v[76:79], v[82:85], v[6:9]
	ds_read_b128 v[76:79], v102 offset:49152
	v_mfma_f32_16x16x32_bf16 v[2:5], v[90:93], v[82:85], v[2:5]
	v_mfma_f32_16x16x32_bf16 v[90:93], v[94:97], v[82:85], v[58:61]
	v_mfma_f32_16x16x32_bf16 v[94:97], v[98:101], v[82:85], v[42:45]
	ds_read_b128 v[82:85], v102 offset:51200
	ds_read_b128 v[98:101], v102 offset:53248
	ds_read_b128 v[102:105], v102 offset:55296
	ds_read_b128 v[42:45], v81 offset:32768
	s_waitcnt lgkmcnt(0)
	v_mfma_f32_16x16x32_bf16 v[62:65], v[76:79], v[42:45], v[62:65]
	v_mfma_f32_16x16x32_bf16 v[58:61], v[82:85], v[42:45], v[54:57]
	v_mfma_f32_16x16x32_bf16 v[54:57], v[98:101], v[42:45], v[50:53]
	v_mfma_f32_16x16x32_bf16 v[50:53], v[102:105], v[42:45], v[46:49]
	v_mfma_f32_16x16x32_bf16 v[46:49], v[76:79], v[106:109], v[38:41]
	v_mfma_f32_16x16x32_bf16 v[42:45], v[82:85], v[106:109], v[34:37]
	v_mfma_f32_16x16x32_bf16 v[38:41], v[98:101], v[106:109], v[30:33]
	v_mfma_f32_16x16x32_bf16 v[34:37], v[102:105], v[106:109], v[26:29]
	ds_read_b128 v[106:109], v81 offset:36864
	v_and_b32_e32 v81, 64, v80
	v_add_u32_e32 v80, s11, v89
	s_waitcnt lgkmcnt(0)
	v_mfma_f32_16x16x32_bf16 v[30:33], v[76:79], v[106:109], v[22:25]
	s_barrier
	v_mfma_f32_16x16x32_bf16 v[26:29], v[82:85], v[106:109], v[18:21]
	v_mfma_f32_16x16x32_bf16 v[22:25], v[98:101], v[106:109], v[14:17]
	s_nop 2
	v_lshlrev_b32_e32 v14, 2, v74
	v_mfma_f32_16x16x32_bf16 v[18:21], v[102:105], v[106:109], v[10:13]
	v_or3_b32 v74, v14, v81, s4
	s_mov_b64 s[4:5], -1
	v_ashrrev_i32_e32 v81, 31, v80
	v_mfma_f32_16x16x32_bf16 v[10:13], v[82:85], v[110:113], v[2:5]
	v_ashrrev_i32_e32 v84, 8, v80
	v_ashrrev_i32_e32 v85, 31, v84
	s_nop 0
	v_and_b32_e32 v2, 0xcf, v80
	v_mfma_f32_16x16x32_bf16 v[14:17], v[76:79], v[110:113], v[6:9]
	v_lshlrev_b32_e32 v82, 1, v2
	v_add_u32_e32 v78, 0xfffff800, v74
	v_mfma_f32_16x16x32_bf16 v[6:9], v[98:101], v[110:113], v[90:93]
	v_mfma_f32_16x16x32_bf16 v[2:5], v[102:105], v[110:113], v[94:97]
	s_cbranch_vccz .LBB0_187
	v_lshlrev_b64 v[76:77], 13, v[80:81]
	v_lshl_add_u64 v[76:77], s[18:19], 0, v[76:77]
	v_mov_b32_e32 v79, v75
	v_lshl_add_u64 v[76:77], v[78:79], 2, v[76:77]
	global_store_dwordx4 v[76:77], v[62:65], off nt sc1
	v_lshlrev_b64 v[76:77], 11, v[84:85]
	v_lshl_add_u64 v[76:77], v[76:77], 0, v[78:79]
	v_mad_u64_u32 v[90:91], s[4:5], v76, s60, v[162:163]
	v_mad_i32_i24 v91, v77, s60, v91
	v_mov_b32_e32 v83, v75
	v_lshl_add_u64 v[76:77], v[90:91], 0, v[82:83]
	v_cvt_pk_bf16_f32 v79, v62, s0
	global_store_short v[76:77], v79, off
	v_cvt_pk_bf16_f32 v79, v63, s0
	global_store_short v[76:77], v79, off offset:576
	v_cvt_pk_bf16_f32 v79, v64, s0
	global_store_short v[76:77], v79, off offset:1152
	v_cvt_pk_bf16_f32 v79, v65, s0
	global_store_short v[76:77], v79, off offset:1728
	s_mov_b64 s[4:5], 0
.LBB0_187:
	s_andn2_b64 vcc, exec, s[4:5]
	v_lshlrev_b32_e32 v76, 1, v74
	s_cbranch_vccnz .LBB0_189
	v_lshlrev_b64 v[90:91], 13, v[80:81]
	v_lshl_add_u64 v[90:91], s[20:21], 0, v[90:91]
	v_lshl_add_u64 v[90:91], v[74:75], 2, v[90:91]
	global_store_dwordx4 v[90:91], v[62:65], off nt sc1
	v_mad_i64_i32 v[90:91], s[4:5], v80, s56, v[168:169]
	v_mov_b32_e32 v77, v75
	v_lshl_add_u64 v[90:91], v[90:91], 0, v[76:77]
	v_cvt_pk_bf16_f32 v62, v62, v63
	v_cvt_pk_bf16_f32 v63, v64, v65
	global_store_dwordx2 v[90:91], v[62:63], off

; DEV void store_bf4(bf16_t* p, f32x4 v) { uint2 w; w.x = cvt_pk_bf16(v[0], v[1]); w.y = cvt_pk_bf16(v[2], v[3]); *(uint2*)p = w; }
;     DEV void operator()(int r, int c, f32x4 v) const {
;     ...
;         if (col < D) {
;             __builtin_nontemporal_store(v, (f32x4*)(out + O_MK + (size_t)row * D + col));
;             store_bf4(mkb + (size_t)row * LDB + col, v);
.LBB0_195:
	v_lshlrev_b64 v[56:57], 13, v[80:81]
	v_lshl_add_u64 v[56:57], s[20:21], 0, v[56:57]
	v_lshl_add_u64 v[56:57], v[74:75], 2, v[56:57]
	global_store_dwordx4 v[56:57], v[50:53], off offset:192 nt sc1
	v_mad_i64_i32 v[56:57], s[6:7], v80, s56, v[168:169]
	v_mov_b32_e32 v77, v75
	v_lshl_add_u64 v[56:57], v[56:57], 0, v[76:77]
	v_cvt_pk_bf16_f32 v50, v50, v51
	v_cvt_pk_bf16_f32 v51, v52, v53
	global_store_dwordx2 v[56:57], v[50:51], off offset:96

; DEV void store_bf4(bf16_t* p, f32x4 v) { uint2 w; w.x = cvt_pk_bf16(v[0], v[1]); w.y = cvt_pk_bf16(v[2], v[3]); *(uint2*)p = w; }
;     DEV void operator()(int r, int c, f32x4 v) const {
;     ...
;         if (col < D) {
;             __builtin_nontemporal_store(v, (f32x4*)(out + O_MK + (size_t)row * D + col));
;             store_bf4(mkb + (size_t)row * LDB + col, v);
.LBB0_204:
	v_lshlrev_b64 v[38:39], 13, v[50:51]
	v_lshl_add_u64 v[38:39], s[20:21], 0, v[38:39]
	v_lshl_add_u64 v[38:39], v[74:75], 2, v[38:39]
	global_store_dwordx4 v[38:39], v[34:37], off offset:192 nt sc1
	v_mad_i64_i32 v[38:39], s[6:7], v50, s56, v[168:169]
	v_mov_b32_e32 v77, v75
	v_lshl_add_u64 v[38:39], v[38:39], 0, v[76:77]
	v_cvt_pk_bf16_f32 v34, v34, v35
	v_cvt_pk_bf16_f32 v35, v36, v37
	global_store_dwordx2 v[38:39], v[34:35], off offset:96

; DEV void store_bf4(bf16_t* p, f32x4 v) { uint2 w; w.x = cvt_pk_bf16(v[0], v[1]); w.y = cvt_pk_bf16(v[2], v[3]); *(uint2*)p = w; }
;     DEV void operator()(int r, int c, f32x4 v) const {
;     ...
;         if (col < D) {
;             __builtin_nontemporal_store(v, (f32x4*)(out + O_MK + (size_t)row * D + col));
;             store_bf4(mkb + (size_t)row * LDB + col, v);
.LBB0_213:
	v_lshlrev_b64 v[22:23], 13, v[34:35]
	v_lshl_add_u64 v[22:23], s[20:21], 0, v[22:23]
	v_lshl_add_u64 v[22:23], v[74:75], 2, v[22:23]
	global_store_dwordx4 v[22:23], v[18:21], off offset:192 nt sc1
	v_mad_i64_i32 v[22:23], s[6:7], v34, s56, v[168:169]
	v_mov_b32_e32 v77, v75
	v_lshl_add_u64 v[22:23], v[22:23], 0, v[76:77]
	v_cvt_pk_bf16_f32 v18, v18, v19
	v_cvt_pk_bf16_f32 v19, v20, v21
	global_store_dwordx2 v[22:23], v[18:19], off offset:96

; DEV void store_bf4(bf16_t* p, f32x4 v) { uint2 w; w.x = cvt_pk_bf16(v[0], v[1]); w.y = cvt_pk_bf16(v[2], v[3]); *(uint2*)p = w; }
;     DEV void operator()(int r, int c, f32x4 v) const {
;     ...
;         if (col < D) {
;             __builtin_nontemporal_store(v, (f32x4*)(out + O_MK + (size_t)row * D + col));
;             store_bf4(mkb + (size_t)row * LDB + col, v);
.LBB0_222:
	v_lshlrev_b64 v[6:7], 13, v[18:19]
	v_lshl_add_u64 v[6:7], s[20:21], 0, v[6:7]
	v_lshl_add_u64 v[6:7], v[74:75], 2, v[6:7]
	global_store_dwordx4 v[6:7], v[2:5], off offset:192 nt sc1
	v_mad_i64_i32 v[6:7], s[4:5], v18, s56, v[168:169]
	v_mov_b32_e32 v77, v75
	v_lshl_add_u64 v[6:7], v[6:7], 0, v[76:77]
	v_cvt_pk_bf16_f32 v2, v2, v3
	v_cvt_pk_bf16_f32 v3, v4, v5
	global_store_dwordx2 v[6:7], v[2:3], off offset:96

; #define GLDS_STAGE(st, kt_) do { \
;         _Pragma("unroll") for (int i_ = 0; i_ < FI; ++i_) { \
;             glds16(ap + (size_t)(32 * i_) * lda + (kt_) * 64, l3a + (st) + tid * 16 + i_ * 4096); \
;             glds16(bp + (size_t)(32 * i_) * ldb + (kt_) * 64, l3a + (st) + OPB + tid * 16 + i_ * 4096); } } while (0)
; #define GLDS_STAGE(st, kt_) do { \
;         _Pragma("unroll") for (int i_ = 0; i_ < 4; ++i_) { \
;             glds16(ap + (size_t)(64 * i_) * lda + (kt_) * 64, l3a + (st) + tid * 16 + i_ * 8192); \
;             glds16(bp + (size_t)(64 * i_) * ldb + (kt_) * 64, l3a + (st) + 32768 + tid * 16 + i_ * 8192); } } while (0)
; template <int WT, class Epi>
; DEV void gemm_tile(const bf16_t* __restrict__ A, int lda, const bf16_t* __restrict__ Bt, int ldb, int K, unsigned char* lds, const Epi& epi) {
;     ...
;     for (int kt = 0; kt < nk; ++kt) {
;         if (NSTG == 4 && kt + 2 < nk) { if (FI == 2) asm volatile("s_waitcnt vmcnt(8)" ::: "memory"); else asm volatile("s_waitcnt vmcnt(0)" ::: "memory"); }
;         else asm volatile("s_waitcnt vmcnt(0)" ::: "memory");
;         __syncthreads();
;         if (kt + NSTG - 1 < nk) GLDS_STAGE(nxt, kt + NSTG - 1);
; #pragma unroll
;         for (int kh = 0; kh < 2; ++kh) {
;             bf16x8 af[FI], bfr[FI];
;             const int ch = ((kh * 4 + fq) ^ sw) << 4;
; #pragma unroll
;             for (int i = 0; i < FI; ++i) { af[i] = *(const bf16x8*)(lds + cur + aoff + i * 2048 + ch); bfr[i] = *(const bf16x8*)(lds + cur + boff + i * 2048 + ch); }
; #pragma unroll
;             for (int mi = 0; mi < FI; ++mi)
; #pragma unroll
;                 for (int ni = 0; ni < FI; ++ni) acc[mi][ni] = __builtin_amdgcn_mfma_f32_16x16x32_bf16(bfr[ni], af[mi], acc[mi][ni], 0, 0, 0);
;         }
;         nxt = cur; cur += STB; if (cur == NSTG * STB) cur = 0;
.LBB0_226:
	v_add_u32_e32 v94, s8, v83
	s_add_i32 s8, s53, s7
	s_waitcnt vmcnt(0)
	s_waitcnt vmcnt(63) expcnt(7) lgkmcnt(15)
	s_barrier
	v_lshl_add_u64 v[90:91], v[78:79], 0, s[4:5]
	v_add_u32_e32 v106, 0x4000, v94
	v_readfirstlane_b32 s9, v94
	v_add_u32_e32 v114, s8, v84
	v_add_u32_e32 v115, s8, v89
	s_mov_b32 s8, m0
	s_mov_b32 m0, s9
	s_nop 0
	global_load_lds_dwordx4 v[90:91], off
	s_mov_b32 m0, s8
	v_lshl_add_u64 v[92:93], v[76:77], 0, s[4:5]
	v_readfirstlane_b32 s8, v106
	s_mov_b32 s13, m0
	s_mov_b32 m0, s8
	s_nop 0
	global_load_lds_dwordx4 v[92:93], off
	s_mov_b32 m0, s13
	v_lshl_add_u64 v[94:95], v[90:91], 0, s[30:31]
	s_add_i32 s11, s9, 0x1000
	s_mov_b32 s38, m0
	s_mov_b32 m0, s11
	s_nop 0
	global_load_lds_dwordx4 v[94:95], off
	s_mov_b32 m0, s38
	v_lshl_add_u64 v[96:97], v[92:93], 0, s[30:31]
	s_add_i32 s13, s8, 0x1000
	s_mov_b32 s11, m0
	s_mov_b32 m0, s13
	s_nop 0
	global_load_lds_dwordx4 v[96:97], off
	s_mov_b32 m0, s11
	v_lshl_add_u64 v[98:99], v[90:91], 0, s[34:35]
	s_add_i32 s12, s9, 0x2000
	s_mov_b32 s11, m0
	s_mov_b32 m0, s12
	s_nop 0
	global_load_lds_dwordx4 v[98:99], off
	s_mov_b32 m0, s11
	v_lshl_add_u64 v[100:101], v[92:93], 0, s[34:35]
	s_add_i32 s26, s8, 0x2000
	s_mov_b32 s11, m0
	s_mov_b32 m0, s26
	s_nop 0
	global_load_lds_dwordx4 v[100:101], off
	s_mov_b32 m0, s11
	v_lshl_add_u64 v[102:103], v[90:91], 0, s[36:37]
	s_addk_i32 s9, 0x3000
	s_mov_b32 s11, m0
	s_mov_b32 m0, s9
	s_nop 0
	global_load_lds_dwordx4 v[102:103], off
	s_mov_b32 m0, s11
	v_lshl_add_u64 v[104:105], v[92:93], 0, s[36:37]
	v_add_u32_e32 v110, v115, v85
	s_addk_i32 s8, 0x3000
	s_mov_b32 s9, m0
	s_mov_b32 m0, s8
	s_nop 0
	global_load_lds_dwordx4 v[104:105], off
	s_mov_b32 m0, s9
	v_add_u32_e32 v116, v114, v85
	ds_read_b128 v[90:93], v110 offset:16384
	ds_read_b128 v[94:97], v110 offset:18432
	ds_read_b128 v[98:101], v116
	ds_read_b128 v[102:105], v116 offset:2048
	ds_read_b128 v[106:109], v110 offset:20480
	ds_read_b128 v[110:113], v110 offset:22528
	s_waitcnt lgkmcnt(3)
	v_mfma_f32_16x16x32_bf16 v[62:65], v[90:93], v[98:101], v[62:65]
	v_add_u32_e32 v114, v114, v82
	v_add_u32_e32 v115, v115, v82
	s_add_i32 s9, s7, 0x8000
	v_mfma_f32_16x16x32_bf16 v[54:57], v[94:97], v[98:101], v[54:57]
	s_cmp_lg_u32 s9, 0x10000
	s_mov_b32 s8, s7
	s_cselect_b32 s7, s9, 0
	s_waitcnt lgkmcnt(1)
	v_mfma_f32_16x16x32_bf16 v[50:53], v[106:109], v[98:101], v[50:53]
	s_add_u32 s4, s4, 0x80
	s_addc_u32 s5, s5, 0
	s_cmpk_eq_i32 s4, 0xf80
	s_waitcnt lgkmcnt(0)
	v_mfma_f32_16x16x32_bf16 v[46:49], v[110:113], v[98:101], v[46:49]
	v_mfma_f32_16x16x32_bf16 v[38:41], v[90:93], v[102:105], v[38:41]
	v_mfma_f32_16x16x32_bf16 v[34:37], v[94:97], v[102:105], v[34:37]
	v_mfma_f32_16x16x32_bf16 v[30:33], v[106:109], v[102:105], v[30:33]
	v_mfma_f32_16x16x32_bf16 v[26:29], v[110:113], v[102:105], v[26:29]
	ds_read_b128 v[98:101], v116 offset:4096
	ds_read_b128 v[102:105], v116 offset:6144
	s_waitcnt lgkmcnt(1)
	v_mfma_f32_16x16x32_bf16 v[22:25], v[90:93], v[98:101], v[22:25]
	v_mfma_f32_16x16x32_bf16 v[18:21], v[94:97], v[98:101], v[18:21]
	v_mfma_f32_16x16x32_bf16 v[14:17], v[106:109], v[98:101], v[14:17]
	v_mfma_f32_16x16x32_bf16 v[10:13], v[110:113], v[98:101], v[10:13]
	s_waitcnt lgkmcnt(0)
	v_mfma_f32_16x16x32_bf16 v[6:9], v[90:93], v[102:105], v[6:9]
	v_mfma_f32_16x16x32_bf16 v[2:5], v[94:97], v[102:105], v[2:5]
	ds_read_b128 v[90:93], v115 offset:16384
	ds_read_b128 v[94:97], v115 offset:18432
	v_mfma_f32_16x16x32_bf16 v[58:61], v[106:109], v[102:105], v[58:61]
	v_mfma_f32_16x16x32_bf16 v[42:45], v[110:113], v[102:105], v[42:45]
	ds_read_b128 v[98:101], v114
	ds_read_b128 v[102:105], v114 offset:2048
	ds_read_b128 v[106:109], v115 offset:20480
	ds_read_b128 v[110:113], v115 offset:22528
	s_waitcnt lgkmcnt(3)
	v_mfma_f32_16x16x32_bf16 v[62:65], v[90:93], v[98:101], v[62:65]
	v_mfma_f32_16x16x32_bf16 v[54:57], v[94:97], v[98:101], v[54:57]
	s_waitcnt lgkmcnt(1)
	v_mfma_f32_16x16x32_bf16 v[50:53], v[106:109], v[98:101], v[50:53]
	s_waitcnt lgkmcnt(0)
	v_mfma_f32_16x16x32_bf16 v[46:49], v[110:113], v[98:101], v[46:49]
	v_mfma_f32_16x16x32_bf16 v[38:41], v[90:93], v[102:105], v[38:41]
	v_mfma_f32_16x16x32_bf16 v[34:37], v[94:97], v[102:105], v[34:37]
	v_mfma_f32_16x16x32_bf16 v[30:33], v[106:109], v[102:105], v[30:33]
	v_mfma_f32_16x16x32_bf16 v[26:29], v[110:113], v[102:105], v[26:29]
	ds_read_b128 v[98:101], v114 offset:4096
	ds_read_b128 v[102:105], v114 offset:6144
	s_waitcnt lgkmcnt(1)
	v_mfma_f32_16x16x32_bf16 v[22:25], v[90:93], v[98:101], v[22:25]
	v_mfma_f32_16x16x32_bf16 v[18:21], v[94:97], v[98:101], v[18:21]
	v_mfma_f32_16x16x32_bf16 v[14:17], v[106:109], v[98:101], v[14:17]
	v_mfma_f32_16x16x32_bf16 v[10:13], v[110:113], v[98:101], v[10:13]
	s_waitcnt lgkmcnt(0)
	v_mfma_f32_16x16x32_bf16 v[6:9], v[90:93], v[102:105], v[6:9]
	v_mfma_f32_16x16x32_bf16 v[2:5], v[94:97], v[102:105], v[2:5]
	v_mfma_f32_16x16x32_bf16 v[58:61], v[106:109], v[102:105], v[58:61]
	v_mfma_f32_16x16x32_bf16 v[42:45], v[110:113], v[102:105], v[42:45]
	s_cbranch_scc0 .LBB0_226
; DEV void store_bf4(bf16_t* p, f32x4 v) { uint2 w; w.x = cvt_pk_bf16(v[0], v[1]); w.y = cvt_pk_bf16(v[2], v[3]); *(uint2*)p = w; }
;     DEV void operator()(int r, int c, f32x4 v) const { store_bf4(dst + (size_t)r * ld + c, v); }
; template <int WT, class Epi>
; DEV void gemm_tile(const bf16_t* __restrict__ A, int lda, const bf16_t* __restrict__ Bt, int ldb, int K, unsigned char* lds, const Epi& epi) {
;     ...
; #pragma unroll
;         for (int kh = 0; kh < 2; ++kh) {
;             bf16x8 af[FI], bfr[FI];
;             const int ch = ((kh * 4 + fq) ^ sw) << 4;
; #pragma unroll
;             for (int i = 0; i < FI; ++i) { af[i] = *(const bf16x8*)(lds + cur + aoff + i * 2048 + ch); bfr[i] = *(const bf16x8*)(lds + cur + boff + i * 2048 + ch); }
; #pragma unroll
;             for (int mi = 0; mi < FI; ++mi)
; #pragma unroll
;                 for (int ni = 0; ni < FI; ++ni) acc[mi][ni] = __builtin_amdgcn_mfma_f32_16x16x32_bf16(bfr[ni], af[mi], acc[mi][ni], 0, 0, 0);
;         }
;         nxt = cur; cur += STB; if (cur == NSTG * STB) cur = 0;
;     }
;     ...
;     __syncthreads();
;     DEV void operator()(int r, int c, f32x4 v) const {
;         const int row = m0 + r, col = n0 + c;
;         if (col < NPJ) {
;             store_bf4(proj + (size_t)row * NPJ + col, v);
;             const bool isconv = col < 3072, ispool = (col >= C_U && col < C_ZB);
;             if (isconv || ispool) {
;                 if (row < TP) {
;                     const int b = row >> 11, t = row & 2047;
;                     if (isconv) { if (t >= 2045) *(f32x4*)(out + O_CP + ((size_t)(b * 3 + (t - 2045))) * 3072 + col) = v; }
;                     else { if (t >= 2033) *(f32x4*)(out + O_PP + ((size_t)(b * 15 + (t - 2033))) * 1024 + (col - C_U)) = v; }
;                 } else {
;                     const int sb = (row - TP) >> 2, t = (row - TP) & 3;
;                     if (isconv) { if (t >= 1) *(f32x4*)(out + O_CS + ((size_t)(sb * 3 + (t - 1))) * 3072 + col) = v; }
;                     else *(f32x4*)(out + O_PS + ((size_t)(sb * 15 + 11 + t)) * 1024 + (col - C_U)) = v;
;                 }
	v_add_u32_e32 v83, s53, v89
	v_add_u32_e32 v89, v83, v85
	s_waitcnt vmcnt(0)
	s_barrier
	ds_read_b128 v[76:79], v89 offset:49152
	ds_read_b128 v[94:97], v89 offset:51200
	ds_read_b128 v[98:101], v89 offset:53248
	ds_read_b128 v[102:105], v89 offset:55296
	v_add_u32_e32 v84, s53, v84
	v_add_u32_e32 v85, v84, v85
	ds_read_b128 v[90:93], v85 offset:32768
	v_add_u32_e32 v89, v84, v82
	ds_read_b128 v[110:113], v89 offset:36864
	s_waitcnt lgkmcnt(1)
	v_mfma_f32_16x16x32_bf16 v[62:65], v[76:79], v[90:93], v[62:65]
	ds_read_b128 v[114:117], v89 offset:38912
	s_lshl_b32 s4, s6, 7
	s_and_b32 s26, s10, 0x7ffffe0
	v_mfma_f32_16x16x32_bf16 v[54:57], v[94:97], v[90:93], v[54:57]
	s_cmpk_lg_i32 s26, 0x80
	s_cselect_b64 s[44:45], -1, 0
	v_mfma_f32_16x16x32_bf16 v[50:53], v[98:101], v[90:93], v[50:53]
	v_mfma_f32_16x16x32_bf16 v[46:49], v[102:105], v[90:93], v[46:49]
	ds_read_b128 v[90:93], v85 offset:34816
	s_waitcnt lgkmcnt(0)
	v_mfma_f32_16x16x32_bf16 v[38:41], v[76:79], v[90:93], v[38:41]
	v_mfma_f32_16x16x32_bf16 v[34:37], v[94:97], v[90:93], v[34:37]
	v_mfma_f32_16x16x32_bf16 v[30:33], v[98:101], v[90:93], v[30:33]
	v_mfma_f32_16x16x32_bf16 v[26:29], v[102:105], v[90:93], v[26:29]
	ds_read_b128 v[90:93], v85 offset:36864
	s_waitcnt lgkmcnt(0)
	v_mfma_f32_16x16x32_bf16 v[22:25], v[76:79], v[90:93], v[22:25]
	v_mfma_f32_16x16x32_bf16 v[18:21], v[94:97], v[90:93], v[18:21]
	v_mfma_f32_16x16x32_bf16 v[14:17], v[98:101], v[90:93], v[14:17]
	v_mfma_f32_16x16x32_bf16 v[10:13], v[102:105], v[90:93], v[10:13]
	ds_read_b128 v[90:93], v85 offset:38912
	s_waitcnt lgkmcnt(0)
	v_mfma_f32_16x16x32_bf16 v[6:9], v[76:79], v[90:93], v[6:9]
	v_add_u32_e32 v76, v83, v82
	ds_read_b128 v[82:85], v76 offset:51200
	ds_read_b128 v[106:109], v76 offset:55296
	v_mfma_f32_16x16x32_bf16 v[2:5], v[94:97], v[90:93], v[2:5]
	v_mfma_f32_16x16x32_bf16 v[94:97], v[98:101], v[90:93], v[58:61]
	ds_read_b128 v[98:101], v76 offset:49152
	v_mfma_f32_16x16x32_bf16 v[90:93], v[102:105], v[90:93], v[42:45]
	ds_read_b128 v[102:105], v76 offset:53248
	ds_read_b128 v[76:79], v89 offset:34816
	s_nop 0
	ds_read_b128 v[42:45], v89 offset:32768
	s_waitcnt lgkmcnt(0)
	v_mfma_f32_16x16x32_bf16 v[62:65], v[98:101], v[42:45], v[62:65]
	s_barrier
	v_mfma_f32_16x16x32_bf16 v[58:61], v[82:85], v[42:45], v[54:57]
	v_mfma_f32_16x16x32_bf16 v[54:57], v[102:105], v[42:45], v[50:53]
	v_mfma_f32_16x16x32_bf16 v[50:53], v[106:109], v[42:45], v[46:49]
	v_mfma_f32_16x16x32_bf16 v[46:49], v[98:101], v[76:79], v[38:41]
	v_mfma_f32_16x16x32_bf16 v[42:45], v[82:85], v[76:79], v[34:37]
	v_mfma_f32_16x16x32_bf16 v[38:41], v[102:105], v[76:79], v[30:33]
	v_mfma_f32_16x16x32_bf16 v[34:37], v[106:109], v[76:79], v[26:29]
	v_and_b32_e32 v76, 64, v80
	v_mfma_f32_16x16x32_bf16 v[26:29], v[82:85], v[110:113], v[18:21]
	s_nop 2
	v_lshlrev_b32_e32 v18, 2, v74
	v_add_u32_e32 v74, s68, v81
	v_or3_b32 v76, v18, v76, s4
	v_mfma_f32_16x16x32_bf16 v[30:33], v[98:101], v[110:113], v[22:25]
	v_ashrrev_i32_e32 v77, 31, v76
	v_cmp_lt_i32_e32 vcc, s62, v76
	s_and_b64 s[38:39], s[44:45], vcc
	v_mfma_f32_16x16x32_bf16 v[22:25], v[102:105], v[110:113], v[14:17]
	v_cmp_gt_i32_e64 s[12:13], s57, v74
	s_nor_b64 s[8:9], s[12:13], s[38:39]
	s_nop 0
	v_mad_i64_i32 v[14:15], s[4:5], v74, s58, v[172:173]
	v_lshl_add_u64 v[78:79], v[76:77], 1, v[14:15]
	v_mfma_f32_16x16x32_bf16 v[18:21], v[106:109], v[110:113], v[10:13]
	v_cmp_gt_i32_e64 s[4:5], s61, v76
	s_nop 1
	v_cvt_pk_bf16_f32 v10, v62, v63
	v_cvt_pk_bf16_f32 v11, v64, v65
	global_store_dwordx2 v[78:79], v[10:11], off
	v_mfma_f32_16x16x32_bf16 v[10:13], v[82:85], v[114:117], v[2:5]
	s_nop 2
	v_add_u32_e32 v2, 0xffffe000, v74
	v_mfma_f32_16x16x32_bf16 v[14:17], v[98:101], v[114:117], v[6:9]
	v_lshrrev_b32_e32 v82, 2, v2
	v_mfma_f32_16x16x32_bf16 v[6:9], v[102:105], v[114:117], v[94:97]
	v_mfma_f32_16x16x32_bf16 v[2:5], v[106:109], v[114:117], v[90:93]
	s_and_saveexec_b64 s[6:7], s[8:9]
	s_cbranch_execz .LBB0_234
	v_and_b32_e32 v74, 3, v80
	s_and_saveexec_b64 s[8:9], s[4:5]
	s_xor_b64 s[8:9], exec, s[8:9]
	s_cbranch_execz .LBB0_232
	v_cmp_ne_u32_e32 vcc, 0, v74
	s_and_saveexec_b64 s[10:11], vcc
	s_cbranch_execz .LBB0_231
	v_lshl_add_u32 v83, v82, 1, v82
	v_add3_u32 v74, v74, v83, -1
	v_mov_b64_e32 v[84:85], s[22:23]
	v_mad_u64_u32 v[84:85], s[40:41], v74, s58, v[84:85]
	v_lshl_add_u64 v[84:85], v[76:77], 2, v[84:85]
	global_store_dwordx4 v[84:85], v[62:65], off sc1

; DEV void store_bf4(bf16_t* p, f32x4 v) { uint2 w; w.x = cvt_pk_bf16(v[0], v[1]); w.y = cvt_pk_bf16(v[2], v[3]); *(uint2*)p = w; }
;     DEV void operator()(int r, int c, f32x4 v) const { store_bf4(dst + (size_t)r * ld + c, v); }
;     DEV void operator()(int r, int c, f32x4 v) const {
;         const int row = m0 + r, col = n0 + c;
;         if (col < NPJ) {
;             store_bf4(proj + (size_t)row * NPJ + col, v);
;             const bool isconv = col < 3072, ispool = (col >= C_U && col < C_ZB);
;             if (isconv || ispool) {
;                 if (row < TP) {
;                     const int b = row >> 11, t = row & 2047;
;                     if (isconv) { if (t >= 2045) *(f32x4*)(out + O_CP + ((size_t)(b * 3 + (t - 2045))) * 3072 + col) = v; }
;                     else { if (t >= 2033) *(f32x4*)(out + O_PP + ((size_t)(b * 15 + (t - 2033))) * 1024 + (col - C_U)) = v; }
;                 } else {
;                     const int sb = (row - TP) >> 2, t = (row - TP) & 3;
;                     if (isconv) { if (t >= 1) *(f32x4*)(out + O_CS + ((size_t)(sb * 3 + (t - 1))) * 3072 + col) = v; }
;                     else *(f32x4*)(out + O_PS + ((size_t)(sb * 15 + 11 + t)) * 1024 + (col - C_U)) = v;
;                 }
.LBB0_232:
	s_andn2_saveexec_b64 s[8:9], s[8:9]
	s_cbranch_execz .LBB0_234
	v_mul_lo_u32 v83, v82, 15
	v_add3_u32 v74, v74, v83, 11
	v_lshlrev_b64 v[84:85], 12, v[74:75]
	v_lshl_add_u64 v[84:85], s[16:17], 0, v[84:85]
	v_lshl_add_u64 v[84:85], v[76:77], 2, v[84:85]
	v_add_co_u32_e32 v84, vcc, 0x9adc000, v84
	s_nop 1
	v_addc_co_u32_e32 v85, vcc, 0, v85, vcc
	global_store_dwordx4 v[84:85], v[62:65], off sc1
.LBB0_234:
	s_or_b64 exec, exec, s[6:7]
	s_nop 0
	v_or_b32_e32 v62, 16, v76
	v_cmp_lt_i32_e32 vcc, s62, v62
	s_and_b64 s[40:41], s[44:45], vcc
	v_cvt_pk_bf16_f32 v64, v58, v59
	v_cvt_pk_bf16_f32 v65, v60, v61
	v_cmp_gt_i32_e64 s[6:7], s61, v62
	s_nor_b64 s[10:11], s[12:13], s[40:41]
	global_store_dwordx2 v[78:79], v[64:65], off offset:32
	s_and_saveexec_b64 s[8:9], s[10:11]
	s_cbranch_execz .LBB0_241
	v_and_b32_e32 v63, 3, v80
	s_and_saveexec_b64 s[10:11], s[6:7]
	s_xor_b64 s[10:11], exec, s[10:11]
	s_cbranch_execz .LBB0_239
	v_cmp_ne_u32_e32 vcc, 0, v63
	s_and_saveexec_b64 s[42:43], vcc
	s_cbranch_execz .LBB0_238
	v_lshl_add_u32 v64, v82, 1, v82
	v_add3_u32 v63, v63, v64, -1
	v_mov_b64_e32 v[64:65], s[22:23]
	v_mad_u64_u32 v[64:65], s[46:47], v63, s58, v[64:65]
	v_lshl_add_u64 v[64:65], v[76:77], 2, v[64:65]
	global_store_dwordx4 v[64:65], v[58:61], off offset:64 sc1

; DEV void store_bf4(bf16_t* p, f32x4 v) { uint2 w; w.x = cvt_pk_bf16(v[0], v[1]); w.y = cvt_pk_bf16(v[2], v[3]); *(uint2*)p = w; }
;     DEV void operator()(int r, int c, f32x4 v) const { store_bf4(dst + (size_t)r * ld + c, v); }
;     DEV void operator()(int r, int c, f32x4 v) const {
;         const int row = m0 + r, col = n0 + c;
;         if (col < NPJ) {
;             store_bf4(proj + (size_t)row * NPJ + col, v);
;             const bool isconv = col < 3072, ispool = (col >= C_U && col < C_ZB);
;             if (isconv || ispool) {
;                 if (row < TP) {
;                     const int b = row >> 11, t = row & 2047;
;                     if (isconv) { if (t >= 2045) *(f32x4*)(out + O_CP + ((size_t)(b * 3 + (t - 2045))) * 3072 + col) = v; }
;                     else { if (t >= 2033) *(f32x4*)(out + O_PP + ((size_t)(b * 15 + (t - 2033))) * 1024 + (col - C_U)) = v; }
;                 } else {
;                     const int sb = (row - TP) >> 2, t = (row - TP) & 3;
;                     if (isconv) { if (t >= 1) *(f32x4*)(out + O_CS + ((size_t)(sb * 3 + (t - 1))) * 3072 + col) = v; }
;                     else *(f32x4*)(out + O_PS + ((size_t)(sb * 15 + 11 + t)) * 1024 + (col - C_U)) = v;
;                 }
.LBB0_239:
	s_andn2_saveexec_b64 s[10:11], s[10:11]
	s_cbranch_execz .LBB0_241
	v_mul_lo_u32 v64, v82, 15
	v_add3_u32 v74, v63, v64, 11
	v_lshlrev_b64 v[64:65], 12, v[74:75]
	v_lshl_add_u64 v[64:65], s[16:17], 0, v[64:65]
	v_lshl_add_u64 v[64:65], v[76:77], 2, v[64:65]
	v_add_co_u32_e32 v64, vcc, 0x9adc000, v64
	s_nop 1
	v_addc_co_u32_e32 v65, vcc, 0, v65, vcc
	global_store_dwordx4 v[64:65], v[58:61], off offset:64 sc1
.LBB0_241:
	s_or_b64 exec, exec, s[8:9]
	s_nop 0
	v_or_b32_e32 v58, 32, v76
	v_cmp_lt_i32_e32 vcc, s62, v58
	s_and_b64 s[42:43], s[44:45], vcc
	v_cvt_pk_bf16_f32 v60, v54, v55
	v_cvt_pk_bf16_f32 v61, v56, v57
	v_cmp_gt_i32_e64 s[8:9], s61, v58
	s_nor_b64 s[46:47], s[12:13], s[42:43]
	global_store_dwordx2 v[78:79], v[60:61], off offset:64
	s_and_saveexec_b64 s[10:11], s[46:47]
	s_cbranch_execz .LBB0_248
	v_and_b32_e32 v59, 3, v80
	s_and_saveexec_b64 s[46:47], s[8:9]
	s_xor_b64 s[46:47], exec, s[46:47]
	s_cbranch_execz .LBB0_246
	v_cmp_ne_u32_e32 vcc, 0, v59
	s_and_saveexec_b64 s[48:49], vcc
	s_cbranch_execz .LBB0_245
	v_lshl_add_u32 v60, v82, 1, v82
	v_add3_u32 v59, v59, v60, -1
	v_mov_b64_e32 v[60:61], s[22:23]
	v_mad_u64_u32 v[60:61], s[50:51], v59, s58, v[60:61]
	v_lshl_add_u64 v[60:61], v[76:77], 2, v[60:61]
	global_store_dwordx4 v[60:61], v[54:57], off offset:128 sc1

; DEV void store_bf4(bf16_t* p, f32x4 v) { uint2 w; w.x = cvt_pk_bf16(v[0], v[1]); w.y = cvt_pk_bf16(v[2], v[3]); *(uint2*)p = w; }
;     DEV void operator()(int r, int c, f32x4 v) const { store_bf4(dst + (size_t)r * ld + c, v); }
;     DEV void operator()(int r, int c, f32x4 v) const {
;         const int row = m0 + r, col = n0 + c;
;         if (col < NPJ) {
;             store_bf4(proj + (size_t)row * NPJ + col, v);
;             const bool isconv = col < 3072, ispool = (col >= C_U && col < C_ZB);
;             if (isconv || ispool) {
;                 if (row < TP) {
;                     const int b = row >> 11, t = row & 2047;
;                     if (isconv) { if (t >= 2045) *(f32x4*)(out + O_CP + ((size_t)(b * 3 + (t - 2045))) * 3072 + col) = v; }
;                     else { if (t >= 2033) *(f32x4*)(out + O_PP + ((size_t)(b * 15 + (t - 2033))) * 1024 + (col - C_U)) = v; }
;                 } else {
;                     const int sb = (row - TP) >> 2, t = (row - TP) & 3;
;                     if (isconv) { if (t >= 1) *(f32x4*)(out + O_CS + ((size_t)(sb * 3 + (t - 1))) * 3072 + col) = v; }
;                     else *(f32x4*)(out + O_PS + ((size_t)(sb * 15 + 11 + t)) * 1024 + (col - C_U)) = v;
;                 }
.LBB0_246:
	s_andn2_saveexec_b64 s[46:47], s[46:47]
	s_cbranch_execz .LBB0_248
	v_mul_lo_u32 v60, v82, 15
	v_add3_u32 v74, v59, v60, 11
	v_lshlrev_b64 v[60:61], 12, v[74:75]
	v_lshl_add_u64 v[60:61], s[16:17], 0, v[60:61]
	v_lshl_add_u64 v[60:61], v[76:77], 2, v[60:61]
	v_add_co_u32_e32 v60, vcc, 0x9adc000, v60
	s_nop 1
	v_addc_co_u32_e32 v61, vcc, 0, v61, vcc
	global_store_dwordx4 v[60:61], v[54:57], off offset:128 sc1
.LBB0_248:
	s_or_b64 exec, exec, s[10:11]
	s_nop 0
	v_or_b32_e32 v54, 48, v76
	v_cmp_lt_i32_e32 vcc, s62, v54
	s_and_b64 s[44:45], s[44:45], vcc
	v_cvt_pk_bf16_f32 v56, v50, v51
	v_cvt_pk_bf16_f32 v57, v52, v53
	v_cmp_gt_i32_e64 s[10:11], s61, v54
	s_nor_b64 s[46:47], s[12:13], s[44:45]
	global_store_dwordx2 v[78:79], v[56:57], off offset:96
	s_and_saveexec_b64 s[12:13], s[46:47]
	s_cbranch_execz .LBB0_255
	v_and_b32_e32 v55, 3, v80
	s_and_saveexec_b64 s[46:47], s[10:11]
	s_xor_b64 s[46:47], exec, s[46:47]
	s_cbranch_execz .LBB0_253
	v_cmp_ne_u32_e32 vcc, 0, v55
	s_and_saveexec_b64 s[48:49], vcc
	s_cbranch_execz .LBB0_252
	v_lshl_add_u32 v56, v82, 1, v82
	v_add3_u32 v55, v55, v56, -1
	v_mov_b64_e32 v[56:57], s[22:23]
	v_mad_u64_u32 v[56:57], s[50:51], v55, s58, v[56:57]
	v_lshl_add_u64 v[56:57], v[76:77], 2, v[56:57]
	global_store_dwordx4 v[56:57], v[50:53], off offset:192 sc1

; DEV void store_bf4(bf16_t* p, f32x4 v) { uint2 w; w.x = cvt_pk_bf16(v[0], v[1]); w.y = cvt_pk_bf16(v[2], v[3]); *(uint2*)p = w; }
;     DEV void operator()(int r, int c, f32x4 v) const { store_bf4(dst + (size_t)r * ld + c, v); }
;     DEV void operator()(int r, int c, f32x4 v) const {
;         const int row = m0 + r, col = n0 + c;
;         if (col < NPJ) {
;             store_bf4(proj + (size_t)row * NPJ + col, v);
;             const bool isconv = col < 3072, ispool = (col >= C_U && col < C_ZB);
;             if (isconv || ispool) {
;                 if (row < TP) {
;                     const int b = row >> 11, t = row & 2047;
;                     if (isconv) { if (t >= 2045) *(f32x4*)(out + O_CP + ((size_t)(b * 3 + (t - 2045))) * 3072 + col) = v; }
;                     else { if (t >= 2033) *(f32x4*)(out + O_PP + ((size_t)(b * 15 + (t - 2033))) * 1024 + (col - C_U)) = v; }
;                 } else {
;                     const int sb = (row - TP) >> 2, t = (row - TP) & 3;
;                     if (isconv) { if (t >= 1) *(f32x4*)(out + O_CS + ((size_t)(sb * 3 + (t - 1))) * 3072 + col) = v; }
;                     else *(f32x4*)(out + O_PS + ((size_t)(sb * 15 + 11 + t)) * 1024 + (col - C_U)) = v;
;                 }
.LBB0_253:
	s_andn2_saveexec_b64 s[46:47], s[46:47]
	s_cbranch_execz .LBB0_255
	v_mul_lo_u32 v56, v82, 15
	v_add3_u32 v74, v55, v56, 11
	v_lshlrev_b64 v[56:57], 12, v[74:75]
	v_lshl_add_u64 v[56:57], s[16:17], 0, v[56:57]
	v_lshl_add_u64 v[56:57], v[76:77], 2, v[56:57]
	v_add_co_u32_e32 v56, vcc, 0x9adc000, v56
	s_nop 1
	v_addc_co_u32_e32 v57, vcc, 0, v57, vcc
	global_store_dwordx4 v[56:57], v[50:53], off offset:192 sc1
.LBB0_255:
	s_or_b64 exec, exec, s[12:13]
	v_add3_u32 v55, s68, v81, 16
	v_mad_i64_i32 v[50:51], s[12:13], v55, s58, v[172:173]
	v_lshl_add_u64 v[50:51], v[76:77], 1, v[50:51]
	v_cvt_pk_bf16_f32 v52, v46, v47
	v_cvt_pk_bf16_f32 v53, v48, v49
	global_store_dwordx2 v[50:51], v[52:53], off
	v_cmp_gt_i32_e64 s[12:13], s57, v55
	v_add_u32_e32 v52, 0xffffe000, v55
	s_nor_b64 s[48:49], s[12:13], s[38:39]
	v_lshrrev_b32_e32 v52, 2, v52
	s_and_saveexec_b64 s[46:47], s[48:49]
	s_cbranch_execz .LBB0_262
	v_and_b32_e32 v53, 3, v80
	s_and_saveexec_b64 s[48:49], s[4:5]
	s_xor_b64 s[48:49], exec, s[48:49]
	s_cbranch_execz .LBB0_260
	v_cmp_ne_u32_e32 vcc, 0, v53
	s_and_saveexec_b64 s[50:51], vcc
	s_cbranch_execz .LBB0_259
	v_lshl_add_u32 v55, v52, 1, v52
	v_add3_u32 v53, v53, v55, -1
	v_mov_b64_e32 v[56:57], s[22:23]
	v_mad_u64_u32 v[56:57], s[70:71], v53, s58, v[56:57]
	v_lshl_add_u64 v[56:57], v[76:77], 2, v[56:57]
	global_store_dwordx4 v[56:57], v[46:49], off sc1

; DEV void store_bf4(bf16_t* p, f32x4 v) { uint2 w; w.x = cvt_pk_bf16(v[0], v[1]); w.y = cvt_pk_bf16(v[2], v[3]); *(uint2*)p = w; }
;     DEV void operator()(int r, int c, f32x4 v) const { store_bf4(dst + (size_t)r * ld + c, v); }
;     DEV void operator()(int r, int c, f32x4 v) const {
;         const int row = m0 + r, col = n0 + c;
;         if (col < NPJ) {
;             store_bf4(proj + (size_t)row * NPJ + col, v);
;             const bool isconv = col < 3072, ispool = (col >= C_U && col < C_ZB);
;             if (isconv || ispool) {
;                 if (row < TP) {
;                     const int b = row >> 11, t = row & 2047;
;                     if (isconv) { if (t >= 2045) *(f32x4*)(out + O_CP + ((size_t)(b * 3 + (t - 2045))) * 3072 + col) = v; }
;                     else { if (t >= 2033) *(f32x4*)(out + O_PP + ((size_t)(b * 15 + (t - 2033))) * 1024 + (col - C_U)) = v; }
;                 } else {
;                     const int sb = (row - TP) >> 2, t = (row - TP) & 3;
;                     if (isconv) { if (t >= 1) *(f32x4*)(out + O_CS + ((size_t)(sb * 3 + (t - 1))) * 3072 + col) = v; }
;                     else *(f32x4*)(out + O_PS + ((size_t)(sb * 15 + 11 + t)) * 1024 + (col - C_U)) = v;
;                 }
.LBB0_260:
	s_andn2_saveexec_b64 s[48:49], s[48:49]
	s_cbranch_execz .LBB0_262
	v_mul_lo_u32 v55, v52, 15
	v_add3_u32 v74, v53, v55, 11
	v_lshlrev_b64 v[56:57], 12, v[74:75]
	v_lshl_add_u64 v[56:57], s[16:17], 0, v[56:57]
	v_lshl_add_u64 v[56:57], v[76:77], 2, v[56:57]
	v_add_co_u32_e32 v56, vcc, 0x9adc000, v56
	s_nop 1
	v_addc_co_u32_e32 v57, vcc, 0, v57, vcc
	global_store_dwordx4 v[56:57], v[46:49], off sc1
.LBB0_262:
	s_or_b64 exec, exec, s[46:47]
	s_nop 0
	v_cvt_pk_bf16_f32 v46, v42, v43
	v_cvt_pk_bf16_f32 v47, v44, v45
	s_nor_b64 s[48:49], s[12:13], s[40:41]
	global_store_dwordx2 v[50:51], v[46:47], off offset:32
	s_and_saveexec_b64 s[46:47], s[48:49]
	s_cbranch_execz .LBB0_269
	v_and_b32_e32 v46, 3, v80
	s_and_saveexec_b64 s[48:49], s[6:7]
	s_xor_b64 s[48:49], exec, s[48:49]
	s_cbranch_execz .LBB0_267
	v_cmp_ne_u32_e32 vcc, 0, v46
	s_and_saveexec_b64 s[50:51], vcc
	s_cbranch_execz .LBB0_266
	v_lshl_add_u32 v47, v52, 1, v52
	v_add3_u32 v48, v46, v47, -1
	v_mov_b64_e32 v[46:47], s[22:23]
	v_mad_u64_u32 v[46:47], s[70:71], v48, s58, v[46:47]
	v_lshl_add_u64 v[46:47], v[76:77], 2, v[46:47]
	global_store_dwordx4 v[46:47], v[42:45], off offset:64 sc1

; DEV void store_bf4(bf16_t* p, f32x4 v) { uint2 w; w.x = cvt_pk_bf16(v[0], v[1]); w.y = cvt_pk_bf16(v[2], v[3]); *(uint2*)p = w; }
;     DEV void operator()(int r, int c, f32x4 v) const { store_bf4(dst + (size_t)r * ld + c, v); }
;     DEV void operator()(int r, int c, f32x4 v) const {
;         const int row = m0 + r, col = n0 + c;
;         if (col < NPJ) {
;             store_bf4(proj + (size_t)row * NPJ + col, v);
;             const bool isconv = col < 3072, ispool = (col >= C_U && col < C_ZB);
;             if (isconv || ispool) {
;                 if (row < TP) {
;                     const int b = row >> 11, t = row & 2047;
;                     if (isconv) { if (t >= 2045) *(f32x4*)(out + O_CP + ((size_t)(b * 3 + (t - 2045))) * 3072 + col) = v; }
;                     else { if (t >= 2033) *(f32x4*)(out + O_PP + ((size_t)(b * 15 + (t - 2033))) * 1024 + (col - C_U)) = v; }
;                 } else {
;                     const int sb = (row - TP) >> 2, t = (row - TP) & 3;
;                     if (isconv) { if (t >= 1) *(f32x4*)(out + O_CS + ((size_t)(sb * 3 + (t - 1))) * 3072 + col) = v; }
;                     else *(f32x4*)(out + O_PS + ((size_t)(sb * 15 + 11 + t)) * 1024 + (col - C_U)) = v;
;                 }
.LBB0_267:
	s_andn2_saveexec_b64 s[48:49], s[48:49]
	s_cbranch_execz .LBB0_269
	v_mul_lo_u32 v47, v52, 15
	v_add3_u32 v74, v46, v47, 11
	v_lshlrev_b64 v[46:47], 12, v[74:75]
	v_lshl_add_u64 v[46:47], s[16:17], 0, v[46:47]
	v_lshl_add_u64 v[46:47], v[76:77], 2, v[46:47]
	v_add_co_u32_e32 v46, vcc, 0x9adc000, v46
	s_nop 1
	v_addc_co_u32_e32 v47, vcc, 0, v47, vcc
	global_store_dwordx4 v[46:47], v[42:45], off offset:64 sc1
.LBB0_269:
	s_or_b64 exec, exec, s[46:47]
	s_nop 0
	v_cvt_pk_bf16_f32 v42, v38, v39
	v_cvt_pk_bf16_f32 v43, v40, v41
	s_nor_b64 s[48:49], s[12:13], s[42:43]
	global_store_dwordx2 v[50:51], v[42:43], off offset:64
	s_and_saveexec_b64 s[46:47], s[48:49]
	s_cbranch_execz .LBB0_276
	v_and_b32_e32 v42, 3, v80
	s_and_saveexec_b64 s[48:49], s[8:9]
	s_xor_b64 s[48:49], exec, s[48:49]
	s_cbranch_execz .LBB0_274
	v_cmp_ne_u32_e32 vcc, 0, v42
	s_and_saveexec_b64 s[50:51], vcc
	s_cbranch_execz .LBB0_273
	v_lshl_add_u32 v43, v52, 1, v52
	v_add3_u32 v44, v42, v43, -1
	v_mov_b64_e32 v[42:43], s[22:23]
	v_mad_u64_u32 v[42:43], s[70:71], v44, s58, v[42:43]
	v_lshl_add_u64 v[42:43], v[76:77], 2, v[42:43]
	global_store_dwordx4 v[42:43], v[38:41], off offset:128 sc1

; DEV void store_bf4(bf16_t* p, f32x4 v) { uint2 w; w.x = cvt_pk_bf16(v[0], v[1]); w.y = cvt_pk_bf16(v[2], v[3]); *(uint2*)p = w; }
;     DEV void operator()(int r, int c, f32x4 v) const { store_bf4(dst + (size_t)r * ld + c, v); }
;     DEV void operator()(int r, int c, f32x4 v) const {
;         const int row = m0 + r, col = n0 + c;
;         if (col < NPJ) {
;             store_bf4(proj + (size_t)row * NPJ + col, v);
;             const bool isconv = col < 3072, ispool = (col >= C_U && col < C_ZB);
;             if (isconv || ispool) {
;                 if (row < TP) {
;                     const int b = row >> 11, t = row & 2047;
;                     if (isconv) { if (t >= 2045) *(f32x4*)(out + O_CP + ((size_t)(b * 3 + (t - 2045))) * 3072 + col) = v; }
;                     else { if (t >= 2033) *(f32x4*)(out + O_PP + ((size_t)(b * 15 + (t - 2033))) * 1024 + (col - C_U)) = v; }
;                 } else {
;                     const int sb = (row - TP) >> 2, t = (row - TP) & 3;
;                     if (isconv) { if (t >= 1) *(f32x4*)(out + O_CS + ((size_t)(sb * 3 + (t - 1))) * 3072 + col) = v; }
;                     else *(f32x4*)(out + O_PS + ((size_t)(sb * 15 + 11 + t)) * 1024 + (col - C_U)) = v;
;                 }
.LBB0_274:
	s_andn2_saveexec_b64 s[48:49], s[48:49]
	s_cbranch_execz .LBB0_276
	v_mul_lo_u32 v43, v52, 15
	v_add3_u32 v74, v42, v43, 11
	v_lshlrev_b64 v[42:43], 12, v[74:75]
	v_lshl_add_u64 v[42:43], s[16:17], 0, v[42:43]
	v_lshl_add_u64 v[42:43], v[76:77], 2, v[42:43]
	v_add_co_u32_e32 v42, vcc, 0x9adc000, v42
	s_nop 1
	v_addc_co_u32_e32 v43, vcc, 0, v43, vcc
	global_store_dwordx4 v[42:43], v[38:41], off offset:128 sc1
.LBB0_276:
	s_or_b64 exec, exec, s[46:47]
	s_nop 0
	v_cvt_pk_bf16_f32 v38, v34, v35
	v_cvt_pk_bf16_f32 v39, v36, v37
	s_nor_b64 s[46:47], s[12:13], s[44:45]
	global_store_dwordx2 v[50:51], v[38:39], off offset:96
	s_and_saveexec_b64 s[12:13], s[46:47]
	s_cbranch_execz .LBB0_283
	v_and_b32_e32 v38, 3, v80
	s_and_saveexec_b64 s[46:47], s[10:11]
	s_xor_b64 s[46:47], exec, s[46:47]
	s_cbranch_execz .LBB0_281
	v_cmp_ne_u32_e32 vcc, 0, v38
	s_and_saveexec_b64 s[48:49], vcc
	s_cbranch_execz .LBB0_280
	v_lshl_add_u32 v39, v52, 1, v52
	v_add3_u32 v40, v38, v39, -1
	v_mov_b64_e32 v[38:39], s[22:23]
	v_mad_u64_u32 v[38:39], s[50:51], v40, s58, v[38:39]
	v_lshl_add_u64 v[38:39], v[76:77], 2, v[38:39]
	global_store_dwordx4 v[38:39], v[34:37], off offset:192 sc1

; DEV void store_bf4(bf16_t* p, f32x4 v) { uint2 w; w.x = cvt_pk_bf16(v[0], v[1]); w.y = cvt_pk_bf16(v[2], v[3]); *(uint2*)p = w; }
;     DEV void operator()(int r, int c, f32x4 v) const { store_bf4(dst + (size_t)r * ld + c, v); }
;     DEV void operator()(int r, int c, f32x4 v) const {
;         const int row = m0 + r, col = n0 + c;
;         if (col < NPJ) {
;             store_bf4(proj + (size_t)row * NPJ + col, v);
;             const bool isconv = col < 3072, ispool = (col >= C_U && col < C_ZB);
;             if (isconv || ispool) {
;                 if (row < TP) {
;                     const int b = row >> 11, t = row & 2047;
;                     if (isconv) { if (t >= 2045) *(f32x4*)(out + O_CP + ((size_t)(b * 3 + (t - 2045))) * 3072 + col) = v; }
;                     else { if (t >= 2033) *(f32x4*)(out + O_PP + ((size_t)(b * 15 + (t - 2033))) * 1024 + (col - C_U)) = v; }
;                 } else {
;                     const int sb = (row - TP) >> 2, t = (row - TP) & 3;
;                     if (isconv) { if (t >= 1) *(f32x4*)(out + O_CS + ((size_t)(sb * 3 + (t - 1))) * 3072 + col) = v; }
;                     else *(f32x4*)(out + O_PS + ((size_t)(sb * 15 + 11 + t)) * 1024 + (col - C_U)) = v;
;                 }
.LBB0_281:
	s_andn2_saveexec_b64 s[46:47], s[46:47]
	s_cbranch_execz .LBB0_283
	v_mul_lo_u32 v39, v52, 15
	v_add3_u32 v74, v38, v39, 11
	v_lshlrev_b64 v[38:39], 12, v[74:75]
	v_lshl_add_u64 v[38:39], s[16:17], 0, v[38:39]
	v_lshl_add_u64 v[38:39], v[76:77], 2, v[38:39]
	v_add_co_u32_e32 v38, vcc, 0x9adc000, v38
	s_nop 1
	v_addc_co_u32_e32 v39, vcc, 0, v39, vcc
	global_store_dwordx4 v[38:39], v[34:37], off offset:192 sc1
.LBB0_283:
	s_or_b64 exec, exec, s[12:13]
	v_add3_u32 v38, s68, v81, 32
	v_mad_i64_i32 v[34:35], s[12:13], v38, s58, v[172:173]
	v_lshl_add_u64 v[34:35], v[76:77], 1, v[34:35]
	v_cvt_pk_bf16_f32 v36, v30, v31
	v_cvt_pk_bf16_f32 v37, v32, v33
	global_store_dwordx2 v[34:35], v[36:37], off
	v_cmp_gt_i32_e64 s[12:13], s57, v38
	v_add_u32_e32 v36, 0xffffe000, v38
	s_nor_b64 s[46:47], s[12:13], s[38:39]
	v_lshrrev_b32_e32 v36, 2, v36
	s_and_saveexec_b64 s[38:39], s[46:47]
	s_cbranch_execz .LBB0_290
	v_and_b32_e32 v37, 3, v80
	s_and_saveexec_b64 s[46:47], s[4:5]
	s_xor_b64 s[4:5], exec, s[46:47]
	s_cbranch_execz .LBB0_288
	v_cmp_ne_u32_e32 vcc, 0, v37
	s_and_saveexec_b64 s[46:47], vcc
	s_cbranch_execz .LBB0_287
	v_lshl_add_u32 v38, v36, 1, v36
	v_add3_u32 v37, v37, v38, -1
	v_mov_b64_e32 v[38:39], s[22:23]
	v_mad_u64_u32 v[38:39], s[48:49], v37, s58, v[38:39]
	v_lshl_add_u64 v[38:39], v[76:77], 2, v[38:39]
	global_store_dwordx4 v[38:39], v[30:33], off sc1

; DEV void store_bf4(bf16_t* p, f32x4 v) { uint2 w; w.x = cvt_pk_bf16(v[0], v[1]); w.y = cvt_pk_bf16(v[2], v[3]); *(uint2*)p = w; }
;     DEV void operator()(int r, int c, f32x4 v) const { store_bf4(dst + (size_t)r * ld + c, v); }
;     DEV void operator()(int r, int c, f32x4 v) const {
;         const int row = m0 + r, col = n0 + c;
;         if (col < NPJ) {
;             store_bf4(proj + (size_t)row * NPJ + col, v);
;             const bool isconv = col < 3072, ispool = (col >= C_U && col < C_ZB);
;             if (isconv || ispool) {
;                 if (row < TP) {
;                     const int b = row >> 11, t = row & 2047;
;                     if (isconv) { if (t >= 2045) *(f32x4*)(out + O_CP + ((size_t)(b * 3 + (t - 2045))) * 3072 + col) = v; }
;                     else { if (t >= 2033) *(f32x4*)(out + O_PP + ((size_t)(b * 15 + (t - 2033))) * 1024 + (col - C_U)) = v; }
;                 } else {
;                     const int sb = (row - TP) >> 2, t = (row - TP) & 3;
;                     if (isconv) { if (t >= 1) *(f32x4*)(out + O_CS + ((size_t)(sb * 3 + (t - 1))) * 3072 + col) = v; }
;                     else *(f32x4*)(out + O_PS + ((size_t)(sb * 15 + 11 + t)) * 1024 + (col - C_U)) = v;
;                 }
.LBB0_288:
	s_andn2_saveexec_b64 s[4:5], s[4:5]
	s_cbranch_execz .LBB0_290
	v_mul_lo_u32 v38, v36, 15
	v_add3_u32 v74, v37, v38, 11
	v_lshlrev_b64 v[38:39], 12, v[74:75]
	v_lshl_add_u64 v[38:39], s[16:17], 0, v[38:39]
	v_lshl_add_u64 v[38:39], v[76:77], 2, v[38:39]
	v_add_co_u32_e32 v38, vcc, 0x9adc000, v38
	s_nop 1
	v_addc_co_u32_e32 v39, vcc, 0, v39, vcc
	global_store_dwordx4 v[38:39], v[30:33], off sc1
.LBB0_290:
	s_or_b64 exec, exec, s[38:39]
	s_nop 0
	v_cvt_pk_bf16_f32 v30, v26, v27
	v_cvt_pk_bf16_f32 v31, v28, v29
	s_nor_b64 s[38:39], s[12:13], s[40:41]
	global_store_dwordx2 v[34:35], v[30:31], off offset:32
	s_and_saveexec_b64 s[4:5], s[38:39]
	s_cbranch_execz .LBB0_297
	v_and_b32_e32 v30, 3, v80
	s_and_saveexec_b64 s[38:39], s[6:7]
	s_xor_b64 s[6:7], exec, s[38:39]
	s_cbranch_execz .LBB0_295
	v_cmp_ne_u32_e32 vcc, 0, v30
	s_and_saveexec_b64 s[38:39], vcc
	s_cbranch_execz .LBB0_294
	v_lshl_add_u32 v31, v36, 1, v36
	v_add3_u32 v32, v30, v31, -1
	v_mov_b64_e32 v[30:31], s[22:23]
	v_mad_u64_u32 v[30:31], s[40:41], v32, s58, v[30:31]
	v_lshl_add_u64 v[30:31], v[76:77], 2, v[30:31]
	global_store_dwordx4 v[30:31], v[26:29], off offset:64 sc1

; DEV void store_bf4(bf16_t* p, f32x4 v) { uint2 w; w.x = cvt_pk_bf16(v[0], v[1]); w.y = cvt_pk_bf16(v[2], v[3]); *(uint2*)p = w; }
;     DEV void operator()(int r, int c, f32x4 v) const { store_bf4(dst + (size_t)r * ld + c, v); }
;     DEV void operator()(int r, int c, f32x4 v) const {
;         const int row = m0 + r, col = n0 + c;
;         if (col < NPJ) {
;             store_bf4(proj + (size_t)row * NPJ + col, v);
;             const bool isconv = col < 3072, ispool = (col >= C_U && col < C_ZB);
;             if (isconv || ispool) {
;                 if (row < TP) {
;                     const int b = row >> 11, t = row & 2047;
;                     if (isconv) { if (t >= 2045) *(f32x4*)(out + O_CP + ((size_t)(b * 3 + (t - 2045))) * 3072 + col) = v; }
;                     else { if (t >= 2033) *(f32x4*)(out + O_PP + ((size_t)(b * 15 + (t - 2033))) * 1024 + (col - C_U)) = v; }
;                 } else {
;                     const int sb = (row - TP) >> 2, t = (row - TP) & 3;
;                     if (isconv) { if (t >= 1) *(f32x4*)(out + O_CS + ((size_t)(sb * 3 + (t - 1))) * 3072 + col) = v; }
;                     else *(f32x4*)(out + O_PS + ((size_t)(sb * 15 + 11 + t)) * 1024 + (col - C_U)) = v;
;                 }
.LBB0_295:
	s_andn2_saveexec_b64 s[6:7], s[6:7]
	s_cbranch_execz .LBB0_297
	v_mul_lo_u32 v31, v36, 15
	v_add3_u32 v74, v30, v31, 11
	v_lshlrev_b64 v[30:31], 12, v[74:75]
	v_lshl_add_u64 v[30:31], s[16:17], 0, v[30:31]
	v_lshl_add_u64 v[30:31], v[76:77], 2, v[30:31]
	v_add_co_u32_e32 v30, vcc, 0x9adc000, v30
	s_nop 1
	v_addc_co_u32_e32 v31, vcc, 0, v31, vcc
	global_store_dwordx4 v[30:31], v[26:29], off offset:64 sc1
.LBB0_297:
	s_or_b64 exec, exec, s[4:5]
	s_nop 0
	v_cvt_pk_bf16_f32 v26, v22, v23
	v_cvt_pk_bf16_f32 v27, v24, v25
	s_nor_b64 s[6:7], s[12:13], s[42:43]
	global_store_dwordx2 v[34:35], v[26:27], off offset:64
	s_and_saveexec_b64 s[4:5], s[6:7]
	s_cbranch_execz .LBB0_304
	v_and_b32_e32 v26, 3, v80
	s_and_saveexec_b64 s[6:7], s[8:9]
	s_xor_b64 s[6:7], exec, s[6:7]
	s_cbranch_execz .LBB0_302
	v_cmp_ne_u32_e32 vcc, 0, v26
	s_and_saveexec_b64 s[8:9], vcc
	s_cbranch_execz .LBB0_301
	v_lshl_add_u32 v27, v36, 1, v36
	v_add3_u32 v28, v26, v27, -1
	v_mov_b64_e32 v[26:27], s[22:23]
	v_mad_u64_u32 v[26:27], s[38:39], v28, s58, v[26:27]
	v_lshl_add_u64 v[26:27], v[76:77], 2, v[26:27]
	global_store_dwordx4 v[26:27], v[22:25], off offset:128 sc1

; DEV void store_bf4(bf16_t* p, f32x4 v) { uint2 w; w.x = cvt_pk_bf16(v[0], v[1]); w.y = cvt_pk_bf16(v[2], v[3]); *(uint2*)p = w; }
;     DEV void operator()(int r, int c, f32x4 v) const { store_bf4(dst + (size_t)r * ld + c, v); }
;     DEV void operator()(int r, int c, f32x4 v) const {
;         const int row = m0 + r, col = n0 + c;
;         if (col < NPJ) {
;             store_bf4(proj + (size_t)row * NPJ + col, v);
;             const bool isconv = col < 3072, ispool = (col >= C_U && col < C_ZB);
;             if (isconv || ispool) {
;                 if (row < TP) {
;                     const int b = row >> 11, t = row & 2047;
;                     if (isconv) { if (t >= 2045) *(f32x4*)(out + O_CP + ((size_t)(b * 3 + (t - 2045))) * 3072 + col) = v; }
;                     else { if (t >= 2033) *(f32x4*)(out + O_PP + ((size_t)(b * 15 + (t - 2033))) * 1024 + (col - C_U)) = v; }
;                 } else {
;                     const int sb = (row - TP) >> 2, t = (row - TP) & 3;
;                     if (isconv) { if (t >= 1) *(f32x4*)(out + O_CS + ((size_t)(sb * 3 + (t - 1))) * 3072 + col) = v; }
;                     else *(f32x4*)(out + O_PS + ((size_t)(sb * 15 + 11 + t)) * 1024 + (col - C_U)) = v;
;                 }
.LBB0_302:
	s_andn2_saveexec_b64 s[6:7], s[6:7]
	s_cbranch_execz .LBB0_304
	v_mul_lo_u32 v27, v36, 15
	v_add3_u32 v74, v26, v27, 11
	v_lshlrev_b64 v[26:27], 12, v[74:75]
	v_lshl_add_u64 v[26:27], s[16:17], 0, v[26:27]
	v_lshl_add_u64 v[26:27], v[76:77], 2, v[26:27]
	v_add_co_u32_e32 v26, vcc, 0x9adc000, v26
	s_nop 1
	v_addc_co_u32_e32 v27, vcc, 0, v27, vcc
	global_store_dwordx4 v[26:27], v[22:25], off offset:128 sc1
.LBB0_304:
	s_or_b64 exec, exec, s[4:5]
	s_nop 0
	v_cvt_pk_bf16_f32 v22, v18, v19
	v_cvt_pk_bf16_f32 v23, v20, v21
	s_nor_b64 s[6:7], s[12:13], s[44:45]
	global_store_dwordx2 v[34:35], v[22:23], off offset:96
	s_and_saveexec_b64 s[4:5], s[6:7]
	s_cbranch_execz .LBB0_311
	v_and_b32_e32 v22, 3, v80
	s_and_saveexec_b64 s[6:7], s[10:11]
	s_xor_b64 s[6:7], exec, s[6:7]
	s_cbranch_execz .LBB0_309
	v_cmp_ne_u32_e32 vcc, 0, v22
	s_and_saveexec_b64 s[8:9], vcc
	s_cbranch_execz .LBB0_308
	v_lshl_add_u32 v23, v36, 1, v36
	v_add3_u32 v24, v22, v23, -1
	v_mov_b64_e32 v[22:23], s[22:23]
	v_mad_u64_u32 v[22:23], s[10:11], v24, s58, v[22:23]
	v_lshl_add_u64 v[22:23], v[76:77], 2, v[22:23]
	global_store_dwordx4 v[22:23], v[18:21], off offset:192 sc1

; DEV void store_bf4(bf16_t* p, f32x4 v) { uint2 w; w.x = cvt_pk_bf16(v[0], v[1]); w.y = cvt_pk_bf16(v[2], v[3]); *(uint2*)p = w; }
;     DEV void operator()(int r, int c, f32x4 v) const { store_bf4(dst + (size_t)r * ld + c, v); }
;     DEV void operator()(int r, int c, f32x4 v) const {
;         const int row = m0 + r, col = n0 + c;
;         if (col < NPJ) {
;             store_bf4(proj + (size_t)row * NPJ + col, v);
;             const bool isconv = col < 3072, ispool = (col >= C_U && col < C_ZB);
;             if (isconv || ispool) {
;                 if (row < TP) {
;                     const int b = row >> 11, t = row & 2047;
;                     if (isconv) { if (t >= 2045) *(f32x4*)(out + O_CP + ((size_t)(b * 3 + (t - 2045))) * 3072 + col) = v; }
;                     else { if (t >= 2033) *(f32x4*)(out + O_PP + ((size_t)(b * 15 + (t - 2033))) * 1024 + (col - C_U)) = v; }
;                 } else {
;                     const int sb = (row - TP) >> 2, t = (row - TP) & 3;
;                     if (isconv) { if (t >= 1) *(f32x4*)(out + O_CS + ((size_t)(sb * 3 + (t - 1))) * 3072 + col) = v; }
;                     else *(f32x4*)(out + O_PS + ((size_t)(sb * 15 + 11 + t)) * 1024 + (col - C_U)) = v;
;                 }
.LBB0_309:
	s_andn2_saveexec_b64 s[6:7], s[6:7]
	s_cbranch_execz .LBB0_311
	v_mul_lo_u32 v23, v36, 15
	v_add3_u32 v74, v22, v23, 11
	v_lshlrev_b64 v[22:23], 12, v[74:75]
	v_lshl_add_u64 v[22:23], s[16:17], 0, v[22:23]
	v_lshl_add_u64 v[22:23], v[76:77], 2, v[22:23]
	v_add_co_u32_e32 v22, vcc, 0x9adc000, v22
	s_nop 1
	v_addc_co_u32_e32 v23, vcc, 0, v23, vcc
	global_store_dwordx4 v[22:23], v[18:21], off offset:192 sc1
.LBB0_311:
	s_or_b64 exec, exec, s[4:5]
	s_nop 0
	v_add3_u32 v20, s68, v81, 48
	s_cmpk_eq_i32 s26, 0x80
	v_mad_i64_i32 v[18:19], s[4:5], v20, s58, v[172:173]
	v_cmp_gt_i32_e32 vcc, s61, v76
	s_cselect_b64 s[6:7], -1, 0
	v_lshl_add_u64 v[18:19], v[76:77], 1, v[18:19]
	v_cvt_pk_bf16_f32 v22, v14, v15
	v_cvt_pk_bf16_f32 v23, v16, v17
	v_cmp_lt_i32_e64 s[4:5], s62, v76
	s_or_b64 s[10:11], s[6:7], vcc
	global_store_dwordx2 v[18:19], v[22:23], off
	s_and_saveexec_b64 s[8:9], s[10:11]
	s_cbranch_execz .LBB0_328
	v_cmp_lt_i32_e32 vcc, s63, v20
	s_and_saveexec_b64 s[10:11], vcc
	s_xor_b64 s[10:11], exec, s[10:11]
	s_cbranch_execz .LBB0_320
	v_add_u32_e32 v21, 0xffffe000, v20
	v_lshrrev_b32_e32 v22, 2, v21
	v_and_b32_e32 v21, 3, v80
	s_and_saveexec_b64 s[12:13], s[4:5]
	s_xor_b64 s[12:13], exec, s[12:13]
	s_cbranch_execz .LBB0_315
	v_mul_lo_u32 v22, v22, 15
	v_add3_u32 v74, v21, v22, 11
	v_lshlrev_b64 v[22:23], 12, v[74:75]
	v_lshl_add_u64 v[22:23], s[16:17], 0, v[22:23]
	v_lshl_add_u64 v[22:23], v[76:77], 2, v[22:23]
	v_add_co_u32_e32 v22, vcc, 0x9adc000, v22
	s_nop 1
	v_addc_co_u32_e32 v23, vcc, 0, v23, vcc
	global_store_dwordx4 v[22:23], v[14:17], off sc1
.LBB0_315:
	s_andn2_saveexec_b64 s[12:13], s[12:13]
	s_cbranch_execz .LBB0_319
	v_cmp_ne_u32_e32 vcc, 0, v21
	s_and_saveexec_b64 s[38:39], vcc
	s_cbranch_execz .LBB0_318
	v_lshl_add_u32 v22, v22, 1, v22
	v_add3_u32 v21, v21, v22, -1
	v_mov_b64_e32 v[22:23], s[22:23]
	v_mad_u64_u32 v[22:23], s[40:41], v21, s58, v[22:23]
	v_lshl_add_u64 v[22:23], v[76:77], 2, v[22:23]
	global_store_dwordx4 v[22:23], v[14:17], off sc1

; DEV void store_bf4(bf16_t* p, f32x4 v) { uint2 w; w.x = cvt_pk_bf16(v[0], v[1]); w.y = cvt_pk_bf16(v[2], v[3]); *(uint2*)p = w; }
;     DEV void operator()(int r, int c, f32x4 v) const { store_bf4(dst + (size_t)r * ld + c, v); }
;     DEV void operator()(int r, int c, f32x4 v) const {
;         const int row = m0 + r, col = n0 + c;
;         if (col < NPJ) {
;             store_bf4(proj + (size_t)row * NPJ + col, v);
;             const bool isconv = col < 3072, ispool = (col >= C_U && col < C_ZB);
;             if (isconv || ispool) {
;                 if (row < TP) {
;                     const int b = row >> 11, t = row & 2047;
;                     if (isconv) { if (t >= 2045) *(f32x4*)(out + O_CP + ((size_t)(b * 3 + (t - 2045))) * 3072 + col) = v; }
;                     else { if (t >= 2033) *(f32x4*)(out + O_PP + ((size_t)(b * 15 + (t - 2033))) * 1024 + (col - C_U)) = v; }
;                 } else {
;                     const int sb = (row - TP) >> 2, t = (row - TP) & 3;
;                     if (isconv) { if (t >= 1) *(f32x4*)(out + O_CS + ((size_t)(sb * 3 + (t - 1))) * 3072 + col) = v; }
;                     else *(f32x4*)(out + O_PS + ((size_t)(sb * 15 + 11 + t)) * 1024 + (col - C_U)) = v;
;                 }
.LBB0_320:
	s_andn2_saveexec_b64 s[10:11], s[10:11]
	s_cbranch_execz .LBB0_328
	v_ashrrev_i32_e32 v22, 11, v20
	v_and_b32_e32 v21, 0x7ff, v20
	s_and_saveexec_b64 s[10:11], s[4:5]
	s_xor_b64 s[4:5], exec, s[10:11]
	s_cbranch_execz .LBB0_325
	v_cmp_lt_u32_e32 vcc, s64, v21
	s_and_saveexec_b64 s[10:11], vcc
	s_cbranch_execz .LBB0_324
	v_mul_i32_i24_e32 v22, 15, v22
	v_add3_u32 v22, v21, v22, s65
	v_ashrrev_i32_e32 v23, 31, v22
	v_lshlrev_b64 v[22:23], 12, v[22:23]
	v_lshl_add_u64 v[22:23], s[16:17], 0, v[22:23]
	v_lshl_add_u64 v[22:23], v[76:77], 2, v[22:23]
	v_add_co_u32_e32 v22, vcc, 0x5620000, v22
	s_nop 1
	v_addc_co_u32_e32 v23, vcc, 0, v23, vcc
	global_store_dwordx4 v[22:23], v[14:17], off sc1

; DEV void store_bf4(bf16_t* p, f32x4 v) { uint2 w; w.x = cvt_pk_bf16(v[0], v[1]); w.y = cvt_pk_bf16(v[2], v[3]); *(uint2*)p = w; }
;     DEV void operator()(int r, int c, f32x4 v) const { store_bf4(dst + (size_t)r * ld + c, v); }
;     DEV void operator()(int r, int c, f32x4 v) const {
;         const int row = m0 + r, col = n0 + c;
;         if (col < NPJ) {
;             store_bf4(proj + (size_t)row * NPJ + col, v);
;             const bool isconv = col < 3072, ispool = (col >= C_U && col < C_ZB);
;             if (isconv || ispool) {
;                 if (row < TP) {
;                     const int b = row >> 11, t = row & 2047;
;                     if (isconv) { if (t >= 2045) *(f32x4*)(out + O_CP + ((size_t)(b * 3 + (t - 2045))) * 3072 + col) = v; }
;                     else { if (t >= 2033) *(f32x4*)(out + O_PP + ((size_t)(b * 15 + (t - 2033))) * 1024 + (col - C_U)) = v; }
;                 } else {
;                     const int sb = (row - TP) >> 2, t = (row - TP) & 3;
;                     if (isconv) { if (t >= 1) *(f32x4*)(out + O_CS + ((size_t)(sb * 3 + (t - 1))) * 3072 + col) = v; }
;                     else *(f32x4*)(out + O_PS + ((size_t)(sb * 15 + 11 + t)) * 1024 + (col - C_U)) = v;
;                 }
.LBB0_325:
	s_andn2_saveexec_b64 s[4:5], s[4:5]
	s_cbranch_execz .LBB0_328
	v_cmp_lt_u32_e32 vcc, s66, v21
	s_and_b64 exec, exec, vcc
	s_cbranch_execz .LBB0_328
	v_mul_i32_i24_e32 v22, 3, v22
	v_add3_u32 v21, v21, v22, s67
	v_mov_b64_e32 v[22:23], s[24:25]
	v_mad_i64_i32 v[22:23], s[4:5], v21, s58, v[22:23]
	v_lshl_add_u64 v[22:23], v[76:77], 2, v[22:23]
	global_store_dwordx4 v[22:23], v[14:17], off sc1
.LBB0_328:
	s_or_b64 exec, exec, s[8:9]
	v_cmp_gt_i32_e32 vcc, s61, v62
	v_cvt_pk_bf16_f32 v14, v10, v11
	v_cvt_pk_bf16_f32 v15, v12, v13
	v_cmp_lt_i32_e64 s[4:5], s62, v62
	s_or_b64 s[10:11], s[6:7], vcc
	global_store_dwordx2 v[18:19], v[14:15], off offset:32
	s_and_saveexec_b64 s[8:9], s[10:11]
	s_cbranch_execz .LBB0_345
	v_cmp_lt_i32_e32 vcc, s63, v20
	s_and_saveexec_b64 s[10:11], vcc
	s_xor_b64 s[10:11], exec, s[10:11]
	s_cbranch_execz .LBB0_337
	v_add_u32_e32 v14, 0xffffe000, v20
	v_lshrrev_b32_e32 v15, 2, v14
	v_and_b32_e32 v14, 3, v80
	s_and_saveexec_b64 s[12:13], s[4:5]
	s_xor_b64 s[12:13], exec, s[12:13]
	s_cbranch_execz .LBB0_332
	v_mul_lo_u32 v15, v15, 15
	v_add3_u32 v74, v14, v15, 11
	v_lshlrev_b64 v[14:15], 12, v[74:75]
	v_lshl_add_u64 v[14:15], s[16:17], 0, v[14:15]
	v_lshl_add_u64 v[14:15], v[76:77], 2, v[14:15]
	v_add_co_u32_e32 v14, vcc, 0x9adc000, v14
	s_nop 1
	v_addc_co_u32_e32 v15, vcc, 0, v15, vcc
	global_store_dwordx4 v[14:15], v[10:13], off offset:64 sc1
.LBB0_332:
	s_andn2_saveexec_b64 s[12:13], s[12:13]
	s_cbranch_execz .LBB0_336
	v_cmp_ne_u32_e32 vcc, 0, v14
	s_and_saveexec_b64 s[38:39], vcc
	s_cbranch_execz .LBB0_335
	v_lshl_add_u32 v15, v15, 1, v15
	v_add3_u32 v16, v14, v15, -1
	v_mov_b64_e32 v[14:15], s[22:23]
	v_mad_u64_u32 v[14:15], s[40:41], v16, s58, v[14:15]
	v_lshl_add_u64 v[14:15], v[76:77], 2, v[14:15]
	global_store_dwordx4 v[14:15], v[10:13], off offset:64 sc1

; DEV void store_bf4(bf16_t* p, f32x4 v) { uint2 w; w.x = cvt_pk_bf16(v[0], v[1]); w.y = cvt_pk_bf16(v[2], v[3]); *(uint2*)p = w; }
;     DEV void operator()(int r, int c, f32x4 v) const { store_bf4(dst + (size_t)r * ld + c, v); }
;     DEV void operator()(int r, int c, f32x4 v) const {
;         const int row = m0 + r, col = n0 + c;
;         if (col < NPJ) {
;             store_bf4(proj + (size_t)row * NPJ + col, v);
;             const bool isconv = col < 3072, ispool = (col >= C_U && col < C_ZB);
;             if (isconv || ispool) {
;                 if (row < TP) {
;                     const int b = row >> 11, t = row & 2047;
;                     if (isconv) { if (t >= 2045) *(f32x4*)(out + O_CP + ((size_t)(b * 3 + (t - 2045))) * 3072 + col) = v; }
;                     else { if (t >= 2033) *(f32x4*)(out + O_PP + ((size_t)(b * 15 + (t - 2033))) * 1024 + (col - C_U)) = v; }
;                 } else {
;                     const int sb = (row - TP) >> 2, t = (row - TP) & 3;
;                     if (isconv) { if (t >= 1) *(f32x4*)(out + O_CS + ((size_t)(sb * 3 + (t - 1))) * 3072 + col) = v; }
;                     else *(f32x4*)(out + O_PS + ((size_t)(sb * 15 + 11 + t)) * 1024 + (col - C_U)) = v;
;                 }
.LBB0_337:
	s_andn2_saveexec_b64 s[10:11], s[10:11]
	s_cbranch_execz .LBB0_345
	v_ashrrev_i32_e32 v15, 11, v20
	v_and_b32_e32 v14, 0x7ff, v20
	s_and_saveexec_b64 s[10:11], s[4:5]
	s_xor_b64 s[4:5], exec, s[10:11]
	s_cbranch_execz .LBB0_342
	v_cmp_lt_u32_e32 vcc, s64, v14
	s_and_saveexec_b64 s[10:11], vcc
	s_cbranch_execz .LBB0_341
	v_mul_i32_i24_e32 v15, 15, v15
	v_add3_u32 v14, v14, v15, s65
	v_ashrrev_i32_e32 v15, 31, v14
	v_lshlrev_b64 v[14:15], 12, v[14:15]
	v_lshl_add_u64 v[14:15], s[16:17], 0, v[14:15]
	v_lshl_add_u64 v[14:15], v[76:77], 2, v[14:15]
	v_add_co_u32_e32 v14, vcc, 0x5620000, v14
	s_nop 1
	v_addc_co_u32_e32 v15, vcc, 0, v15, vcc
	global_store_dwordx4 v[14:15], v[10:13], off offset:64 sc1

; DEV void store_bf4(bf16_t* p, f32x4 v) { uint2 w; w.x = cvt_pk_bf16(v[0], v[1]); w.y = cvt_pk_bf16(v[2], v[3]); *(uint2*)p = w; }
;     DEV void operator()(int r, int c, f32x4 v) const { store_bf4(dst + (size_t)r * ld + c, v); }
;     DEV void operator()(int r, int c, f32x4 v) const {
;         const int row = m0 + r, col = n0 + c;
;         if (col < NPJ) {
;             store_bf4(proj + (size_t)row * NPJ + col, v);
;             const bool isconv = col < 3072, ispool = (col >= C_U && col < C_ZB);
;             if (isconv || ispool) {
;                 if (row < TP) {
;                     const int b = row >> 11, t = row & 2047;
;                     if (isconv) { if (t >= 2045) *(f32x4*)(out + O_CP + ((size_t)(b * 3 + (t - 2045))) * 3072 + col) = v; }
;                     else { if (t >= 2033) *(f32x4*)(out + O_PP + ((size_t)(b * 15 + (t - 2033))) * 1024 + (col - C_U)) = v; }
;                 } else {
;                     const int sb = (row - TP) >> 2, t = (row - TP) & 3;
;                     if (isconv) { if (t >= 1) *(f32x4*)(out + O_CS + ((size_t)(sb * 3 + (t - 1))) * 3072 + col) = v; }
;                     else *(f32x4*)(out + O_PS + ((size_t)(sb * 15 + 11 + t)) * 1024 + (col - C_U)) = v;
;                 }
.LBB0_342:
	s_andn2_saveexec_b64 s[4:5], s[4:5]
	s_cbranch_execz .LBB0_345
	v_cmp_lt_u32_e32 vcc, s66, v14
	s_and_b64 exec, exec, vcc
	s_cbranch_execz .LBB0_345
	v_mul_i32_i24_e32 v15, 3, v15
	v_add3_u32 v16, v14, v15, s67
	v_mov_b64_e32 v[14:15], s[24:25]
	v_mad_i64_i32 v[14:15], s[4:5], v16, s58, v[14:15]
	v_lshl_add_u64 v[14:15], v[76:77], 2, v[14:15]
	global_store_dwordx4 v[14:15], v[10:13], off offset:64 sc1
.LBB0_345:
	s_or_b64 exec, exec, s[8:9]
	v_cmp_gt_i32_e32 vcc, s61, v58
	v_cvt_pk_bf16_f32 v10, v6, v7
	v_cvt_pk_bf16_f32 v11, v8, v9
	v_cmp_lt_i32_e64 s[4:5], s62, v58
	s_or_b64 s[10:11], s[6:7], vcc
	global_store_dwordx2 v[18:19], v[10:11], off offset:64
	s_and_saveexec_b64 s[8:9], s[10:11]
	s_cbranch_execz .LBB0_362
	v_cmp_lt_i32_e32 vcc, s63, v20
	s_and_saveexec_b64 s[10:11], vcc
	s_xor_b64 s[10:11], exec, s[10:11]
	s_cbranch_execz .LBB0_354
	v_add_u32_e32 v10, 0xffffe000, v20
	v_lshrrev_b32_e32 v11, 2, v10
	v_and_b32_e32 v10, 3, v80
	s_and_saveexec_b64 s[12:13], s[4:5]
	s_xor_b64 s[12:13], exec, s[12:13]
	s_cbranch_execz .LBB0_349
	v_mul_lo_u32 v11, v11, 15
	v_add3_u32 v74, v10, v11, 11
	v_lshlrev_b64 v[10:11], 12, v[74:75]
	v_lshl_add_u64 v[10:11], s[16:17], 0, v[10:11]
	v_lshl_add_u64 v[10:11], v[76:77], 2, v[10:11]
	v_add_co_u32_e32 v10, vcc, 0x9adc000, v10
	s_nop 1
	v_addc_co_u32_e32 v11, vcc, 0, v11, vcc
	global_store_dwordx4 v[10:11], v[6:9], off offset:128 sc1
.LBB0_349:
	s_andn2_saveexec_b64 s[12:13], s[12:13]
	s_cbranch_execz .LBB0_353
	v_cmp_ne_u32_e32 vcc, 0, v10
	s_and_saveexec_b64 s[38:39], vcc
	s_cbranch_execz .LBB0_352
	v_lshl_add_u32 v11, v11, 1, v11
	v_add3_u32 v12, v10, v11, -1
	v_mov_b64_e32 v[10:11], s[22:23]
	v_mad_u64_u32 v[10:11], s[40:41], v12, s58, v[10:11]
	v_lshl_add_u64 v[10:11], v[76:77], 2, v[10:11]
	global_store_dwordx4 v[10:11], v[6:9], off offset:128 sc1

; DEV void store_bf4(bf16_t* p, f32x4 v) { uint2 w; w.x = cvt_pk_bf16(v[0], v[1]); w.y = cvt_pk_bf16(v[2], v[3]); *(uint2*)p = w; }
;     DEV void operator()(int r, int c, f32x4 v) const { store_bf4(dst + (size_t)r * ld + c, v); }
;     DEV void operator()(int r, int c, f32x4 v) const {
;         const int row = m0 + r, col = n0 + c;
;         if (col < NPJ) {
;             store_bf4(proj + (size_t)row * NPJ + col, v);
;             const bool isconv = col < 3072, ispool = (col >= C_U && col < C_ZB);
;             if (isconv || ispool) {
;                 if (row < TP) {
;                     const int b = row >> 11, t = row & 2047;
;                     if (isconv) { if (t >= 2045) *(f32x4*)(out + O_CP + ((size_t)(b * 3 + (t - 2045))) * 3072 + col) = v; }
;                     else { if (t >= 2033) *(f32x4*)(out + O_PP + ((size_t)(b * 15 + (t - 2033))) * 1024 + (col - C_U)) = v; }
;                 } else {
;                     const int sb = (row - TP) >> 2, t = (row - TP) & 3;
;                     if (isconv) { if (t >= 1) *(f32x4*)(out + O_CS + ((size_t)(sb * 3 + (t - 1))) * 3072 + col) = v; }
;                     else *(f32x4*)(out + O_PS + ((size_t)(sb * 15 + 11 + t)) * 1024 + (col - C_U)) = v;
;                 }
.LBB0_354:
	s_andn2_saveexec_b64 s[10:11], s[10:11]
	s_cbranch_execz .LBB0_362
	v_ashrrev_i32_e32 v11, 11, v20
	v_and_b32_e32 v10, 0x7ff, v20
	s_and_saveexec_b64 s[10:11], s[4:5]
	s_xor_b64 s[4:5], exec, s[10:11]
	s_cbranch_execz .LBB0_359
	v_cmp_lt_u32_e32 vcc, s64, v10
	s_and_saveexec_b64 s[10:11], vcc
	s_cbranch_execz .LBB0_358
	v_mul_i32_i24_e32 v11, 15, v11
	v_add3_u32 v10, v10, v11, s65
	v_ashrrev_i32_e32 v11, 31, v10
	v_lshlrev_b64 v[10:11], 12, v[10:11]
	v_lshl_add_u64 v[10:11], s[16:17], 0, v[10:11]
	v_lshl_add_u64 v[10:11], v[76:77], 2, v[10:11]
	v_add_co_u32_e32 v10, vcc, 0x5620000, v10
	s_nop 1
	v_addc_co_u32_e32 v11, vcc, 0, v11, vcc
	global_store_dwordx4 v[10:11], v[6:9], off offset:128 sc1

; DEV void store_bf4(bf16_t* p, f32x4 v) { uint2 w; w.x = cvt_pk_bf16(v[0], v[1]); w.y = cvt_pk_bf16(v[2], v[3]); *(uint2*)p = w; }
;     DEV void operator()(int r, int c, f32x4 v) const { store_bf4(dst + (size_t)r * ld + c, v); }
;     DEV void operator()(int r, int c, f32x4 v) const {
;         const int row = m0 + r, col = n0 + c;
;         if (col < NPJ) {
;             store_bf4(proj + (size_t)row * NPJ + col, v);
;             const bool isconv = col < 3072, ispool = (col >= C_U && col < C_ZB);
;             if (isconv || ispool) {
;                 if (row < TP) {
;                     const int b = row >> 11, t = row & 2047;
;                     if (isconv) { if (t >= 2045) *(f32x4*)(out + O_CP + ((size_t)(b * 3 + (t - 2045))) * 3072 + col) = v; }
;                     else { if (t >= 2033) *(f32x4*)(out + O_PP + ((size_t)(b * 15 + (t - 2033))) * 1024 + (col - C_U)) = v; }
;                 } else {
;                     const int sb = (row - TP) >> 2, t = (row - TP) & 3;
;                     if (isconv) { if (t >= 1) *(f32x4*)(out + O_CS + ((size_t)(sb * 3 + (t - 1))) * 3072 + col) = v; }
;                     else *(f32x4*)(out + O_PS + ((size_t)(sb * 15 + 11 + t)) * 1024 + (col - C_U)) = v;
;                 }
.LBB0_359:
	s_andn2_saveexec_b64 s[4:5], s[4:5]
	s_cbranch_execz .LBB0_362
	v_cmp_lt_u32_e32 vcc, s66, v10
	s_and_b64 exec, exec, vcc
	s_cbranch_execz .LBB0_362
	v_mul_i32_i24_e32 v11, 3, v11
	v_add3_u32 v12, v10, v11, s67
	v_mov_b64_e32 v[10:11], s[24:25]
	v_mad_i64_i32 v[10:11], s[4:5], v12, s58, v[10:11]
	v_lshl_add_u64 v[10:11], v[76:77], 2, v[10:11]
	global_store_dwordx4 v[10:11], v[6:9], off offset:128 sc1
.LBB0_362:
	s_or_b64 exec, exec, s[8:9]
	v_cmp_gt_i32_e32 vcc, s61, v54
	v_cvt_pk_bf16_f32 v6, v2, v3
	v_cvt_pk_bf16_f32 v7, v4, v5
	v_cmp_lt_i32_e64 s[4:5], s62, v54
	s_or_b64 s[8:9], s[6:7], vcc
	global_store_dwordx2 v[18:19], v[6:7], off offset:96
	s_and_saveexec_b64 s[6:7], s[8:9]
	s_cbranch_execz .LBB0_180
	v_cmp_lt_i32_e32 vcc, s63, v20
	s_and_saveexec_b64 s[8:9], vcc
	s_xor_b64 s[8:9], exec, s[8:9]
	s_cbranch_execz .LBB0_371
	v_add_u32_e32 v6, 0xffffe000, v20
	v_lshrrev_b32_e32 v7, 2, v6
	v_and_b32_e32 v6, 3, v80
	s_and_saveexec_b64 s[10:11], s[4:5]
	s_xor_b64 s[10:11], exec, s[10:11]
	s_cbranch_execz .LBB0_366
	v_mul_lo_u32 v7, v7, 15
	v_add3_u32 v74, v6, v7, 11
	v_lshlrev_b64 v[6:7], 12, v[74:75]
	v_lshl_add_u64 v[6:7], s[16:17], 0, v[6:7]
	v_lshl_add_u64 v[6:7], v[76:77], 2, v[6:7]
	v_add_co_u32_e32 v6, vcc, 0x9adc000, v6
	s_nop 1
	v_addc_co_u32_e32 v7, vcc, 0, v7, vcc
	global_store_dwordx4 v[6:7], v[2:5], off offset:192 sc1
.LBB0_366:
	s_andn2_saveexec_b64 s[10:11], s[10:11]
	s_cbranch_execz .LBB0_370
	v_cmp_ne_u32_e32 vcc, 0, v6
	s_and_saveexec_b64 s[12:13], vcc
	s_cbranch_execz .LBB0_369
	v_lshl_add_u32 v7, v7, 1, v7
	v_add3_u32 v8, v6, v7, -1
	v_mov_b64_e32 v[6:7], s[22:23]
	v_mad_u64_u32 v[6:7], s[38:39], v8, s58, v[6:7]
	v_lshl_add_u64 v[6:7], v[76:77], 2, v[6:7]
	global_store_dwordx4 v[6:7], v[2:5], off offset:192 sc1

; DEV void store_bf4(bf16_t* p, f32x4 v) { uint2 w; w.x = cvt_pk_bf16(v[0], v[1]); w.y = cvt_pk_bf16(v[2], v[3]); *(uint2*)p = w; }
;     DEV void operator()(int r, int c, f32x4 v) const { store_bf4(dst + (size_t)r * ld + c, v); }
;     DEV void operator()(int r, int c, f32x4 v) const {
;         const int row = m0 + r, col = n0 + c;
;         if (col < NPJ) {
;             store_bf4(proj + (size_t)row * NPJ + col, v);
;             const bool isconv = col < 3072, ispool = (col >= C_U && col < C_ZB);
;             if (isconv || ispool) {
;                 if (row < TP) {
;                     const int b = row >> 11, t = row & 2047;
;                     if (isconv) { if (t >= 2045) *(f32x4*)(out + O_CP + ((size_t)(b * 3 + (t - 2045))) * 3072 + col) = v; }
;                     else { if (t >= 2033) *(f32x4*)(out + O_PP + ((size_t)(b * 15 + (t - 2033))) * 1024 + (col - C_U)) = v; }
;                 } else {
;                     const int sb = (row - TP) >> 2, t = (row - TP) & 3;
;                     if (isconv) { if (t >= 1) *(f32x4*)(out + O_CS + ((size_t)(sb * 3 + (t - 1))) * 3072 + col) = v; }
;                     else *(f32x4*)(out + O_PS + ((size_t)(sb * 15 + 11 + t)) * 1024 + (col - C_U)) = v;
;                 }
.LBB0_371:
	s_andn2_saveexec_b64 s[8:9], s[8:9]
	s_cbranch_execz .LBB0_180
	v_ashrrev_i32_e32 v7, 11, v20
	v_and_b32_e32 v6, 0x7ff, v20
	s_and_saveexec_b64 s[8:9], s[4:5]
	s_xor_b64 s[4:5], exec, s[8:9]
	s_cbranch_execz .LBB0_376
	v_cmp_lt_u32_e32 vcc, s64, v6
	s_and_saveexec_b64 s[8:9], vcc
	s_cbranch_execz .LBB0_375
	v_mul_i32_i24_e32 v7, 15, v7
	v_add3_u32 v6, v6, v7, s65
	v_ashrrev_i32_e32 v7, 31, v6
	v_lshlrev_b64 v[6:7], 12, v[6:7]
	v_lshl_add_u64 v[6:7], s[16:17], 0, v[6:7]
	v_lshl_add_u64 v[6:7], v[76:77], 2, v[6:7]
	v_add_co_u32_e32 v6, vcc, 0x5620000, v6
	s_nop 1
	v_addc_co_u32_e32 v7, vcc, 0, v7, vcc
	global_store_dwordx4 v[6:7], v[2:5], off offset:192 sc1

; DEV bf16_t f2bf(float f) { return (bf16_t)(cvt_pk_bf16(f, 0.f) & 0xffffu); }
; DEV void store_bf4(bf16_t* p, f32x4 v) { uint2 w; w.x = cvt_pk_bf16(v[0], v[1]); w.y = cvt_pk_bf16(v[2], v[3]); *(uint2*)p = w; }
;     DEV void operator()(int r, int c, f32x4 v) const { store_bf4(dst + (size_t)r * ld + c, v); }
;     DEV void operator()(int r, int c, f32x4 v) const {
;     ...
;                     if (isconv) { if (t >= 1) *(f32x4*)(out + O_CS + ((size_t)(sb * 3 + (t - 1))) * 3072 + col) = v; }
;                     else *(f32x4*)(out + O_PS + ((size_t)(sb * 15 + 11 + t)) * 1024 + (col - C_U)) = v;
;     DEV void operator()(int r, int c, f32x4 v) const {
;         const int row = m0 + r, col = n0 + c;
;         if (col < D) {
;             __builtin_nontemporal_store(v, (f32x4*)(out + O_MK + (size_t)row * D + col));
;             store_bf4(mkb + (size_t)row * LDB + col, v);
;         } else {
;             const int cc = col - D, b = row >> 8, m = row & 255;
;             __builtin_nontemporal_store(v, (f32x4*)(out + O_MV + (size_t)row * D + cc));
;             bf16_t* p = mvt + ((size_t)b * D + cc) * LDM + m;
;             p[0] = f2bf(v[0]); p[LDM] = f2bf(v[1]); p[2 * LDM] = f2bf(v[2]); p[3 * LDM] = f2bf(v[3]);
;         }
.LBB0_376:
	s_andn2_saveexec_b64 s[4:5], s[4:5]
	s_cbranch_execz .LBB0_180
	v_cmp_lt_u32_e32 vcc, s66, v6
	s_and_b64 exec, exec, vcc
	s_cbranch_execz .LBB0_180
	v_mul_i32_i24_e32 v7, 3, v7
	v_add3_u32 v8, v6, v7, s67
	v_mov_b64_e32 v[6:7], s[24:25]
	v_mad_i64_i32 v[6:7], s[4:5], v8, s58, v[6:7]
	v_lshl_add_u64 v[6:7], v[76:77], 2, v[6:7]
	global_store_dwordx4 v[6:7], v[2:5], off offset:192 sc1
	s_branch .LBB0_180
.LBB0_379:
	v_lshlrev_b64 v[64:65], 13, v[80:81]
	v_lshl_add_u64 v[64:65], s[18:19], 0, v[64:65]
	v_mov_b32_e32 v63, v75
	v_lshl_add_u64 v[64:65], v[62:63], 2, v[64:65]
	global_store_dwordx4 v[64:65], v[58:61], off nt sc1
	v_lshlrev_b64 v[64:65], 11, v[84:85]
	v_lshl_add_u64 v[64:65], v[64:65], 0, v[62:63]
	v_mad_u64_u32 v[90:91], s[6:7], v64, s60, v[162:163]
	v_mad_i32_i24 v91, v65, s60, v91
	v_mov_b32_e32 v83, v75
	v_lshl_add_u64 v[64:65], v[90:91], 0, v[82:83]
	v_cvt_pk_bf16_f32 v63, v58, s0
	global_store_short v[64:65], v63, off
	v_cvt_pk_bf16_f32 v63, v59, s0
	global_store_short v[64:65], v63, off offset:576
	v_cvt_pk_bf16_f32 v63, v60, s0
	global_store_short v[64:65], v63, off offset:1152
	v_cvt_pk_bf16_f32 v63, v61, s0
	global_store_short v[64:65], v63, off offset:1728
	s_cbranch_execnz .LBB0_191
.LBB0_380:
	v_lshlrev_b64 v[64:65], 13, v[80:81]
	v_lshl_add_u64 v[64:65], s[20:21], 0, v[64:65]
	v_lshl_add_u64 v[64:65], v[74:75], 2, v[64:65]
	global_store_dwordx4 v[64:65], v[58:61], off offset:64 nt sc1
	v_mad_i64_i32 v[64:65], s[6:7], v80, s56, v[168:169]
	v_mov_b32_e32 v77, v75
	v_lshl_add_u64 v[64:65], v[64:65], 0, v[76:77]
	v_cvt_pk_bf16_f32 v58, v58, v59
	v_cvt_pk_bf16_f32 v59, v60, v61
	global_store_dwordx2 v[64:65], v[58:59], off offset:32
	s_mov_b64 s[6:7], -1
	s_and_b64 vcc, exec, s[4:5]
	v_add_u32_e32 v58, 0xfffff820, v74
	s_cbranch_vccnz .LBB0_192
.LBB0_381:
	v_lshlrev_b64 v[60:61], 13, v[80:81]
	v_lshl_add_u64 v[60:61], s[18:19], 0, v[60:61]
	v_mov_b32_e32 v59, v75
	v_lshl_add_u64 v[60:61], v[58:59], 2, v[60:61]
	global_store_dwordx4 v[60:61], v[54:57], off nt sc1
	v_lshlrev_b64 v[60:61], 11, v[84:85]
	v_lshl_add_u64 v[60:61], v[60:61], 0, v[58:59]
	v_mad_u64_u32 v[64:65], s[6:7], v60, s60, v[162:163]
	v_mad_i32_i24 v65, v61, s60, v65
	v_mov_b32_e32 v83, v75
	v_lshl_add_u64 v[60:61], v[64:65], 0, v[82:83]
	v_cvt_pk_bf16_f32 v59, v54, s0
	global_store_short v[60:61], v59, off
	v_cvt_pk_bf16_f32 v59, v55, s0
	global_store_short v[60:61], v59, off offset:576
	v_cvt_pk_bf16_f32 v59, v56, s0
	global_store_short v[60:61], v59, off offset:1152
	v_cvt_pk_bf16_f32 v59, v57, s0
	global_store_short v[60:61], v59, off offset:1728
	s_cbranch_execnz .LBB0_193
.LBB0_382:
	v_lshlrev_b64 v[60:61], 13, v[80:81]
	v_lshl_add_u64 v[60:61], s[20:21], 0, v[60:61]
	v_lshl_add_u64 v[60:61], v[74:75], 2, v[60:61]
	global_store_dwordx4 v[60:61], v[54:57], off offset:128 nt sc1
	v_mad_i64_i32 v[60:61], s[6:7], v80, s56, v[168:169]
	v_mov_b32_e32 v77, v75
	v_lshl_add_u64 v[60:61], v[60:61], 0, v[76:77]
	v_cvt_pk_bf16_f32 v54, v54, v55
	v_cvt_pk_bf16_f32 v55, v56, v57
	global_store_dwordx2 v[60:61], v[54:55], off offset:64
	s_mov_b64 s[6:7], -1
	s_and_b64 vcc, exec, s[4:5]
	v_add_u32_e32 v54, 0xfffff830, v74
	s_cbranch_vccnz .LBB0_194
.LBB0_383:
	v_lshlrev_b64 v[56:57], 13, v[80:81]
	v_lshl_add_u64 v[56:57], s[18:19], 0, v[56:57]
	v_mov_b32_e32 v55, v75
	v_lshl_add_u64 v[56:57], v[54:55], 2, v[56:57]
	global_store_dwordx4 v[56:57], v[50:53], off nt sc1
	v_lshlrev_b64 v[56:57], 11, v[84:85]
	v_lshl_add_u64 v[56:57], v[56:57], 0, v[54:55]
	v_mad_u64_u32 v[60:61], s[6:7], v56, s60, v[162:163]
	v_mad_i32_i24 v61, v57, s60, v61
	v_mov_b32_e32 v83, v75
	v_lshl_add_u64 v[56:57], v[60:61], 0, v[82:83]
	v_cvt_pk_bf16_f32 v55, v50, s0
	global_store_short v[56:57], v55, off
	v_cvt_pk_bf16_f32 v55, v51, s0
	global_store_short v[56:57], v55, off offset:576
	v_cvt_pk_bf16_f32 v55, v52, s0
	global_store_short v[56:57], v55, off offset:1152
	v_cvt_pk_bf16_f32 v55, v53, s0
	global_store_short v[56:57], v55, off offset:1728
	s_cbranch_execz .LBB0_195
	s_branch .LBB0_196
.LBB0_384:
	v_lshlrev_b64 v[60:61], 13, v[50:51]
	v_lshl_add_u64 v[60:61], s[18:19], 0, v[60:61]
	v_mov_b32_e32 v79, v75
	v_lshl_add_u64 v[60:61], v[78:79], 2, v[60:61]
	global_store_dwordx4 v[60:61], v[46:49], off nt sc1
	v_lshlrev_b64 v[60:61], 11, v[56:57]
	v_lshl_add_u64 v[60:61], v[60:61], 0, v[78:79]
	v_mad_u64_u32 v[64:65], s[6:7], v60, s60, v[162:163]
	v_mad_i32_i24 v65, v61, s60, v65
	v_mov_b32_e32 v53, v75
	v_lshl_add_u64 v[60:61], v[64:65], 0, v[52:53]
	v_cvt_pk_bf16_f32 v53, v46, s0
	global_store_short v[60:61], v53, off
	v_cvt_pk_bf16_f32 v53, v47, s0
	global_store_short v[60:61], v53, off offset:576
	v_cvt_pk_bf16_f32 v53, v48, s0
	global_store_short v[60:61], v53, off offset:1152
	v_cvt_pk_bf16_f32 v53, v49, s0
	global_store_short v[60:61], v53, off offset:1728
	s_cbranch_execnz .LBB0_198
.LBB0_385:
	v_lshlrev_b64 v[60:61], 13, v[50:51]
	v_lshl_add_u64 v[60:61], s[20:21], 0, v[60:61]
	v_lshl_add_u64 v[60:61], v[74:75], 2, v[60:61]
	global_store_dwordx4 v[60:61], v[46:49], off nt sc1
	v_mad_i64_i32 v[60:61], s[6:7], v50, s56, v[168:169]
	v_mov_b32_e32 v77, v75
	v_lshl_add_u64 v[60:61], v[60:61], 0, v[76:77]
	v_cvt_pk_bf16_f32 v46, v46, v47
	v_cvt_pk_bf16_f32 v47, v48, v49
	global_store_dwordx2 v[60:61], v[46:47], off
	s_and_b64 vcc, exec, s[4:5]
	s_mov_b64 s[6:7], -1
	s_cbranch_vccnz .LBB0_199
; DEV bf16_t f2bf(float f) { return (bf16_t)(cvt_pk_bf16(f, 0.f) & 0xffffu); }
; DEV void store_bf4(bf16_t* p, f32x4 v) { uint2 w; w.x = cvt_pk_bf16(v[0], v[1]); w.y = cvt_pk_bf16(v[2], v[3]); *(uint2*)p = w; }
;     DEV void operator()(int r, int c, f32x4 v) const { store_bf4(dst + (size_t)r * ld + c, v); }
;     DEV void operator()(int r, int c, f32x4 v) const {
;         const int row = m0 + r, col = n0 + c;
;         if (col < D) {
;             __builtin_nontemporal_store(v, (f32x4*)(out + O_MK + (size_t)row * D + col));
;             store_bf4(mkb + (size_t)row * LDB + col, v);
;         } else {
;             const int cc = col - D, b = row >> 8, m = row & 255;
;             __builtin_nontemporal_store(v, (f32x4*)(out + O_MV + (size_t)row * D + cc));
;             bf16_t* p = mvt + ((size_t)b * D + cc) * LDM + m;
;             p[0] = f2bf(v[0]); p[LDM] = f2bf(v[1]); p[2 * LDM] = f2bf(v[2]); p[3 * LDM] = f2bf(v[3]);
;         }
.LBB0_386:
	v_lshlrev_b64 v[46:47], 13, v[50:51]
	v_lshl_add_u64 v[46:47], s[18:19], 0, v[46:47]
	v_mov_b32_e32 v63, v75
	v_lshl_add_u64 v[46:47], v[62:63], 2, v[46:47]
	global_store_dwordx4 v[46:47], v[42:45], off nt sc1
	v_lshlrev_b64 v[46:47], 11, v[56:57]
	v_lshl_add_u64 v[46:47], v[46:47], 0, v[62:63]
	v_mad_u64_u32 v[48:49], s[6:7], v46, s60, v[162:163]
	v_mad_i32_i24 v49, v47, s60, v49
	v_mov_b32_e32 v53, v75
	v_lshl_add_u64 v[46:47], v[48:49], 0, v[52:53]
	v_cvt_pk_bf16_f32 v48, v42, s0
	global_store_short v[46:47], v48, off
	v_cvt_pk_bf16_f32 v48, v43, s0
	global_store_short v[46:47], v48, off offset:576
	v_cvt_pk_bf16_f32 v48, v44, s0
	global_store_short v[46:47], v48, off offset:1152
	v_cvt_pk_bf16_f32 v48, v45, s0
	global_store_short v[46:47], v48, off offset:1728
	s_cbranch_execnz .LBB0_200
.LBB0_387:
	v_lshlrev_b64 v[46:47], 13, v[50:51]
	v_lshl_add_u64 v[46:47], s[20:21], 0, v[46:47]
	v_lshl_add_u64 v[46:47], v[74:75], 2, v[46:47]
	global_store_dwordx4 v[46:47], v[42:45], off offset:64 nt sc1
	v_mad_i64_i32 v[46:47], s[6:7], v50, s56, v[168:169]
	v_mov_b32_e32 v77, v75
	v_lshl_add_u64 v[46:47], v[46:47], 0, v[76:77]
	v_cvt_pk_bf16_f32 v42, v42, v43
	v_cvt_pk_bf16_f32 v43, v44, v45
	global_store_dwordx2 v[46:47], v[42:43], off offset:32
	s_and_b64 vcc, exec, s[4:5]
	s_mov_b64 s[6:7], -1
	s_cbranch_vccnz .LBB0_201
.LBB0_388:
	v_lshlrev_b64 v[42:43], 13, v[50:51]
	v_lshl_add_u64 v[42:43], s[18:19], 0, v[42:43]
	v_mov_b32_e32 v59, v75
	v_lshl_add_u64 v[42:43], v[58:59], 2, v[42:43]
	global_store_dwordx4 v[42:43], v[38:41], off nt sc1
	v_lshlrev_b64 v[42:43], 11, v[56:57]
	v_lshl_add_u64 v[42:43], v[42:43], 0, v[58:59]
	v_mad_u64_u32 v[44:45], s[6:7], v42, s60, v[162:163]
	v_mad_i32_i24 v45, v43, s60, v45
	v_mov_b32_e32 v53, v75
	v_lshl_add_u64 v[42:43], v[44:45], 0, v[52:53]
	v_cvt_pk_bf16_f32 v44, v38, s0
	global_store_short v[42:43], v44, off
	v_cvt_pk_bf16_f32 v44, v39, s0
	global_store_short v[42:43], v44, off offset:576
	v_cvt_pk_bf16_f32 v44, v40, s0
	global_store_short v[42:43], v44, off offset:1152
	v_cvt_pk_bf16_f32 v44, v41, s0
	global_store_short v[42:43], v44, off offset:1728
	s_cbranch_execnz .LBB0_202
.LBB0_389:
	v_lshlrev_b64 v[42:43], 13, v[50:51]
	v_lshl_add_u64 v[42:43], s[20:21], 0, v[42:43]
	v_lshl_add_u64 v[42:43], v[74:75], 2, v[42:43]
	global_store_dwordx4 v[42:43], v[38:41], off offset:128 nt sc1
	v_mad_i64_i32 v[42:43], s[6:7], v50, s56, v[168:169]
	v_mov_b32_e32 v77, v75
	v_lshl_add_u64 v[42:43], v[42:43], 0, v[76:77]
	v_cvt_pk_bf16_f32 v38, v38, v39
	v_cvt_pk_bf16_f32 v39, v40, v41
	global_store_dwordx2 v[42:43], v[38:39], off offset:64
	s_and_b64 vcc, exec, s[4:5]
	s_mov_b64 s[6:7], -1
	s_cbranch_vccnz .LBB0_203
.LBB0_390:
	v_lshlrev_b64 v[38:39], 13, v[50:51]
	v_lshl_add_u64 v[38:39], s[18:19], 0, v[38:39]
	v_mov_b32_e32 v55, v75
	v_lshl_add_u64 v[38:39], v[54:55], 2, v[38:39]
	global_store_dwordx4 v[38:39], v[34:37], off nt sc1
	v_lshlrev_b64 v[38:39], 11, v[56:57]
	v_lshl_add_u64 v[38:39], v[38:39], 0, v[54:55]
	v_mad_u64_u32 v[40:41], s[6:7], v38, s60, v[162:163]
	v_mad_i32_i24 v41, v39, s60, v41
	v_mov_b32_e32 v53, v75
	v_lshl_add_u64 v[38:39], v[40:41], 0, v[52:53]
	v_cvt_pk_bf16_f32 v40, v34, s0
	global_store_short v[38:39], v40, off
	v_cvt_pk_bf16_f32 v40, v35, s0
	global_store_short v[38:39], v40, off offset:576
	v_cvt_pk_bf16_f32 v40, v36, s0
	global_store_short v[38:39], v40, off offset:1152
	v_cvt_pk_bf16_f32 v40, v37, s0
	global_store_short v[38:39], v40, off offset:1728
	s_cbranch_execz .LBB0_204
	s_branch .LBB0_205
.LBB0_391:
	v_lshlrev_b64 v[40:41], 13, v[34:35]
	v_lshl_add_u64 v[40:41], s[18:19], 0, v[40:41]
	v_mov_b32_e32 v79, v75
	v_lshl_add_u64 v[40:41], v[78:79], 2, v[40:41]
	global_store_dwordx4 v[40:41], v[30:33], off nt sc1
	v_lshlrev_b64 v[40:41], 11, v[38:39]
	v_lshl_add_u64 v[40:41], v[40:41], 0, v[78:79]
	v_mad_u64_u32 v[42:43], s[6:7], v40, s60, v[162:163]
	v_mad_i32_i24 v43, v41, s60, v43
	v_mov_b32_e32 v37, v75
	v_lshl_add_u64 v[40:41], v[42:43], 0, v[36:37]
	v_cvt_pk_bf16_f32 v37, v30, s0
	global_store_short v[40:41], v37, off
	v_cvt_pk_bf16_f32 v37, v31, s0
	global_store_short v[40:41], v37, off offset:576
	v_cvt_pk_bf16_f32 v37, v32, s0
	global_store_short v[40:41], v37, off offset:1152
	v_cvt_pk_bf16_f32 v37, v33, s0
	global_store_short v[40:41], v37, off offset:1728
	s_cbranch_execnz .LBB0_207
.LBB0_392:
	v_lshlrev_b64 v[40:41], 13, v[34:35]
	v_lshl_add_u64 v[40:41], s[20:21], 0, v[40:41]
	v_lshl_add_u64 v[40:41], v[74:75], 2, v[40:41]
	global_store_dwordx4 v[40:41], v[30:33], off nt sc1
	v_mad_i64_i32 v[40:41], s[6:7], v34, s56, v[168:169]
	v_mov_b32_e32 v77, v75
	v_lshl_add_u64 v[40:41], v[40:41], 0, v[76:77]
	v_cvt_pk_bf16_f32 v30, v30, v31
	v_cvt_pk_bf16_f32 v31, v32, v33
	global_store_dwordx2 v[40:41], v[30:31], off
	s_and_b64 vcc, exec, s[4:5]
	s_mov_b64 s[6:7], -1
	s_cbranch_vccnz .LBB0_208
.LBB0_393:
	v_lshlrev_b64 v[30:31], 13, v[34:35]
	v_lshl_add_u64 v[30:31], s[18:19], 0, v[30:31]
	v_mov_b32_e32 v63, v75
	v_lshl_add_u64 v[30:31], v[62:63], 2, v[30:31]
	global_store_dwordx4 v[30:31], v[26:29], off nt sc1
	v_lshlrev_b64 v[30:31], 11, v[38:39]
	v_lshl_add_u64 v[30:31], v[30:31], 0, v[62:63]
	v_mad_u64_u32 v[32:33], s[6:7], v30, s60, v[162:163]
	v_mad_i32_i24 v33, v31, s60, v33
	v_mov_b32_e32 v37, v75
	v_lshl_add_u64 v[30:31], v[32:33], 0, v[36:37]
	v_cvt_pk_bf16_f32 v32, v26, s0
	global_store_short v[30:31], v32, off
	v_cvt_pk_bf16_f32 v32, v27, s0
	global_store_short v[30:31], v32, off offset:576
	v_cvt_pk_bf16_f32 v32, v28, s0
	global_store_short v[30:31], v32, off offset:1152
	v_cvt_pk_bf16_f32 v32, v29, s0
	global_store_short v[30:31], v32, off offset:1728
	s_cbranch_execnz .LBB0_209
; DEV bf16_t f2bf(float f) { return (bf16_t)(cvt_pk_bf16(f, 0.f) & 0xffffu); }
; DEV void store_bf4(bf16_t* p, f32x4 v) { uint2 w; w.x = cvt_pk_bf16(v[0], v[1]); w.y = cvt_pk_bf16(v[2], v[3]); *(uint2*)p = w; }
;     DEV void operator()(int r, int c, f32x4 v) const { store_bf4(dst + (size_t)r * ld + c, v); }
;     DEV void operator()(int r, int c, f32x4 v) const {
;         const int row = m0 + r, col = n0 + c;
;         if (col < D) {
;             __builtin_nontemporal_store(v, (f32x4*)(out + O_MK + (size_t)row * D + col));
;             store_bf4(mkb + (size_t)row * LDB + col, v);
;         } else {
;             const int cc = col - D, b = row >> 8, m = row & 255;
;             __builtin_nontemporal_store(v, (f32x4*)(out + O_MV + (size_t)row * D + cc));
;             bf16_t* p = mvt + ((size_t)b * D + cc) * LDM + m;
;             p[0] = f2bf(v[0]); p[LDM] = f2bf(v[1]); p[2 * LDM] = f2bf(v[2]); p[3 * LDM] = f2bf(v[3]);
;         }
.LBB0_394:
	v_lshlrev_b64 v[30:31], 13, v[34:35]
	v_lshl_add_u64 v[30:31], s[20:21], 0, v[30:31]
	v_lshl_add_u64 v[30:31], v[74:75], 2, v[30:31]
	global_store_dwordx4 v[30:31], v[26:29], off offset:64 nt sc1
	v_mad_i64_i32 v[30:31], s[6:7], v34, s56, v[168:169]
	v_mov_b32_e32 v77, v75
	v_lshl_add_u64 v[30:31], v[30:31], 0, v[76:77]
	v_cvt_pk_bf16_f32 v26, v26, v27
	v_cvt_pk_bf16_f32 v27, v28, v29
	global_store_dwordx2 v[30:31], v[26:27], off offset:32
	s_and_b64 vcc, exec, s[4:5]
	s_mov_b64 s[6:7], -1
	s_cbranch_vccnz .LBB0_210
.LBB0_395:
	v_lshlrev_b64 v[26:27], 13, v[34:35]
	v_lshl_add_u64 v[26:27], s[18:19], 0, v[26:27]
	v_mov_b32_e32 v59, v75
	v_lshl_add_u64 v[26:27], v[58:59], 2, v[26:27]
	global_store_dwordx4 v[26:27], v[22:25], off nt sc1
	v_lshlrev_b64 v[26:27], 11, v[38:39]
	v_lshl_add_u64 v[26:27], v[26:27], 0, v[58:59]
	v_mad_u64_u32 v[28:29], s[6:7], v26, s60, v[162:163]
	v_mad_i32_i24 v29, v27, s60, v29
	v_mov_b32_e32 v37, v75
	v_lshl_add_u64 v[26:27], v[28:29], 0, v[36:37]
	v_cvt_pk_bf16_f32 v28, v22, s0
	global_store_short v[26:27], v28, off
	v_cvt_pk_bf16_f32 v28, v23, s0
	global_store_short v[26:27], v28, off offset:576
	v_cvt_pk_bf16_f32 v28, v24, s0
	global_store_short v[26:27], v28, off offset:1152
	v_cvt_pk_bf16_f32 v28, v25, s0
	global_store_short v[26:27], v28, off offset:1728
	s_cbranch_execnz .LBB0_211
.LBB0_396:
	v_lshlrev_b64 v[26:27], 13, v[34:35]
	v_lshl_add_u64 v[26:27], s[20:21], 0, v[26:27]
	v_lshl_add_u64 v[26:27], v[74:75], 2, v[26:27]
	global_store_dwordx4 v[26:27], v[22:25], off offset:128 nt sc1
	v_mad_i64_i32 v[26:27], s[6:7], v34, s56, v[168:169]
	v_mov_b32_e32 v77, v75
	v_lshl_add_u64 v[26:27], v[26:27], 0, v[76:77]
	v_cvt_pk_bf16_f32 v22, v22, v23
	v_cvt_pk_bf16_f32 v23, v24, v25
	global_store_dwordx2 v[26:27], v[22:23], off offset:64
	s_and_b64 vcc, exec, s[4:5]
	s_mov_b64 s[6:7], -1
	s_cbranch_vccnz .LBB0_212
.LBB0_397:
	v_lshlrev_b64 v[22:23], 13, v[34:35]
	v_lshl_add_u64 v[22:23], s[18:19], 0, v[22:23]
	v_mov_b32_e32 v55, v75
	v_lshl_add_u64 v[22:23], v[54:55], 2, v[22:23]
	global_store_dwordx4 v[22:23], v[18:21], off nt sc1
	v_lshlrev_b64 v[22:23], 11, v[38:39]
	v_lshl_add_u64 v[22:23], v[22:23], 0, v[54:55]
	v_mad_u64_u32 v[24:25], s[6:7], v22, s60, v[162:163]
	v_mad_i32_i24 v25, v23, s60, v25
	v_mov_b32_e32 v37, v75
	v_lshl_add_u64 v[22:23], v[24:25], 0, v[36:37]
	v_cvt_pk_bf16_f32 v24, v18, s0
	global_store_short v[22:23], v24, off
	v_cvt_pk_bf16_f32 v24, v19, s0
	global_store_short v[22:23], v24, off offset:576
	v_cvt_pk_bf16_f32 v24, v20, s0
	global_store_short v[22:23], v24, off offset:1152
	v_cvt_pk_bf16_f32 v24, v21, s0
	global_store_short v[22:23], v24, off offset:1728
	s_cbranch_execz .LBB0_213
	s_branch .LBB0_214
.LBB0_398:
	v_lshlrev_b64 v[24:25], 13, v[18:19]
	v_lshl_add_u64 v[24:25], s[18:19], 0, v[24:25]
	v_mov_b32_e32 v79, v75
	v_lshl_add_u64 v[24:25], v[78:79], 2, v[24:25]
	global_store_dwordx4 v[24:25], v[14:17], off nt sc1
	v_lshlrev_b64 v[24:25], 11, v[22:23]
	v_lshl_add_u64 v[24:25], v[24:25], 0, v[78:79]
	v_mad_u64_u32 v[26:27], s[6:7], v24, s60, v[162:163]
	v_mad_i32_i24 v27, v25, s60, v27
	v_mov_b32_e32 v21, v75
	v_lshl_add_u64 v[24:25], v[26:27], 0, v[20:21]
	v_cvt_pk_bf16_f32 v21, v14, s0
	global_store_short v[24:25], v21, off
	v_cvt_pk_bf16_f32 v21, v15, s0
	global_store_short v[24:25], v21, off offset:576
	v_cvt_pk_bf16_f32 v21, v16, s0
	global_store_short v[24:25], v21, off offset:1152
	v_cvt_pk_bf16_f32 v21, v17, s0
	global_store_short v[24:25], v21, off offset:1728
	s_cbranch_execnz .LBB0_216
; DEV bf16_t f2bf(float f) { return (bf16_t)(cvt_pk_bf16(f, 0.f) & 0xffffu); }
; DEV void store_bf4(bf16_t* p, f32x4 v) { uint2 w; w.x = cvt_pk_bf16(v[0], v[1]); w.y = cvt_pk_bf16(v[2], v[3]); *(uint2*)p = w; }
;     DEV void operator()(int r, int c, f32x4 v) const { store_bf4(dst + (size_t)r * ld + c, v); }
;     DEV void operator()(int r, int c, f32x4 v) const {
;         const int row = m0 + r, col = n0 + c;
;         if (col < D) {
;             __builtin_nontemporal_store(v, (f32x4*)(out + O_MK + (size_t)row * D + col));
;             store_bf4(mkb + (size_t)row * LDB + col, v);
;         } else {
;             const int cc = col - D, b = row >> 8, m = row & 255;
;             __builtin_nontemporal_store(v, (f32x4*)(out + O_MV + (size_t)row * D + cc));
;             bf16_t* p = mvt + ((size_t)b * D + cc) * LDM + m;
;             p[0] = f2bf(v[0]); p[LDM] = f2bf(v[1]); p[2 * LDM] = f2bf(v[2]); p[3 * LDM] = f2bf(v[3]);
;         }
.LBB0_399:
	v_lshlrev_b64 v[24:25], 13, v[18:19]
	v_lshl_add_u64 v[24:25], s[20:21], 0, v[24:25]
	v_lshl_add_u64 v[24:25], v[74:75], 2, v[24:25]
	global_store_dwordx4 v[24:25], v[14:17], off nt sc1
	v_mad_i64_i32 v[24:25], s[6:7], v18, s56, v[168:169]
	v_mov_b32_e32 v77, v75
	v_lshl_add_u64 v[24:25], v[24:25], 0, v[76:77]
	v_cvt_pk_bf16_f32 v14, v14, v15
	v_cvt_pk_bf16_f32 v15, v16, v17
	global_store_dwordx2 v[24:25], v[14:15], off
	s_and_b64 vcc, exec, s[4:5]
	s_mov_b64 s[6:7], -1
	s_cbranch_vccnz .LBB0_217
.LBB0_400:
	v_lshlrev_b64 v[14:15], 13, v[18:19]
	v_lshl_add_u64 v[14:15], s[18:19], 0, v[14:15]
	v_mov_b32_e32 v63, v75
	v_lshl_add_u64 v[14:15], v[62:63], 2, v[14:15]
	global_store_dwordx4 v[14:15], v[10:13], off nt sc1
	v_lshlrev_b64 v[14:15], 11, v[22:23]
	v_lshl_add_u64 v[14:15], v[14:15], 0, v[62:63]
	v_mad_u64_u32 v[16:17], s[6:7], v14, s60, v[162:163]
	v_mad_i32_i24 v17, v15, s60, v17
	v_mov_b32_e32 v21, v75
	v_lshl_add_u64 v[14:15], v[16:17], 0, v[20:21]
	v_cvt_pk_bf16_f32 v16, v10, s0
	global_store_short v[14:15], v16, off
	v_cvt_pk_bf16_f32 v16, v11, s0
	global_store_short v[14:15], v16, off offset:576
	v_cvt_pk_bf16_f32 v16, v12, s0
	global_store_short v[14:15], v16, off offset:1152
	v_cvt_pk_bf16_f32 v16, v13, s0
	global_store_short v[14:15], v16, off offset:1728
	s_cbranch_execnz .LBB0_218
.LBB0_401:
	v_lshlrev_b64 v[14:15], 13, v[18:19]
	v_lshl_add_u64 v[14:15], s[20:21], 0, v[14:15]
	v_lshl_add_u64 v[14:15], v[74:75], 2, v[14:15]
	global_store_dwordx4 v[14:15], v[10:13], off offset:64 nt sc1
	v_mad_i64_i32 v[14:15], s[6:7], v18, s56, v[168:169]
	v_mov_b32_e32 v77, v75
	v_lshl_add_u64 v[14:15], v[14:15], 0, v[76:77]
	v_cvt_pk_bf16_f32 v10, v10, v11
	v_cvt_pk_bf16_f32 v11, v12, v13
	global_store_dwordx2 v[14:15], v[10:11], off offset:32
	s_and_b64 vcc, exec, s[4:5]
	s_mov_b64 s[6:7], -1
	s_cbranch_vccnz .LBB0_219
.LBB0_402:
	v_lshlrev_b64 v[10:11], 13, v[18:19]
	v_lshl_add_u64 v[10:11], s[18:19], 0, v[10:11]
	v_mov_b32_e32 v59, v75
	v_lshl_add_u64 v[10:11], v[58:59], 2, v[10:11]
	global_store_dwordx4 v[10:11], v[6:9], off nt sc1
	v_lshlrev_b64 v[10:11], 11, v[22:23]
	v_lshl_add_u64 v[10:11], v[10:11], 0, v[58:59]
	v_mad_u64_u32 v[12:13], s[6:7], v10, s60, v[162:163]
	v_mad_i32_i24 v13, v11, s60, v13
	v_mov_b32_e32 v21, v75
	v_lshl_add_u64 v[10:11], v[12:13], 0, v[20:21]
	v_cvt_pk_bf16_f32 v12, v6, s0
	global_store_short v[10:11], v12, off
	v_cvt_pk_bf16_f32 v12, v7, s0
	global_store_short v[10:11], v12, off offset:576
	v_cvt_pk_bf16_f32 v12, v8, s0
	global_store_short v[10:11], v12, off offset:1152
	v_cvt_pk_bf16_f32 v12, v9, s0
	global_store_short v[10:11], v12, off offset:1728
	s_cbranch_execnz .LBB0_220
.LBB0_403:
	v_lshlrev_b64 v[10:11], 13, v[18:19]
	v_lshl_add_u64 v[10:11], s[20:21], 0, v[10:11]
	v_lshl_add_u64 v[10:11], v[74:75], 2, v[10:11]
	global_store_dwordx4 v[10:11], v[6:9], off offset:128 nt sc1
	v_mad_i64_i32 v[10:11], s[6:7], v18, s56, v[168:169]
	v_mov_b32_e32 v77, v75
	v_lshl_add_u64 v[10:11], v[10:11], 0, v[76:77]
	v_cvt_pk_bf16_f32 v6, v6, v7
	v_cvt_pk_bf16_f32 v7, v8, v9
	global_store_dwordx2 v[10:11], v[6:7], off offset:64
	s_and_b64 vcc, exec, s[4:5]
	s_mov_b64 s[4:5], -1
	s_cbranch_vccnz .LBB0_221
.LBB0_404:
	v_lshlrev_b64 v[6:7], 13, v[18:19]
	v_lshl_add_u64 v[6:7], s[18:19], 0, v[6:7]
	v_mov_b32_e32 v55, v75
	v_lshl_add_u64 v[6:7], v[54:55], 2, v[6:7]
	global_store_dwordx4 v[6:7], v[2:5], off nt sc1
	v_lshlrev_b64 v[6:7], 11, v[22:23]
	v_lshl_add_u64 v[6:7], v[6:7], 0, v[54:55]
	v_mad_u64_u32 v[8:9], s[4:5], v6, s60, v[162:163]
	v_mad_i32_i24 v9, v7, s60, v9
	v_mov_b32_e32 v21, v75
	v_lshl_add_u64 v[6:7], v[8:9], 0, v[20:21]
	v_cvt_pk_bf16_f32 v8, v2, s0
	global_store_short v[6:7], v8, off
	v_cvt_pk_bf16_f32 v8, v3, s0
	global_store_short v[6:7], v8, off offset:576
	v_cvt_pk_bf16_f32 v8, v4, s0
	global_store_short v[6:7], v8, off offset:1152
	v_cvt_pk_bf16_f32 v8, v5, s0
	global_store_short v[6:7], v8, off offset:1728
	s_cbranch_execz .LBB0_222
	s_branch .LBB0_223

; DEV void ab_rows16(const bf16_t* __restrict__ h, const bf16_t* __restrict__ wab, float* __restrict__ ab4, int rt, int kq, int lane) {
;     const int fr = lane & 15, fq = lane >> 4;
;     const bf16_t* ap = h + (size_t)(rt * 16 + fr) * LDB + kq * 512 + fq * 8;
;     const bf16_t* bp = wab + (size_t)fr * LDB + kq * 512 + fq * 8;
;     bf16x8 a[16], b[16];
; #pragma unroll
;     for (int s = 0; s < 16; ++s) { a[s] = *(const bf16x8*)(ap + s * 32); b[s] = *(const bf16x8*)(bp + s * 32); }
;     f32x4 acc = {0.f, 0.f, 0.f, 0.f};
; #pragma unroll
;     for (int s = 0; s < 16; ++s) acc = __builtin_amdgcn_mfma_f32_16x16x32_bf16(b[s], a[s], acc, 0, 0, 0);
;     *(f32x4*)(ab4 + (size_t)kq * TT * 16 + (size_t)(rt * 16 + fr) * 16 + fq * 4) = acc;
; }
.LBB0_407:
	v_and_or_b32 v84, v1, -16, v71
	v_mad_i64_i32 v[86:87], s[12:13], v84, s10, v[66:67]
	s_nop 0
	global_load_dwordx4 v[72:75], v[86:87], off
	global_load_dwordx4 v[76:79], v[86:87], off offset:64
	global_load_dwordx4 v[80:83], v[86:87], off offset:128
	v_add_u32_e32 v70, s8, v70
	v_ashrrev_i32_e32 v85, 31, v84
	v_cmp_lt_i32_e32 vcc, s11, v70
	v_add_u32_e32 v1, s9, v1
	s_or_b64 s[6:7], vcc, s[6:7]
	s_waitcnt vmcnt(2)
	v_mfma_f32_16x16x32_bf16 v[72:75], v[58:61], v[72:75], 0
	s_waitcnt vmcnt(1)
	v_mfma_f32_16x16x32_bf16 v[72:75], v[2:5], v[76:79], v[72:75]
	global_load_dwordx4 v[76:79], v[86:87], off offset:192
	s_waitcnt vmcnt(1)
	v_mfma_f32_16x16x32_bf16 v[72:75], v[6:9], v[80:83], v[72:75]
	global_load_dwordx4 v[80:83], v[86:87], off offset:256
	s_waitcnt vmcnt(1)
	v_mfma_f32_16x16x32_bf16 v[72:75], v[10:13], v[76:79], v[72:75]
	global_load_dwordx4 v[76:79], v[86:87], off offset:320
	s_waitcnt vmcnt(1)
	v_mfma_f32_16x16x32_bf16 v[72:75], v[14:17], v[80:83], v[72:75]
	global_load_dwordx4 v[80:83], v[86:87], off offset:384
	s_waitcnt vmcnt(1)
	v_mfma_f32_16x16x32_bf16 v[72:75], v[18:21], v[76:79], v[72:75]
	global_load_dwordx4 v[76:79], v[86:87], off offset:448
	s_waitcnt vmcnt(1)
	v_mfma_f32_16x16x32_bf16 v[72:75], v[22:25], v[80:83], v[72:75]
	global_load_dwordx4 v[80:83], v[86:87], off offset:512
	s_waitcnt vmcnt(1)
	v_mfma_f32_16x16x32_bf16 v[72:75], v[26:29], v[76:79], v[72:75]
	global_load_dwordx4 v[76:79], v[86:87], off offset:576
	s_waitcnt vmcnt(1)
	v_mfma_f32_16x16x32_bf16 v[72:75], v[30:33], v[80:83], v[72:75]
	global_load_dwordx4 v[80:83], v[86:87], off offset:640
	s_waitcnt vmcnt(1)
	v_mfma_f32_16x16x32_bf16 v[72:75], v[34:37], v[76:79], v[72:75]
	global_load_dwordx4 v[76:79], v[86:87], off offset:704
	s_waitcnt vmcnt(1)
	v_mfma_f32_16x16x32_bf16 v[72:75], v[38:41], v[80:83], v[72:75]
	global_load_dwordx4 v[80:83], v[86:87], off offset:768
	s_waitcnt vmcnt(1)
	v_mfma_f32_16x16x32_bf16 v[72:75], v[42:45], v[76:79], v[72:75]
	global_load_dwordx4 v[76:79], v[86:87], off offset:832
	s_waitcnt vmcnt(1)
	v_mfma_f32_16x16x32_bf16 v[72:75], v[46:49], v[80:83], v[72:75]
	global_load_dwordx4 v[80:83], v[86:87], off offset:896
	s_waitcnt vmcnt(1)
	v_mfma_f32_16x16x32_bf16 v[72:75], v[50:53], v[76:79], v[72:75]
	global_load_dwordx4 v[76:79], v[86:87], off offset:960
	s_waitcnt vmcnt(1)
	v_mfma_f32_16x16x32_bf16 v[72:75], v[54:57], v[80:83], v[72:75]
	s_waitcnt vmcnt(0)
	v_mfma_f32_16x16x32_bf16 v[72:75], v[62:65], v[76:79], v[72:75]
	v_lshlrev_b64 v[76:77], 6, v[84:85]
	v_lshl_add_u64 v[76:77], v[68:69], 0, v[76:77]
	s_nop 5
	global_store_dwordx4 v[76:77], v[72:75], off sc1
	s_andn2_b64 exec, exec, s[6:7]
	s_cbranch_execnz .LBB0_407

; DEV unsigned cvt_pk_bf16(float lo, float hi) { const f32x2_t v = {lo, hi}; const bf16x2_t b = __builtin_convertvector(v, bf16x2_t); return __builtin_bit_cast(unsigned, b); }
; DEV bf16_t f2bf(float f) { return (bf16_t)(cvt_pk_bf16(f, 0.f) & 0xffffu); }
; DEV float bf2f(unsigned b) { return __uint_as_float(b << 16); }
; DEV float bflo(unsigned u) { return __uint_as_float(u << 16); }
; DEV float bfhi(unsigned u) { return __uint_as_float(u & 0xffff0000u); }
; DEV void gdn_prep_chunk(const Params& p, int item, unsigned char* lds) {
;     ...
;         const float glast = gcs[63];
;         if (tid == 0) *gE = __expf(glast);
; #pragma unroll
;         for (int i = 0; i < 4; ++i) {
;             const int ci = tid + 256 * i, t = ci >> 4, cc = (ci & 15) * 8;
;             const uint4 u = *(const uint4*)(qs + t * QS + cc);
;             const float e = __expf(gcs[t]);
;             uint4 o; o.x = cvt_pk_bf16(bflo(u.x) * e, bfhi(u.x) * e); o.y = cvt_pk_bf16(bflo(u.y) * e, bfhi(u.y) * e);
;             o.z = cvt_pk_bf16(bflo(u.z) * e, bfhi(u.z) * e); o.w = cvt_pk_bf16(bflo(u.w) * e, bfhi(u.w) * e);
;             *(uint4*)(gQ + (cc >> 5) * 2048 + t * 32 + (cc & 31)) = o;
;         }
;         const float dk = __expf(glast - gcs[lane]);
; #pragma unroll 8
;         for (int i = 0; i < 32; ++i) { const int d = wid * 32 + i; gKT[(lane >> 5) * 4096 + d * 32 + (lane & 31)] = f2bf(bf2f(ks[lane * QS + d]) * dk);     }
.LBB0_511:
	s_or_b64 exec, exec, s[4:5]
	v_lshlrev_b32_e32 v3, 4, v130
	v_and_b32_e32 v4, 0xf0, v3
	v_add_u32_e32 v12, s39, v4
	v_ashrrev_i32_e32 v13, 4, v130
	v_mad_u64_u32 v[4:5], s[34:35], v13, s57, v[12:13]
	v_lshl_add_u32 v9, v13, 2, s39
	ds_read_b128 v[4:7], v4
	ds_read_b32 v10, v9 offset:52224
	s_lshl_b64 s[4:5], s[30:31], 14
	s_add_u32 s6, s45, s4
	v_lshlrev_b32_e32 v8, 10, v130
	s_addc_u32 s7, s46, s5
	v_and_b32_e32 v142, 0x3000, v8
	v_lshl_add_u64 v[8:9], s[6:7], 0, v[142:143]
	v_and_b32_e32 v142, 48, v3
	s_waitcnt lgkmcnt(0)
	v_mul_f32_e32 v3, 0x3fb8aa3b, v10
	v_lshl_add_u64 v[14:15], v[8:9], 0, v[142:143]
	v_exp_f32_e32 v8, v3
	v_lshlrev_b32_e32 v10, 16, v4
	v_and_b32_e32 v11, 0xffff0000, v4
	v_mov_b32_e32 v3, s39
	v_pk_mul_f32 v[10:11], v[8:9], v[10:11] op_sel_hi:[0,1]
	v_cvt_pk_bf16_f32 v4, v10, v11
	v_lshlrev_b32_e32 v10, 16, v5
	v_and_b32_e32 v11, 0xffff0000, v5
	v_pk_mul_f32 v[10:11], v[8:9], v[10:11] op_sel_hi:[0,1]
	v_cvt_pk_bf16_f32 v5, v10, v11
	v_lshlrev_b32_e32 v10, 16, v6
	v_and_b32_e32 v11, 0xffff0000, v6
	v_pk_mul_f32 v[10:11], v[8:9], v[10:11] op_sel_hi:[0,1]
	v_cvt_pk_bf16_f32 v6, v10, v11
	v_lshlrev_b32_e32 v10, 16, v7
	v_and_b32_e32 v11, 0xffff0000, v7
	v_add_u32_e32 v7, 0x100, v130
	v_ashrrev_i32_e32 v19, 4, v7
	v_pk_mul_f32 v[16:17], v[8:9], v[10:11] op_sel_hi:[0,1]
	v_mad_u64_u32 v[8:9], s[6:7], v19, s57, v[12:13]
	v_lshl_add_u32 v7, v19, 2, s39
	ds_read_b128 v[8:11], v8
	ds_read_b32 v18, v7 offset:52224
	v_cvt_pk_bf16_f32 v7, v16, v17
	v_lshlrev_b32_e32 v16, 5, v13
	v_ashrrev_i32_e32 v17, 31, v16
	v_lshl_add_u64 v[16:17], v[16:17], 1, v[14:15]
	s_waitcnt lgkmcnt(0)
	v_mul_f32_e32 v13, 0x3fb8aa3b, v18
	v_exp_f32_e32 v18, v13
	global_store_dwordx4 v[16:17], v[4:7], off sc1
	v_mad_u32_u24 v20, v34, s57, v3
	v_lshl_add_u32 v3, v131, 6, v20
	v_lshlrev_b32_e32 v4, 16, v8
	v_and_b32_e32 v5, 0xffff0000, v8
	v_lshlrev_b32_e32 v6, 16, v9
	v_and_b32_e32 v7, 0xffff0000, v9
	v_pk_mul_f32 v[4:5], v[18:19], v[4:5] op_sel_hi:[0,1]
	v_pk_mul_f32 v[6:7], v[18:19], v[6:7] op_sel_hi:[0,1]
	v_cvt_pk_bf16_f32 v4, v4, v5
	v_cvt_pk_bf16_f32 v5, v6, v7
	v_lshlrev_b32_e32 v6, 16, v10
	v_and_b32_e32 v7, 0xffff0000, v10
	v_pk_mul_f32 v[6:7], v[18:19], v[6:7] op_sel_hi:[0,1]
	v_cvt_pk_bf16_f32 v6, v6, v7
	v_add_u32_e32 v7, 0x200, v130
	v_lshlrev_b32_e32 v8, 16, v11
	v_and_b32_e32 v9, 0xffff0000, v11
	v_ashrrev_i32_e32 v13, 4, v7
	v_pk_mul_f32 v[16:17], v[18:19], v[8:9] op_sel_hi:[0,1]
	v_mad_u64_u32 v[8:9], s[6:7], v13, s57, v[12:13]
	v_lshl_add_u32 v7, v13, 2, s39
	ds_read_b128 v[8:11], v8
	ds_read_b32 v18, v7 offset:52224
	v_cvt_pk_bf16_f32 v7, v16, v17
	v_lshlrev_b32_e32 v16, 5, v19
	v_ashrrev_i32_e32 v17, 31, v16
	v_lshl_add_u64 v[16:17], v[16:17], 1, v[14:15]
	s_waitcnt lgkmcnt(0)
	v_mul_f32_e32 v18, 0x3fb8aa3b, v18
	v_exp_f32_e32 v18, v18
	global_store_dwordx4 v[16:17], v[4:7], off sc1
	v_and_b32_e32 v38, 31, v130
	s_add_u32 s4, s47, s4
	v_lshlrev_b32_e32 v4, 16, v8
	v_and_b32_e32 v5, 0xffff0000, v8
	v_lshlrev_b32_e32 v6, 16, v9
	v_and_b32_e32 v7, 0xffff0000, v9
	v_pk_mul_f32 v[4:5], v[18:19], v[4:5] op_sel_hi:[0,1]
	v_pk_mul_f32 v[6:7], v[18:19], v[6:7] op_sel_hi:[0,1]
	v_cvt_pk_bf16_f32 v4, v4, v5
	v_cvt_pk_bf16_f32 v5, v6, v7
	v_lshlrev_b32_e32 v6, 16, v10
	v_and_b32_e32 v7, 0xffff0000, v10
	v_lshlrev_b32_e32 v8, 16, v11
	v_and_b32_e32 v9, 0xffff0000, v11
	v_pk_mul_f32 v[6:7], v[18:19], v[6:7] op_sel_hi:[0,1]
	v_pk_mul_f32 v[8:9], v[18:19], v[8:9] op_sel_hi:[0,1]
	v_cvt_pk_bf16_f32 v6, v6, v7
	v_cvt_pk_bf16_f32 v7, v8, v9
	v_lshlrev_b32_e32 v8, 5, v13
	v_ashrrev_i32_e32 v9, 31, v8
	v_lshl_add_u64 v[16:17], v[8:9], 1, v[14:15]
	v_add_u32_e32 v8, 0x300, v130
	v_ashrrev_i32_e32 v19, 4, v8
	v_mad_u64_u32 v[8:9], s[6:7], v19, s57, v[12:13]
	v_lshl_add_u32 v9, v19, 2, s39
	ds_read_b32 v18, v9 offset:52224
	v_lshl_add_u32 v12, v34, 2, s39
	ds_read_b128 v[8:11], v8
	ds_read_b32 v21, v12 offset:52224
	ds_read_b64 v[12:13], v3 offset:17408
	global_store_dwordx4 v[16:17], v[4:7], off sc1
	s_addc_u32 s5, s48, s5
	s_waitcnt lgkmcnt(3)
	v_mul_f32_e32 v3, 0x3fb8aa3b, v18
	v_exp_f32_e32 v18, v3
	s_waitcnt lgkmcnt(2)
	v_lshlrev_b32_e32 v4, 16, v8
	v_and_b32_e32 v5, 0xffff0000, v8
	v_lshlrev_b32_e32 v6, 16, v9
	v_and_b32_e32 v7, 0xffff0000, v9
	v_pk_mul_f32 v[4:5], v[18:19], v[4:5] op_sel_hi:[0,1]
	v_pk_mul_f32 v[6:7], v[18:19], v[6:7] op_sel_hi:[0,1]
	v_cvt_pk_bf16_f32 v4, v4, v5
	v_cvt_pk_bf16_f32 v5, v6, v7
	v_lshlrev_b32_e32 v6, 16, v10
	v_and_b32_e32 v7, 0xffff0000, v10
	v_lshlrev_b32_e32 v8, 16, v11
	v_and_b32_e32 v9, 0xffff0000, v11
	s_waitcnt lgkmcnt(1)
	v_sub_f32_e32 v2, v2, v21
	v_pk_mul_f32 v[6:7], v[18:19], v[6:7] op_sel_hi:[0,1]
	v_pk_mul_f32 v[8:9], v[18:19], v[8:9] op_sel_hi:[0,1]
	v_mul_f32_e32 v2, 0x3fb8aa3b, v2
	v_cvt_pk_bf16_f32 v6, v6, v7
	v_cvt_pk_bf16_f32 v7, v8, v9
	v_lshlrev_b32_e32 v8, 5, v19
	v_exp_f32_e32 v2, v2
	v_ashrrev_i32_e32 v9, 31, v8
	v_lshl_add_u64 v[8:9], v[8:9], 1, v[14:15]
	v_lshlrev_b32_e32 v3, 7, v34
	global_store_dwordx4 v[8:9], v[4:7], off sc1
	v_and_or_b32 v3, v3, s63, v38
	v_lshlrev_b32_e32 v22, 5, v131
	s_waitcnt lgkmcnt(0)
	v_and_b32_e32 v5, 0xffff0000, v13
	v_lshlrev_b32_e32 v4, 16, v13
	v_and_b32_e32 v7, 0xffff0000, v12
	v_lshlrev_b32_e32 v6, 16, v12
	v_pk_mul_f32 v[4:5], v[2:3], v[4:5] op_sel_hi:[0,1]
	v_pk_mul_f32 v[6:7], v[2:3], v[6:7] op_sel_hi:[0,1]
	v_cvt_pk_bf16_f32 v15, v4, s0
	v_lshl_add_u32 v4, v131, 10, v3
	v_cvt_pk_bf16_f32 v17, v6, s0
	v_or_b32_e32 v6, 32, v4
	v_cvt_pk_bf16_f32 v14, v5, s0
	v_cvt_pk_bf16_f32 v16, v7, s0
	v_or_b32_e32 v8, 64, v4
	v_or_b32_e32 v10, 0x60, v4
	v_ashrrev_i32_e32 v7, 31, v6
	v_ashrrev_i32_e32 v5, 31, v4
	v_ashrrev_i32_e32 v11, 31, v10
	v_ashrrev_i32_e32 v9, 31, v8
	v_lshl_add_u64 v[12:13], v[4:5], 1, s[4:5]
	v_lshl_add_u64 v[6:7], v[6:7], 1, s[4:5]
	v_or_b32_e32 v5, 4, v22
	v_lshl_add_u64 v[8:9], v[8:9], 1, s[4:5]
	v_lshl_add_u64 v[10:11], v[10:11], 1, s[4:5]
	global_store_short v[12:13], v17, off
	global_store_short v[6:7], v16, off
	global_store_short v[8:9], v15, off
	global_store_short v[10:11], v14, off
	v_lshl_add_u32 v6, v5, 1, v20
	ds_read_b64 v[6:7], v6 offset:17408
	v_or_b32_e32 v21, 8, v22
	v_or_b32_e32 v23, 12, v22
	v_or_b32_e32 v24, 16, v22
	v_lshl_add_u32 v8, v21, 1, v20
	s_waitcnt lgkmcnt(0)
; DEV bf16_t f2bf(float f) { return (bf16_t)(cvt_pk_bf16(f, 0.f) & 0xffffu); }
; DEV float bf2f(unsigned b) { return __uint_as_float(b << 16); }
; DEV void gdn_prep_chunk(const Params& p, int item, unsigned char* lds) {
;     ...
;         for (int i = 0; i < 32; ++i) { const int d = wid * 32 + i; gKT[(lane >> 5) * 4096 + d * 32 + (lane & 31)] = f2bf(bf2f(ks[lane * QS + d]) * dk);     }
;     }
;     f32x4 kk[4], qk[4];
;     {
;         const int fr = lane & 15, fq = lane >> 4, it = wid;
;         bf16x8 kfi[4], qfi[4];
; #pragma unroll
;         for (int s = 0; s < 4; ++s) { kfi[s] = *(const bf16x8*)(ks + (it * 16 + fr) * QS + s * 32 + fq * 8); qfi[s] = *(const bf16x8*)(qs + (it * 16 + fr) * QS + s * 32 + fq * 8); }
; #pragma unroll
;         for (int jt = 0; jt < 4; ++jt) {
;             kk[jt] = (f32x4){0.f, 0.f, 0.f, 0.f}; qk[jt] = (f32x4){0.f, 0.f, 0.f, 0.f};
; #pragma unroll
;             for (int s = 0; s < 4; ++s) {
;                 const bf16x8 kfj = *(const bf16x8*)(ks + (jt * 16 + fr) * QS + s * 32 + fq * 8);
;                 kk[jt] = __builtin_amdgcn_mfma_f32_16x16x32_bf16(kfi[s], kfj, kk[jt], 0, 0, 0);
;                 qk[jt] = __builtin_amdgcn_mfma_f32_16x16x32_bf16(kfj, qfi[s], qk[jt], 0, 0, 0);
;             }
;         }
	v_and_b32_e32 v15, 0xffff0000, v7
	v_lshlrev_b32_e32 v14, 16, v7
	v_and_b32_e32 v7, 0xffff0000, v6
	v_lshlrev_b32_e32 v6, 16, v6
	v_lshl_add_u32 v10, v23, 1, v20
	v_lshl_add_u32 v12, v24, 1, v20
	v_pk_mul_f32 v[6:7], v[2:3], v[6:7] op_sel_hi:[0,1]
	ds_read_b64 v[8:9], v8 offset:17408
	ds_read_b64 v[10:11], v10 offset:17408
	ds_read_b64 v[12:13], v12 offset:17408
	v_pk_mul_f32 v[14:15], v[2:3], v[14:15] op_sel_hi:[0,1]
	v_cvt_pk_bf16_f32 v28, v6, s0
	v_lshl_add_u32 v6, v5, 5, v3
	v_cvt_pk_bf16_f32 v26, v14, s0
	v_cvt_pk_bf16_f32 v27, v7, s0
	v_or_b32_e32 v14, 0xa0, v4
	v_or_b32_e32 v16, 0xc0, v4
	v_or_b32_e32 v18, 0xe0, v4
	v_ashrrev_i32_e32 v7, 31, v6
	v_cvt_pk_bf16_f32 v25, v15, s0
	v_ashrrev_i32_e32 v19, 31, v18
	v_ashrrev_i32_e32 v17, 31, v16
	v_ashrrev_i32_e32 v15, 31, v14
	v_lshl_add_u64 v[6:7], v[6:7], 1, s[4:5]
	v_lshl_add_u64 v[14:15], v[14:15], 1, s[4:5]
	v_lshl_add_u64 v[16:17], v[16:17], 1, s[4:5]
	v_lshl_add_u64 v[18:19], v[18:19], 1, s[4:5]
	global_store_short v[6:7], v28, off
	global_store_short v[14:15], v27, off
	global_store_short v[16:17], v26, off
	global_store_short v[18:19], v25, off
	s_waitcnt lgkmcnt(2)
	v_and_b32_e32 v7, 0xffff0000, v9
	v_lshlrev_b32_e32 v6, 16, v9
	v_and_b32_e32 v9, 0xffff0000, v8
	v_lshlrev_b32_e32 v8, 16, v8
	v_pk_mul_f32 v[6:7], v[2:3], v[6:7] op_sel_hi:[0,1]
	v_pk_mul_f32 v[8:9], v[2:3], v[8:9] op_sel_hi:[0,1]
	v_cvt_pk_bf16_f32 v18, v6, s0
	v_lshl_add_u32 v6, v21, 5, v3
	v_cvt_pk_bf16_f32 v5, v7, s0
	v_cvt_pk_bf16_f32 v25, v8, s0
	v_or_b32_e32 v8, 0x120, v4
	v_or_b32_e32 v14, 0x140, v4
	v_or_b32_e32 v16, 0x160, v4
	v_ashrrev_i32_e32 v7, 31, v6
	v_cvt_pk_bf16_f32 v19, v9, s0
	v_ashrrev_i32_e32 v17, 31, v16
	v_ashrrev_i32_e32 v15, 31, v14
	v_ashrrev_i32_e32 v9, 31, v8
	v_lshl_add_u64 v[6:7], v[6:7], 1, s[4:5]
	v_lshl_add_u64 v[8:9], v[8:9], 1, s[4:5]
	v_lshl_add_u64 v[14:15], v[14:15], 1, s[4:5]
	v_lshl_add_u64 v[16:17], v[16:17], 1, s[4:5]
	global_store_short v[6:7], v25, off
	global_store_short v[8:9], v19, off
	global_store_short v[14:15], v18, off
	global_store_short v[16:17], v5, off
	s_waitcnt lgkmcnt(1)
	v_and_b32_e32 v7, 0xffff0000, v11
	v_lshlrev_b32_e32 v6, 16, v11
	v_and_b32_e32 v9, 0xffff0000, v10
	v_lshlrev_b32_e32 v8, 16, v10
	v_pk_mul_f32 v[6:7], v[2:3], v[6:7] op_sel_hi:[0,1]
	v_pk_mul_f32 v[8:9], v[2:3], v[8:9] op_sel_hi:[0,1]
	v_cvt_pk_bf16_f32 v16, v6, s0
	v_lshl_add_u32 v6, v23, 5, v3
	v_cvt_pk_bf16_f32 v5, v7, s0
	v_cvt_pk_bf16_f32 v18, v8, s0
	v_or_b32_e32 v8, 0x1a0, v4
	v_or_b32_e32 v10, 0x1c0, v4
	v_or_b32_e32 v14, 0x1e0, v4
	v_ashrrev_i32_e32 v7, 31, v6
	v_cvt_pk_bf16_f32 v17, v9, s0
	v_ashrrev_i32_e32 v15, 31, v14
	v_ashrrev_i32_e32 v11, 31, v10
	v_ashrrev_i32_e32 v9, 31, v8
	v_lshl_add_u64 v[6:7], v[6:7], 1, s[4:5]
	v_lshl_add_u64 v[8:9], v[8:9], 1, s[4:5]
	v_lshl_add_u64 v[10:11], v[10:11], 1, s[4:5]
	v_lshl_add_u64 v[14:15], v[14:15], 1, s[4:5]
	global_store_short v[6:7], v18, off
	global_store_short v[8:9], v17, off
	global_store_short v[10:11], v16, off
	global_store_short v[14:15], v5, off
	s_waitcnt lgkmcnt(0)
	v_and_b32_e32 v7, 0xffff0000, v13
	v_lshlrev_b32_e32 v6, 16, v13
	v_and_b32_e32 v9, 0xffff0000, v12
	v_lshlrev_b32_e32 v8, 16, v12
	v_pk_mul_f32 v[6:7], v[2:3], v[6:7] op_sel_hi:[0,1]
	v_pk_mul_f32 v[8:9], v[2:3], v[8:9] op_sel_hi:[0,1]
	v_cvt_pk_bf16_f32 v14, v6, s0
	v_lshl_add_u32 v6, v24, 5, v3
	v_cvt_pk_bf16_f32 v5, v7, s0
	v_cvt_pk_bf16_f32 v16, v8, s0
	v_or_b32_e32 v8, 0x220, v4
	v_or_b32_e32 v10, 0x240, v4
	v_or_b32_e32 v12, 0x260, v4
	v_ashrrev_i32_e32 v7, 31, v6
	v_cvt_pk_bf16_f32 v15, v9, s0
	v_ashrrev_i32_e32 v13, 31, v12
	v_ashrrev_i32_e32 v11, 31, v10
	v_ashrrev_i32_e32 v9, 31, v8
	v_lshl_add_u64 v[6:7], v[6:7], 1, s[4:5]
	v_lshl_add_u64 v[8:9], v[8:9], 1, s[4:5]
	v_lshl_add_u64 v[10:11], v[10:11], 1, s[4:5]
	v_lshl_add_u64 v[12:13], v[12:13], 1, s[4:5]
	global_store_short v[6:7], v16, off
	global_store_short v[8:9], v15, off
	global_store_short v[10:11], v14, off
	global_store_short v[12:13], v5, off
	v_or_b32_e32 v5, 20, v22
	v_lshl_add_u32 v6, v5, 1, v20
	v_or_b32_e32 v35, 24, v22
	ds_read_b64 v[14:15], v6 offset:17408
	v_lshl_add_u32 v6, v35, 1, v20
	v_or_b32_e32 v44, 28, v22
	v_lshl_add_u32 v7, v44, 1, v20
	ds_read_b64 v[36:37], v6 offset:17408
	ds_read_b64 v[82:83], v7 offset:17408
	v_and_b32_e32 v145, 15, v130
	v_lshlrev_b32_e32 v45, 4, v131
	v_and_b32_e32 v6, 48, v34
	v_or_b32_e32 v39, v45, v145
	v_add_u32_e32 v10, s39, v6
	v_mad_u64_u32 v[26:27], s[6:7], v39, s57, v[10:11]
	ds_read_b128 v[6:9], v26 offset:17408
	v_mad_u32_u24 v90, v145, s57, v10
	ds_read_b128 v[10:13], v90 offset:17408
	s_waitcnt lgkmcnt(4)
	v_and_b32_e32 v23, 0xffff0000, v15
	v_lshlrev_b32_e32 v22, 16, v15
	v_and_b32_e32 v25, 0xffff0000, v14
	v_lshlrev_b32_e32 v24, 16, v14
	ds_read_b128 v[40:43], v26
	ds_read_b128 v[46:49], v26 offset:17472
	ds_read_b128 v[14:17], v90 offset:17472
	ds_read_b128 v[50:53], v26 offset:64
	ds_read_b128 v[54:57], v26 offset:17536
	s_waitcnt lgkmcnt(5)
	v_mfma_f32_16x16x32_bf16 v[18:21], v[6:9], v[10:13], 0
	v_mul_f32_e64 v24, v2, v24
	v_mul_f32_e64 v25, v2, v25
	v_pk_mul_f32 v[22:23], v[2:3], v[22:23] op_sel_hi:[0,1]
	v_cvt_pk_bf16_f32 v74, v23, s0
	s_waitcnt lgkmcnt(4)
	v_mfma_f32_16x16x32_bf16 v[10:13], v[10:13], v[40:43], 0
	v_cvt_pk_bf16_f32 v75, v22, s0
	v_cvt_pk_bf16_f32 v76, v25, s0
	v_cvt_pk_bf16_f32 v77, v24, s0
	ds_read_b128 v[22:25], v90 offset:17536
	s_waitcnt lgkmcnt(3)
	v_mfma_f32_16x16x32_bf16 v[18:21], v[46:49], v[14:17], v[18:21]
	v_lshl_add_u32 v70, v5, 5, v3
	v_or_b32_e32 v72, 0x2a0, v4
	v_ashrrev_i32_e32 v71, 31, v70
	s_waitcnt lgkmcnt(2)
; DEV void gdn_prep_chunk(const Params& p, int item, unsigned char* lds) {
;     ...
;     f32x4 kk[4], qk[4];
;     {
;         const int fr = lane & 15, fq = lane >> 4, it = wid;
;         bf16x8 kfi[4], qfi[4];
; #pragma unroll
;         for (int s = 0; s < 4; ++s) { kfi[s] = *(const bf16x8*)(ks + (it * 16 + fr) * QS + s * 32 + fq * 8); qfi[s] = *(const bf16x8*)(qs + (it * 16 + fr) * QS + s * 32 + fq * 8); }
; #pragma unroll
;         for (int jt = 0; jt < 4; ++jt) {
;             kk[jt] = (f32x4){0.f, 0.f, 0.f, 0.f}; qk[jt] = (f32x4){0.f, 0.f, 0.f, 0.f};
; #pragma unroll
;             for (int s = 0; s < 4; ++s) {
;                 const bf16x8 kfj = *(const bf16x8*)(ks + (jt * 16 + fr) * QS + s * 32 + fq * 8);
;                 kk[jt] = __builtin_amdgcn_mfma_f32_16x16x32_bf16(kfi[s], kfj, kk[jt], 0, 0, 0);
;                 qk[jt] = __builtin_amdgcn_mfma_f32_16x16x32_bf16(kfj, qfi[s], qk[jt], 0, 0, 0);
;             }
;         }
;     }
;     __syncthreads();
;     {
;         const int fr = lane & 15, fq = lane >> 4, it = wid;
; #pragma unroll
;         for (int jt = 0; jt < 4; ++jt) {
;             const int j = jt * 16 + fr; const float gj = gcs[j];
;             f32x4 lv;
; #pragma unroll
;             for (int e = 0; e < 4; ++e) { const int i = it * 16 + fq * 4 + e; lv[e] = (i > j) ? bts[i] * kk[jt][e] * __expf(gcs[i] - gj) : 0.f; }
;             *(f32x4*)(lowT + j * 68 + it * 16 + fq * 4) = lv;
	v_mfma_f32_16x16x32_bf16 v[10:13], v[14:17], v[50:53], v[10:13]
	ds_read_b128 v[58:61], v26 offset:128
	ds_read_b128 v[62:65], v26 offset:17600
	ds_read_b128 v[14:17], v90 offset:17600
	ds_read_b128 v[66:69], v26 offset:192
	v_ashrrev_i32_e32 v73, 31, v72
	s_waitcnt lgkmcnt(4)
	v_mfma_f32_16x16x32_bf16 v[18:21], v[54:57], v[22:25], v[18:21]
	v_lshl_add_u64 v[70:71], v[70:71], 1, s[4:5]
	v_lshl_add_u64 v[72:73], v[72:73], 1, s[4:5]
	v_or_b32_e32 v78, 0x360, v4
	s_waitcnt lgkmcnt(3)
	v_mfma_f32_16x16x32_bf16 v[10:13], v[22:25], v[58:61], v[10:13]
	v_or_b32_e32 v22, 0x2c0, v4
	v_or_b32_e32 v24, 0x2e0, v4
	v_ashrrev_i32_e32 v25, 31, v24
	s_waitcnt lgkmcnt(1)
	v_mfma_f32_16x16x32_bf16 v[30:33], v[62:65], v[14:17], v[18:21]
	v_ashrrev_i32_e32 v23, 31, v22
	v_lshl_add_u64 v[22:23], v[22:23], 1, s[4:5]
	v_lshl_add_u64 v[24:25], v[24:25], 1, s[4:5]
	ds_read_b128 v[18:21], v90 offset:21760
	s_waitcnt lgkmcnt(1)
	v_mfma_f32_16x16x32_bf16 v[26:29], v[14:17], v[66:69], v[10:13]
	v_ashrrev_i32_e32 v79, 31, v78
	v_lshl_add_u64 v[88:89], v[78:79], 1, s[4:5]
	v_lshrrev_b32_e32 v34, 2, v34
	ds_read_b128 v[10:13], v90 offset:21824
	s_waitcnt lgkmcnt(1)
	v_mfma_f32_16x16x32_bf16 v[14:17], v[6:9], v[18:21], 0
	global_store_short v[70:71], v77, off
	global_store_short v[72:73], v76, off
	global_store_short v[22:23], v75, off
	global_store_short v[24:25], v74, off
	ds_read_b128 v[22:25], v90 offset:21888
	v_mfma_f32_16x16x32_bf16 v[18:21], v[18:21], v[40:43], 0
	v_and_b32_e32 v71, 0xffff0000, v37
	v_lshlrev_b32_e32 v70, 16, v37
	v_pk_mul_f32 v[70:71], v[2:3], v[70:71] op_sel_hi:[0,1]
	s_waitcnt lgkmcnt(1)
	v_mfma_f32_16x16x32_bf16 v[14:17], v[46:49], v[10:13], v[14:17]
	v_cvt_pk_bf16_f32 v5, v71, s0
	v_cvt_pk_bf16_f32 v91, v70, s0
	v_or_b32_e32 v74, 0x320, v4
	v_mfma_f32_16x16x32_bf16 v[10:13], v[10:13], v[50:53], v[18:21]
	v_or_b32_e32 v76, 0x340, v4
	v_ashrrev_i32_e32 v77, 31, v76
	v_ashrrev_i32_e32 v75, 31, v74
	ds_read_b128 v[18:21], v90 offset:21952
	s_waitcnt lgkmcnt(1)
	v_mfma_f32_16x16x32_bf16 v[14:17], v[54:57], v[22:25], v[14:17]
	v_and_b32_e32 v37, 0xffff0000, v36
	v_lshlrev_b32_e32 v36, 16, v36
	v_lshl_add_u64 v[84:85], v[74:75], 1, s[4:5]
	v_mfma_f32_16x16x32_bf16 v[10:13], v[22:25], v[58:61], v[10:13]
	v_lshl_add_u64 v[86:87], v[76:77], 1, s[4:5]
	ds_read_b128 v[74:77], v90 offset:26240
	v_pk_mul_f32 v[36:37], v[2:3], v[36:37] op_sel_hi:[0,1]
	s_waitcnt lgkmcnt(1)
	v_mfma_f32_16x16x32_bf16 v[22:25], v[62:65], v[18:21], v[14:17]
	v_cvt_pk_bf16_f32 v80, v36, s0
	v_lshl_add_u32 v36, v35, 5, v3
	v_cvt_pk_bf16_f32 v92, v37, s0
	ds_read_b128 v[14:17], v90 offset:26112
	v_mfma_f32_16x16x32_bf16 v[18:21], v[18:21], v[66:69], v[10:13]
	v_ashrrev_i32_e32 v37, 31, v36
	v_lshl_add_u64 v[36:37], v[36:37], 1, s[4:5]
	global_store_short v[36:37], v80, off
	ds_read_b128 v[10:13], v90 offset:26176
	s_waitcnt lgkmcnt(1)
	v_mfma_f32_16x16x32_bf16 v[70:73], v[6:9], v[14:17], 0
	ds_read_b128 v[78:81], v90 offset:26304
	global_store_short v[84:85], v92, off
	global_store_short v[86:87], v91, off
	global_store_short v[88:89], v5, off
	v_and_b32_e32 v37, 0xffff0000, v83
	v_mfma_f32_16x16x32_bf16 v[14:17], v[14:17], v[40:43], 0
	v_lshlrev_b32_e32 v36, 16, v83
	v_pk_mul_f32 v[36:37], v[2:3], v[36:37] op_sel_hi:[0,1]
	v_cvt_pk_bf16_f32 v35, v37, s0
	s_waitcnt lgkmcnt(1)
	v_mfma_f32_16x16x32_bf16 v[70:73], v[46:49], v[10:13], v[70:73]
	v_mfma_f32_16x16x32_bf16 v[10:13], v[10:13], v[50:53], v[14:17]
	v_mfma_f32_16x16x32_bf16 v[14:17], v[54:57], v[74:77], v[70:73]
	s_nop 5
	v_and_b32_e32 v71, 0xffff0000, v82
	v_lshlrev_b32_e32 v70, 16, v82
	v_pk_mul_f32 v[82:83], v[2:3], v[70:71] op_sel_hi:[0,1]
	ds_read_b128 v[70:73], v90 offset:30464
	v_mfma_f32_16x16x32_bf16 v[10:13], v[74:77], v[58:61], v[10:13]
	ds_read_b128 v[74:77], v90 offset:30528
	v_cvt_pk_bf16_f32 v82, v82, s0
	s_waitcnt lgkmcnt(2)
	v_mfma_f32_16x16x32_bf16 v[14:17], v[62:65], v[78:81], v[14:17]
	v_mfma_f32_16x16x32_bf16 v[10:13], v[78:81], v[66:69], v[10:13]
	v_cvt_pk_bf16_f32 v80, v36, s0
	v_lshl_add_u32 v36, v44, 5, v3
	v_or_b32_e32 v78, 0x3e0, v4
	s_waitcnt lgkmcnt(1)
	v_mfma_f32_16x16x32_bf16 v[6:9], v[6:9], v[70:73], 0
	v_ashrrev_i32_e32 v79, 31, v78
	v_ashrrev_i32_e32 v37, 31, v36
	v_cvt_pk_bf16_f32 v81, v83, s0
	v_mfma_f32_16x16x32_bf16 v[40:43], v[70:73], v[40:43], 0
	v_or_b32_e32 v70, 0x3a0, v4
	v_or_b32_e32 v72, 0x3c0, v4
	ds_read_b128 v[2:5], v90 offset:30592
	s_waitcnt lgkmcnt(1)
	v_mfma_f32_16x16x32_bf16 v[6:9], v[46:49], v[74:77], v[6:9]
	ds_read_b128 v[46:49], v90 offset:30656
	v_ashrrev_i32_e32 v71, 31, v70
	v_ashrrev_i32_e32 v73, 31, v72
	v_mfma_f32_16x16x32_bf16 v[40:43], v[74:77], v[50:53], v[40:43]
	v_lshl_add_u64 v[36:37], v[36:37], 1, s[4:5]
	v_lshl_add_u64 v[50:51], v[70:71], 1, s[4:5]
	global_store_short v[36:37], v82, off
	s_waitcnt lgkmcnt(1)
	v_mfma_f32_16x16x32_bf16 v[6:9], v[54:57], v[2:5], v[6:9]
	v_mov_b32_e32 v36, 0
	v_mfma_f32_16x16x32_bf16 v[2:5], v[2:5], v[58:61], v[40:43]
	s_nop 2
	v_lshl_add_u64 v[42:43], v[78:79], 1, s[4:5]
	v_lshl_add_u64 v[40:41], v[72:73], 1, s[4:5]
	global_store_short v[50:51], v81, off
	global_store_short v[40:41], v80, off
	global_store_short v[42:43], v35, off
	v_lshl_add_u32 v43, v145, 2, s39
	s_waitcnt lgkmcnt(0)
	v_mfma_f32_16x16x32_bf16 v[6:9], v[62:65], v[46:49], v[6:9]
	s_waitcnt vmcnt(63) expcnt(7) lgkmcnt(15)
	s_barrier
	v_mfma_f32_16x16x32_bf16 v[2:5], v[46:49], v[66:69], v[2:5]
	ds_read_b32 v46, v43 offset:52224
	v_and_b32_e32 v40, 12, v34
	v_or_b32_e32 v41, v40, v45
	v_cmp_gt_i32_e32 vcc, v41, v145
	v_mov_b32_e32 v34, 0
	s_and_saveexec_b64 s[4:5], vcc
	s_cbranch_execz .LBB0_513
	v_lshl_add_u32 v34, v41, 2, s39
	ds_read2st64_b32 v[34:35], v34 offset0:204 offset1:205
	s_waitcnt lgkmcnt(0)
	v_sub_f32_e32 v34, v34, v46
	v_mul_f32_e32 v34, 0x3fb8aa3b, v34
	v_exp_f32_e32 v34, v34
	v_mul_f32_e32 v30, v30, v35
	v_mul_f32_e32 v34, v30, v34

; DEV unsigned cvt_pk_bf16(float lo, float hi) { const f32x2_t v = {lo, hi}; const bf16x2_t b = __builtin_convertvector(v, bf16x2_t); return __builtin_bit_cast(unsigned, b); }
; DEV float bflo(unsigned u) { return __uint_as_float(u << 16); }
; DEV float bfhi(unsigned u) { return __uint_as_float(u & 0xffff0000u); }
; template <int WIN>
; DEV void pool_d_prompt8(const bf16_t* __restrict__ proj, bf16_t* __restrict__ dpl, int row0, int c8) {
;     const int t0 = row0 & 2047;
;     uint4 u[WIN + 7];
; #pragma unroll
;     for (int i = 0; i < WIN + 7; ++i) { const int tt = t0 - (WIN - 1) + i; u[i] = (tt >= 0) ? *(const uint4*)(proj + (size_t)(row0 - (WIN - 1) + i) * NPJ + C_U + c8) : make_uint4(0u, 0u, 0u, 0u); }
;     float acc[8] = {0.f, 0.f, 0.f, 0.f, 0.f, 0.f, 0.f, 0.f};
; #pragma unroll
;     for (int i = 0; i < WIN - 1; ++i) { acc[0] += bflo(u[i].x); acc[1] += bfhi(u[i].x); acc[2] += bflo(u[i].y); acc[3] += bfhi(u[i].y); acc[4] += bflo(u[i].z); acc[5] += bfhi(u[i].z); acc[6] += bflo(u[i].w); acc[7] += bfhi(u[i].w); }
; #pragma unroll
;     for (int j = 0; j < 8; ++j) {
;         const uint4 x = u[j + WIN - 1];
;         const float xs[8] = {bflo(x.x), bfhi(x.x), bflo(x.y), bfhi(x.y), bflo(x.z), bfhi(x.z), bflo(x.w), bfhi(x.w)};
; #pragma unroll
;         for (int e_ = 0; e_ < 8; ++e_) acc[e_] += xs[e_];
;         const float ic = 1.f / (float)min(WIN, t0 + j + 1);
;         uint4 o;
;         o.x = cvt_pk_bf16(acc[0] * ic - xs[0], acc[1] * ic - xs[1]); o.y = cvt_pk_bf16(acc[2] * ic - xs[2], acc[3] * ic - xs[3]);
;         o.z = cvt_pk_bf16(acc[4] * ic - xs[4], acc[5] * ic - xs[5]); o.w = cvt_pk_bf16(acc[6] * ic - xs[6], acc[7] * ic - xs[7]);
;         *(uint4*)(dpl + (size_t)(row0 + j) * LDP + c8) = o;
;         const uint4 y = u[j];
;         acc[0] -= bflo(y.x); acc[1] -= bfhi(y.x); acc[2] -= bflo(y.y); acc[3] -= bfhi(y.y); acc[4] -= bflo(y.z); acc[5] -= bfhi(y.z); acc[6] -= bflo(y.w); acc[7] -= bfhi(y.w);
;     }
.LBB0_681:
	s_or_b64 exec, exec, s[16:17]
	v_mad_i64_i32 v[2:3], s[16:17], v145, s25, v[172:173]
	v_lshlrev_b32_e32 v94, 1, v143
	v_lshl_add_u64 v[2:3], v[2:3], 0, v[94:95]
	v_add_co_u32_e32 v2, vcc, 0x2000, v2
	v_or_b32_e32 v66, 1, v145
	s_nop 0
	v_addc_co_u32_e32 v3, vcc, 0, v3, vcc
	global_load_dwordx4 v[16:19], v[2:3], off
	v_mad_i64_i32 v[2:3], s[16:17], v66, s25, v[172:173]
	v_lshl_add_u64 v[2:3], v[2:3], 0, v[94:95]
	v_or_b32_e32 v69, 4, v145
	v_or_b32_e32 v70, 5, v145
	v_add_co_u32_e32 v2, vcc, 0x2000, v2
	v_mad_i64_i32 v[20:21], s[16:17], v69, s25, v[172:173]
	v_mad_i64_i32 v[22:23], s[16:17], v70, s25, v[172:173]
	v_addc_co_u32_e32 v3, vcc, 0, v3, vcc
	v_lshl_add_u64 v[32:33], v[20:21], 0, v[94:95]
	v_lshl_add_u64 v[34:35], v[22:23], 0, v[94:95]
	global_load_dwordx4 v[20:23], v[2:3], off
	v_or_b32_e32 v67, 2, v145
	v_mad_i64_i32 v[4:5], s[16:17], v67, s25, v[172:173]
	v_or_b32_e32 v68, 3, v145
	v_lshl_add_u64 v[4:5], v[4:5], 0, v[94:95]
	v_mad_i64_i32 v[12:13], s[16:17], v68, s25, v[172:173]
	v_add_co_u32_e32 v4, vcc, 0x2000, v4
	v_or_b32_e32 v72, 6, v145
	v_or_b32_e32 v96, 7, v98
	v_lshl_add_u64 v[12:13], v[12:13], 0, v[94:95]
	v_addc_co_u32_e32 v5, vcc, 0, v5, vcc
	v_mad_i64_i32 v[24:25], s[16:17], v72, s25, v[172:173]
	v_mad_i64_i32 v[26:27], s[16:17], v96, s25, v[172:173]
	v_add_co_u32_e32 v2, vcc, 0x2000, v12
	v_lshl_add_u64 v[40:41], v[24:25], 0, v[94:95]
	v_lshl_add_u64 v[42:43], v[26:27], 0, v[94:95]
	v_addc_co_u32_e32 v3, vcc, 0, v13, vcc
	global_load_dwordx4 v[24:27], v[4:5], off
	global_load_dwordx4 v[28:31], v[2:3], off
	v_add_co_u32_e32 v12, vcc, 0x2000, v32

; DEV unsigned cvt_pk_bf16(float lo, float hi) { const f32x2_t v = {lo, hi}; const bf16x2_t b = __builtin_convertvector(v, bf16x2_t); return __builtin_bit_cast(unsigned, b); }
; DEV float bflo(unsigned u) { return __uint_as_float(u << 16); }
; DEV float bfhi(unsigned u) { return __uint_as_float(u & 0xffff0000u); }
; template <int WIN>
; DEV void pool_d_prompt8(const bf16_t* __restrict__ proj, bf16_t* __restrict__ dpl, int row0, int c8) {
;     const int t0 = row0 & 2047;
;     uint4 u[WIN + 7];
; #pragma unroll
;     for (int i = 0; i < WIN + 7; ++i) { const int tt = t0 - (WIN - 1) + i; u[i] = (tt >= 0) ? *(const uint4*)(proj + (size_t)(row0 - (WIN - 1) + i) * NPJ + C_U + c8) : make_uint4(0u, 0u, 0u, 0u); }
;     float acc[8] = {0.f, 0.f, 0.f, 0.f, 0.f, 0.f, 0.f, 0.f};
; #pragma unroll
;     for (int i = 0; i < WIN - 1; ++i) { acc[0] += bflo(u[i].x); acc[1] += bfhi(u[i].x); acc[2] += bflo(u[i].y); acc[3] += bfhi(u[i].y); acc[4] += bflo(u[i].z); acc[5] += bfhi(u[i].z); acc[6] += bflo(u[i].w); acc[7] += bfhi(u[i].w); }
; #pragma unroll
;     for (int j = 0; j < 8; ++j) {
;         const uint4 x = u[j + WIN - 1];
;         const float xs[8] = {bflo(x.x), bfhi(x.x), bflo(x.y), bfhi(x.y), bflo(x.z), bfhi(x.z), bflo(x.w), bfhi(x.w)};
; #pragma unroll
;         for (int e_ = 0; e_ < 8; ++e_) acc[e_] += xs[e_];
;         const float ic = 1.f / (float)min(WIN, t0 + j + 1);
;         uint4 o;
;         o.x = cvt_pk_bf16(acc[0] * ic - xs[0], acc[1] * ic - xs[1]); o.y = cvt_pk_bf16(acc[2] * ic - xs[2], acc[3] * ic - xs[3]);
;         o.z = cvt_pk_bf16(acc[4] * ic - xs[4], acc[5] * ic - xs[5]); o.w = cvt_pk_bf16(acc[6] * ic - xs[6], acc[7] * ic - xs[7]);
;         *(uint4*)(dpl + (size_t)(row0 + j) * LDP + c8) = o;
;         const uint4 y = u[j];
;         acc[0] -= bflo(y.x); acc[1] -= bfhi(y.x); acc[2] -= bflo(y.y); acc[3] -= bfhi(y.y); acc[4] -= bflo(y.z); acc[5] -= bfhi(y.z); acc[6] -= bflo(y.w); acc[7] -= bfhi(y.w);
;     }
	s_nop 0
	s_nop 0
	v_addc_co_u32_e32 v13, vcc, 0, v33, vcc
	v_add_co_u32_e32 v2, vcc, 0x2000, v34

; DEV unsigned cvt_pk_bf16(float lo, float hi) { const f32x2_t v = {lo, hi}; const bf16x2_t b = __builtin_convertvector(v, bf16x2_t); return __builtin_bit_cast(unsigned, b); }
; DEV float bflo(unsigned u) { return __uint_as_float(u << 16); }
; DEV float bfhi(unsigned u) { return __uint_as_float(u & 0xffff0000u); }
; template <int WIN>
; DEV void pool_d_prompt8(const bf16_t* __restrict__ proj, bf16_t* __restrict__ dpl, int row0, int c8) {
;     const int t0 = row0 & 2047;
;     uint4 u[WIN + 7];
; #pragma unroll
;     for (int i = 0; i < WIN + 7; ++i) { const int tt = t0 - (WIN - 1) + i; u[i] = (tt >= 0) ? *(const uint4*)(proj + (size_t)(row0 - (WIN - 1) + i) * NPJ + C_U + c8) : make_uint4(0u, 0u, 0u, 0u); }
;     float acc[8] = {0.f, 0.f, 0.f, 0.f, 0.f, 0.f, 0.f, 0.f};
; #pragma unroll
;     for (int i = 0; i < WIN - 1; ++i) { acc[0] += bflo(u[i].x); acc[1] += bfhi(u[i].x); acc[2] += bflo(u[i].y); acc[3] += bfhi(u[i].y); acc[4] += bflo(u[i].z); acc[5] += bfhi(u[i].z); acc[6] += bflo(u[i].w); acc[7] += bfhi(u[i].w); }
; #pragma unroll
;     for (int j = 0; j < 8; ++j) {
;         const uint4 x = u[j + WIN - 1];
;         const float xs[8] = {bflo(x.x), bfhi(x.x), bflo(x.y), bfhi(x.y), bflo(x.z), bfhi(x.z), bflo(x.w), bfhi(x.w)};
; #pragma unroll
;         for (int e_ = 0; e_ < 8; ++e_) acc[e_] += xs[e_];
;         const float ic = 1.f / (float)min(WIN, t0 + j + 1);
;         uint4 o;
;         o.x = cvt_pk_bf16(acc[0] * ic - xs[0], acc[1] * ic - xs[1]); o.y = cvt_pk_bf16(acc[2] * ic - xs[2], acc[3] * ic - xs[3]);
;         o.z = cvt_pk_bf16(acc[4] * ic - xs[4], acc[5] * ic - xs[5]); o.w = cvt_pk_bf16(acc[6] * ic - xs[6], acc[7] * ic - xs[7]);
;         *(uint4*)(dpl + (size_t)(row0 + j) * LDP + c8) = o;
;         const uint4 y = u[j];
;         acc[0] -= bflo(y.x); acc[1] -= bfhi(y.x); acc[2] -= bflo(y.y); acc[3] -= bfhi(y.y); acc[4] -= bflo(y.z); acc[5] -= bfhi(y.z); acc[6] -= bflo(y.w); acc[7] -= bfhi(y.w);
;     }
	s_nop 0
	s_nop 0
	v_addc_co_u32_e32 v3, vcc, 0, v35, vcc
	global_load_dwordx4 v[32:35], v[12:13], off
	global_load_dwordx4 v[36:39], v[2:3], off
	v_add_co_u32_e32 v44, vcc, 0x2000, v40
	v_lshl_add_u64 v[10:11], v[140:141], 0, v[94:95]
	s_nop 0
	v_addc_co_u32_e32 v45, vcc, 0, v41, vcc
	v_add_co_u32_e32 v12, vcc, s26, v42
	v_ashrrev_i32_e32 v97, 31, v96
	s_nop 0
	v_addc_co_u32_e32 v13, vcc, 0, v43, vcc
	global_load_dwordx4 v[40:43], v[44:45], off
	global_load_dwordx4 v[2:5], v[12:13], off
	s_waitcnt vmcnt(7)
	v_lshlrev_b32_e32 v46, 16, v18
	v_and_b32_e32 v47, 0xffff0000, v18


; DEV unsigned cvt_pk_bf16(float lo, float hi) { const f32x2_t v = {lo, hi}; const bf16x2_t b = __builtin_convertvector(v, bf16x2_t); return __builtin_bit_cast(unsigned, b); }
; DEV float bflo(unsigned u) { return __uint_as_float(u << 16); }
; DEV float bfhi(unsigned u) { return __uint_as_float(u & 0xffff0000u); }
; template <int WIN>
; DEV void pool_d_prompt8(const bf16_t* __restrict__ proj, bf16_t* __restrict__ dpl, int row0, int c8) {
;     const int t0 = row0 & 2047;
;     uint4 u[WIN + 7];
; #pragma unroll
;     for (int i = 0; i < WIN + 7; ++i) { const int tt = t0 - (WIN - 1) + i; u[i] = (tt >= 0) ? *(const uint4*)(proj + (size_t)(row0 - (WIN - 1) + i) * NPJ + C_U + c8) : make_uint4(0u, 0u, 0u, 0u); }
;     float acc[8] = {0.f, 0.f, 0.f, 0.f, 0.f, 0.f, 0.f, 0.f};
; #pragma unroll
;     for (int i = 0; i < WIN - 1; ++i) { acc[0] += bflo(u[i].x); acc[1] += bfhi(u[i].x); acc[2] += bflo(u[i].y); acc[3] += bfhi(u[i].y); acc[4] += bflo(u[i].z); acc[5] += bfhi(u[i].z); acc[6] += bflo(u[i].w); acc[7] += bfhi(u[i].w); }
; #pragma unroll
;     for (int j = 0; j < 8; ++j) {
;         const uint4 x = u[j + WIN - 1];
;         const float xs[8] = {bflo(x.x), bfhi(x.x), bflo(x.y), bfhi(x.y), bflo(x.z), bfhi(x.z), bflo(x.w), bfhi(x.w)};
; #pragma unroll
;         for (int e_ = 0; e_ < 8; ++e_) acc[e_] += xs[e_];
;         const float ic = 1.f / (float)min(WIN, t0 + j + 1);
;         uint4 o;
;         o.x = cvt_pk_bf16(acc[0] * ic - xs[0], acc[1] * ic - xs[1]); o.y = cvt_pk_bf16(acc[2] * ic - xs[2], acc[3] * ic - xs[3]);
;         o.z = cvt_pk_bf16(acc[4] * ic - xs[4], acc[5] * ic - xs[5]); o.w = cvt_pk_bf16(acc[6] * ic - xs[6], acc[7] * ic - xs[7]);
;         *(uint4*)(dpl + (size_t)(row0 + j) * LDP + c8) = o;
;         const uint4 y = u[j];
;         acc[0] -= bflo(y.x); acc[1] -= bfhi(y.x); acc[2] -= bflo(y.y); acc[3] -= bfhi(y.y); acc[4] -= bflo(y.z); acc[5] -= bfhi(y.z); acc[6] -= bflo(y.w); acc[7] -= bfhi(y.w);
;     }
	v_lshlrev_b32_e32 v12, 16, v19
	v_and_b32_e32 v13, 0xffff0000, v19


; DEV unsigned cvt_pk_bf16(float lo, float hi) { const f32x2_t v = {lo, hi}; const bf16x2_t b = __builtin_convertvector(v, bf16x2_t); return __builtin_bit_cast(unsigned, b); }
; DEV float bflo(unsigned u) { return __uint_as_float(u << 16); }
; DEV float bfhi(unsigned u) { return __uint_as_float(u & 0xffff0000u); }
; template <int WIN>
; DEV void pool_d_prompt8(const bf16_t* __restrict__ proj, bf16_t* __restrict__ dpl, int row0, int c8) {
;     const int t0 = row0 & 2047;
;     uint4 u[WIN + 7];
; #pragma unroll
;     for (int i = 0; i < WIN + 7; ++i) { const int tt = t0 - (WIN - 1) + i; u[i] = (tt >= 0) ? *(const uint4*)(proj + (size_t)(row0 - (WIN - 1) + i) * NPJ + C_U + c8) : make_uint4(0u, 0u, 0u, 0u); }
;     float acc[8] = {0.f, 0.f, 0.f, 0.f, 0.f, 0.f, 0.f, 0.f};
; #pragma unroll
;     for (int i = 0; i < WIN - 1; ++i) { acc[0] += bflo(u[i].x); acc[1] += bfhi(u[i].x); acc[2] += bflo(u[i].y); acc[3] += bfhi(u[i].y); acc[4] += bflo(u[i].z); acc[5] += bfhi(u[i].z); acc[6] += bflo(u[i].w); acc[7] += bfhi(u[i].w); }
; #pragma unroll
;     for (int j = 0; j < 8; ++j) {
;         const uint4 x = u[j + WIN - 1];
;         const float xs[8] = {bflo(x.x), bfhi(x.x), bflo(x.y), bfhi(x.y), bflo(x.z), bfhi(x.z), bflo(x.w), bfhi(x.w)};
; #pragma unroll
;         for (int e_ = 0; e_ < 8; ++e_) acc[e_] += xs[e_];
;         const float ic = 1.f / (float)min(WIN, t0 + j + 1);
;         uint4 o;
;         o.x = cvt_pk_bf16(acc[0] * ic - xs[0], acc[1] * ic - xs[1]); o.y = cvt_pk_bf16(acc[2] * ic - xs[2], acc[3] * ic - xs[3]);
;         o.z = cvt_pk_bf16(acc[4] * ic - xs[4], acc[5] * ic - xs[5]); o.w = cvt_pk_bf16(acc[6] * ic - xs[6], acc[7] * ic - xs[7]);
;         *(uint4*)(dpl + (size_t)(row0 + j) * LDP + c8) = o;
	v_lshlrev_b32_e32 v18, 16, v6
	v_and_b32_e32 v19, 0xffff0000, v6
	v_lshlrev_b32_e32 v44, 16, v16
	v_and_b32_e32 v45, 0xffff0000, v16
	v_pk_add_f32 v[48:49], v[18:19], 0 op_sel_hi:[1,0]
	v_rcp_f32_e32 v15, v14
	s_nop 0
	v_mul_f32_e32 v14, 1.0, v15
	v_pk_add_f32 v[48:49], v[48:49], v[44:45]
	v_lshlrev_b32_e32 v16, 16, v17
	v_pk_fma_f32 v[50:51], v[14:15], v[48:49], v[44:45] op_sel_hi:[0,1,1] neg_lo:[0,0,1] neg_hi:[0,0,1]
	v_cvt_pk_bf16_f32 v6, v50, v51
	v_lshlrev_b32_e32 v50, 16, v7
	v_and_b32_e32 v51, 0xffff0000, v7
	v_and_b32_e32 v17, 0xffff0000, v17
	v_pk_add_f32 v[52:53], v[50:51], 0 op_sel_hi:[1,0]
	s_waitcnt vmcnt(6)
	v_lshlrev_b32_e32 v62, 16, v22
	v_pk_add_f32 v[52:53], v[52:53], v[16:17]
	v_and_b32_e32 v63, 0xffff0000, v22
	v_pk_fma_f32 v[54:55], v[14:15], v[52:53], v[16:17] op_sel_hi:[0,1,1] neg_lo:[0,0,1] neg_hi:[0,0,1]
	v_cvt_pk_bf16_f32 v7, v54, v55
	v_lshlrev_b32_e32 v54, 16, v8
	v_and_b32_e32 v55, 0xffff0000, v8
	v_pk_add_f32 v[56:57], v[54:55], 0 op_sel_hi:[1,0]
	v_lshlrev_b32_e32 v64, 16, v23
	v_pk_add_f32 v[56:57], v[56:57], v[46:47]
	v_and_b32_e32 v65, 0xffff0000, v23
	v_pk_fma_f32 v[58:59], v[14:15], v[56:57], v[46:47] op_sel_hi:[0,1,1] neg_lo:[0,0,1] neg_hi:[0,0,1]
	v_cvt_pk_bf16_f32 v8, v58, v59
	v_lshlrev_b32_e32 v58, 16, v9
	v_and_b32_e32 v59, 0xffff0000, v9
	v_pk_add_f32 v[60:61], v[58:59], 0 op_sel_hi:[1,0]
	s_waitcnt vmcnt(1)
	v_and_b32_e32 v71, 0xffff0000, v42
	v_pk_add_f32 v[60:61], v[60:61], v[12:13]
	s_nop 0
	v_pk_fma_f32 v[14:15], v[14:15], v[60:61], v[12:13] op_sel_hi:[0,1,1] neg_lo:[0,0,1] neg_hi:[0,0,1]
	v_cvt_pk_bf16_f32 v9, v14, v15
	v_mad_i64_i32 v[14:15], s[16:17], v145, s27, v[10:11]
	global_store_dwordx4 v[14:15], v[6:9], off sc1
	v_lshlrev_b32_e32 v14, 16, v20
	v_and_b32_e32 v15, 0xffff0000, v20
	v_lshlrev_b32_e32 v20, 16, v21
	v_and_b32_e32 v21, 0xffff0000, v21
	v_pk_add_f32 v[6:7], v[48:49], v[18:19] neg_lo:[0,1] neg_hi:[0,1]
	v_pk_add_f32 v[8:9], v[52:53], v[50:51] neg_lo:[0,1] neg_hi:[0,1]
	v_pk_add_f32 v[18:19], v[6:7], v[14:15]
	v_pk_add_f32 v[22:23], v[8:9], v[20:21]
	v_pk_fma_f32 v[6:7], v[18:19], 0.5, v[14:15] op_sel_hi:[1,0,1] neg_lo:[0,0,1] neg_hi:[0,0,1]
	v_pk_fma_f32 v[8:9], v[22:23], 0.5, v[20:21] op_sel_hi:[1,0,1] neg_lo:[0,0,1] neg_hi:[0,0,1]
	v_cvt_pk_bf16_f32 v6, v6, v7
	v_cvt_pk_bf16_f32 v7, v8, v9
	v_pk_add_f32 v[8:9], v[56:57], v[54:55] neg_lo:[0,1] neg_hi:[0,1]
	v_pk_add_f32 v[50:51], v[60:61], v[58:59] neg_lo:[0,1] neg_hi:[0,1]
	v_pk_add_f32 v[48:49], v[8:9], v[62:63]
	v_pk_add_f32 v[50:51], v[50:51], v[64:65]
	v_pk_fma_f32 v[8:9], v[48:49], 0.5, v[62:63] op_sel_hi:[1,0,1] neg_lo:[0,0,1] neg_hi:[0,0,1]
	v_pk_fma_f32 v[52:53], v[50:51], 0.5, v[64:65] op_sel_hi:[1,0,1] neg_lo:[0,0,1] neg_hi:[0,0,1]
	v_cvt_pk_bf16_f32 v8, v8, v9
	v_cvt_pk_bf16_f32 v9, v52, v53
	v_mad_i64_i32 v[52:53], s[16:17], v66, s27, v[10:11]
	global_store_dwordx4 v[52:53], v[6:9], off sc1
	v_lshlrev_b32_e32 v52, 16, v24
	v_and_b32_e32 v53, 0xffff0000, v24
	v_lshlrev_b32_e32 v24, 16, v25
	v_and_b32_e32 v25, 0xffff0000, v25
	v_pk_add_f32 v[6:7], v[18:19], v[44:45] neg_lo:[0,1] neg_hi:[0,1]
	v_pk_add_f32 v[8:9], v[22:23], v[16:17] neg_lo:[0,1] neg_hi:[0,1]
	v_pk_add_f32 v[18:19], v[6:7], v[52:53]
	v_pk_add_f32 v[16:17], v[8:9], v[24:25]
	v_lshlrev_b32_e32 v54, 16, v26
	v_and_b32_e32 v55, 0xffff0000, v26
	v_lshlrev_b32_e32 v56, 16, v27
	v_and_b32_e32 v57, 0xffff0000, v27
	v_pk_fma_f32 v[6:7], v[18:19], 0.5, v[52:53] op_sel_hi:[1,0,1] neg_lo:[0,0,1] neg_hi:[0,0,1]
	v_pk_fma_f32 v[8:9], v[16:17], 0.5, v[24:25] op_sel_hi:[1,0,1] neg_lo:[0,0,1] neg_hi:[0,0,1]
	v_lshlrev_b32_e32 v26, 16, v28
	v_and_b32_e32 v27, 0xffff0000, v28
	v_lshlrev_b32_e32 v28, 16, v29
	v_and_b32_e32 v29, 0xffff0000, v29
	v_pk_add_f32 v[14:15], v[18:19], v[14:15] neg_lo:[0,1] neg_hi:[0,1]
	v_pk_add_f32 v[16:17], v[16:17], v[20:21] neg_lo:[0,1] neg_hi:[0,1]
	v_cvt_pk_bf16_f32 v6, v6, v7
	v_cvt_pk_bf16_f32 v7, v8, v9
	v_pk_add_f32 v[8:9], v[48:49], v[46:47] neg_lo:[0,1] neg_hi:[0,1]
	v_pk_add_f32 v[18:19], v[14:15], v[26:27]
	v_pk_add_f32 v[20:21], v[16:17], v[28:29]
	v_pk_add_f32 v[22:23], v[8:9], v[54:55]
	v_lshlrev_b32_e32 v46, 16, v30
	v_and_b32_e32 v47, 0xffff0000, v30
	v_lshlrev_b32_e32 v48, 16, v31
	v_and_b32_e32 v49, 0xffff0000, v31
	v_pk_fma_f32 v[14:15], v[18:19], 0.5, v[26:27] op_sel_hi:[1,0,1] neg_lo:[0,0,1] neg_hi:[0,0,1]
	v_pk_fma_f32 v[16:17], v[20:21], 0.5, v[28:29] op_sel_hi:[1,0,1] neg_lo:[0,0,1] neg_hi:[0,0,1]
	v_lshlrev_b32_e32 v30, 16, v32
	v_and_b32_e32 v31, 0xffff0000, v32
	v_lshlrev_b32_e32 v32, 16, v33
	v_and_b32_e32 v33, 0xffff0000, v33
	v_pk_add_f32 v[18:19], v[18:19], v[52:53] neg_lo:[0,1] neg_hi:[0,1]
	v_pk_add_f32 v[20:21], v[20:21], v[24:25] neg_lo:[0,1] neg_hi:[0,1]
	v_cvt_pk_bf16_f32 v14, v14, v15
	v_cvt_pk_bf16_f32 v15, v16, v17
	v_pk_add_f32 v[16:17], v[22:23], v[62:63] neg_lo:[0,1] neg_hi:[0,1]
	v_lshlrev_b32_e32 v60, 16, v34
	v_and_b32_e32 v61, 0xffff0000, v34
	v_lshlrev_b32_e32 v62, 16, v35
	v_and_b32_e32 v63, 0xffff0000, v35
	v_pk_add_f32 v[34:35], v[18:19], v[30:31]
	v_pk_add_f32 v[24:25], v[20:21], v[32:33]
	v_pk_fma_f32 v[8:9], v[22:23], 0.5, v[54:55] op_sel_hi:[1,0,1] neg_lo:[0,0,1] neg_hi:[0,0,1]
	v_pk_add_f32 v[22:23], v[16:17], v[46:47]
	v_pk_fma_f32 v[18:19], v[34:35], 0.5, v[30:31] op_sel_hi:[1,0,1] neg_lo:[0,0,1] neg_hi:[0,0,1]
	v_pk_fma_f32 v[20:21], v[24:25], 0.5, v[32:33] op_sel_hi:[1,0,1] neg_lo:[0,0,1] neg_hi:[0,0,1]
	v_mad_i64_i32 v[44:45], s[16:17], v67, s27, v[10:11]
	v_pk_fma_f32 v[16:17], v[22:23], 0.5, v[46:47] op_sel_hi:[1,0,1] neg_lo:[0,0,1] neg_hi:[0,0,1]
	v_cvt_pk_bf16_f32 v18, v18, v19
	v_cvt_pk_bf16_f32 v19, v20, v21
; DEV unsigned cvt_pk_bf16(float lo, float hi) { const f32x2_t v = {lo, hi}; const bf16x2_t b = __builtin_convertvector(v, bf16x2_t); return __builtin_bit_cast(unsigned, b); }
; DEV float bflo(unsigned u) { return __uint_as_float(u << 16); }
; DEV float bfhi(unsigned u) { return __uint_as_float(u & 0xffff0000u); }
; template <int WIN>
; DEV void pool_d_prompt8(const bf16_t* __restrict__ proj, bf16_t* __restrict__ dpl, int row0, int c8) {
;     ...
;         const uint4 x = u[j + WIN - 1];
;         const float xs[8] = {bflo(x.x), bfhi(x.x), bflo(x.y), bfhi(x.y), bflo(x.z), bfhi(x.z), bflo(x.w), bfhi(x.w)};
; #pragma unroll
;         for (int e_ = 0; e_ < 8; ++e_) acc[e_] += xs[e_];
;         const float ic = 1.f / (float)min(WIN, t0 + j + 1);
;         uint4 o;
;         o.x = cvt_pk_bf16(acc[0] * ic - xs[0], acc[1] * ic - xs[1]); o.y = cvt_pk_bf16(acc[2] * ic - xs[2], acc[3] * ic - xs[3]);
;         o.z = cvt_pk_bf16(acc[4] * ic - xs[4], acc[5] * ic - xs[5]); o.w = cvt_pk_bf16(acc[6] * ic - xs[6], acc[7] * ic - xs[7]);
;         *(uint4*)(dpl + (size_t)(row0 + j) * LDP + c8) = o;
;         const uint4 y = u[j];
;         acc[0] -= bflo(y.x); acc[1] -= bfhi(y.x); acc[2] -= bflo(y.y); acc[3] -= bfhi(y.y); acc[4] -= bflo(y.z); acc[5] -= bfhi(y.z); acc[6] -= bflo(y.w); acc[7] -= bfhi(y.w);
;     }
; __global__ void __launch_bounds__(512) hymba_fwd(Params p) {
;     ...
;         for (int i = bid * 512 + tid; i < (TP / 8) * 128; i += G * 512) {
;             const int row0 = (i >> 7) * 8, c8 = (i & 127) * 8, g = c8 >> 8;
;             if (g == 0) pool_d_prompt8<2>(proj, dpl, row0, c8); else if (g == 1) pool_d_prompt8<4>(proj, dpl, row0, c8);
;             else if (g == 2) pool_d_prompt8<8>(proj, dpl, row0, c8); else pool_d_prompt8<16>(proj, dpl, row0, c8);
;         }
	v_pk_add_f32 v[20:21], v[22:23], v[54:55] neg_lo:[0,1] neg_hi:[0,1]
	v_lshlrev_b32_e32 v66, 16, v36
	v_and_b32_e32 v67, 0xffff0000, v36
	v_lshlrev_b32_e32 v36, 16, v37
	v_and_b32_e32 v37, 0xffff0000, v37
	v_pk_add_f32 v[22:23], v[34:35], v[26:27] neg_lo:[0,1] neg_hi:[0,1]
	v_pk_add_f32 v[24:25], v[24:25], v[28:29] neg_lo:[0,1] neg_hi:[0,1]
	v_pk_add_f32 v[26:27], v[22:23], v[66:67]
	v_pk_add_f32 v[28:29], v[24:25], v[36:37]
	v_pk_add_f32 v[52:53], v[20:21], v[60:61]
	v_pk_fma_f32 v[22:23], v[26:27], 0.5, v[66:67] op_sel_hi:[1,0,1] neg_lo:[0,0,1] neg_hi:[0,0,1]
	v_pk_fma_f32 v[24:25], v[28:29], 0.5, v[36:37] op_sel_hi:[1,0,1] neg_lo:[0,0,1] neg_hi:[0,0,1]
	v_pk_fma_f32 v[20:21], v[52:53], 0.5, v[60:61] op_sel_hi:[1,0,1] neg_lo:[0,0,1] neg_hi:[0,0,1]
	v_cvt_pk_bf16_f32 v22, v22, v23
	v_cvt_pk_bf16_f32 v23, v24, v25
	v_pk_add_f32 v[24:25], v[52:53], v[46:47] neg_lo:[0,1] neg_hi:[0,1]
	v_lshlrev_b32_e32 v52, 16, v40
	v_and_b32_e32 v53, 0xffff0000, v40
	v_lshlrev_b32_e32 v40, 16, v41
	v_and_b32_e32 v41, 0xffff0000, v41
	v_pk_add_f32 v[26:27], v[26:27], v[30:31] neg_lo:[0,1] neg_hi:[0,1]
	v_pk_add_f32 v[28:29], v[28:29], v[32:33] neg_lo:[0,1] neg_hi:[0,1]
	v_mad_i64_i32 v[58:59], s[16:17], v68, s27, v[10:11]
	v_mad_i64_i32 v[54:55], s[16:17], v69, s27, v[10:11]
	v_lshlrev_b32_e32 v68, 16, v38
	v_and_b32_e32 v69, 0xffff0000, v38
	v_pk_add_f32 v[26:27], v[26:27], v[52:53]
	v_pk_add_f32 v[28:29], v[28:29], v[40:41]
	v_pk_add_f32 v[34:35], v[24:25], v[68:69]
	v_pk_fma_f32 v[30:31], v[26:27], 0.5, v[52:53] op_sel_hi:[1,0,1] neg_lo:[0,0,1] neg_hi:[0,0,1]
	v_pk_fma_f32 v[32:33], v[28:29], 0.5, v[40:41] op_sel_hi:[1,0,1] neg_lo:[0,0,1] neg_hi:[0,0,1]
	v_mad_i64_i32 v[46:47], s[16:17], v70, s27, v[10:11]
	v_lshlrev_b32_e32 v70, 16, v42
	v_cvt_pk_bf16_f32 v30, v30, v31
	v_cvt_pk_bf16_f32 v31, v32, v33
	v_pk_add_f32 v[32:33], v[34:35], v[60:61] neg_lo:[0,1] neg_hi:[0,1]
	s_waitcnt vmcnt(2)
	v_lshlrev_b32_e32 v40, 16, v2
	v_and_b32_e32 v41, 0xffff0000, v2
	v_lshlrev_b32_e32 v2, 16, v3
	v_and_b32_e32 v3, 0xffff0000, v3
	v_pk_add_f32 v[28:29], v[28:29], v[36:37] neg_lo:[0,1] neg_hi:[0,1]
	v_pk_fma_f32 v[24:25], v[34:35], 0.5, v[68:69] op_sel_hi:[1,0,1] neg_lo:[0,0,1] neg_hi:[0,0,1]
	v_pk_add_f32 v[34:35], v[32:33], v[70:71]
	v_pk_add_f32 v[28:29], v[28:29], v[2:3]
	v_lshlrev_b32_e32 v52, 16, v4
	v_and_b32_e32 v53, 0xffff0000, v4
	v_pk_fma_f32 v[28:29], v[28:29], 0.5, v[2:3] op_sel_hi:[1,0,1] neg_lo:[0,0,1] neg_hi:[0,0,1]
	v_pk_add_f32 v[2:3], v[34:35], v[68:69] neg_lo:[0,1] neg_hi:[0,1]
	v_pk_fma_f32 v[32:33], v[34:35], 0.5, v[70:71] op_sel_hi:[1,0,1] neg_lo:[0,0,1] neg_hi:[0,0,1]
	v_pk_add_f32 v[2:3], v[2:3], v[52:53]
	v_cvt_pk_bf16_f32 v8, v8, v9
	v_pk_fma_f32 v[34:35], v[2:3], 0.5, v[52:53] op_sel_hi:[1,0,1] neg_lo:[0,0,1] neg_hi:[0,0,1]
	v_pk_add_f32 v[2:3], v[50:51], v[12:13] neg_lo:[0,1] neg_hi:[0,1]
	v_cvt_pk_bf16_f32 v16, v16, v17
	v_pk_add_f32 v[2:3], v[2:3], v[56:57]
	v_lshlrev_b32_e32 v38, 16, v39
	v_pk_fma_f32 v[12:13], v[2:3], 0.5, v[56:57] op_sel_hi:[1,0,1] neg_lo:[0,0,1] neg_hi:[0,0,1]
	v_pk_add_f32 v[2:3], v[2:3], v[64:65] neg_lo:[0,1] neg_hi:[0,1]
	v_cvt_pk_bf16_f32 v9, v12, v13
	v_pk_add_f32 v[2:3], v[2:3], v[48:49]
	global_store_dwordx4 v[44:45], v[6:9], off sc1
	v_and_b32_e32 v39, 0xffff0000, v39
	v_cvt_pk_bf16_f32 v20, v20, v21
	v_pk_fma_f32 v[6:7], v[2:3], 0.5, v[48:49] op_sel_hi:[1,0,1] neg_lo:[0,0,1] neg_hi:[0,0,1]
	v_pk_add_f32 v[2:3], v[2:3], v[56:57] neg_lo:[0,1] neg_hi:[0,1]
	v_cvt_pk_bf16_f32 v17, v6, v7
	v_pk_add_f32 v[2:3], v[2:3], v[62:63]
	v_lshlrev_b32_e32 v42, 16, v43
	v_pk_fma_f32 v[6:7], v[2:3], 0.5, v[62:63] op_sel_hi:[1,0,1] neg_lo:[0,0,1] neg_hi:[0,0,1]
	v_pk_add_f32 v[2:3], v[2:3], v[48:49] neg_lo:[0,1] neg_hi:[0,1]
	v_and_b32_e32 v43, 0xffff0000, v43
	v_pk_add_f32 v[2:3], v[2:3], v[38:39]
	v_cvt_pk_bf16_f32 v21, v6, v7
	v_pk_fma_f32 v[6:7], v[2:3], 0.5, v[38:39] op_sel_hi:[1,0,1] neg_lo:[0,0,1] neg_hi:[0,0,1]
	v_pk_add_f32 v[2:3], v[2:3], v[62:63] neg_lo:[0,1] neg_hi:[0,1]
	v_cvt_pk_bf16_f32 v24, v24, v25
	v_pk_add_f32 v[2:3], v[2:3], v[42:43]
	v_lshlrev_b32_e32 v4, 16, v5
	v_and_b32_e32 v5, 0xffff0000, v5
	v_pk_add_f32 v[26:27], v[26:27], v[66:67] neg_lo:[0,1] neg_hi:[0,1]
	v_cvt_pk_bf16_f32 v25, v6, v7
	v_pk_fma_f32 v[6:7], v[2:3], 0.5, v[42:43] op_sel_hi:[1,0,1] neg_lo:[0,0,1] neg_hi:[0,0,1]
	v_pk_add_f32 v[2:3], v[2:3], v[38:39] neg_lo:[0,1] neg_hi:[0,1]
	v_pk_add_f32 v[26:27], v[26:27], v[40:41]
	v_pk_add_f32 v[2:3], v[2:3], v[4:5]
	v_cvt_pk_bf16_f32 v32, v32, v33
	v_mad_i64_i32 v[10:11], s[16:17], v72, s27, v[10:11]
	v_pk_fma_f32 v[26:27], v[26:27], 0.5, v[40:41] op_sel_hi:[1,0,1] neg_lo:[0,0,1] neg_hi:[0,0,1]
	v_cvt_pk_bf16_f32 v33, v6, v7
	v_pk_fma_f32 v[2:3], v[2:3], 0.5, v[4:5] op_sel_hi:[1,0,1] neg_lo:[0,0,1] neg_hi:[0,0,1]
	global_store_dwordx4 v[58:59], v[14:17], off sc1
	global_store_dwordx4 v[54:55], v[18:21], off sc1
	global_store_dwordx4 v[46:47], v[22:25], off sc1
	global_store_dwordx4 v[10:11], v[30:33], off sc1
.LBB0_682:
	s_or_b64 exec, exec, s[4:5]
	v_lshlrev_b32_e32 v94, 1, v143
	v_lshl_add_u64 v[8:9], v[140:141], 0, v[94:95]
	v_cvt_pk_bf16_f32 v7, v2, v3
	v_mad_u64_u32 v[2:3], s[4:5], v96, s27, v[8:9]
	v_mov_b32_e32 v8, v3
	v_add_u32_e32 v142, s11, v142
	v_mad_u64_u32 v[8:9], s[4:5], v97, s27, v[8:9]
	v_cmp_lt_i32_e32 vcc, s30, v142
	v_cvt_pk_bf16_f32 v6, v34, v35
	v_cvt_pk_bf16_f32 v5, v28, v29
	v_cvt_pk_bf16_f32 v4, v26, v27
	v_mov_b32_e32 v3, v8
	s_or_b64 s[8:9], vcc, s[8:9]
	v_add_u32_e32 v137, s13, v137
	global_store_dwordx4 v[2:3], v[4:7], off sc1
	s_andn2_b64 exec, exec, s[8:9]
	s_cbranch_execz .LBB0_746

; DEV unsigned cvt_pk_bf16(float lo, float hi) { const f32x2_t v = {lo, hi}; const bf16x2_t b = __builtin_convertvector(v, bf16x2_t); return __builtin_bit_cast(unsigned, b); }
; DEV float bflo(unsigned u) { return __uint_as_float(u << 16); }
; DEV float bfhi(unsigned u) { return __uint_as_float(u & 0xffff0000u); }
; template <int WIN>
; DEV void pool_d_prompt8(const bf16_t* __restrict__ proj, bf16_t* __restrict__ dpl, int row0, int c8) {
;     const int t0 = row0 & 2047;
;     uint4 u[WIN + 7];
; #pragma unroll
;     for (int i = 0; i < WIN + 7; ++i) { const int tt = t0 - (WIN - 1) + i; u[i] = (tt >= 0) ? *(const uint4*)(proj + (size_t)(row0 - (WIN - 1) + i) * NPJ + C_U + c8) : make_uint4(0u, 0u, 0u, 0u); }
;     float acc[8] = {0.f, 0.f, 0.f, 0.f, 0.f, 0.f, 0.f, 0.f};
; #pragma unroll
;     for (int i = 0; i < WIN - 1; ++i) { acc[0] += bflo(u[i].x); acc[1] += bfhi(u[i].x); acc[2] += bflo(u[i].y); acc[3] += bfhi(u[i].y); acc[4] += bflo(u[i].z); acc[5] += bfhi(u[i].z); acc[6] += bflo(u[i].w); acc[7] += bfhi(u[i].w); }
; #pragma unroll
;     for (int j = 0; j < 8; ++j) {
;         const uint4 x = u[j + WIN - 1];
;         const float xs[8] = {bflo(x.x), bfhi(x.x), bflo(x.y), bfhi(x.y), bflo(x.z), bfhi(x.z), bflo(x.w), bfhi(x.w)};
; #pragma unroll
;         for (int e_ = 0; e_ < 8; ++e_) acc[e_] += xs[e_];
;         const float ic = 1.f / (float)min(WIN, t0 + j + 1);
;         uint4 o;
;         o.x = cvt_pk_bf16(acc[0] * ic - xs[0], acc[1] * ic - xs[1]); o.y = cvt_pk_bf16(acc[2] * ic - xs[2], acc[3] * ic - xs[3]);
;         o.z = cvt_pk_bf16(acc[4] * ic - xs[4], acc[5] * ic - xs[5]); o.w = cvt_pk_bf16(acc[6] * ic - xs[6], acc[7] * ic - xs[7]);
;         *(uint4*)(dpl + (size_t)(row0 + j) * LDP + c8) = o;
;         const uint4 y = u[j];
;         acc[0] -= bflo(y.x); acc[1] -= bfhi(y.x); acc[2] -= bflo(y.y); acc[3] -= bfhi(y.y); acc[4] -= bflo(y.z); acc[5] -= bfhi(y.z); acc[6] -= bflo(y.w); acc[7] -= bfhi(y.w);
;     }
.LBB0_716:
	s_or_b64 exec, exec, s[22:23]
	v_mad_i64_i32 v[14:15], s[4:5], v145, s25, v[172:173]
	v_lshlrev_b32_e32 v94, 1, v143
	v_lshl_add_u64 v[14:15], v[14:15], 0, v[94:95]
	v_or_b32_e32 v149, 1, v145
	v_add_co_u32_e32 v14, vcc, 0x2000, v14
	v_mad_i64_i32 v[16:17], s[4:5], v149, s25, v[172:173]
	s_nop 0
	v_addc_co_u32_e32 v15, vcc, 0, v15, vcc
	v_lshl_add_u64 v[16:17], v[16:17], 0, v[94:95]
	v_add_co_u32_e32 v16, vcc, 0x2000, v16
	v_or_b32_e32 v200, 2, v145
	s_nop 0
	v_addc_co_u32_e32 v17, vcc, 0, v17, vcc
	global_load_dwordx4 v[90:93], v[14:15], off
	global_load_dwordx4 v[78:81], v[16:17], off
	v_mad_i64_i32 v[14:15], s[4:5], v200, s25, v[172:173]
	v_lshl_add_u64 v[14:15], v[14:15], 0, v[94:95]
	v_or_b32_e32 v201, 3, v145
	v_add_co_u32_e32 v14, vcc, 0x2000, v14
	v_mad_i64_i32 v[16:17], s[4:5], v201, s25, v[172:173]
	s_nop 0
	v_addc_co_u32_e32 v15, vcc, 0, v15, vcc
	v_lshl_add_u64 v[16:17], v[16:17], 0, v[94:95]
	v_add_co_u32_e32 v16, vcc, 0x2000, v16
	v_or_b32_e32 v148, 4, v145
	s_nop 0
	v_addc_co_u32_e32 v17, vcc, 0, v17, vcc
	global_load_dwordx4 v[74:77], v[14:15], off
	global_load_dwordx4 v[62:65], v[16:17], off
	v_mad_i64_i32 v[14:15], s[4:5], v148, s25, v[172:173]
	v_lshl_add_u64 v[14:15], v[14:15], 0, v[94:95]
	v_or_b32_e32 v147, 5, v145
	v_add_co_u32_e32 v14, vcc, 0x2000, v14
	v_mad_i64_i32 v[16:17], s[4:5], v147, s25, v[172:173]
	s_waitcnt vmcnt(4)
	v_lshlrev_b32_e32 v134, 16, v10
	v_and_b32_e32 v135, 0xffff0000, v10
	v_addc_co_u32_e32 v15, vcc, 0, v15, vcc
	v_lshl_add_u64 v[16:17], v[16:17], 0, v[94:95]
	v_lshlrev_b32_e32 v132, 16, v11
	v_and_b32_e32 v133, 0xffff0000, v11
	v_lshlrev_b32_e32 v10, 16, v6
	v_and_b32_e32 v11, 0xffff0000, v6
	v_lshlrev_b32_e32 v128, 16, v7
	v_and_b32_e32 v129, 0xffff0000, v7
	v_pk_add_f32 v[6:7], v[134:135], 0 op_sel_hi:[1,0]
	v_lshlrev_b32_e32 v176, 16, v54
	v_and_b32_e32 v177, 0xffff0000, v54
	v_lshlrev_b32_e32 v178, 16, v55
	v_and_b32_e32 v179, 0xffff0000, v55
	v_lshlrev_b32_e32 v186, 16, v72
	v_and_b32_e32 v187, 0xffff0000, v72
	v_lshlrev_b32_e32 v54, 16, v73
	v_and_b32_e32 v55, 0xffff0000, v73
	v_lshlrev_b32_e32 v72, 16, v66
	v_and_b32_e32 v73, 0xffff0000, v66
	v_min_u32_e32 v66, 15, v144
	v_add_co_u32_e32 v16, vcc, 0x2000, v16
	v_lshlrev_b32_e32 v126, 16, v22
	v_and_b32_e32 v127, 0xffff0000, v22
	v_pk_add_f32 v[6:7], v[6:7], v[10:11]
	v_add_u32_e32 v66, 1, v66
	v_addc_co_u32_e32 v17, vcc, 0, v17, vcc
	v_or_b32_e32 v146, 6, v145
	v_or_b32_e32 v96, 7, v98
	v_lshlrev_b32_e32 v120, 16, v18
	v_and_b32_e32 v121, 0xffff0000, v18
	v_pk_add_f32 v[6:7], v[6:7], v[126:127]
	v_lshlrev_b32_e32 v190, 16, v68
	v_and_b32_e32 v191, 0xffff0000, v68
	v_cvt_f32_ubyte0_e32 v68, v66
	global_load_dwordx4 v[50:53], v[14:15], off
	global_load_dwordx4 v[34:37], v[16:17], off
	v_mad_i64_i32 v[14:15], s[4:5], v146, s25, v[172:173]
	v_mad_i64_i32 v[16:17], s[4:5], v96, s25, v[172:173]
	v_lshlrev_b32_e32 v122, 16, v24
	v_and_b32_e32 v123, 0xffff0000, v24
	v_lshlrev_b32_e32 v100, 16, v25
	v_and_b32_e32 v101, 0xffff0000, v25
	v_lshlrev_b32_e32 v114, 16, v46
	v_and_b32_e32 v115, 0xffff0000, v46
	v_lshlrev_b32_e32 v110, 16, v48
	v_and_b32_e32 v111, 0xffff0000, v48
	v_lshlrev_b32_e32 v24, 16, v49
	v_and_b32_e32 v25, 0xffff0000, v49
	v_lshlrev_b32_e32 v108, 16, v38
	v_and_b32_e32 v109, 0xffff0000, v38
	v_lshlrev_b32_e32 v106, 16, v39
	v_and_b32_e32 v107, 0xffff0000, v39
	v_pk_add_f32 v[6:7], v[6:7], v[120:121]
	v_lshlrev_b32_e32 v48, 16, v44
	v_and_b32_e32 v49, 0xffff0000, v44
	v_lshlrev_b32_e32 v38, 16, v45
	v_and_b32_e32 v39, 0xffff0000, v45
	v_lshlrev_b32_e32 v180, 16, v56
	v_and_b32_e32 v181, 0xffff0000, v56
	v_lshlrev_b32_e32 v44, 16, v57
	v_and_b32_e32 v45, 0xffff0000, v57
	v_lshlrev_b32_e32 v56, 16, v69
	v_and_b32_e32 v57, 0xffff0000, v69

; DEV unsigned cvt_pk_bf16(float lo, float hi) { const f32x2_t v = {lo, hi}; const bf16x2_t b = __builtin_convertvector(v, bf16x2_t); return __builtin_bit_cast(unsigned, b); }
; DEV float bflo(unsigned u) { return __uint_as_float(u << 16); }
; DEV float bfhi(unsigned u) { return __uint_as_float(u & 0xffff0000u); }
; template <int WIN>
; DEV void pool_d_prompt8(const bf16_t* __restrict__ proj, bf16_t* __restrict__ dpl, int row0, int c8) {
;     const int t0 = row0 & 2047;
;     uint4 u[WIN + 7];
; #pragma unroll
;     for (int i = 0; i < WIN + 7; ++i) { const int tt = t0 - (WIN - 1) + i; u[i] = (tt >= 0) ? *(const uint4*)(proj + (size_t)(row0 - (WIN - 1) + i) * NPJ + C_U + c8) : make_uint4(0u, 0u, 0u, 0u); }
;     float acc[8] = {0.f, 0.f, 0.f, 0.f, 0.f, 0.f, 0.f, 0.f};
; #pragma unroll
;     for (int i = 0; i < WIN - 1; ++i) { acc[0] += bflo(u[i].x); acc[1] += bfhi(u[i].x); acc[2] += bflo(u[i].y); acc[3] += bfhi(u[i].y); acc[4] += bflo(u[i].z); acc[5] += bfhi(u[i].z); acc[6] += bflo(u[i].w); acc[7] += bfhi(u[i].w); }
; #pragma unroll
;     for (int j = 0; j < 8; ++j) {
;         const uint4 x = u[j + WIN - 1];
;         const float xs[8] = {bflo(x.x), bfhi(x.x), bflo(x.y), bfhi(x.y), bflo(x.z), bfhi(x.z), bflo(x.w), bfhi(x.w)};
; #pragma unroll
;         for (int e_ = 0; e_ < 8; ++e_) acc[e_] += xs[e_];
;         const float ic = 1.f / (float)min(WIN, t0 + j + 1);
;         uint4 o;
;         o.x = cvt_pk_bf16(acc[0] * ic - xs[0], acc[1] * ic - xs[1]); o.y = cvt_pk_bf16(acc[2] * ic - xs[2], acc[3] * ic - xs[3]);
;         o.z = cvt_pk_bf16(acc[4] * ic - xs[4], acc[5] * ic - xs[5]); o.w = cvt_pk_bf16(acc[6] * ic - xs[6], acc[7] * ic - xs[7]);
;         *(uint4*)(dpl + (size_t)(row0 + j) * LDP + c8) = o;
;         const uint4 y = u[j];
;         acc[0] -= bflo(y.x); acc[1] -= bfhi(y.x); acc[2] -= bflo(y.y); acc[3] -= bfhi(y.y); acc[4] -= bflo(y.z); acc[5] -= bfhi(y.z); acc[6] -= bflo(y.w); acc[7] -= bfhi(y.w);
;     }
	v_lshl_add_u64 v[14:15], v[14:15], 0, v[94:95]
	v_lshl_add_u64 v[16:17], v[16:17], 0, v[94:95]
	v_lshlrev_b32_e32 v130, 16, v12
	v_and_b32_e32 v131, 0xffff0000, v12
	v_lshlrev_b32_e32 v104, 16, v13
	v_and_b32_e32 v105, 0xffff0000, v13
	v_lshlrev_b32_e32 v12, 16, v8
	v_and_b32_e32 v13, 0xffff0000, v8
	v_lshlrev_b32_e32 v102, 16, v9
	v_and_b32_e32 v103, 0xffff0000, v9
	v_pk_add_f32 v[6:7], v[6:7], v[114:115]
	v_pk_add_f32 v[8:9], v[132:133], 0 op_sel_hi:[1,0]
	v_lshlrev_b32_e32 v182, 16, v70
	v_and_b32_e32 v183, 0xffff0000, v70
	v_lshlrev_b32_e32 v184, 16, v71
	v_and_b32_e32 v185, 0xffff0000, v71
	v_lshl_add_u64 v[70:71], v[140:141], 0, v[94:95]

; DEV unsigned cvt_pk_bf16(float lo, float hi) { const f32x2_t v = {lo, hi}; const bf16x2_t b = __builtin_convertvector(v, bf16x2_t); return __builtin_bit_cast(unsigned, b); }
; DEV float bflo(unsigned u) { return __uint_as_float(u << 16); }
; DEV float bfhi(unsigned u) { return __uint_as_float(u & 0xffff0000u); }
; template <int WIN>
; DEV void pool_d_prompt8(const bf16_t* __restrict__ proj, bf16_t* __restrict__ dpl, int row0, int c8) {
;     const int t0 = row0 & 2047;
;     uint4 u[WIN + 7];
; #pragma unroll
;     for (int i = 0; i < WIN + 7; ++i) { const int tt = t0 - (WIN - 1) + i; u[i] = (tt >= 0) ? *(const uint4*)(proj + (size_t)(row0 - (WIN - 1) + i) * NPJ + C_U + c8) : make_uint4(0u, 0u, 0u, 0u); }
;     float acc[8] = {0.f, 0.f, 0.f, 0.f, 0.f, 0.f, 0.f, 0.f};
; #pragma unroll
;     for (int i = 0; i < WIN - 1; ++i) { acc[0] += bflo(u[i].x); acc[1] += bfhi(u[i].x); acc[2] += bflo(u[i].y); acc[3] += bfhi(u[i].y); acc[4] += bflo(u[i].z); acc[5] += bfhi(u[i].z); acc[6] += bflo(u[i].w); acc[7] += bfhi(u[i].w); }
; #pragma unroll
;     for (int j = 0; j < 8; ++j) {
;         const uint4 x = u[j + WIN - 1];
;         const float xs[8] = {bflo(x.x), bfhi(x.x), bflo(x.y), bfhi(x.y), bflo(x.z), bfhi(x.z), bflo(x.w), bfhi(x.w)};
; #pragma unroll
;         for (int e_ = 0; e_ < 8; ++e_) acc[e_] += xs[e_];
;         const float ic = 1.f / (float)min(WIN, t0 + j + 1);
;         uint4 o;
;         o.x = cvt_pk_bf16(acc[0] * ic - xs[0], acc[1] * ic - xs[1]); o.y = cvt_pk_bf16(acc[2] * ic - xs[2], acc[3] * ic - xs[3]);
;         o.z = cvt_pk_bf16(acc[4] * ic - xs[4], acc[5] * ic - xs[5]); o.w = cvt_pk_bf16(acc[6] * ic - xs[6], acc[7] * ic - xs[7]);
;         *(uint4*)(dpl + (size_t)(row0 + j) * LDP + c8) = o;
;         const uint4 y = u[j];
;         acc[0] -= bflo(y.x); acc[1] -= bfhi(y.x); acc[2] -= bflo(y.y); acc[3] -= bfhi(y.y); acc[4] -= bflo(y.z); acc[5] -= bfhi(y.z); acc[6] -= bflo(y.w); acc[7] -= bfhi(y.w);
;     }
	v_add_co_u32_e32 v14, vcc, 0x2000, v14
	v_lshlrev_b32_e32 v124, 16, v23
	v_and_b32_e32 v125, 0xffff0000, v23
	v_lshlrev_b32_e32 v112, 16, v47
	v_and_b32_e32 v113, 0xffff0000, v47
	v_lshlrev_b32_e32 v46, 16, v40
	v_and_b32_e32 v47, 0xffff0000, v40
	v_lshlrev_b32_e32 v22, 16, v41
	v_and_b32_e32 v23, 0xffff0000, v41
	v_lshlrev_b32_e32 v40, 16, v42
	v_and_b32_e32 v41, 0xffff0000, v42
	v_pk_add_f32 v[6:7], v[6:7], v[108:109]
	v_pk_add_f32 v[8:9], v[8:9], v[128:129]
	v_addc_co_u32_e32 v15, vcc, 0, v15, vcc
	v_lshlrev_b32_e32 v118, 16, v19
	v_and_b32_e32 v119, 0xffff0000, v19
	v_lshlrev_b32_e32 v116, 16, v20
	v_and_b32_e32 v117, 0xffff0000, v20
	v_lshlrev_b32_e32 v98, 16, v21
	v_and_b32_e32 v99, 0xffff0000, v21
	v_pk_add_f32 v[6:7], v[6:7], v[40:41]
	v_pk_add_f32 v[8:9], v[8:9], v[124:125]
	v_lshlrev_b32_e32 v20, 16, v30
	v_and_b32_e32 v21, 0xffff0000, v30
	v_add_co_u32_e32 v16, vcc, s26, v16
	v_pk_add_f32 v[8:9], v[8:9], v[118:119]
	v_lshlrev_b32_e32 v154, 16, v58
	v_and_b32_e32 v155, 0xffff0000, v58
	v_pk_add_f32 v[6:7], v[6:7], v[20:21]
	v_addc_co_u32_e32 v17, vcc, 0, v17, vcc
	v_pk_add_f32 v[8:9], v[8:9], v[112:113]
	v_pk_add_f32 v[18:19], v[130:131], 0 op_sel_hi:[1,0]
	s_waitcnt vmcnt(5)
	v_lshlrev_b32_e32 v198, 16, v92
	v_and_b32_e32 v199, 0xffff0000, v92

; DEV float bflo(unsigned u) { return __uint_as_float(u << 16); }
; DEV float bfhi(unsigned u) { return __uint_as_float(u & 0xffff0000u); }
; template <int WIN>
; DEV void pool_d_prompt8(const bf16_t* __restrict__ proj, bf16_t* __restrict__ dpl, int row0, int c8) {
;     ...
;     for (int i = 0; i < WIN - 1; ++i) { acc[0] += bflo(u[i].x); acc[1] += bfhi(u[i].x); acc[2] += bflo(u[i].y); acc[3] += bfhi(u[i].y); acc[4] += bflo(u[i].z); acc[5] += bfhi(u[i].z); acc[6] += bflo(u[i].w); acc[7] += bfhi(u[i].w); }
	v_pk_add_f32 v[6:7], v[6:7], v[154:155]
	v_lshlrev_b32_e32 v42, 16, v43
	v_and_b32_e32 v43, 0xffff0000, v43
	v_pk_add_f32 v[8:9], v[8:9], v[106:107]
	v_pk_add_f32 v[18:19], v[18:19], v[12:13]


; DEV float bflo(unsigned u) { return __uint_as_float(u << 16); }
; DEV float bfhi(unsigned u) { return __uint_as_float(u & 0xffff0000u); }
; template <int WIN>
; DEV void pool_d_prompt8(const bf16_t* __restrict__ proj, bf16_t* __restrict__ dpl, int row0, int c8) {
;     ...
;     for (int i = 0; i < WIN - 1; ++i) { acc[0] += bflo(u[i].x); acc[1] += bfhi(u[i].x); acc[2] += bflo(u[i].y); acc[3] += bfhi(u[i].y); acc[4] += bflo(u[i].z); acc[5] += bfhi(u[i].z); acc[6] += bflo(u[i].w); acc[7] += bfhi(u[i].w); }
	v_pk_add_f32 v[6:7], v[6:7], v[176:177]
	v_pk_add_f32 v[8:9], v[8:9], v[42:43]
	v_pk_add_f32 v[18:19], v[18:19], v[122:123]
	v_lshlrev_b32_e32 v150, 16, v31
	v_and_b32_e32 v151, 0xffff0000, v31
	v_lshlrev_b32_e32 v188, 16, v67
	v_and_b32_e32 v189, 0xffff0000, v67
	v_lshlrev_b32_e32 v66, 16, v93
	v_and_b32_e32 v67, 0xffff0000, v93

; DEV float bflo(unsigned u) { return __uint_as_float(u << 16); }
; DEV float bfhi(unsigned u) { return __uint_as_float(u & 0xffff0000u); }
; template <int WIN>
; DEV void pool_d_prompt8(const bf16_t* __restrict__ proj, bf16_t* __restrict__ dpl, int row0, int c8) {
;     ...
;     for (int i = 0; i < WIN - 1; ++i) { acc[0] += bflo(u[i].x); acc[1] += bfhi(u[i].x); acc[2] += bflo(u[i].y); acc[3] += bfhi(u[i].y); acc[4] += bflo(u[i].z); acc[5] += bfhi(u[i].z); acc[6] += bflo(u[i].w); acc[7] += bfhi(u[i].w); }
	v_pk_add_f32 v[6:7], v[6:7], v[182:183]
	v_pk_add_f32 v[18:19], v[18:19], v[116:117]
	v_lshlrev_b32_e32 v156, 16, v59
	v_and_b32_e32 v157, 0xffff0000, v59
	v_lshlrev_b32_e32 v192, 16, v86
	v_and_b32_e32 v193, 0xffff0000, v86

; DEV float bflo(unsigned u) { return __uint_as_float(u << 16); }
; DEV float bfhi(unsigned u) { return __uint_as_float(u & 0xffff0000u); }
; template <int WIN>
; DEV void pool_d_prompt8(const bf16_t* __restrict__ proj, bf16_t* __restrict__ dpl, int row0, int c8) {
;     ...
;     for (int i = 0; i < WIN - 1; ++i) { acc[0] += bflo(u[i].x); acc[1] += bfhi(u[i].x); acc[2] += bflo(u[i].y); acc[3] += bfhi(u[i].y); acc[4] += bflo(u[i].z); acc[5] += bfhi(u[i].z); acc[6] += bflo(u[i].w); acc[7] += bfhi(u[i].w); }
	v_pk_add_f32 v[6:7], v[6:7], v[72:73]
	v_pk_add_f32 v[8:9], v[8:9], v[150:151]
	v_pk_add_f32 v[18:19], v[18:19], v[110:111]
	v_lshlrev_b32_e32 v194, 16, v88
	v_and_b32_e32 v195, 0xffff0000, v88
	v_lshlrev_b32_e32 v58, 16, v89
	v_and_b32_e32 v59, 0xffff0000, v89
	v_lshlrev_b32_e32 v88, 16, v82
	v_and_b32_e32 v89, 0xffff0000, v82

; DEV float bflo(unsigned u) { return __uint_as_float(u << 16); }
; DEV float bfhi(unsigned u) { return __uint_as_float(u & 0xffff0000u); }
; template <int WIN>
; DEV void pool_d_prompt8(const bf16_t* __restrict__ proj, bf16_t* __restrict__ dpl, int row0, int c8) {
;     ...
;     for (int i = 0; i < WIN - 1; ++i) { acc[0] += bflo(u[i].x); acc[1] += bfhi(u[i].x); acc[2] += bflo(u[i].y); acc[3] += bfhi(u[i].y); acc[4] += bflo(u[i].z); acc[5] += bfhi(u[i].z); acc[6] += bflo(u[i].w); acc[7] += bfhi(u[i].w); }
	v_pk_add_f32 v[6:7], v[6:7], v[192:193]
	v_pk_add_f32 v[8:9], v[8:9], v[156:157]
	v_pk_add_f32 v[18:19], v[18:19], v[46:47]

; DEV float bflo(unsigned u) { return __uint_as_float(u << 16); }
; DEV float bfhi(unsigned u) { return __uint_as_float(u & 0xffff0000u); }
; template <int WIN>
; DEV void pool_d_prompt8(const bf16_t* __restrict__ proj, bf16_t* __restrict__ dpl, int row0, int c8) {
;     ...
;     for (int i = 0; i < WIN - 1; ++i) { acc[0] += bflo(u[i].x); acc[1] += bfhi(u[i].x); acc[2] += bflo(u[i].y); acc[3] += bfhi(u[i].y); acc[4] += bflo(u[i].z); acc[5] += bfhi(u[i].z); acc[6] += bflo(u[i].w); acc[7] += bfhi(u[i].w); }
	v_pk_add_f32 v[6:7], v[6:7], v[88:89]
	v_lshlrev_b32_e32 v20, 16, v2
	v_and_b32_e32 v21, 0xffff0000, v2
	v_pk_add_f32 v[8:9], v[8:9], v[178:179]
	v_pk_add_f32 v[18:19], v[18:19], v[48:49]
	v_lshlrev_b32_e32 v152, 16, v32
	v_and_b32_e32 v153, 0xffff0000, v32
	v_lshlrev_b32_e32 v30, 16, v33
	v_and_b32_e32 v31, 0xffff0000, v33
	v_lshlrev_b32_e32 v174, 16, v60
	v_and_b32_e32 v175, 0xffff0000, v60
	v_lshlrev_b32_e32 v32, 16, v61
	v_and_b32_e32 v33, 0xffff0000, v61
	v_lshlrev_b32_e32 v196, 16, v84
	v_and_b32_e32 v197, 0xffff0000, v84
	v_lshlrev_b32_e32 v60, 16, v85
	v_and_b32_e32 v61, 0xffff0000, v85
	v_lshlrev_b32_e32 v84, 16, v90
	v_and_b32_e32 v85, 0xffff0000, v90

; DEV unsigned cvt_pk_bf16(float lo, float hi) { const f32x2_t v = {lo, hi}; const bf16x2_t b = __builtin_convertvector(v, bf16x2_t); return __builtin_bit_cast(unsigned, b); }
; DEV float bflo(unsigned u) { return __uint_as_float(u << 16); }
; DEV float bfhi(unsigned u) { return __uint_as_float(u & 0xffff0000u); }
; template <int WIN>
; DEV void pool_d_prompt8(const bf16_t* __restrict__ proj, bf16_t* __restrict__ dpl, int row0, int c8) {
;     ...
;     for (int j = 0; j < 8; ++j) {
;         const uint4 x = u[j + WIN - 1];
;         const float xs[8] = {bflo(x.x), bfhi(x.x), bflo(x.y), bfhi(x.y), bflo(x.z), bfhi(x.z), bflo(x.w), bfhi(x.w)};
; #pragma unroll
;         for (int e_ = 0; e_ < 8; ++e_) acc[e_] += xs[e_];
;         const float ic = 1.f / (float)min(WIN, t0 + j + 1);
;         uint4 o;
;         o.x = cvt_pk_bf16(acc[0] * ic - xs[0], acc[1] * ic - xs[1]); o.y = cvt_pk_bf16(acc[2] * ic - xs[2], acc[3] * ic - xs[3]);
	v_pk_add_f32 v[6:7], v[6:7], v[20:21]
	v_pk_add_f32 v[8:9], v[8:9], v[184:185]
	v_lshlrev_b32_e32 v86, 16, v87
	v_and_b32_e32 v87, 0xffff0000, v87
	v_rcp_f32_e32 v69, v68
	s_nop 0
	v_mul_f32_e32 v68, 1.0, v69
	v_pk_add_f32 v[6:7], v[6:7], v[84:85]
	v_pk_add_f32 v[8:9], v[8:9], v[188:189]
	v_pk_add_f32 v[18:19], v[18:19], v[152:153]
	v_lshlrev_b32_e32 v82, 16, v83
	v_and_b32_e32 v83, 0xffff0000, v83
	v_pk_fma_f32 v[20:21], v[68:69], v[6:7], v[84:85] op_sel_hi:[0,1,1] neg_lo:[0,0,1] neg_hi:[0,0,1]
	v_pk_add_f32 v[8:9], v[8:9], v[86:87]
	v_pk_add_f32 v[18:19], v[18:19], v[174:175]
	v_cvt_pk_bf16_f32 v2, v20, v21
	v_pk_add_f32 v[8:9], v[8:9], v[82:83]
	v_lshlrev_b32_e32 v20, 16, v3
	v_and_b32_e32 v21, 0xffff0000, v3
	v_pk_add_f32 v[18:19], v[18:19], v[180:181]
	v_lshlrev_b32_e32 v90, 16, v91
	v_and_b32_e32 v91, 0xffff0000, v91
	v_pk_add_f32 v[8:9], v[8:9], v[20:21]
	v_pk_add_f32 v[18:19], v[18:19], v[186:187]
	v_pk_add_f32 v[8:9], v[8:9], v[90:91]
	v_pk_add_f32 v[18:19], v[18:19], v[190:191]
	v_pk_fma_f32 v[20:21], v[68:69], v[8:9], v[90:91] op_sel_hi:[0,1,1] neg_lo:[0,0,1] neg_hi:[0,0,1]
	v_pk_add_f32 v[18:19], v[18:19], v[194:195]
	v_cvt_pk_bf16_f32 v3, v20, v21
	v_pk_add_f32 v[18:19], v[18:19], v[196:197]
	v_lshlrev_b32_e32 v20, 16, v4
	v_and_b32_e32 v21, 0xffff0000, v4
	v_pk_add_f32 v[18:19], v[18:19], v[20:21]
	s_waitcnt vmcnt(4)
	v_lshlrev_b32_e32 v84, 16, v80
	v_pk_add_f32 v[18:19], v[18:19], v[198:199]
	v_and_b32_e32 v85, 0xffff0000, v80
	v_pk_fma_f32 v[20:21], v[68:69], v[18:19], v[198:199] op_sel_hi:[0,1,1] neg_lo:[0,0,1] neg_hi:[0,0,1]
	v_min_u32_e32 v69, 14, v144
	v_add_u32_e32 v69, 2, v69
	v_cvt_f32_ubyte0_e32 v69, v69


; DEV unsigned cvt_pk_bf16(float lo, float hi) { const f32x2_t v = {lo, hi}; const bf16x2_t b = __builtin_convertvector(v, bf16x2_t); return __builtin_bit_cast(unsigned, b); }
; template <int WIN>
; DEV void pool_d_prompt8(const bf16_t* __restrict__ proj, bf16_t* __restrict__ dpl, int row0, int c8) {
;     ...
;         o.x = cvt_pk_bf16(acc[0] * ic - xs[0], acc[1] * ic - xs[1]); o.y = cvt_pk_bf16(acc[2] * ic - xs[2], acc[3] * ic - xs[3]);
;         o.z = cvt_pk_bf16(acc[4] * ic - xs[4], acc[5] * ic - xs[5]); o.w = cvt_pk_bf16(acc[6] * ic - xs[6], acc[7] * ic - xs[7]);
	v_cvt_pk_bf16_f32 v4, v20, v21
	v_lshlrev_b32_e32 v20, 16, v78
	v_and_b32_e32 v21, 0xffff0000, v78


; DEV float bflo(unsigned u) { return __uint_as_float(u << 16); }
; DEV float bfhi(unsigned u) { return __uint_as_float(u & 0xffff0000u); }
; template <int WIN>
; DEV void pool_d_prompt8(const bf16_t* __restrict__ proj, bf16_t* __restrict__ dpl, int row0, int c8) {
;     ...
;         const float xs[8] = {bflo(x.x), bfhi(x.x), bflo(x.y), bfhi(x.y), bflo(x.z), bfhi(x.z), bflo(x.w), bfhi(x.w)};
	v_lshlrev_b32_e32 v82, 16, v79
	v_and_b32_e32 v83, 0xffff0000, v79
	v_lshlrev_b32_e32 v78, 16, v81
	v_and_b32_e32 v79, 0xffff0000, v81

; template <int WIN>
; DEV void pool_d_prompt8(const bf16_t* __restrict__ proj, bf16_t* __restrict__ dpl, int row0, int c8) {
;     ...
;     for (int i = 0; i < WIN + 7; ++i) { const int tt = t0 - (WIN - 1) + i; u[i] = (tt >= 0) ? *(const uint4*)(proj + (size_t)(row0 - (WIN - 1) + i) * NPJ + C_U + c8) : make_uint4(0u, 0u, 0u, 0u); }
	global_load_dwordx4 v[26:29], v[14:15], off
	s_nop 0
	global_load_dwordx4 v[14:17], v[16:17], off


; DEV unsigned cvt_pk_bf16(float lo, float hi) { const f32x2_t v = {lo, hi}; const bf16x2_t b = __builtin_convertvector(v, bf16x2_t); return __builtin_bit_cast(unsigned, b); }
; DEV float bflo(unsigned u) { return __uint_as_float(u << 16); }
; DEV float bfhi(unsigned u) { return __uint_as_float(u & 0xffff0000u); }
; template <int WIN>
; DEV void pool_d_prompt8(const bf16_t* __restrict__ proj, bf16_t* __restrict__ dpl, int row0, int c8) {
;     ...
;         for (int e_ = 0; e_ < 8; ++e_) acc[e_] += xs[e_];
;         const float ic = 1.f / (float)min(WIN, t0 + j + 1);
;         uint4 o;
;         o.x = cvt_pk_bf16(acc[0] * ic - xs[0], acc[1] * ic - xs[1]); o.y = cvt_pk_bf16(acc[2] * ic - xs[2], acc[3] * ic - xs[3]);
;         o.z = cvt_pk_bf16(acc[4] * ic - xs[4], acc[5] * ic - xs[5]); o.w = cvt_pk_bf16(acc[6] * ic - xs[6], acc[7] * ic - xs[7]);
;         *(uint4*)(dpl + (size_t)(row0 + j) * LDP + c8) = o;
;         const uint4 y = u[j];
;         acc[0] -= bflo(y.x); acc[1] -= bfhi(y.x); acc[2] -= bflo(y.y); acc[3] -= bfhi(y.y); acc[4] -= bflo(y.z); acc[5] -= bfhi(y.z); acc[6] -= bflo(y.w); acc[7] -= bfhi(y.w);
	v_pk_add_f32 v[6:7], v[6:7], v[134:135] neg_lo:[0,1] neg_hi:[0,1]
	v_rcp_f32_e32 v80, v69
	s_nop 0
	v_mul_f32_e32 v80, 1.0, v80
	v_pk_add_f32 v[86:87], v[6:7], v[20:21]
	v_pk_add_f32 v[8:9], v[8:9], v[132:133] neg_lo:[0,1] neg_hi:[0,1]
	v_pk_fma_f32 v[6:7], v[80:81], v[86:87], v[20:21] op_sel_hi:[0,1,1] neg_lo:[0,0,1] neg_hi:[0,0,1]
	v_pk_add_f32 v[20:21], v[8:9], v[82:83]
	v_cvt_pk_bf16_f32 v6, v6, v7
	v_pk_fma_f32 v[8:9], v[80:81], v[20:21], v[82:83] op_sel_hi:[0,1,1] neg_lo:[0,0,1] neg_hi:[0,0,1]
	v_cvt_pk_bf16_f32 v7, v8, v9
	v_pk_add_f32 v[8:9], v[18:19], v[130:131] neg_lo:[0,1] neg_hi:[0,1]
	s_waitcnt vmcnt(5)
	v_lshlrev_b32_e32 v90, 16, v76
	v_pk_add_f32 v[18:19], v[8:9], v[84:85]
	v_and_b32_e32 v91, 0xffff0000, v76
	v_pk_fma_f32 v[8:9], v[80:81], v[18:19], v[84:85] op_sel_hi:[0,1,1] neg_lo:[0,0,1] neg_hi:[0,0,1]
	v_cvt_pk_bf16_f32 v8, v8, v9
	v_min_u32_e32 v9, 13, v144
	v_add_u32_e32 v9, 3, v9
	v_cvt_f32_ubyte0_e32 v9, v9


; DEV float bflo(unsigned u) { return __uint_as_float(u << 16); }
; DEV float bfhi(unsigned u) { return __uint_as_float(u & 0xffff0000u); }
; template <int WIN>
; DEV void pool_d_prompt8(const bf16_t* __restrict__ proj, bf16_t* __restrict__ dpl, int row0, int c8) {
;     ...
;         const float xs[8] = {bflo(x.x), bfhi(x.x), bflo(x.y), bfhi(x.y), bflo(x.z), bfhi(x.z), bflo(x.w), bfhi(x.w)};
	v_lshlrev_b32_e32 v84, 16, v74
	v_and_b32_e32 v85, 0xffff0000, v74
	v_lshlrev_b32_e32 v88, 16, v75


; DEV float bflo(unsigned u) { return __uint_as_float(u << 16); }
; DEV float bfhi(unsigned u) { return __uint_as_float(u & 0xffff0000u); }
; template <int WIN>
; DEV void pool_d_prompt8(const bf16_t* __restrict__ proj, bf16_t* __restrict__ dpl, int row0, int c8) {
;     ...
;         const float xs[8] = {bflo(x.x), bfhi(x.x), bflo(x.y), bfhi(x.y), bflo(x.z), bfhi(x.z), bflo(x.w), bfhi(x.w)};
	v_and_b32_e32 v89, 0xffff0000, v75
	v_lshlrev_b32_e32 v74, 16, v77
	v_and_b32_e32 v75, 0xffff0000, v77


; DEV unsigned cvt_pk_bf16(float lo, float hi) { const f32x2_t v = {lo, hi}; const bf16x2_t b = __builtin_convertvector(v, bf16x2_t); return __builtin_bit_cast(unsigned, b); }
; DEV float bflo(unsigned u) { return __uint_as_float(u << 16); }
; DEV float bfhi(unsigned u) { return __uint_as_float(u & 0xffff0000u); }
; template <int WIN>
; DEV void pool_d_prompt8(const bf16_t* __restrict__ proj, bf16_t* __restrict__ dpl, int row0, int c8) {
;     ...
;         for (int e_ = 0; e_ < 8; ++e_) acc[e_] += xs[e_];
;         const float ic = 1.f / (float)min(WIN, t0 + j + 1);
;         uint4 o;
;         o.x = cvt_pk_bf16(acc[0] * ic - xs[0], acc[1] * ic - xs[1]); o.y = cvt_pk_bf16(acc[2] * ic - xs[2], acc[3] * ic - xs[3]);
;         o.z = cvt_pk_bf16(acc[4] * ic - xs[4], acc[5] * ic - xs[5]); o.w = cvt_pk_bf16(acc[6] * ic - xs[6], acc[7] * ic - xs[7]);
;         *(uint4*)(dpl + (size_t)(row0 + j) * LDP + c8) = o;
;         const uint4 y = u[j];
;         acc[0] -= bflo(y.x); acc[1] -= bfhi(y.x); acc[2] -= bflo(y.y); acc[3] -= bfhi(y.y); acc[4] -= bflo(y.z); acc[5] -= bfhi(y.z); acc[6] -= bflo(y.w); acc[7] -= bfhi(y.w);
	v_pk_add_f32 v[10:11], v[86:87], v[10:11] neg_lo:[0,1] neg_hi:[0,1]
	v_pk_add_f32 v[20:21], v[20:21], v[128:129] neg_lo:[0,1] neg_hi:[0,1]
	v_rcp_f32_e32 v69, v9
	s_nop 0
	v_mul_f32_e32 v76, 1.0, v69
	v_pk_add_f32 v[86:87], v[10:11], v[84:85]
	v_pk_add_f32 v[20:21], v[20:21], v[88:89]
	v_pk_add_f32 v[12:13], v[18:19], v[12:13] neg_lo:[0,1] neg_hi:[0,1]
	v_min_u32_e32 v9, 12, v144
	v_pk_fma_f32 v[10:11], v[76:77], v[86:87], v[84:85] op_sel_hi:[0,1,1] neg_lo:[0,0,1] neg_hi:[0,0,1]
	v_pk_fma_f32 v[84:85], v[76:77], v[20:21], v[88:89] op_sel_hi:[0,1,1] neg_lo:[0,0,1] neg_hi:[0,0,1]
	v_pk_add_f32 v[88:89], v[12:13], v[90:91]
	v_add_u32_e32 v9, 4, v9
	v_pk_fma_f32 v[12:13], v[76:77], v[88:89], v[90:91] op_sel_hi:[0,1,1] neg_lo:[0,0,1] neg_hi:[0,0,1]
	v_cvt_f32_ubyte0_e32 v9, v9
	v_cvt_pk_bf16_f32 v12, v12, v13


; DEV float bflo(unsigned u) { return __uint_as_float(u << 16); }
; DEV float bfhi(unsigned u) { return __uint_as_float(u & 0xffff0000u); }
; template <int WIN>
; DEV void pool_d_prompt8(const bf16_t* __restrict__ proj, bf16_t* __restrict__ dpl, int row0, int c8) {
;     ...
;         const float xs[8] = {bflo(x.x), bfhi(x.x), bflo(x.y), bfhi(x.y), bflo(x.z), bfhi(x.z), bflo(x.w), bfhi(x.w)};
	s_waitcnt vmcnt(4)
	v_lshlrev_b32_e32 v92, 16, v64
	v_and_b32_e32 v93, 0xffff0000, v64
	v_lshlrev_b32_e32 v18, 16, v62


; DEV float bflo(unsigned u) { return __uint_as_float(u << 16); }
; DEV float bfhi(unsigned u) { return __uint_as_float(u & 0xffff0000u); }
; template <int WIN>
; DEV void pool_d_prompt8(const bf16_t* __restrict__ proj, bf16_t* __restrict__ dpl, int row0, int c8) {
;     ...
;         const float xs[8] = {bflo(x.x), bfhi(x.x), bflo(x.y), bfhi(x.y), bflo(x.z), bfhi(x.z), bflo(x.w), bfhi(x.w)};
	v_and_b32_e32 v19, 0xffff0000, v62
	v_lshlrev_b32_e32 v90, 16, v63
	v_and_b32_e32 v91, 0xffff0000, v63
	v_lshlrev_b32_e32 v62, 16, v65
	v_and_b32_e32 v63, 0xffff0000, v65


; DEV unsigned cvt_pk_bf16(float lo, float hi) { const f32x2_t v = {lo, hi}; const bf16x2_t b = __builtin_convertvector(v, bf16x2_t); return __builtin_bit_cast(unsigned, b); }
; DEV float bflo(unsigned u) { return __uint_as_float(u << 16); }
; DEV float bfhi(unsigned u) { return __uint_as_float(u & 0xffff0000u); }
; template <int WIN>
; DEV void pool_d_prompt8(const bf16_t* __restrict__ proj, bf16_t* __restrict__ dpl, int row0, int c8) {
;     ...
;         for (int e_ = 0; e_ < 8; ++e_) acc[e_] += xs[e_];
;         const float ic = 1.f / (float)min(WIN, t0 + j + 1);
;         uint4 o;
;         o.x = cvt_pk_bf16(acc[0] * ic - xs[0], acc[1] * ic - xs[1]); o.y = cvt_pk_bf16(acc[2] * ic - xs[2], acc[3] * ic - xs[3]);
;         o.z = cvt_pk_bf16(acc[4] * ic - xs[4], acc[5] * ic - xs[5]); o.w = cvt_pk_bf16(acc[6] * ic - xs[6], acc[7] * ic - xs[7]);
;         *(uint4*)(dpl + (size_t)(row0 + j) * LDP + c8) = o;
;         const uint4 y = u[j];
;         acc[0] -= bflo(y.x); acc[1] -= bfhi(y.x); acc[2] -= bflo(y.y); acc[3] -= bfhi(y.y); acc[4] -= bflo(y.z); acc[5] -= bfhi(y.z); acc[6] -= bflo(y.w); acc[7] -= bfhi(y.w);
	v_pk_add_f32 v[86:87], v[86:87], v[126:127] neg_lo:[0,1] neg_hi:[0,1]
	v_pk_add_f32 v[20:21], v[20:21], v[124:125] neg_lo:[0,1] neg_hi:[0,1]
	v_rcp_f32_e32 v13, v9
	s_nop 0
	v_mul_f32_e32 v64, 1.0, v13
	v_pk_add_f32 v[126:127], v[86:87], v[18:19]
	v_pk_add_f32 v[124:125], v[20:21], v[90:91]
	v_pk_fma_f32 v[18:19], v[64:65], v[126:127], v[18:19] op_sel_hi:[0,1,1] neg_lo:[0,0,1] neg_hi:[0,0,1]
	v_pk_fma_f32 v[20:21], v[64:65], v[124:125], v[90:91] op_sel_hi:[0,1,1] neg_lo:[0,0,1] neg_hi:[0,0,1]
	v_min_u32_e32 v9, 11, v144
	v_cvt_pk_bf16_f32 v18, v18, v19
	v_cvt_pk_bf16_f32 v19, v20, v21
	v_pk_add_f32 v[20:21], v[88:89], v[122:123] neg_lo:[0,1] neg_hi:[0,1]
	v_add_u32_e32 v9, 5, v9
	v_pk_add_f32 v[90:91], v[20:21], v[92:93]
	v_cvt_f32_ubyte0_e32 v9, v9
	v_pk_fma_f32 v[20:21], v[64:65], v[90:91], v[92:93] op_sel_hi:[0,1,1] neg_lo:[0,0,1] neg_hi:[0,0,1]

; DEV unsigned cvt_pk_bf16(float lo, float hi) { const f32x2_t v = {lo, hi}; const bf16x2_t b = __builtin_convertvector(v, bf16x2_t); return __builtin_bit_cast(unsigned, b); }
; template <int WIN>
; DEV void pool_d_prompt8(const bf16_t* __restrict__ proj, bf16_t* __restrict__ dpl, int row0, int c8) {
;     ...
;         o.x = cvt_pk_bf16(acc[0] * ic - xs[0], acc[1] * ic - xs[1]); o.y = cvt_pk_bf16(acc[2] * ic - xs[2], acc[3] * ic - xs[3]);
	v_cvt_pk_bf16_f32 v20, v20, v21

; DEV float bflo(unsigned u) { return __uint_as_float(u << 16); }
; DEV float bfhi(unsigned u) { return __uint_as_float(u & 0xffff0000u); }
; template <int WIN>
; DEV void pool_d_prompt8(const bf16_t* __restrict__ proj, bf16_t* __restrict__ dpl, int row0, int c8) {
;     ...
;         const float xs[8] = {bflo(x.x), bfhi(x.x), bflo(x.y), bfhi(x.y), bflo(x.z), bfhi(x.z), bflo(x.w), bfhi(x.w)};
	s_waitcnt vmcnt(3)
	v_lshlrev_b32_e32 v122, 16, v52
	v_and_b32_e32 v123, 0xffff0000, v52
	v_lshlrev_b32_e32 v88, 16, v50


; DEV float bflo(unsigned u) { return __uint_as_float(u << 16); }
; DEV float bfhi(unsigned u) { return __uint_as_float(u & 0xffff0000u); }
; template <int WIN>
; DEV void pool_d_prompt8(const bf16_t* __restrict__ proj, bf16_t* __restrict__ dpl, int row0, int c8) {
;     ...
;         const float xs[8] = {bflo(x.x), bfhi(x.x), bflo(x.y), bfhi(x.y), bflo(x.z), bfhi(x.z), bflo(x.w), bfhi(x.w)};
	v_and_b32_e32 v89, 0xffff0000, v50
	v_lshlrev_b32_e32 v92, 16, v51
	v_and_b32_e32 v93, 0xffff0000, v51
	v_lshlrev_b32_e32 v50, 16, v53
	v_and_b32_e32 v51, 0xffff0000, v53


; template <int WIN>
; DEV void pool_d_prompt8(const bf16_t* __restrict__ proj, bf16_t* __restrict__ dpl, int row0, int c8) {
;     ...
;         const float ic = 1.f / (float)min(WIN, t0 + j + 1);
	v_rcp_f32_e32 v13, v9
	s_nop 0
	v_mul_f32_e32 v52, 1.0, v13
	v_min_u32_e32 v9, 10, v144
	v_add_u32_e32 v9, 6, v9
	v_cvt_f32_ubyte0_e32 v9, v9

; DEV float bflo(unsigned u) { return __uint_as_float(u << 16); }
; DEV float bfhi(unsigned u) { return __uint_as_float(u & 0xffff0000u); }
; template <int WIN>
; DEV void pool_d_prompt8(const bf16_t* __restrict__ proj, bf16_t* __restrict__ dpl, int row0, int c8) {
;     ...
;         acc[0] -= bflo(y.x); acc[1] -= bfhi(y.x); acc[2] -= bflo(y.y); acc[3] -= bfhi(y.y); acc[4] -= bflo(y.z); acc[5] -= bfhi(y.z); acc[6] -= bflo(y.w); acc[7] -= bfhi(y.w);
	v_pk_add_f32 v[120:121], v[126:127], v[120:121] neg_lo:[0,1] neg_hi:[0,1]
	v_pk_add_f32 v[118:119], v[124:125], v[118:119] neg_lo:[0,1] neg_hi:[0,1]

; DEV unsigned cvt_pk_bf16(float lo, float hi) { const f32x2_t v = {lo, hi}; const bf16x2_t b = __builtin_convertvector(v, bf16x2_t); return __builtin_bit_cast(unsigned, b); }
; template <int WIN>
; DEV void pool_d_prompt8(const bf16_t* __restrict__ proj, bf16_t* __restrict__ dpl, int row0, int c8) {
;     ...
;         for (int e_ = 0; e_ < 8; ++e_) acc[e_] += xs[e_];
;         const float ic = 1.f / (float)min(WIN, t0 + j + 1);
;         uint4 o;
;         o.x = cvt_pk_bf16(acc[0] * ic - xs[0], acc[1] * ic - xs[1]); o.y = cvt_pk_bf16(acc[2] * ic - xs[2], acc[3] * ic - xs[3]);
;         o.z = cvt_pk_bf16(acc[4] * ic - xs[4], acc[5] * ic - xs[5]); o.w = cvt_pk_bf16(acc[6] * ic - xs[6], acc[7] * ic - xs[7]);
	v_pk_add_f32 v[120:121], v[120:121], v[88:89]
	v_pk_add_f32 v[118:119], v[118:119], v[92:93]
	v_pk_fma_f32 v[88:89], v[52:53], v[120:121], v[88:89] op_sel_hi:[0,1,1] neg_lo:[0,0,1] neg_hi:[0,0,1]
	v_pk_fma_f32 v[92:93], v[52:53], v[118:119], v[92:93] op_sel_hi:[0,1,1] neg_lo:[0,0,1] neg_hi:[0,0,1]
	v_pk_add_f32 v[90:91], v[90:91], v[116:117] neg_lo:[0,1] neg_hi:[0,1]
	v_cvt_pk_bf16_f32 v88, v88, v89
	v_cvt_pk_bf16_f32 v89, v92, v93
	v_pk_add_f32 v[92:93], v[90:91], v[122:123]
	s_waitcnt vmcnt(2)
	v_lshlrev_b32_e32 v116, 16, v34
	v_pk_fma_f32 v[90:91], v[52:53], v[92:93], v[122:123] op_sel_hi:[0,1,1] neg_lo:[0,0,1] neg_hi:[0,0,1]


; template <int WIN>
; DEV void pool_d_prompt8(const bf16_t* __restrict__ proj, bf16_t* __restrict__ dpl, int row0, int c8) {
;     ...
;         const float ic = 1.f / (float)min(WIN, t0 + j + 1);
	v_rcp_f32_e32 v13, v9
	s_nop 0
	v_mul_f32_e32 v94, 1.0, v13
	v_min_u32_e32 v9, 9, v144
	v_add_u32_e32 v9, 7, v9
	v_cvt_f32_ubyte0_e32 v9, v9


; DEV unsigned cvt_pk_bf16(float lo, float hi) { const f32x2_t v = {lo, hi}; const bf16x2_t b = __builtin_convertvector(v, bf16x2_t); return __builtin_bit_cast(unsigned, b); }
; DEV float bflo(unsigned u) { return __uint_as_float(u << 16); }
; DEV float bfhi(unsigned u) { return __uint_as_float(u & 0xffff0000u); }
; template <int WIN>
; DEV void pool_d_prompt8(const bf16_t* __restrict__ proj, bf16_t* __restrict__ dpl, int row0, int c8) {
;     ...
;         for (int e_ = 0; e_ < 8; ++e_) acc[e_] += xs[e_];
;         const float ic = 1.f / (float)min(WIN, t0 + j + 1);
;         uint4 o;
;         o.x = cvt_pk_bf16(acc[0] * ic - xs[0], acc[1] * ic - xs[1]); o.y = cvt_pk_bf16(acc[2] * ic - xs[2], acc[3] * ic - xs[3]);
;         o.z = cvt_pk_bf16(acc[4] * ic - xs[4], acc[5] * ic - xs[5]); o.w = cvt_pk_bf16(acc[6] * ic - xs[6], acc[7] * ic - xs[7]);
;         *(uint4*)(dpl + (size_t)(row0 + j) * LDP + c8) = o;
;         const uint4 y = u[j];
;         acc[0] -= bflo(y.x); acc[1] -= bfhi(y.x); acc[2] -= bflo(y.y); acc[3] -= bfhi(y.y); acc[4] -= bflo(y.z); acc[5] -= bfhi(y.z); acc[6] -= bflo(y.w); acc[7] -= bfhi(y.w);
	v_and_b32_e32 v117, 0xffff0000, v34
	v_lshlrev_b32_e32 v34, 16, v35
	v_and_b32_e32 v35, 0xffff0000, v35
	v_pk_add_f32 v[114:115], v[120:121], v[114:115] neg_lo:[0,1] neg_hi:[0,1]
	v_pk_add_f32 v[112:113], v[118:119], v[112:113] neg_lo:[0,1] neg_hi:[0,1]
	v_pk_add_f32 v[120:121], v[114:115], v[116:117]
	v_pk_add_f32 v[112:113], v[112:113], v[34:35]
	v_pk_fma_f32 v[114:115], v[94:95], v[120:121], v[116:117] op_sel_hi:[0,1,1] neg_lo:[0,0,1] neg_hi:[0,0,1]
	v_pk_fma_f32 v[34:35], v[94:95], v[112:113], v[34:35] op_sel_hi:[0,1,1] neg_lo:[0,0,1] neg_hi:[0,0,1]
	v_lshlrev_b32_e32 v124, 16, v36
	v_and_b32_e32 v125, 0xffff0000, v36
	v_cvt_pk_bf16_f32 v114, v114, v115
	v_cvt_pk_bf16_f32 v115, v34, v35
	v_pk_add_f32 v[34:35], v[92:93], v[110:111] neg_lo:[0,1] neg_hi:[0,1]
	s_waitcnt vmcnt(1)
	v_lshlrev_b32_e32 v118, 16, v28
	v_and_b32_e32 v119, 0xffff0000, v28

; template <int WIN>
; DEV void pool_d_prompt8(const bf16_t* __restrict__ proj, bf16_t* __restrict__ dpl, int row0, int c8) {
;     ...
;         for (int e_ = 0; e_ < 8; ++e_) acc[e_] += xs[e_];
	v_pk_add_f32 v[34:35], v[34:35], v[124:125]


; DEV unsigned cvt_pk_bf16(float lo, float hi) { const f32x2_t v = {lo, hi}; const bf16x2_t b = __builtin_convertvector(v, bf16x2_t); return __builtin_bit_cast(unsigned, b); }
; template <int WIN>
; DEV void pool_d_prompt8(const bf16_t* __restrict__ proj, bf16_t* __restrict__ dpl, int row0, int c8) {
;     ...
;         o.x = cvt_pk_bf16(acc[0] * ic - xs[0], acc[1] * ic - xs[1]); o.y = cvt_pk_bf16(acc[2] * ic - xs[2], acc[3] * ic - xs[3]);
	v_pk_fma_f32 v[92:93], v[94:95], v[34:35], v[124:125] op_sel_hi:[0,1,1] neg_lo:[0,0,1] neg_hi:[0,0,1]
	v_lshlrev_b32_e32 v124, 16, v29
	v_and_b32_e32 v125, 0xffff0000, v29


; template <int WIN>
; DEV void pool_d_prompt8(const bf16_t* __restrict__ proj, bf16_t* __restrict__ dpl, int row0, int c8) {
;     ...
;         const float ic = 1.f / (float)min(WIN, t0 + j + 1);
	v_rcp_f32_e32 v13, v9
	s_nop 0
	v_mul_f32_e32 v126, 1.0, v13
	v_min_u32_e32 v9, 8, v144
	v_add_u32_e32 v9, 8, v9
	v_cvt_f32_ubyte0_e32 v9, v9


; DEV unsigned cvt_pk_bf16(float lo, float hi) { const f32x2_t v = {lo, hi}; const bf16x2_t b = __builtin_convertvector(v, bf16x2_t); return __builtin_bit_cast(unsigned, b); }
; DEV float bflo(unsigned u) { return __uint_as_float(u << 16); }
; DEV float bfhi(unsigned u) { return __uint_as_float(u & 0xffff0000u); }
; template <int WIN>
; DEV void pool_d_prompt8(const bf16_t* __restrict__ proj, bf16_t* __restrict__ dpl, int row0, int c8) {
;     ...
;         const float xs[8] = {bflo(x.x), bfhi(x.x), bflo(x.y), bfhi(x.y), bflo(x.z), bfhi(x.z), bflo(x.w), bfhi(x.w)};
; #pragma unroll
;         for (int e_ = 0; e_ < 8; ++e_) acc[e_] += xs[e_];
;         const float ic = 1.f / (float)min(WIN, t0 + j + 1);
;         uint4 o;
;         o.x = cvt_pk_bf16(acc[0] * ic - xs[0], acc[1] * ic - xs[1]); o.y = cvt_pk_bf16(acc[2] * ic - xs[2], acc[3] * ic - xs[3]);
;         o.z = cvt_pk_bf16(acc[4] * ic - xs[4], acc[5] * ic - xs[5]); o.w = cvt_pk_bf16(acc[6] * ic - xs[6], acc[7] * ic - xs[7]);
;         *(uint4*)(dpl + (size_t)(row0 + j) * LDP + c8) = o;
;         const uint4 y = u[j];
;         acc[0] -= bflo(y.x); acc[1] -= bfhi(y.x); acc[2] -= bflo(y.y); acc[3] -= bfhi(y.y); acc[4] -= bflo(y.z); acc[5] -= bfhi(y.z); acc[6] -= bflo(y.w); acc[7] -= bfhi(y.w);
	v_lshlrev_b32_e32 v110, 16, v26
	v_and_b32_e32 v111, 0xffff0000, v26
	v_lshlrev_b32_e32 v26, 16, v27
	v_and_b32_e32 v27, 0xffff0000, v27
	v_pk_add_f32 v[28:29], v[120:121], v[108:109] neg_lo:[0,1] neg_hi:[0,1]
	v_pk_add_f32 v[106:107], v[112:113], v[106:107] neg_lo:[0,1] neg_hi:[0,1]

; template <int WIN>
; DEV void pool_d_prompt8(const bf16_t* __restrict__ proj, bf16_t* __restrict__ dpl, int row0, int c8) {
;     ...
;         for (int e_ = 0; e_ < 8; ++e_) acc[e_] += xs[e_];
	v_pk_add_f32 v[28:29], v[28:29], v[110:111]
	v_pk_add_f32 v[106:107], v[106:107], v[26:27]


; DEV unsigned cvt_pk_bf16(float lo, float hi) { const f32x2_t v = {lo, hi}; const bf16x2_t b = __builtin_convertvector(v, bf16x2_t); return __builtin_bit_cast(unsigned, b); }
; template <int WIN>
; DEV void pool_d_prompt8(const bf16_t* __restrict__ proj, bf16_t* __restrict__ dpl, int row0, int c8) {
;     ...
;         o.x = cvt_pk_bf16(acc[0] * ic - xs[0], acc[1] * ic - xs[1]); o.y = cvt_pk_bf16(acc[2] * ic - xs[2], acc[3] * ic - xs[3]);
	v_pk_fma_f32 v[108:109], v[126:127], v[28:29], v[110:111] op_sel_hi:[0,1,1] neg_lo:[0,0,1] neg_hi:[0,0,1]
	v_pk_fma_f32 v[26:27], v[126:127], v[106:107], v[26:27] op_sel_hi:[0,1,1] neg_lo:[0,0,1] neg_hi:[0,0,1]

; DEV unsigned cvt_pk_bf16(float lo, float hi) { const f32x2_t v = {lo, hi}; const bf16x2_t b = __builtin_convertvector(v, bf16x2_t); return __builtin_bit_cast(unsigned, b); }
; DEV float bflo(unsigned u) { return __uint_as_float(u << 16); }
; DEV float bfhi(unsigned u) { return __uint_as_float(u & 0xffff0000u); }
; template <int WIN>
; DEV void pool_d_prompt8(const bf16_t* __restrict__ proj, bf16_t* __restrict__ dpl, int row0, int c8) {
;     ...
;         o.x = cvt_pk_bf16(acc[0] * ic - xs[0], acc[1] * ic - xs[1]); o.y = cvt_pk_bf16(acc[2] * ic - xs[2], acc[3] * ic - xs[3]);
;         o.z = cvt_pk_bf16(acc[4] * ic - xs[4], acc[5] * ic - xs[5]); o.w = cvt_pk_bf16(acc[6] * ic - xs[6], acc[7] * ic - xs[7]);
;         *(uint4*)(dpl + (size_t)(row0 + j) * LDP + c8) = o;
;         const uint4 y = u[j];
;         acc[0] -= bflo(y.x); acc[1] -= bfhi(y.x); acc[2] -= bflo(y.y); acc[3] -= bfhi(y.y); acc[4] -= bflo(y.z); acc[5] -= bfhi(y.z); acc[6] -= bflo(y.w); acc[7] -= bfhi(y.w);
	v_cvt_pk_bf16_f32 v108, v108, v109
	v_cvt_pk_bf16_f32 v109, v26, v27
	v_pk_add_f32 v[26:27], v[34:35], v[46:47] neg_lo:[0,1] neg_hi:[0,1]

; template <int WIN>
; DEV void pool_d_prompt8(const bf16_t* __restrict__ proj, bf16_t* __restrict__ dpl, int row0, int c8) {
;     ...
;         for (int e_ = 0; e_ < 8; ++e_) acc[e_] += xs[e_];
	v_pk_add_f32 v[34:35], v[26:27], v[118:119]

; DEV unsigned cvt_pk_bf16(float lo, float hi) { const f32x2_t v = {lo, hi}; const bf16x2_t b = __builtin_convertvector(v, bf16x2_t); return __builtin_bit_cast(unsigned, b); }
; template <int WIN>
; DEV void pool_d_prompt8(const bf16_t* __restrict__ proj, bf16_t* __restrict__ dpl, int row0, int c8) {
;     ...
;         o.x = cvt_pk_bf16(acc[0] * ic - xs[0], acc[1] * ic - xs[1]); o.y = cvt_pk_bf16(acc[2] * ic - xs[2], acc[3] * ic - xs[3]);
	v_pk_fma_f32 v[26:27], v[126:127], v[34:35], v[118:119] op_sel_hi:[0,1,1] neg_lo:[0,0,1] neg_hi:[0,0,1]

; DEV unsigned cvt_pk_bf16(float lo, float hi) { const f32x2_t v = {lo, hi}; const bf16x2_t b = __builtin_convertvector(v, bf16x2_t); return __builtin_bit_cast(unsigned, b); }
; DEV float bflo(unsigned u) { return __uint_as_float(u << 16); }
; DEV float bfhi(unsigned u) { return __uint_as_float(u & 0xffff0000u); }
; template <int WIN>
; DEV void pool_d_prompt8(const bf16_t* __restrict__ proj, bf16_t* __restrict__ dpl, int row0, int c8) {
;     ...
;         const float xs[8] = {bflo(x.x), bfhi(x.x), bflo(x.y), bfhi(x.y), bflo(x.z), bfhi(x.z), bflo(x.w), bfhi(x.w)};
; #pragma unroll
;         for (int e_ = 0; e_ < 8; ++e_) acc[e_] += xs[e_];
;         const float ic = 1.f / (float)min(WIN, t0 + j + 1);
;         uint4 o;
;         o.x = cvt_pk_bf16(acc[0] * ic - xs[0], acc[1] * ic - xs[1]); o.y = cvt_pk_bf16(acc[2] * ic - xs[2], acc[3] * ic - xs[3]);
	v_cvt_pk_bf16_f32 v110, v26, v27
	s_waitcnt vmcnt(0)
	v_lshlrev_b32_e32 v26, 16, v14
	v_and_b32_e32 v27, 0xffff0000, v14

; DEV unsigned cvt_pk_bf16(float lo, float hi) { const f32x2_t v = {lo, hi}; const bf16x2_t b = __builtin_convertvector(v, bf16x2_t); return __builtin_bit_cast(unsigned, b); }
; DEV float bflo(unsigned u) { return __uint_as_float(u << 16); }
; DEV float bfhi(unsigned u) { return __uint_as_float(u & 0xffff0000u); }
; template <int WIN>
; DEV void pool_d_prompt8(const bf16_t* __restrict__ proj, bf16_t* __restrict__ dpl, int row0, int c8) {
;     ...
;     for (int i = 0; i < WIN - 1; ++i) { acc[0] += bflo(u[i].x); acc[1] += bfhi(u[i].x); acc[2] += bflo(u[i].y); acc[3] += bfhi(u[i].y); acc[4] += bflo(u[i].z); acc[5] += bfhi(u[i].z); acc[6] += bflo(u[i].w); acc[7] += bfhi(u[i].w); }
; #pragma unroll
;     for (int j = 0; j < 8; ++j) {
;         const uint4 x = u[j + WIN - 1];
;         const float xs[8] = {bflo(x.x), bfhi(x.x), bflo(x.y), bfhi(x.y), bflo(x.z), bfhi(x.z), bflo(x.w), bfhi(x.w)};
; #pragma unroll
;         for (int e_ = 0; e_ < 8; ++e_) acc[e_] += xs[e_];
;         const float ic = 1.f / (float)min(WIN, t0 + j + 1);
;         uint4 o;
;         o.x = cvt_pk_bf16(acc[0] * ic - xs[0], acc[1] * ic - xs[1]); o.y = cvt_pk_bf16(acc[2] * ic - xs[2], acc[3] * ic - xs[3]);
;         o.z = cvt_pk_bf16(acc[4] * ic - xs[4], acc[5] * ic - xs[5]); o.w = cvt_pk_bf16(acc[6] * ic - xs[6], acc[7] * ic - xs[7]);
;         *(uint4*)(dpl + (size_t)(row0 + j) * LDP + c8) = o;
	v_pk_add_f32 v[28:29], v[28:29], v[40:41] neg_lo:[0,1] neg_hi:[0,1]
	v_rcp_f32_e32 v13, v9
	s_nop 0
	v_mul_f32_e32 v112, 1.0, v13
	v_pk_add_f32 v[28:29], v[28:29], v[26:27]
	v_lshlrev_b32_e32 v14, 16, v15
	v_and_b32_e32 v15, 0xffff0000, v15
	v_pk_fma_f32 v[26:27], v[112:113], v[28:29], v[26:27] op_sel_hi:[0,1,1] neg_lo:[0,0,1] neg_hi:[0,0,1]
	v_pk_add_f32 v[28:29], v[106:107], v[42:43] neg_lo:[0,1] neg_hi:[0,1]
	v_mad_i64_i32 v[72:73], s[4:5], v145, s27, v[70:71]
	v_pk_add_f32 v[28:29], v[28:29], v[14:15]
	v_mad_i64_i32 v[82:83], s[4:5], v149, s27, v[70:71]
	v_cvt_pk_bf16_f32 v10, v10, v11
	v_cvt_pk_bf16_f32 v11, v84, v85
	v_mad_i64_i32 v[84:85], s[4:5], v200, s27, v[70:71]
	v_mad_i64_i32 v[86:87], s[4:5], v201, s27, v[70:71]
	v_mad_i64_i32 v[122:123], s[4:5], v148, s27, v[70:71]
	v_cvt_pk_bf16_f32 v116, v92, v93
	v_mad_i64_i32 v[92:93], s[4:5], v147, s27, v[70:71]
	v_mad_i64_i32 v[46:47], s[4:5], v146, s27, v[70:71]
	v_lshlrev_b32_e32 v70, 16, v16
	v_and_b32_e32 v71, 0xffff0000, v16
	v_pk_fma_f32 v[28:29], v[112:113], v[28:29], v[14:15] op_sel_hi:[0,1,1] neg_lo:[0,0,1] neg_hi:[0,0,1]
	v_pk_add_f32 v[14:15], v[34:35], v[48:49] neg_lo:[0,1] neg_hi:[0,1]
	v_lshlrev_b32_e32 v40, 16, v5
	v_pk_add_f32 v[14:15], v[14:15], v[70:71]
	v_and_b32_e32 v41, 0xffff0000, v5
	v_pk_fma_f32 v[34:35], v[112:113], v[14:15], v[70:71] op_sel_hi:[0,1,1] neg_lo:[0,0,1] neg_hi:[0,0,1]
	v_pk_add_f32 v[14:15], v[104:105], 0 op_sel_hi:[1,0]
	v_lshlrev_b32_e32 v36, 16, v37
	v_pk_add_f32 v[14:15], v[14:15], v[102:103]
	v_and_b32_e32 v37, 0xffff0000, v37
	v_pk_add_f32 v[14:15], v[14:15], v[100:101]
	v_cvt_pk_bf16_f32 v90, v90, v91
	v_pk_add_f32 v[14:15], v[14:15], v[98:99]
	v_lshlrev_b32_e32 v16, 16, v17
	v_pk_add_f32 v[14:15], v[14:15], v[24:25]
	v_and_b32_e32 v17, 0xffff0000, v17
	v_pk_add_f32 v[14:15], v[14:15], v[22:23]
	v_ashrrev_i32_e32 v97, 31, v96
	v_pk_add_f32 v[14:15], v[14:15], v[38:39]
	s_nop 0
	v_pk_add_f32 v[14:15], v[14:15], v[30:31]
	s_nop 0
	v_pk_add_f32 v[14:15], v[14:15], v[32:33]
	s_nop 0
	v_pk_add_f32 v[14:15], v[14:15], v[44:45]
	s_nop 0
	v_pk_add_f32 v[14:15], v[14:15], v[54:55]
	s_nop 0
	v_pk_add_f32 v[14:15], v[14:15], v[56:57]
	s_nop 0
	v_pk_add_f32 v[14:15], v[14:15], v[58:59]
	s_nop 0
	v_pk_add_f32 v[14:15], v[14:15], v[60:61]
	s_nop 0
	v_pk_add_f32 v[14:15], v[14:15], v[40:41]
	s_nop 0
	v_pk_add_f32 v[14:15], v[14:15], v[66:67]
	s_nop 0
	v_pk_fma_f32 v[30:31], v[68:69], v[14:15], v[66:67] op_sel_hi:[0,1,1] neg_lo:[0,0,1] neg_hi:[0,0,1]
	v_cvt_pk_bf16_f32 v5, v30, v31
	global_store_dwordx4 v[72:73], v[2:5], off sc1
	s_nop 1
	v_pk_add_f32 v[2:3], v[14:15], v[104:105] neg_lo:[0,1] neg_hi:[0,1]
	s_nop 0
	v_pk_add_f32 v[2:3], v[2:3], v[78:79]
	s_nop 0
	v_pk_fma_f32 v[4:5], v[80:81], v[2:3], v[78:79] op_sel_hi:[0,1,1] neg_lo:[0,0,1] neg_hi:[0,0,1]
	v_pk_add_f32 v[2:3], v[2:3], v[102:103] neg_lo:[0,1] neg_hi:[0,1]
	v_cvt_pk_bf16_f32 v9, v4, v5
	v_pk_add_f32 v[2:3], v[2:3], v[74:75]
	global_store_dwordx4 v[82:83], v[6:9], off sc1
	v_pk_fma_f32 v[4:5], v[76:77], v[2:3], v[74:75] op_sel_hi:[0,1,1] neg_lo:[0,0,1] neg_hi:[0,0,1]
	v_pk_add_f32 v[2:3], v[2:3], v[100:101] neg_lo:[0,1] neg_hi:[0,1]
	v_cvt_pk_bf16_f32 v13, v4, v5
	v_pk_add_f32 v[2:3], v[2:3], v[62:63]
	global_store_dwordx4 v[84:85], v[10:13], off sc1
	v_pk_fma_f32 v[4:5], v[64:65], v[2:3], v[62:63] op_sel_hi:[0,1,1] neg_lo:[0,0,1] neg_hi:[0,0,1]
	v_pk_add_f32 v[2:3], v[2:3], v[98:99] neg_lo:[0,1] neg_hi:[0,1]
	v_cvt_pk_bf16_f32 v21, v4, v5
	v_pk_add_f32 v[2:3], v[2:3], v[50:51]
	global_store_dwordx4 v[86:87], v[18:21], off sc1
	v_pk_fma_f32 v[4:5], v[52:53], v[2:3], v[50:51] op_sel_hi:[0,1,1] neg_lo:[0,0,1] neg_hi:[0,0,1]
	v_pk_add_f32 v[2:3], v[2:3], v[24:25] neg_lo:[0,1] neg_hi:[0,1]
	v_cvt_pk_bf16_f32 v91, v4, v5
	v_pk_add_f32 v[2:3], v[2:3], v[36:37]
	global_store_dwordx4 v[122:123], v[88:91], off sc1
	v_pk_fma_f32 v[4:5], v[94:95], v[2:3], v[36:37] op_sel_hi:[0,1,1] neg_lo:[0,0,1] neg_hi:[0,0,1]
	v_pk_add_f32 v[2:3], v[2:3], v[22:23] neg_lo:[0,1] neg_hi:[0,1]
	v_cvt_pk_bf16_f32 v117, v4, v5
	v_pk_add_f32 v[2:3], v[2:3], v[124:125]
	global_store_dwordx4 v[92:93], v[114:117], off sc1
	v_pk_fma_f32 v[4:5], v[126:127], v[2:3], v[124:125] op_sel_hi:[0,1,1] neg_lo:[0,0,1] neg_hi:[0,0,1]
	v_pk_add_f32 v[2:3], v[2:3], v[38:39] neg_lo:[0,1] neg_hi:[0,1]
	v_cvt_pk_bf16_f32 v111, v4, v5
	v_pk_add_f32 v[2:3], v[2:3], v[16:17]
	global_store_dwordx4 v[46:47], v[108:111], off sc1
	v_pk_fma_f32 v[2:3], v[112:113], v[2:3], v[16:17] op_sel_hi:[0,1,1] neg_lo:[0,0,1] neg_hi:[0,0,1]

; DEV float bflo(unsigned u) { return __uint_as_float(u << 16); }
; DEV float bfhi(unsigned u) { return __uint_as_float(u & 0xffff0000u); }
; template <int WIN>
; DEV void pool_d_prompt8(const bf16_t* __restrict__ proj, bf16_t* __restrict__ dpl, int row0, int c8) {
;     const int t0 = row0 & 2047;
;     uint4 u[WIN + 7];
; #pragma unroll
;     for (int i = 0; i < WIN + 7; ++i) { const int tt = t0 - (WIN - 1) + i; u[i] = (tt >= 0) ? *(const uint4*)(proj + (size_t)(row0 - (WIN - 1) + i) * NPJ + C_U + c8) : make_uint4(0u, 0u, 0u, 0u); }
;     float acc[8] = {0.f, 0.f, 0.f, 0.f, 0.f, 0.f, 0.f, 0.f};
; #pragma unroll
;     for (int i = 0; i < WIN - 1; ++i) { acc[0] += bflo(u[i].x); acc[1] += bfhi(u[i].x); acc[2] += bflo(u[i].y); acc[3] += bfhi(u[i].y); acc[4] += bflo(u[i].z); acc[5] += bfhi(u[i].z); acc[6] += bflo(u[i].w); acc[7] += bfhi(u[i].w); }
; #pragma unroll
;     for (int j = 0; j < 8; ++j) {
;         const uint4 x = u[j + WIN - 1];
;         const float xs[8] = {bflo(x.x), bfhi(x.x), bflo(x.y), bfhi(x.y), bflo(x.z), bfhi(x.z), bflo(x.w), bfhi(x.w)};
; #pragma unroll
;         for (int e_ = 0; e_ < 8; ++e_) acc[e_] += xs[e_];
;         const float ic = 1.f / (float)min(WIN, t0 + j + 1);
.LBB0_732:
	s_or_b64 exec, exec, s[22:23]
	v_mad_i64_i32 v[2:3], s[4:5], v145, s25, v[172:173]
	v_lshlrev_b32_e32 v94, 1, v143
	v_lshl_add_u64 v[2:3], v[2:3], 0, v[94:95]
	v_or_b32_e32 v118, 1, v145
	v_add_co_u32_e32 v2, vcc, 0x2000, v2
	v_mad_i64_i32 v[4:5], s[4:5], v118, s25, v[172:173]
	s_nop 0
	v_addc_co_u32_e32 v3, vcc, 0, v3, vcc
	v_lshl_add_u64 v[4:5], v[4:5], 0, v[94:95]
	v_add_co_u32_e32 v4, vcc, 0x2000, v4
	v_or_b32_e32 v119, 2, v145
	s_nop 0
	v_addc_co_u32_e32 v5, vcc, 0, v5, vcc
	global_load_dwordx4 v[100:103], v[2:3], off
	global_load_dwordx4 v[104:107], v[4:5], off
	v_mad_i64_i32 v[2:3], s[4:5], v119, s25, v[172:173]
	v_lshl_add_u64 v[2:3], v[2:3], 0, v[94:95]
	v_or_b32_e32 v120, 3, v145
	v_add_co_u32_e32 v2, vcc, 0x2000, v2
	v_mad_i64_i32 v[4:5], s[4:5], v120, s25, v[172:173]
	s_nop 0
	v_addc_co_u32_e32 v3, vcc, 0, v3, vcc
	v_lshl_add_u64 v[4:5], v[4:5], 0, v[94:95]
	v_add_co_u32_e32 v4, vcc, 0x2000, v4
	v_or_b32_e32 v121, 4, v145
	s_nop 0
	v_addc_co_u32_e32 v5, vcc, 0, v5, vcc
	global_load_dwordx4 v[38:41], v[2:3], off
	global_load_dwordx4 v[26:29], v[4:5], off
	v_mad_i64_i32 v[2:3], s[4:5], v121, s25, v[172:173]
	v_lshl_add_u64 v[2:3], v[2:3], 0, v[94:95]
	v_or_b32_e32 v122, 5, v145
	v_add_co_u32_e32 v2, vcc, 0x2000, v2
	v_mad_i64_i32 v[4:5], s[4:5], v122, s25, v[172:173]
	s_nop 0
	v_addc_co_u32_e32 v3, vcc, 0, v3, vcc
	v_lshl_add_u64 v[4:5], v[4:5], 0, v[94:95]
	s_waitcnt vmcnt(4)
	v_lshlrev_b32_e32 v108, 16, v23
	v_and_b32_e32 v109, 0xffff0000, v23
	v_min_u32_e32 v23, 7, v144
	v_add_co_u32_e32 v4, vcc, 0x2000, v4
	v_or_b32_e32 v123, 6, v145
	v_add_u32_e32 v23, 1, v23
	v_addc_co_u32_e32 v5, vcc, 0, v5, vcc
	global_load_dwordx4 v[18:21], v[2:3], off
	global_load_dwordx4 v[10:13], v[4:5], off
	v_mad_i64_i32 v[2:3], s[4:5], v123, s25, v[172:173]
	v_lshlrev_b32_e32 v110, 16, v24
	v_and_b32_e32 v111, 0xffff0000, v24
	v_cvt_f32_ubyte0_e32 v24, v23
	v_lshl_add_u64 v[2:3], v[2:3], 0, v[94:95]
	v_lshlrev_b32_e32 v60, 16, v25
	v_and_b32_e32 v61, 0xffff0000, v25

; template <int WIN>
; DEV void pool_d_prompt8(const bf16_t* __restrict__ proj, bf16_t* __restrict__ dpl, int row0, int c8) {
;     ...
;     for (int i = 0; i < WIN + 7; ++i) { const int tt = t0 - (WIN - 1) + i; u[i] = (tt >= 0) ? *(const uint4*)(proj + (size_t)(row0 - (WIN - 1) + i) * NPJ + C_U + c8) : make_uint4(0u, 0u, 0u, 0u); }
	v_add_co_u32_e32 v54, vcc, 0x2000, v2
	v_or_b32_e32 v96, 7, v98
	v_lshlrev_b32_e32 v86, 16, v30
	v_and_b32_e32 v87, 0xffff0000, v30

; template <int WIN>
; DEV void pool_d_prompt8(const bf16_t* __restrict__ proj, bf16_t* __restrict__ dpl, int row0, int c8) {
;     ...
;     for (int i = 0; i < WIN + 7; ++i) { const int tt = t0 - (WIN - 1) + i; u[i] = (tt >= 0) ? *(const uint4*)(proj + (size_t)(row0 - (WIN - 1) + i) * NPJ + C_U + c8) : make_uint4(0u, 0u, 0u, 0u); }
	v_addc_co_u32_e32 v55, vcc, 0, v3, vcc
	v_mad_i64_i32 v[2:3], s[4:5], v96, s25, v[172:173]
	v_lshl_add_u64 v[2:3], v[2:3], 0, v[94:95]
	v_add_co_u32_e32 v56, vcc, s26, v2
	v_lshlrev_b32_e32 v80, 16, v31
	s_nop 0
	v_addc_co_u32_e32 v57, vcc, 0, v3, vcc
	v_and_b32_e32 v81, 0xffff0000, v31


; DEV float bflo(unsigned u) { return __uint_as_float(u << 16); }
; DEV float bfhi(unsigned u) { return __uint_as_float(u & 0xffff0000u); }
; template <int WIN>
; DEV void pool_d_prompt8(const bf16_t* __restrict__ proj, bf16_t* __restrict__ dpl, int row0, int c8) {
;     ...
;     for (int i = 0; i < WIN - 1; ++i) { acc[0] += bflo(u[i].x); acc[1] += bfhi(u[i].x); acc[2] += bflo(u[i].y); acc[3] += bfhi(u[i].y); acc[4] += bflo(u[i].z); acc[5] += bfhi(u[i].z); acc[6] += bflo(u[i].w); acc[7] += bfhi(u[i].w); }
	v_lshlrev_b32_e32 v78, 16, v32
	v_and_b32_e32 v79, 0xffff0000, v32

; template <int WIN>
; DEV void pool_d_prompt8(const bf16_t* __restrict__ proj, bf16_t* __restrict__ dpl, int row0, int c8) {
;     ...
;     for (int i = 0; i < WIN + 7; ++i) { const int tt = t0 - (WIN - 1) + i; u[i] = (tt >= 0) ? *(const uint4*)(proj + (size_t)(row0 - (WIN - 1) + i) * NPJ + C_U + c8) : make_uint4(0u, 0u, 0u, 0u); }
	global_load_dwordx4 v[6:9], v[54:55], off
	global_load_dwordx4 v[2:5], v[56:57], off
	v_lshlrev_b32_e32 v54, 16, v33
	v_and_b32_e32 v55, 0xffff0000, v33


; DEV float bflo(unsigned u) { return __uint_as_float(u << 16); }
; DEV float bfhi(unsigned u) { return __uint_as_float(u & 0xffff0000u); }
; template <int WIN>
; DEV void pool_d_prompt8(const bf16_t* __restrict__ proj, bf16_t* __restrict__ dpl, int row0, int c8) {
;     ...
;     for (int i = 0; i < WIN - 1; ++i) { acc[0] += bflo(u[i].x); acc[1] += bfhi(u[i].x); acc[2] += bflo(u[i].y); acc[3] += bfhi(u[i].y); acc[4] += bflo(u[i].z); acc[5] += bfhi(u[i].z); acc[6] += bflo(u[i].w); acc[7] += bfhi(u[i].w); }
	v_lshlrev_b32_e32 v88, 16, v22
	v_and_b32_e32 v89, 0xffff0000, v22

; DEV unsigned cvt_pk_bf16(float lo, float hi) { const f32x2_t v = {lo, hi}; const bf16x2_t b = __builtin_convertvector(v, bf16x2_t); return __builtin_bit_cast(unsigned, b); }
; DEV float bflo(unsigned u) { return __uint_as_float(u << 16); }
; DEV float bfhi(unsigned u) { return __uint_as_float(u & 0xffff0000u); }
; template <int WIN>
; DEV void pool_d_prompt8(const bf16_t* __restrict__ proj, bf16_t* __restrict__ dpl, int row0, int c8) {
;     const int t0 = row0 & 2047;
;     uint4 u[WIN + 7];
; #pragma unroll
;     for (int i = 0; i < WIN + 7; ++i) { const int tt = t0 - (WIN - 1) + i; u[i] = (tt >= 0) ? *(const uint4*)(proj + (size_t)(row0 - (WIN - 1) + i) * NPJ + C_U + c8) : make_uint4(0u, 0u, 0u, 0u); }
;     float acc[8] = {0.f, 0.f, 0.f, 0.f, 0.f, 0.f, 0.f, 0.f};
; #pragma unroll
;     for (int i = 0; i < WIN - 1; ++i) { acc[0] += bflo(u[i].x); acc[1] += bfhi(u[i].x); acc[2] += bflo(u[i].y); acc[3] += bfhi(u[i].y); acc[4] += bflo(u[i].z); acc[5] += bfhi(u[i].z); acc[6] += bflo(u[i].w); acc[7] += bfhi(u[i].w); }
; #pragma unroll
;     for (int j = 0; j < 8; ++j) {
;         const uint4 x = u[j + WIN - 1];
;         const float xs[8] = {bflo(x.x), bfhi(x.x), bflo(x.y), bfhi(x.y), bflo(x.z), bfhi(x.z), bflo(x.w), bfhi(x.w)};
; #pragma unroll
;         for (int e_ = 0; e_ < 8; ++e_) acc[e_] += xs[e_];
;         const float ic = 1.f / (float)min(WIN, t0 + j + 1);
;         uint4 o;
;         o.x = cvt_pk_bf16(acc[0] * ic - xs[0], acc[1] * ic - xs[1]); o.y = cvt_pk_bf16(acc[2] * ic - xs[2], acc[3] * ic - xs[3]);
	v_lshlrev_b32_e32 v112, 16, v14
	v_and_b32_e32 v113, 0xffff0000, v14
	v_lshlrev_b32_e32 v114, 16, v15
	v_and_b32_e32 v115, 0xffff0000, v15
	v_lshlrev_b32_e32 v68, 16, v52
	v_and_b32_e32 v69, 0xffff0000, v52
	v_rcp_f32_e32 v25, v24
	s_nop 0
	v_mul_f32_e32 v52, 1.0, v25
	v_pk_add_f32 v[24:25], v[88:89], 0 op_sel_hi:[1,0]
	v_pk_add_f32 v[30:31], v[108:109], 0 op_sel_hi:[1,0]
	v_lshlrev_b32_e32 v98, 16, v34
	v_and_b32_e32 v99, 0xffff0000, v34
	v_lshlrev_b32_e32 v92, 16, v35
	v_and_b32_e32 v93, 0xffff0000, v35
	v_pk_add_f32 v[24:25], v[24:25], v[112:113]
	v_pk_add_f32 v[30:31], v[30:31], v[114:115]
	v_pk_add_f32 v[24:25], v[24:25], v[98:99]
	v_pk_add_f32 v[30:31], v[30:31], v[92:93]
	v_lshlrev_b32_e32 v74, 16, v50
	v_and_b32_e32 v75, 0xffff0000, v50
	v_lshlrev_b32_e32 v72, 16, v51
	v_and_b32_e32 v73, 0xffff0000, v51
	v_pk_add_f32 v[24:25], v[24:25], v[86:87]
	v_pk_add_f32 v[30:31], v[30:31], v[80:81]
	v_lshlrev_b32_e32 v66, 16, v46
	v_and_b32_e32 v67, 0xffff0000, v46
	v_lshlrev_b32_e32 v64, 16, v47
	v_and_b32_e32 v65, 0xffff0000, v47
	v_pk_add_f32 v[24:25], v[24:25], v[74:75]
	v_pk_add_f32 v[30:31], v[30:31], v[72:73]
	v_pk_add_f32 v[24:25], v[24:25], v[66:67]
	v_lshlrev_b32_e32 v70, 16, v42
	v_and_b32_e32 v71, 0xffff0000, v42
	v_pk_add_f32 v[30:31], v[30:31], v[64:65]
	v_lshlrev_b32_e32 v76, 16, v43
	v_and_b32_e32 v77, 0xffff0000, v43
	v_lshlrev_b32_e32 v116, 16, v16
	v_and_b32_e32 v117, 0xffff0000, v16
	v_lshlrev_b32_e32 v58, 16, v17
	v_and_b32_e32 v59, 0xffff0000, v17
	s_waitcnt vmcnt(7)
	v_lshlrev_b32_e32 v14, 16, v100
	v_and_b32_e32 v15, 0xffff0000, v100
	v_lshlrev_b32_e32 v16, 16, v101
	v_and_b32_e32 v17, 0xffff0000, v101
	v_pk_add_f32 v[24:25], v[24:25], v[70:71]
	v_pk_add_f32 v[30:31], v[30:31], v[76:77]
	v_pk_add_f32 v[24:25], v[24:25], v[14:15]
	v_pk_add_f32 v[30:31], v[30:31], v[16:17]
	v_pk_fma_f32 v[14:15], v[52:53], v[24:25], v[14:15] op_sel_hi:[0,1,1] neg_lo:[0,0,1] neg_hi:[0,0,1]
	v_pk_fma_f32 v[16:17], v[52:53], v[30:31], v[16:17] op_sel_hi:[0,1,1] neg_lo:[0,0,1] neg_hi:[0,0,1]
	v_cvt_pk_bf16_f32 v14, v14, v15
	v_cvt_pk_bf16_f32 v15, v16, v17
	v_pk_add_f32 v[16:17], v[110:111], 0 op_sel_hi:[1,0]
	v_lshlrev_b32_e32 v90, 16, v36
	v_and_b32_e32 v91, 0xffff0000, v36
	v_pk_add_f32 v[16:17], v[16:17], v[116:117]
	v_lshlrev_b32_e32 v62, 16, v48
	v_pk_add_f32 v[16:17], v[16:17], v[90:91]
	v_and_b32_e32 v63, 0xffff0000, v48
	v_pk_add_f32 v[16:17], v[16:17], v[78:79]
	v_lshlrev_b32_e32 v84, 16, v44
	v_pk_add_f32 v[16:17], v[16:17], v[68:69]
	v_and_b32_e32 v85, 0xffff0000, v44
	v_pk_add_f32 v[16:17], v[16:17], v[62:63]
	v_lshlrev_b32_e32 v22, 16, v102
	v_and_b32_e32 v23, 0xffff0000, v102
	v_pk_add_f32 v[16:17], v[16:17], v[84:85]
	v_lshlrev_b32_e32 v50, 16, v53
	v_pk_add_f32 v[32:33], v[16:17], v[22:23]
	v_and_b32_e32 v51, 0xffff0000, v53
	v_pk_fma_f32 v[16:17], v[52:53], v[32:33], v[22:23] op_sel_hi:[0,1,1] neg_lo:[0,0,1] neg_hi:[0,0,1]
	v_cvt_pk_bf16_f32 v16, v16, v17
	v_min_u32_e32 v17, 6, v144
	v_add_u32_e32 v17, 2, v17
	v_cvt_f32_ubyte0_e32 v17, v17


; DEV float bflo(unsigned u) { return __uint_as_float(u << 16); }
; DEV float bfhi(unsigned u) { return __uint_as_float(u & 0xffff0000u); }
; template <int WIN>
; DEV void pool_d_prompt8(const bf16_t* __restrict__ proj, bf16_t* __restrict__ dpl, int row0, int c8) {
;     const int t0 = row0 & 2047;
;     uint4 u[WIN + 7];
; #pragma unroll
;     for (int i = 0; i < WIN + 7; ++i) { const int tt = t0 - (WIN - 1) + i; u[i] = (tt >= 0) ? *(const uint4*)(proj + (size_t)(row0 - (WIN - 1) + i) * NPJ + C_U + c8) : make_uint4(0u, 0u, 0u, 0u); }
;     float acc[8] = {0.f, 0.f, 0.f, 0.f, 0.f, 0.f, 0.f, 0.f};
; #pragma unroll
;     for (int i = 0; i < WIN - 1; ++i) { acc[0] += bflo(u[i].x); acc[1] += bfhi(u[i].x); acc[2] += bflo(u[i].y); acc[3] += bfhi(u[i].y); acc[4] += bflo(u[i].z); acc[5] += bfhi(u[i].z); acc[6] += bflo(u[i].w); acc[7] += bfhi(u[i].w); }
; #pragma unroll
;     for (int j = 0; j < 8; ++j) {
;         const uint4 x = u[j + WIN - 1];
	v_lshl_add_u64 v[34:35], v[140:141], 0, v[94:95]
	s_waitcnt vmcnt(6)
	v_lshlrev_b32_e32 v22, 16, v104
	v_and_b32_e32 v23, 0xffff0000, v104


; DEV float bflo(unsigned u) { return __uint_as_float(u << 16); }
; DEV float bfhi(unsigned u) { return __uint_as_float(u & 0xffff0000u); }
; template <int WIN>
; DEV void pool_d_prompt8(const bf16_t* __restrict__ proj, bf16_t* __restrict__ dpl, int row0, int c8) {
;     ...
;         const uint4 x = u[j + WIN - 1];
;         const float xs[8] = {bflo(x.x), bfhi(x.x), bflo(x.y), bfhi(x.y), bflo(x.z), bfhi(x.z), bflo(x.w), bfhi(x.w)};
	v_lshlrev_b32_e32 v100, 16, v105
	v_and_b32_e32 v101, 0xffff0000, v105


; DEV float bflo(unsigned u) { return __uint_as_float(u << 16); }
; DEV float bfhi(unsigned u) { return __uint_as_float(u & 0xffff0000u); }
; template <int WIN>
; DEV void pool_d_prompt8(const bf16_t* __restrict__ proj, bf16_t* __restrict__ dpl, int row0, int c8) {
;     ...
;         acc[0] -= bflo(y.x); acc[1] -= bfhi(y.x); acc[2] -= bflo(y.y); acc[3] -= bfhi(y.y); acc[4] -= bflo(y.z); acc[5] -= bfhi(y.z); acc[6] -= bflo(y.w); acc[7] -= bfhi(y.w);
	v_pk_add_f32 v[24:25], v[24:25], v[88:89] neg_lo:[0,1] neg_hi:[0,1]

; DEV unsigned cvt_pk_bf16(float lo, float hi) { const f32x2_t v = {lo, hi}; const bf16x2_t b = __builtin_convertvector(v, bf16x2_t); return __builtin_bit_cast(unsigned, b); }
; DEV float bflo(unsigned u) { return __uint_as_float(u << 16); }
; DEV float bfhi(unsigned u) { return __uint_as_float(u & 0xffff0000u); }
; template <int WIN>
; DEV void pool_d_prompt8(const bf16_t* __restrict__ proj, bf16_t* __restrict__ dpl, int row0, int c8) {
;     ...
;         const uint4 x = u[j + WIN - 1];
;         const float xs[8] = {bflo(x.x), bfhi(x.x), bflo(x.y), bfhi(x.y), bflo(x.z), bfhi(x.z), bflo(x.w), bfhi(x.w)};
; #pragma unroll
;         for (int e_ = 0; e_ < 8; ++e_) acc[e_] += xs[e_];
;         const float ic = 1.f / (float)min(WIN, t0 + j + 1);
;         uint4 o;
;         o.x = cvt_pk_bf16(acc[0] * ic - xs[0], acc[1] * ic - xs[1]); o.y = cvt_pk_bf16(acc[2] * ic - xs[2], acc[3] * ic - xs[3]);
;         o.z = cvt_pk_bf16(acc[4] * ic - xs[4], acc[5] * ic - xs[5]); o.w = cvt_pk_bf16(acc[6] * ic - xs[6], acc[7] * ic - xs[7]);
;         *(uint4*)(dpl + (size_t)(row0 + j) * LDP + c8) = o;
	v_pk_add_f32 v[104:105], v[24:25], v[22:23]
	v_pk_add_f32 v[24:25], v[30:31], v[108:109] neg_lo:[0,1] neg_hi:[0,1]
	v_lshlrev_b32_e32 v56, 16, v37
	v_and_b32_e32 v57, 0xffff0000, v37
	v_lshlrev_b32_e32 v46, 16, v49
	v_and_b32_e32 v47, 0xffff0000, v49
	v_lshlrev_b32_e32 v36, 16, v45
	v_and_b32_e32 v37, 0xffff0000, v45
	v_lshlrev_b32_e32 v48, 16, v103
	v_and_b32_e32 v49, 0xffff0000, v103
	v_lshlrev_b32_e32 v102, 16, v106
	v_and_b32_e32 v103, 0xffff0000, v106
	v_lshlrev_b32_e32 v44, 16, v107
	v_and_b32_e32 v45, 0xffff0000, v107
	v_rcp_f32_e32 v53, v17
	s_nop 0
	v_mul_f32_e32 v82, 1.0, v53
	v_pk_add_f32 v[106:107], v[24:25], v[100:101]
	v_pk_fma_f32 v[22:23], v[82:83], v[104:105], v[22:23] op_sel_hi:[0,1,1] neg_lo:[0,0,1] neg_hi:[0,0,1]
	v_pk_fma_f32 v[24:25], v[82:83], v[106:107], v[100:101] op_sel_hi:[0,1,1] neg_lo:[0,0,1] neg_hi:[0,0,1]
	v_cvt_pk_bf16_f32 v22, v22, v23
	v_cvt_pk_bf16_f32 v23, v24, v25
	v_pk_add_f32 v[24:25], v[32:33], v[110:111] neg_lo:[0,1] neg_hi:[0,1]
	v_min_u32_e32 v17, 5, v144
	v_pk_add_f32 v[32:33], v[24:25], v[102:103]
	v_add_u32_e32 v17, 3, v17
	v_pk_fma_f32 v[24:25], v[82:83], v[32:33], v[102:103] op_sel_hi:[0,1,1] neg_lo:[0,0,1] neg_hi:[0,0,1]
	v_cvt_f32_ubyte0_e32 v17, v17
	v_cvt_pk_bf16_f32 v24, v24, v25


; DEV float bflo(unsigned u) { return __uint_as_float(u << 16); }
; DEV float bfhi(unsigned u) { return __uint_as_float(u & 0xffff0000u); }
; template <int WIN>
; DEV void pool_d_prompt8(const bf16_t* __restrict__ proj, bf16_t* __restrict__ dpl, int row0, int c8) {
;     ...
;         const uint4 x = u[j + WIN - 1];
;         const float xs[8] = {bflo(x.x), bfhi(x.x), bflo(x.y), bfhi(x.y), bflo(x.z), bfhi(x.z), bflo(x.w), bfhi(x.w)};
	s_waitcnt vmcnt(5)
	v_lshlrev_b32_e32 v102, 16, v40
	v_and_b32_e32 v103, 0xffff0000, v40
	v_lshlrev_b32_e32 v30, 16, v38


; DEV float bflo(unsigned u) { return __uint_as_float(u << 16); }
; DEV float bfhi(unsigned u) { return __uint_as_float(u & 0xffff0000u); }
; template <int WIN>
; DEV void pool_d_prompt8(const bf16_t* __restrict__ proj, bf16_t* __restrict__ dpl, int row0, int c8) {
;     ...
;         const uint4 x = u[j + WIN - 1];
;         const float xs[8] = {bflo(x.x), bfhi(x.x), bflo(x.y), bfhi(x.y), bflo(x.z), bfhi(x.z), bflo(x.w), bfhi(x.w)};
	v_and_b32_e32 v31, 0xffff0000, v38
	v_lshlrev_b32_e32 v100, 16, v39
	v_and_b32_e32 v101, 0xffff0000, v39
	v_lshlrev_b32_e32 v38, 16, v41
	v_and_b32_e32 v39, 0xffff0000, v41


; DEV unsigned cvt_pk_bf16(float lo, float hi) { const f32x2_t v = {lo, hi}; const bf16x2_t b = __builtin_convertvector(v, bf16x2_t); return __builtin_bit_cast(unsigned, b); }
; template <int WIN>
; DEV void pool_d_prompt8(const bf16_t* __restrict__ proj, bf16_t* __restrict__ dpl, int row0, int c8) {
;     ...
;         for (int e_ = 0; e_ < 8; ++e_) acc[e_] += xs[e_];
;         const float ic = 1.f / (float)min(WIN, t0 + j + 1);
;         uint4 o;
;         o.x = cvt_pk_bf16(acc[0] * ic - xs[0], acc[1] * ic - xs[1]); o.y = cvt_pk_bf16(acc[2] * ic - xs[2], acc[3] * ic - xs[3]);
	v_rcp_f32_e32 v25, v17
	s_nop 0
	v_mul_f32_e32 v40, 1.0, v25
	v_min_u32_e32 v17, 4, v144
	v_pk_add_f32 v[32:33], v[32:33], v[116:117] neg_lo:[0,1] neg_hi:[0,1]
	v_add_u32_e32 v17, 4, v17
	v_pk_add_f32 v[108:109], v[32:33], v[102:103]
	v_cvt_f32_ubyte0_e32 v17, v17
	v_pk_fma_f32 v[32:33], v[40:41], v[108:109], v[102:103] op_sel_hi:[0,1,1] neg_lo:[0,0,1] neg_hi:[0,0,1]

; DEV unsigned cvt_pk_bf16(float lo, float hi) { const f32x2_t v = {lo, hi}; const bf16x2_t b = __builtin_convertvector(v, bf16x2_t); return __builtin_bit_cast(unsigned, b); }
; template <int WIN>
; DEV void pool_d_prompt8(const bf16_t* __restrict__ proj, bf16_t* __restrict__ dpl, int row0, int c8) {
;     ...
;         o.x = cvt_pk_bf16(acc[0] * ic - xs[0], acc[1] * ic - xs[1]); o.y = cvt_pk_bf16(acc[2] * ic - xs[2], acc[3] * ic - xs[3]);
	v_cvt_pk_bf16_f32 v32, v32, v33

; DEV float bflo(unsigned u) { return __uint_as_float(u << 16); }
; DEV float bfhi(unsigned u) { return __uint_as_float(u & 0xffff0000u); }
; template <int WIN>
; DEV void pool_d_prompt8(const bf16_t* __restrict__ proj, bf16_t* __restrict__ dpl, int row0, int c8) {
;     ...
;         const uint4 x = u[j + WIN - 1];
;     ...
;         acc[0] -= bflo(y.x); acc[1] -= bfhi(y.x); acc[2] -= bflo(y.y); acc[3] -= bfhi(y.y); acc[4] -= bflo(y.z); acc[5] -= bfhi(y.z); acc[6] -= bflo(y.w); acc[7] -= bfhi(y.w);
	v_pk_add_f32 v[104:105], v[104:105], v[112:113] neg_lo:[0,1] neg_hi:[0,1]
	s_waitcnt vmcnt(4)
	v_lshlrev_b32_e32 v112, 16, v28
	v_and_b32_e32 v113, 0xffff0000, v28

; DEV float bflo(unsigned u) { return __uint_as_float(u << 16); }
; DEV float bfhi(unsigned u) { return __uint_as_float(u & 0xffff0000u); }
; template <int WIN>
; DEV void pool_d_prompt8(const bf16_t* __restrict__ proj, bf16_t* __restrict__ dpl, int row0, int c8) {
;     ...
;         acc[0] -= bflo(y.x); acc[1] -= bfhi(y.x); acc[2] -= bflo(y.y); acc[3] -= bfhi(y.y); acc[4] -= bflo(y.z); acc[5] -= bfhi(y.z); acc[6] -= bflo(y.w); acc[7] -= bfhi(y.w);
	v_pk_add_f32 v[106:107], v[106:107], v[114:115] neg_lo:[0,1] neg_hi:[0,1]


; template <int WIN>
; DEV void pool_d_prompt8(const bf16_t* __restrict__ proj, bf16_t* __restrict__ dpl, int row0, int c8) {
;     ...
;         for (int e_ = 0; e_ < 8; ++e_) acc[e_] += xs[e_];
	v_pk_add_f32 v[104:105], v[104:105], v[30:31]
	v_pk_add_f32 v[106:107], v[106:107], v[100:101]
	v_lshlrev_b32_e32 v102, 16, v29
	v_and_b32_e32 v103, 0xffff0000, v29

; DEV unsigned cvt_pk_bf16(float lo, float hi) { const f32x2_t v = {lo, hi}; const bf16x2_t b = __builtin_convertvector(v, bf16x2_t); return __builtin_bit_cast(unsigned, b); }
; template <int WIN>
; DEV void pool_d_prompt8(const bf16_t* __restrict__ proj, bf16_t* __restrict__ dpl, int row0, int c8) {
;     ...
;         o.x = cvt_pk_bf16(acc[0] * ic - xs[0], acc[1] * ic - xs[1]); o.y = cvt_pk_bf16(acc[2] * ic - xs[2], acc[3] * ic - xs[3]);
;         o.z = cvt_pk_bf16(acc[4] * ic - xs[4], acc[5] * ic - xs[5]); o.w = cvt_pk_bf16(acc[6] * ic - xs[6], acc[7] * ic - xs[7]);
	v_pk_fma_f32 v[30:31], v[40:41], v[104:105], v[30:31] op_sel_hi:[0,1,1] neg_lo:[0,0,1] neg_hi:[0,0,1]
	v_pk_fma_f32 v[100:101], v[40:41], v[106:107], v[100:101] op_sel_hi:[0,1,1] neg_lo:[0,0,1] neg_hi:[0,0,1]


; DEV unsigned cvt_pk_bf16(float lo, float hi) { const f32x2_t v = {lo, hi}; const bf16x2_t b = __builtin_convertvector(v, bf16x2_t); return __builtin_bit_cast(unsigned, b); }
; DEV float bflo(unsigned u) { return __uint_as_float(u << 16); }
; DEV float bfhi(unsigned u) { return __uint_as_float(u & 0xffff0000u); }
; template <int WIN>
; DEV void pool_d_prompt8(const bf16_t* __restrict__ proj, bf16_t* __restrict__ dpl, int row0, int c8) {
;     ...
;         const uint4 x = u[j + WIN - 1];
;         const float xs[8] = {bflo(x.x), bfhi(x.x), bflo(x.y), bfhi(x.y), bflo(x.z), bfhi(x.z), bflo(x.w), bfhi(x.w)};
; #pragma unroll
;         for (int e_ = 0; e_ < 8; ++e_) acc[e_] += xs[e_];
;         const float ic = 1.f / (float)min(WIN, t0 + j + 1);
;         uint4 o;
;         o.x = cvt_pk_bf16(acc[0] * ic - xs[0], acc[1] * ic - xs[1]); o.y = cvt_pk_bf16(acc[2] * ic - xs[2], acc[3] * ic - xs[3]);
;         o.z = cvt_pk_bf16(acc[4] * ic - xs[4], acc[5] * ic - xs[5]); o.w = cvt_pk_bf16(acc[6] * ic - xs[6], acc[7] * ic - xs[7]);
;         *(uint4*)(dpl + (size_t)(row0 + j) * LDP + c8) = o;
;         const uint4 y = u[j];
;         acc[0] -= bflo(y.x); acc[1] -= bfhi(y.x); acc[2] -= bflo(y.y); acc[3] -= bfhi(y.y); acc[4] -= bflo(y.z); acc[5] -= bfhi(y.z); acc[6] -= bflo(y.w); acc[7] -= bfhi(y.w);
	v_lshlrev_b32_e32 v110, 16, v26
	v_and_b32_e32 v111, 0xffff0000, v26
	v_rcp_f32_e32 v25, v17
	s_nop 0
	v_mul_f32_e32 v94, 1.0, v25
	v_pk_add_f32 v[28:29], v[104:105], v[98:99] neg_lo:[0,1] neg_hi:[0,1]
	v_min_u32_e32 v17, 3, v144
	v_lshlrev_b32_e32 v26, 16, v27
	v_and_b32_e32 v27, 0xffff0000, v27
	v_pk_add_f32 v[28:29], v[28:29], v[110:111]
	v_pk_add_f32 v[92:93], v[106:107], v[92:93] neg_lo:[0,1] neg_hi:[0,1]
	v_add_u32_e32 v17, 5, v17
	v_pk_fma_f32 v[98:99], v[94:95], v[28:29], v[110:111] op_sel_hi:[0,1,1] neg_lo:[0,0,1] neg_hi:[0,0,1]
	v_pk_add_f32 v[92:93], v[92:93], v[26:27]
	v_cvt_f32_ubyte0_e32 v17, v17
	v_cvt_pk_bf16_f32 v104, v98, v99
	v_pk_fma_f32 v[26:27], v[94:95], v[92:93], v[26:27] op_sel_hi:[0,1,1] neg_lo:[0,0,1] neg_hi:[0,0,1]
	s_waitcnt vmcnt(3)
	v_lshlrev_b32_e32 v98, 16, v18
	v_and_b32_e32 v99, 0xffff0000, v18

; DEV unsigned cvt_pk_bf16(float lo, float hi) { const f32x2_t v = {lo, hi}; const bf16x2_t b = __builtin_convertvector(v, bf16x2_t); return __builtin_bit_cast(unsigned, b); }
; DEV float bflo(unsigned u) { return __uint_as_float(u << 16); }
; DEV float bfhi(unsigned u) { return __uint_as_float(u & 0xffff0000u); }
; template <int WIN>
; DEV void pool_d_prompt8(const bf16_t* __restrict__ proj, bf16_t* __restrict__ dpl, int row0, int c8) {
;     ...
;         o.x = cvt_pk_bf16(acc[0] * ic - xs[0], acc[1] * ic - xs[1]); o.y = cvt_pk_bf16(acc[2] * ic - xs[2], acc[3] * ic - xs[3]);
;         o.z = cvt_pk_bf16(acc[4] * ic - xs[4], acc[5] * ic - xs[5]); o.w = cvt_pk_bf16(acc[6] * ic - xs[6], acc[7] * ic - xs[7]);
;         *(uint4*)(dpl + (size_t)(row0 + j) * LDP + c8) = o;
;         const uint4 y = u[j];
;         acc[0] -= bflo(y.x); acc[1] -= bfhi(y.x); acc[2] -= bflo(y.y); acc[3] -= bfhi(y.y); acc[4] -= bflo(y.z); acc[5] -= bfhi(y.z); acc[6] -= bflo(y.w); acc[7] -= bfhi(y.w);
	v_cvt_pk_bf16_f32 v105, v26, v27
	v_pk_add_f32 v[26:27], v[108:109], v[90:91] neg_lo:[0,1] neg_hi:[0,1]
	v_lshlrev_b32_e32 v108, 16, v19
	v_and_b32_e32 v109, 0xffff0000, v19

; DEV float bflo(unsigned u) { return __uint_as_float(u << 16); }
; DEV float bfhi(unsigned u) { return __uint_as_float(u & 0xffff0000u); }
; template <int WIN>
; DEV void pool_d_prompt8(const bf16_t* __restrict__ proj, bf16_t* __restrict__ dpl, int row0, int c8) {
;     ...
;         const uint4 x = u[j + WIN - 1];
;         const float xs[8] = {bflo(x.x), bfhi(x.x), bflo(x.y), bfhi(x.y), bflo(x.z), bfhi(x.z), bflo(x.w), bfhi(x.w)};
; #pragma unroll
;         for (int e_ = 0; e_ < 8; ++e_) acc[e_] += xs[e_];
	v_lshlrev_b32_e32 v110, 16, v20
	v_and_b32_e32 v111, 0xffff0000, v20
	v_pk_add_f32 v[26:27], v[26:27], v[112:113]


; DEV unsigned cvt_pk_bf16(float lo, float hi) { const f32x2_t v = {lo, hi}; const bf16x2_t b = __builtin_convertvector(v, bf16x2_t); return __builtin_bit_cast(unsigned, b); }
; template <int WIN>
; DEV void pool_d_prompt8(const bf16_t* __restrict__ proj, bf16_t* __restrict__ dpl, int row0, int c8) {
;     ...
;         o.x = cvt_pk_bf16(acc[0] * ic - xs[0], acc[1] * ic - xs[1]); o.y = cvt_pk_bf16(acc[2] * ic - xs[2], acc[3] * ic - xs[3]);
	v_pk_fma_f32 v[90:91], v[94:95], v[26:27], v[112:113] op_sel_hi:[0,1,1] neg_lo:[0,0,1] neg_hi:[0,0,1]
	v_lshlrev_b32_e32 v112, 16, v21
	v_and_b32_e32 v113, 0xffff0000, v21


; DEV unsigned cvt_pk_bf16(float lo, float hi) { const f32x2_t v = {lo, hi}; const bf16x2_t b = __builtin_convertvector(v, bf16x2_t); return __builtin_bit_cast(unsigned, b); }
; DEV float bflo(unsigned u) { return __uint_as_float(u << 16); }
; DEV float bfhi(unsigned u) { return __uint_as_float(u & 0xffff0000u); }
; template <int WIN>
; DEV void pool_d_prompt8(const bf16_t* __restrict__ proj, bf16_t* __restrict__ dpl, int row0, int c8) {
;     ...
;         const float ic = 1.f / (float)min(WIN, t0 + j + 1);
;         uint4 o;
;         o.x = cvt_pk_bf16(acc[0] * ic - xs[0], acc[1] * ic - xs[1]); o.y = cvt_pk_bf16(acc[2] * ic - xs[2], acc[3] * ic - xs[3]);
;         o.z = cvt_pk_bf16(acc[4] * ic - xs[4], acc[5] * ic - xs[5]); o.w = cvt_pk_bf16(acc[6] * ic - xs[6], acc[7] * ic - xs[7]);
;         *(uint4*)(dpl + (size_t)(row0 + j) * LDP + c8) = o;
;         const uint4 y = u[j];
;         acc[0] -= bflo(y.x); acc[1] -= bfhi(y.x); acc[2] -= bflo(y.y); acc[3] -= bfhi(y.y); acc[4] -= bflo(y.z); acc[5] -= bfhi(y.z); acc[6] -= bflo(y.w); acc[7] -= bfhi(y.w);
	v_rcp_f32_e32 v18, v17
	s_nop 0
	v_mul_f32_e32 v114, 1.0, v18
	v_pk_add_f32 v[18:19], v[28:29], v[86:87] neg_lo:[0,1] neg_hi:[0,1]
	s_waitcnt vmcnt(2)
	v_lshlrev_b32_e32 v86, 16, v10
	v_and_b32_e32 v87, 0xffff0000, v10
	v_min_u32_e32 v10, 2, v144
	v_add_u32_e32 v10, 6, v10
	v_cvt_f32_ubyte0_e32 v10, v10
	v_pk_add_f32 v[20:21], v[92:93], v[80:81] neg_lo:[0,1] neg_hi:[0,1]
	v_lshlrev_b32_e32 v92, 16, v11
	v_and_b32_e32 v93, 0xffff0000, v11


; DEV unsigned cvt_pk_bf16(float lo, float hi) { const f32x2_t v = {lo, hi}; const bf16x2_t b = __builtin_convertvector(v, bf16x2_t); return __builtin_bit_cast(unsigned, b); }
; template <int WIN>
; DEV void pool_d_prompt8(const bf16_t* __restrict__ proj, bf16_t* __restrict__ dpl, int row0, int c8) {
;     ...
;         for (int e_ = 0; e_ < 8; ++e_) acc[e_] += xs[e_];
;         const float ic = 1.f / (float)min(WIN, t0 + j + 1);
;         uint4 o;
;         o.x = cvt_pk_bf16(acc[0] * ic - xs[0], acc[1] * ic - xs[1]); o.y = cvt_pk_bf16(acc[2] * ic - xs[2], acc[3] * ic - xs[3]);
;         o.z = cvt_pk_bf16(acc[4] * ic - xs[4], acc[5] * ic - xs[5]); o.w = cvt_pk_bf16(acc[6] * ic - xs[6], acc[7] * ic - xs[7]);
;         *(uint4*)(dpl + (size_t)(row0 + j) * LDP + c8) = o;
	v_pk_add_f32 v[28:29], v[18:19], v[98:99]
	v_pk_add_f32 v[80:81], v[20:21], v[108:109]
	v_pk_fma_f32 v[18:19], v[114:115], v[28:29], v[98:99] op_sel_hi:[0,1,1] neg_lo:[0,0,1] neg_hi:[0,0,1]
	v_pk_fma_f32 v[20:21], v[114:115], v[80:81], v[108:109] op_sel_hi:[0,1,1] neg_lo:[0,0,1] neg_hi:[0,0,1]
	v_cvt_pk_bf16_f32 v18, v18, v19
	v_cvt_pk_bf16_f32 v19, v20, v21
	v_pk_add_f32 v[20:21], v[26:27], v[78:79] neg_lo:[0,1] neg_hi:[0,1]
	v_lshlrev_b32_e32 v98, 16, v12
	v_and_b32_e32 v99, 0xffff0000, v12

; template <int WIN>
; DEV void pool_d_prompt8(const bf16_t* __restrict__ proj, bf16_t* __restrict__ dpl, int row0, int c8) {
;     ...
;         for (int e_ = 0; e_ < 8; ++e_) acc[e_] += xs[e_];
	v_pk_add_f32 v[26:27], v[20:21], v[110:111]


; DEV unsigned cvt_pk_bf16(float lo, float hi) { const f32x2_t v = {lo, hi}; const bf16x2_t b = __builtin_convertvector(v, bf16x2_t); return __builtin_bit_cast(unsigned, b); }
; template <int WIN>
; DEV void pool_d_prompt8(const bf16_t* __restrict__ proj, bf16_t* __restrict__ dpl, int row0, int c8) {
;     ...
;         o.x = cvt_pk_bf16(acc[0] * ic - xs[0], acc[1] * ic - xs[1]); o.y = cvt_pk_bf16(acc[2] * ic - xs[2], acc[3] * ic - xs[3]);
	v_pk_fma_f32 v[20:21], v[114:115], v[26:27], v[110:111] op_sel_hi:[0,1,1] neg_lo:[0,0,1] neg_hi:[0,0,1]
	v_lshlrev_b32_e32 v108, 16, v13
	v_and_b32_e32 v109, 0xffff0000, v13

; DEV unsigned cvt_pk_bf16(float lo, float hi) { const f32x2_t v = {lo, hi}; const bf16x2_t b = __builtin_convertvector(v, bf16x2_t); return __builtin_bit_cast(unsigned, b); }
; template <int WIN>
; DEV void pool_d_prompt8(const bf16_t* __restrict__ proj, bf16_t* __restrict__ dpl, int row0, int c8) {
;     ...
;         o.z = cvt_pk_bf16(acc[4] * ic - xs[4], acc[5] * ic - xs[5]); o.w = cvt_pk_bf16(acc[6] * ic - xs[6], acc[7] * ic - xs[7]);
	v_cvt_pk_bf16_f32 v20, v20, v21


; DEV unsigned cvt_pk_bf16(float lo, float hi) { const f32x2_t v = {lo, hi}; const bf16x2_t b = __builtin_convertvector(v, bf16x2_t); return __builtin_bit_cast(unsigned, b); }
; DEV float bflo(unsigned u) { return __uint_as_float(u << 16); }
; DEV float bfhi(unsigned u) { return __uint_as_float(u & 0xffff0000u); }
; template <int WIN>
; DEV void pool_d_prompt8(const bf16_t* __restrict__ proj, bf16_t* __restrict__ dpl, int row0, int c8) {
;     ...
;         const float ic = 1.f / (float)min(WIN, t0 + j + 1);
;         uint4 o;
;         o.x = cvt_pk_bf16(acc[0] * ic - xs[0], acc[1] * ic - xs[1]); o.y = cvt_pk_bf16(acc[2] * ic - xs[2], acc[3] * ic - xs[3]);
;         o.z = cvt_pk_bf16(acc[4] * ic - xs[4], acc[5] * ic - xs[5]); o.w = cvt_pk_bf16(acc[6] * ic - xs[6], acc[7] * ic - xs[7]);
;         *(uint4*)(dpl + (size_t)(row0 + j) * LDP + c8) = o;
;         const uint4 y = u[j];
;         acc[0] -= bflo(y.x); acc[1] -= bfhi(y.x); acc[2] -= bflo(y.y); acc[3] -= bfhi(y.y); acc[4] -= bflo(y.z); acc[5] -= bfhi(y.z); acc[6] -= bflo(y.w); acc[7] -= bfhi(y.w);
	v_rcp_f32_e32 v11, v10
	s_nop 0
	v_mul_f32_e32 v110, 1.0, v11
	v_pk_add_f32 v[10:11], v[28:29], v[74:75] neg_lo:[0,1] neg_hi:[0,1]
	s_waitcnt vmcnt(1)
	v_lshlrev_b32_e32 v74, 16, v6
	v_and_b32_e32 v75, 0xffff0000, v6

; DEV float bflo(unsigned u) { return __uint_as_float(u << 16); }
; DEV float bfhi(unsigned u) { return __uint_as_float(u & 0xffff0000u); }
; template <int WIN>
; DEV void pool_d_prompt8(const bf16_t* __restrict__ proj, bf16_t* __restrict__ dpl, int row0, int c8) {
;     ...
;         const uint4 x = u[j + WIN - 1];
;     ...
;         acc[0] -= bflo(y.x); acc[1] -= bfhi(y.x); acc[2] -= bflo(y.y); acc[3] -= bfhi(y.y); acc[4] -= bflo(y.z); acc[5] -= bfhi(y.z); acc[6] -= bflo(y.w); acc[7] -= bfhi(y.w);
	v_pk_add_f32 v[12:13], v[80:81], v[72:73] neg_lo:[0,1] neg_hi:[0,1]
	v_lshlrev_b32_e32 v80, 16, v7
	v_and_b32_e32 v81, 0xffff0000, v7

; DEV unsigned cvt_pk_bf16(float lo, float hi) { const f32x2_t v = {lo, hi}; const bf16x2_t b = __builtin_convertvector(v, bf16x2_t); return __builtin_bit_cast(unsigned, b); }
; DEV float bflo(unsigned u) { return __uint_as_float(u << 16); }
; DEV float bfhi(unsigned u) { return __uint_as_float(u & 0xffff0000u); }
; template <int WIN>
; DEV void pool_d_prompt8(const bf16_t* __restrict__ proj, bf16_t* __restrict__ dpl, int row0, int c8) {
;     ...
;         for (int e_ = 0; e_ < 8; ++e_) acc[e_] += xs[e_];
;         const float ic = 1.f / (float)min(WIN, t0 + j + 1);
;         uint4 o;
;         o.x = cvt_pk_bf16(acc[0] * ic - xs[0], acc[1] * ic - xs[1]); o.y = cvt_pk_bf16(acc[2] * ic - xs[2], acc[3] * ic - xs[3]);
;         o.z = cvt_pk_bf16(acc[4] * ic - xs[4], acc[5] * ic - xs[5]); o.w = cvt_pk_bf16(acc[6] * ic - xs[6], acc[7] * ic - xs[7]);
;         *(uint4*)(dpl + (size_t)(row0 + j) * LDP + c8) = o;
;         const uint4 y = u[j];
;         acc[0] -= bflo(y.x); acc[1] -= bfhi(y.x); acc[2] -= bflo(y.y); acc[3] -= bfhi(y.y); acc[4] -= bflo(y.z); acc[5] -= bfhi(y.z); acc[6] -= bflo(y.w); acc[7] -= bfhi(y.w);
	v_pk_add_f32 v[28:29], v[10:11], v[86:87]
	v_pk_add_f32 v[72:73], v[12:13], v[92:93]
	v_pk_fma_f32 v[10:11], v[110:111], v[28:29], v[86:87] op_sel_hi:[0,1,1] neg_lo:[0,0,1] neg_hi:[0,0,1]
	v_pk_fma_f32 v[12:13], v[110:111], v[72:73], v[92:93] op_sel_hi:[0,1,1] neg_lo:[0,0,1] neg_hi:[0,0,1]
	v_cvt_pk_bf16_f32 v10, v10, v11
	v_cvt_pk_bf16_f32 v11, v12, v13
	v_pk_add_f32 v[12:13], v[26:27], v[68:69] neg_lo:[0,1] neg_hi:[0,1]
	v_lshlrev_b32_e32 v86, 16, v8
	v_and_b32_e32 v87, 0xffff0000, v8

; template <int WIN>
; DEV void pool_d_prompt8(const bf16_t* __restrict__ proj, bf16_t* __restrict__ dpl, int row0, int c8) {
;     ...
;         for (int e_ = 0; e_ < 8; ++e_) acc[e_] += xs[e_];
	v_pk_add_f32 v[26:27], v[12:13], v[98:99]


; DEV unsigned cvt_pk_bf16(float lo, float hi) { const f32x2_t v = {lo, hi}; const bf16x2_t b = __builtin_convertvector(v, bf16x2_t); return __builtin_bit_cast(unsigned, b); }
; template <int WIN>
; DEV void pool_d_prompt8(const bf16_t* __restrict__ proj, bf16_t* __restrict__ dpl, int row0, int c8) {
;     ...
;         o.x = cvt_pk_bf16(acc[0] * ic - xs[0], acc[1] * ic - xs[1]); o.y = cvt_pk_bf16(acc[2] * ic - xs[2], acc[3] * ic - xs[3]);
	v_pk_fma_f32 v[12:13], v[110:111], v[26:27], v[98:99] op_sel_hi:[0,1,1] neg_lo:[0,0,1] neg_hi:[0,0,1]
	v_lshlrev_b32_e32 v92, 16, v9
	v_and_b32_e32 v93, 0xffff0000, v9

; DEV unsigned cvt_pk_bf16(float lo, float hi) { const f32x2_t v = {lo, hi}; const bf16x2_t b = __builtin_convertvector(v, bf16x2_t); return __builtin_bit_cast(unsigned, b); }
; template <int WIN>
; DEV void pool_d_prompt8(const bf16_t* __restrict__ proj, bf16_t* __restrict__ dpl, int row0, int c8) {
;     ...
;         o.z = cvt_pk_bf16(acc[4] * ic - xs[4], acc[5] * ic - xs[5]); o.w = cvt_pk_bf16(acc[6] * ic - xs[6], acc[7] * ic - xs[7]);
	v_cvt_pk_bf16_f32 v12, v12, v13


; DEV unsigned cvt_pk_bf16(float lo, float hi) { const f32x2_t v = {lo, hi}; const bf16x2_t b = __builtin_convertvector(v, bf16x2_t); return __builtin_bit_cast(unsigned, b); }
; DEV float bflo(unsigned u) { return __uint_as_float(u << 16); }
; DEV float bfhi(unsigned u) { return __uint_as_float(u & 0xffff0000u); }
; template <int WIN>
; DEV void pool_d_prompt8(const bf16_t* __restrict__ proj, bf16_t* __restrict__ dpl, int row0, int c8) {
;     ...
;     for (int i = 0; i < WIN + 7; ++i) { const int tt = t0 - (WIN - 1) + i; u[i] = (tt >= 0) ? *(const uint4*)(proj + (size_t)(row0 - (WIN - 1) + i) * NPJ + C_U + c8) : make_uint4(0u, 0u, 0u, 0u); }
;     float acc[8] = {0.f, 0.f, 0.f, 0.f, 0.f, 0.f, 0.f, 0.f};
; #pragma unroll
;     for (int i = 0; i < WIN - 1; ++i) { acc[0] += bflo(u[i].x); acc[1] += bfhi(u[i].x); acc[2] += bflo(u[i].y); acc[3] += bfhi(u[i].y); acc[4] += bflo(u[i].z); acc[5] += bfhi(u[i].z); acc[6] += bflo(u[i].w); acc[7] += bfhi(u[i].w); }
; #pragma unroll
;     for (int j = 0; j < 8; ++j) {
;         const uint4 x = u[j + WIN - 1];
;         const float xs[8] = {bflo(x.x), bfhi(x.x), bflo(x.y), bfhi(x.y), bflo(x.z), bfhi(x.z), bflo(x.w), bfhi(x.w)};
; #pragma unroll
;         for (int e_ = 0; e_ < 8; ++e_) acc[e_] += xs[e_];
;         const float ic = 1.f / (float)min(WIN, t0 + j + 1);
;         uint4 o;
;         o.x = cvt_pk_bf16(acc[0] * ic - xs[0], acc[1] * ic - xs[1]); o.y = cvt_pk_bf16(acc[2] * ic - xs[2], acc[3] * ic - xs[3]);
;         o.z = cvt_pk_bf16(acc[4] * ic - xs[4], acc[5] * ic - xs[5]); o.w = cvt_pk_bf16(acc[6] * ic - xs[6], acc[7] * ic - xs[7]);
;         *(uint4*)(dpl + (size_t)(row0 + j) * LDP + c8) = o;
;         const uint4 y = u[j];
;         acc[0] -= bflo(y.x); acc[1] -= bfhi(y.x); acc[2] -= bflo(y.y); acc[3] -= bfhi(y.y); acc[4] -= bflo(y.z); acc[5] -= bfhi(y.z); acc[6] -= bflo(y.w); acc[7] -= bfhi(y.w);
;     }
	v_rcp_f32_e32 v6, v83
	s_nop 0
	v_mul_f32_e32 v98, 1.0, v6
	v_pk_add_f32 v[6:7], v[28:29], v[66:67] neg_lo:[0,1] neg_hi:[0,1]
	v_pk_add_f32 v[8:9], v[72:73], v[64:65] neg_lo:[0,1] neg_hi:[0,1]
	v_pk_add_f32 v[28:29], v[6:7], v[74:75]
	v_pk_add_f32 v[64:65], v[8:9], v[80:81]
	v_pk_fma_f32 v[6:7], v[98:99], v[28:29], v[74:75] op_sel_hi:[0,1,1] neg_lo:[0,0,1] neg_hi:[0,0,1]
	v_pk_fma_f32 v[8:9], v[98:99], v[64:65], v[80:81] op_sel_hi:[0,1,1] neg_lo:[0,0,1] neg_hi:[0,0,1]
	v_cvt_pk_bf16_f32 v6, v6, v7
	v_cvt_pk_bf16_f32 v7, v8, v9
	v_pk_add_f32 v[8:9], v[26:27], v[62:63] neg_lo:[0,1] neg_hi:[0,1]
	s_waitcnt vmcnt(0)
	v_lshlrev_b32_e32 v26, 16, v2
	v_and_b32_e32 v27, 0xffff0000, v2
	v_pk_add_f32 v[28:29], v[28:29], v[70:71] neg_lo:[0,1] neg_hi:[0,1]
	v_lshlrev_b32_e32 v2, 16, v3
	v_pk_add_f32 v[28:29], v[28:29], v[26:27]
	v_and_b32_e32 v3, 0xffff0000, v3
	v_pk_fma_f32 v[26:27], v[28:29], s[10:11], v[26:27] op_sel_hi:[1,0,1] neg_lo:[0,0,1] neg_hi:[0,0,1]
	v_pk_add_f32 v[28:29], v[64:65], v[76:77] neg_lo:[0,1] neg_hi:[0,1]
	v_pk_add_f32 v[62:63], v[8:9], v[86:87]
	v_pk_add_f32 v[28:29], v[28:29], v[2:3]
	v_mad_i64_i32 v[42:43], s[4:5], v145, s27, v[34:35]
	v_mad_i64_i32 v[88:89], s[4:5], v118, s27, v[34:35]
	v_cvt_pk_bf16_f32 v30, v30, v31
	v_cvt_pk_bf16_f32 v31, v100, v101
	v_mad_i64_i32 v[100:101], s[4:5], v119, s27, v[34:35]
	v_cvt_pk_bf16_f32 v106, v90, v91
	v_mad_i64_i32 v[90:91], s[4:5], v120, s27, v[34:35]
	v_mad_i64_i32 v[78:79], s[4:5], v121, s27, v[34:35]
	v_mad_i64_i32 v[68:69], s[4:5], v122, s27, v[34:35]
	v_mad_i64_i32 v[66:67], s[4:5], v123, s27, v[34:35]
	v_lshlrev_b32_e32 v34, 16, v4
	v_and_b32_e32 v35, 0xffff0000, v4
	v_pk_fma_f32 v[28:29], v[28:29], s[10:11], v[2:3] op_sel_hi:[1,0,1] neg_lo:[0,0,1] neg_hi:[0,0,1]
	v_pk_add_f32 v[2:3], v[62:63], v[84:85] neg_lo:[0,1] neg_hi:[0,1]
	v_lshlrev_b32_e32 v4, 16, v5
	v_pk_add_f32 v[2:3], v[2:3], v[34:35]
	v_and_b32_e32 v5, 0xffff0000, v5
	v_pk_fma_f32 v[34:35], v[2:3], s[10:11], v[34:35] op_sel_hi:[1,0,1] neg_lo:[0,0,1] neg_hi:[0,0,1]
	v_pk_add_f32 v[2:3], v[60:61], 0 op_sel_hi:[1,0]
	v_pk_fma_f32 v[8:9], v[98:99], v[62:63], v[86:87] op_sel_hi:[0,1,1] neg_lo:[0,0,1] neg_hi:[0,0,1]
	v_pk_add_f32 v[2:3], v[2:3], v[58:59]
	v_ashrrev_i32_e32 v97, 31, v96
	v_pk_add_f32 v[2:3], v[2:3], v[56:57]
	v_cvt_pk_bf16_f32 v8, v8, v9
	v_pk_add_f32 v[2:3], v[2:3], v[54:55]
	s_nop 0
	v_pk_add_f32 v[2:3], v[2:3], v[50:51]
	s_nop 0
	v_pk_add_f32 v[2:3], v[2:3], v[46:47]
	s_nop 0
	v_pk_add_f32 v[2:3], v[2:3], v[36:37]
	s_nop 0
	v_pk_add_f32 v[2:3], v[2:3], v[48:49]
	s_nop 0
	v_pk_fma_f32 v[48:49], v[52:53], v[2:3], v[48:49] op_sel_hi:[0,1,1] neg_lo:[0,0,1] neg_hi:[0,0,1]
	v_pk_add_f32 v[2:3], v[2:3], v[60:61] neg_lo:[0,1] neg_hi:[0,1]
	v_cvt_pk_bf16_f32 v17, v48, v49
	v_pk_add_f32 v[2:3], v[2:3], v[44:45]
	global_store_dwordx4 v[42:43], v[14:17], off sc1
	s_nop 1
	v_pk_fma_f32 v[14:15], v[82:83], v[2:3], v[44:45] op_sel_hi:[0,1,1] neg_lo:[0,0,1] neg_hi:[0,0,1]
	v_pk_add_f32 v[2:3], v[2:3], v[58:59] neg_lo:[0,1] neg_hi:[0,1]
	v_cvt_pk_bf16_f32 v25, v14, v15
	v_pk_add_f32 v[2:3], v[2:3], v[38:39]
	global_store_dwordx4 v[88:89], v[22:25], off sc1
	v_pk_fma_f32 v[14:15], v[40:41], v[2:3], v[38:39] op_sel_hi:[0,1,1] neg_lo:[0,0,1] neg_hi:[0,0,1]
	v_pk_add_f32 v[2:3], v[2:3], v[56:57] neg_lo:[0,1] neg_hi:[0,1]
	v_cvt_pk_bf16_f32 v33, v14, v15
	v_pk_add_f32 v[2:3], v[2:3], v[102:103]
	global_store_dwordx4 v[100:101], v[30:33], off sc1
	v_pk_fma_f32 v[14:15], v[94:95], v[2:3], v[102:103] op_sel_hi:[0,1,1] neg_lo:[0,0,1] neg_hi:[0,0,1]
	v_pk_add_f32 v[2:3], v[2:3], v[54:55] neg_lo:[0,1] neg_hi:[0,1]
	v_cvt_pk_bf16_f32 v107, v14, v15
	v_pk_add_f32 v[2:3], v[2:3], v[112:113]
	global_store_dwordx4 v[90:91], v[104:107], off sc1
	v_pk_fma_f32 v[14:15], v[114:115], v[2:3], v[112:113] op_sel_hi:[0,1,1] neg_lo:[0,0,1] neg_hi:[0,0,1]
	v_pk_add_f32 v[2:3], v[2:3], v[50:51] neg_lo:[0,1] neg_hi:[0,1]
	v_cvt_pk_bf16_f32 v21, v14, v15
	v_pk_add_f32 v[2:3], v[2:3], v[108:109]
	global_store_dwordx4 v[78:79], v[18:21], off sc1
	v_pk_fma_f32 v[14:15], v[110:111], v[2:3], v[108:109] op_sel_hi:[0,1,1] neg_lo:[0,0,1] neg_hi:[0,0,1]
	v_pk_add_f32 v[2:3], v[2:3], v[46:47] neg_lo:[0,1] neg_hi:[0,1]
	v_cvt_pk_bf16_f32 v13, v14, v15
	v_pk_add_f32 v[2:3], v[2:3], v[92:93]
	global_store_dwordx4 v[68:69], v[10:13], off sc1
	s_nop 1
	v_pk_fma_f32 v[10:11], v[98:99], v[2:3], v[92:93] op_sel_hi:[0,1,1] neg_lo:[0,0,1] neg_hi:[0,0,1]
	v_pk_add_f32 v[2:3], v[2:3], v[36:37] neg_lo:[0,1] neg_hi:[0,1]
	v_cvt_pk_bf16_f32 v9, v10, v11
	v_pk_add_f32 v[2:3], v[2:3], v[4:5]
	global_store_dwordx4 v[66:67], v[6:9], off sc1
	v_pk_fma_f32 v[2:3], v[2:3], s[10:11], v[4:5] op_sel_hi:[1,0,1] neg_lo:[0,0,1] neg_hi:[0,0,1]

; DEV float bflo(unsigned u) { return __uint_as_float(u << 16); }
; DEV float bfhi(unsigned u) { return __uint_as_float(u & 0xffff0000u); }
; template <int WIN>
; DEV void pool_d_prompt8(const bf16_t* __restrict__ proj, bf16_t* __restrict__ dpl, int row0, int c8) {
;     const int t0 = row0 & 2047;
;     uint4 u[WIN + 7];
; #pragma unroll
;     for (int i = 0; i < WIN + 7; ++i) { const int tt = t0 - (WIN - 1) + i; u[i] = (tt >= 0) ? *(const uint4*)(proj + (size_t)(row0 - (WIN - 1) + i) * NPJ + C_U + c8) : make_uint4(0u, 0u, 0u, 0u); }
;     float acc[8] = {0.f, 0.f, 0.f, 0.f, 0.f, 0.f, 0.f, 0.f};
; #pragma unroll
;     for (int i = 0; i < WIN - 1; ++i) { acc[0] += bflo(u[i].x); acc[1] += bfhi(u[i].x); acc[2] += bflo(u[i].y); acc[3] += bfhi(u[i].y); acc[4] += bflo(u[i].z); acc[5] += bfhi(u[i].z); acc[6] += bflo(u[i].w); acc[7] += bfhi(u[i].w); }
; #pragma unroll
;     for (int j = 0; j < 8; ++j) {
;         const uint4 x = u[j + WIN - 1];
.LBB0_741:
	s_or_b64 exec, exec, s[20:21]
	v_mad_i64_i32 v[6:7], s[4:5], v145, s25, v[172:173]
	v_lshlrev_b32_e32 v94, 1, v143
	v_lshl_add_u64 v[6:7], v[6:7], 0, v[94:95]
	v_or_b32_e32 v85, 1, v145
	v_add_co_u32_e32 v6, vcc, 0x2000, v6
	v_mad_i64_i32 v[8:9], s[4:5], v85, s25, v[172:173]
	s_nop 0
	v_addc_co_u32_e32 v7, vcc, 0, v7, vcc
	v_lshl_add_u64 v[8:9], v[8:9], 0, v[94:95]
	v_add_co_u32_e32 v8, vcc, 0x2000, v8
	v_or_b32_e32 v91, 2, v145
	s_nop 0
	v_addc_co_u32_e32 v9, vcc, 0, v9, vcc
	global_load_dwordx4 v[34:37], v[6:7], off
	global_load_dwordx4 v[38:41], v[8:9], off
	v_mad_i64_i32 v[6:7], s[4:5], v91, s25, v[172:173]
	v_lshl_add_u64 v[6:7], v[6:7], 0, v[94:95]
	v_or_b32_e32 v100, 3, v145
	v_add_co_u32_e32 v6, vcc, 0x2000, v6
	v_mad_i64_i32 v[8:9], s[4:5], v100, s25, v[172:173]
	s_nop 0
	v_addc_co_u32_e32 v7, vcc, 0, v7, vcc
	v_lshl_add_u64 v[8:9], v[8:9], 0, v[94:95]
	v_add_co_u32_e32 v8, vcc, 0x2000, v8
	v_or_b32_e32 v104, 4, v145
	s_nop 0
	v_addc_co_u32_e32 v9, vcc, 0, v9, vcc
	global_load_dwordx4 v[42:45], v[6:7], off
	global_load_dwordx4 v[46:49], v[8:9], off
	v_mad_i64_i32 v[6:7], s[4:5], v104, s25, v[172:173]
	v_lshl_add_u64 v[6:7], v[6:7], 0, v[94:95]
	v_or_b32_e32 v105, 5, v145
	v_add_co_u32_e32 v6, vcc, 0x2000, v6
	v_mad_i64_i32 v[8:9], s[4:5], v105, s25, v[172:173]
	s_nop 0
	v_addc_co_u32_e32 v7, vcc, 0, v7, vcc
	v_lshl_add_u64 v[8:9], v[8:9], 0, v[94:95]
	v_add_co_u32_e32 v8, vcc, 0x2000, v8
	v_or_b32_e32 v106, 6, v145
	s_nop 0
	v_addc_co_u32_e32 v9, vcc, 0, v9, vcc
	global_load_dwordx4 v[18:21], v[6:7], off
	global_load_dwordx4 v[14:17], v[8:9], off
	v_mad_i64_i32 v[6:7], s[4:5], v106, s25, v[172:173]
	v_lshl_add_u64 v[6:7], v[6:7], 0, v[94:95]
	v_add_co_u32_e32 v30, vcc, 0x2000, v6
	v_or_b32_e32 v96, 7, v98
	s_nop 0
	v_addc_co_u32_e32 v31, vcc, 0, v7, vcc
	v_mad_i64_i32 v[6:7], s[4:5], v96, s25, v[172:173]
	v_lshl_add_u64 v[6:7], v[6:7], 0, v[94:95]
	v_add_co_u32_e32 v50, vcc, s26, v6
	s_waitcnt vmcnt(6)
	v_lshlrev_b32_e32 v54, 16, v28
	v_addc_co_u32_e32 v51, vcc, 0, v7, vcc
	global_load_dwordx4 v[10:13], v[30:31], off
	global_load_dwordx4 v[6:9], v[50:51], off
	v_and_b32_e32 v55, 0xffff0000, v28
	v_lshlrev_b32_e32 v30, 16, v29
	v_and_b32_e32 v31, 0xffff0000, v29
	v_lshlrev_b32_e32 v28, 16, v22
	v_and_b32_e32 v29, 0xffff0000, v22
	v_min_u32_e32 v22, 3, v144
	v_add_u32_e32 v22, 1, v22
	v_cvt_f32_ubyte0_e32 v32, v22


; DEV float bflo(unsigned u) { return __uint_as_float(u << 16); }
; DEV float bfhi(unsigned u) { return __uint_as_float(u & 0xffff0000u); }
; template <int WIN>
; DEV void pool_d_prompt8(const bf16_t* __restrict__ proj, bf16_t* __restrict__ dpl, int row0, int c8) {
;     ...
;     for (int i = 0; i < WIN - 1; ++i) { acc[0] += bflo(u[i].x); acc[1] += bfhi(u[i].x); acc[2] += bflo(u[i].y); acc[3] += bfhi(u[i].y); acc[4] += bflo(u[i].z); acc[5] += bfhi(u[i].z); acc[6] += bflo(u[i].w); acc[7] += bfhi(u[i].w); }
; #pragma unroll
;     for (int j = 0; j < 8; ++j) {
;         const uint4 x = u[j + WIN - 1];
;         const float xs[8] = {bflo(x.x), bfhi(x.x), bflo(x.y), bfhi(x.y), bflo(x.z), bfhi(x.z), bflo(x.w), bfhi(x.w)};
	v_lshlrev_b32_e32 v56, 16, v23
	v_and_b32_e32 v57, 0xffff0000, v23
	v_lshlrev_b32_e32 v50, 16, v26
	v_and_b32_e32 v51, 0xffff0000, v26
	v_lshlrev_b32_e32 v52, 16, v27
	v_and_b32_e32 v53, 0xffff0000, v27
	v_lshlrev_b32_e32 v68, 16, v3
	v_and_b32_e32 v69, 0xffff0000, v3
	v_lshlrev_b32_e32 v58, 16, v24
	v_and_b32_e32 v59, 0xffff0000, v24
	v_lshlrev_b32_e32 v72, 16, v4
	v_and_b32_e32 v73, 0xffff0000, v4
	v_lshl_add_u64 v[26:27], v[140:141], 0, v[94:95]
	v_mad_i64_i32 v[76:77], s[4:5], v145, s27, v[26:27]
	v_lshlrev_b32_e32 v24, 16, v25
	s_waitcnt vmcnt(7)
	v_lshlrev_b32_e32 v62, 16, v36
	v_and_b32_e32 v63, 0xffff0000, v36


; DEV float bflo(unsigned u) { return __uint_as_float(u << 16); }
; DEV float bfhi(unsigned u) { return __uint_as_float(u & 0xffff0000u); }
; template <int WIN>
; DEV void pool_d_prompt8(const bf16_t* __restrict__ proj, bf16_t* __restrict__ dpl, int row0, int c8) {
;     ...
;         const float xs[8] = {bflo(x.x), bfhi(x.x), bflo(x.y), bfhi(x.y), bflo(x.z), bfhi(x.z), bflo(x.w), bfhi(x.w)};
	v_lshlrev_b32_e32 v22, 16, v37
	v_and_b32_e32 v23, 0xffff0000, v37


; DEV unsigned cvt_pk_bf16(float lo, float hi) { const f32x2_t v = {lo, hi}; const bf16x2_t b = __builtin_convertvector(v, bf16x2_t); return __builtin_bit_cast(unsigned, b); }
; DEV float bflo(unsigned u) { return __uint_as_float(u << 16); }
; DEV float bfhi(unsigned u) { return __uint_as_float(u & 0xffff0000u); }
; template <int WIN>
; DEV void pool_d_prompt8(const bf16_t* __restrict__ proj, bf16_t* __restrict__ dpl, int row0, int c8) {
;     ...
;     for (int i = 0; i < WIN - 1; ++i) { acc[0] += bflo(u[i].x); acc[1] += bfhi(u[i].x); acc[2] += bflo(u[i].y); acc[3] += bfhi(u[i].y); acc[4] += bflo(u[i].z); acc[5] += bfhi(u[i].z); acc[6] += bflo(u[i].w); acc[7] += bfhi(u[i].w); }
; #pragma unroll
;     for (int j = 0; j < 8; ++j) {
;         const uint4 x = u[j + WIN - 1];
;         const float xs[8] = {bflo(x.x), bfhi(x.x), bflo(x.y), bfhi(x.y), bflo(x.z), bfhi(x.z), bflo(x.w), bfhi(x.w)};
; #pragma unroll
;         for (int e_ = 0; e_ < 8; ++e_) acc[e_] += xs[e_];
;         const float ic = 1.f / (float)min(WIN, t0 + j + 1);
;         uint4 o;
;         o.x = cvt_pk_bf16(acc[0] * ic - xs[0], acc[1] * ic - xs[1]); o.y = cvt_pk_bf16(acc[2] * ic - xs[2], acc[3] * ic - xs[3]);
;         o.z = cvt_pk_bf16(acc[4] * ic - xs[4], acc[5] * ic - xs[5]); o.w = cvt_pk_bf16(acc[6] * ic - xs[6], acc[7] * ic - xs[7]);
;         *(uint4*)(dpl + (size_t)(row0 + j) * LDP + c8) = o;
	v_rcp_f32_e32 v36, v32
	s_nop 0
	v_mul_f32_e32 v32, 1.0, v36
	v_pk_add_f32 v[36:37], v[50:51], 0 op_sel_hi:[1,0]
	v_lshlrev_b32_e32 v64, 16, v2
	v_pk_add_f32 v[36:37], v[36:37], v[28:29]
	v_and_b32_e32 v65, 0xffff0000, v2
	v_lshlrev_b32_e32 v60, 16, v34
	v_and_b32_e32 v61, 0xffff0000, v34
	v_pk_add_f32 v[36:37], v[36:37], v[64:65]
	v_lshlrev_b32_e32 v34, 16, v35
	v_pk_add_f32 v[66:67], v[36:37], v[60:61]
	v_and_b32_e32 v35, 0xffff0000, v35
	v_pk_fma_f32 v[36:37], v[32:33], v[66:67], v[60:61] op_sel_hi:[0,1,1] neg_lo:[0,0,1] neg_hi:[0,0,1]
	v_cvt_pk_bf16_f32 v2, v36, v37
	v_pk_add_f32 v[36:37], v[52:53], 0 op_sel_hi:[1,0]
	s_waitcnt vmcnt(6)
	v_lshlrev_b32_e32 v78, 16, v38
	v_pk_add_f32 v[36:37], v[36:37], v[56:57]
	v_and_b32_e32 v79, 0xffff0000, v38
	v_pk_add_f32 v[36:37], v[36:37], v[68:69]
	v_lshlrev_b32_e32 v80, 16, v39
	v_pk_add_f32 v[70:71], v[36:37], v[34:35]
	v_and_b32_e32 v81, 0xffff0000, v39
	v_pk_fma_f32 v[36:37], v[32:33], v[70:71], v[34:35] op_sel_hi:[0,1,1] neg_lo:[0,0,1] neg_hi:[0,0,1]
	v_cvt_pk_bf16_f32 v3, v36, v37
	v_pk_add_f32 v[36:37], v[54:55], 0 op_sel_hi:[1,0]
	v_lshlrev_b32_e32 v82, 16, v40
	v_pk_add_f32 v[36:37], v[36:37], v[58:59]
	v_and_b32_e32 v83, 0xffff0000, v40
	v_pk_add_f32 v[36:37], v[36:37], v[72:73]
	s_waitcnt vmcnt(5)
	v_and_b32_e32 v87, 0xffff0000, v44
	v_pk_add_f32 v[74:75], v[36:37], v[62:63]
	v_lshlrev_b32_e32 v88, 16, v45
	v_pk_fma_f32 v[36:37], v[32:33], v[74:75], v[62:63] op_sel_hi:[0,1,1] neg_lo:[0,0,1] neg_hi:[0,0,1]
	v_cvt_pk_bf16_f32 v4, v36, v37
	v_min_u32_e32 v36, 2, v144
	v_add_u32_e32 v36, 2, v36
	v_cvt_f32_ubyte0_e32 v38, v36


; DEV float bflo(unsigned u) { return __uint_as_float(u << 16); }
; DEV float bfhi(unsigned u) { return __uint_as_float(u & 0xffff0000u); }
; template <int WIN>
; DEV void pool_d_prompt8(const bf16_t* __restrict__ proj, bf16_t* __restrict__ dpl, int row0, int c8) {
;     ...
;         const uint4 x = u[j + WIN - 1];
;         const float xs[8] = {bflo(x.x), bfhi(x.x), bflo(x.y), bfhi(x.y), bflo(x.z), bfhi(x.z), bflo(x.w), bfhi(x.w)};
	v_lshlrev_b32_e32 v36, 16, v41
	v_and_b32_e32 v37, 0xffff0000, v41
	v_and_b32_e32 v89, 0xffff0000, v45


; DEV unsigned cvt_pk_bf16(float lo, float hi) { const f32x2_t v = {lo, hi}; const bf16x2_t b = __builtin_convertvector(v, bf16x2_t); return __builtin_bit_cast(unsigned, b); }
; DEV float bflo(unsigned u) { return __uint_as_float(u << 16); }
; DEV float bfhi(unsigned u) { return __uint_as_float(u & 0xffff0000u); }
; template <int WIN>
; DEV void pool_d_prompt8(const bf16_t* __restrict__ proj, bf16_t* __restrict__ dpl, int row0, int c8) {
;     ...
;         for (int e_ = 0; e_ < 8; ++e_) acc[e_] += xs[e_];
;         const float ic = 1.f / (float)min(WIN, t0 + j + 1);
;         uint4 o;
;         o.x = cvt_pk_bf16(acc[0] * ic - xs[0], acc[1] * ic - xs[1]); o.y = cvt_pk_bf16(acc[2] * ic - xs[2], acc[3] * ic - xs[3]);
;         o.z = cvt_pk_bf16(acc[4] * ic - xs[4], acc[5] * ic - xs[5]); o.w = cvt_pk_bf16(acc[6] * ic - xs[6], acc[7] * ic - xs[7]);
;         *(uint4*)(dpl + (size_t)(row0 + j) * LDP + c8) = o;
;         const uint4 y = u[j];
;         acc[0] -= bflo(y.x); acc[1] -= bfhi(y.x); acc[2] -= bflo(y.y); acc[3] -= bfhi(y.y); acc[4] -= bflo(y.z); acc[5] -= bfhi(y.z); acc[6] -= bflo(y.w); acc[7] -= bfhi(y.w);
	v_rcp_f32_e32 v39, v38
	s_nop 0
	v_mul_f32_e32 v84, 1.0, v39
	v_pk_add_f32 v[38:39], v[66:67], v[50:51] neg_lo:[0,1] neg_hi:[0,1]
	v_pk_add_f32 v[40:41], v[70:71], v[52:53] neg_lo:[0,1] neg_hi:[0,1]
	v_pk_add_f32 v[50:51], v[38:39], v[78:79]
	v_pk_add_f32 v[52:53], v[40:41], v[80:81]
	v_pk_fma_f32 v[38:39], v[84:85], v[50:51], v[78:79] op_sel_hi:[0,1,1] neg_lo:[0,0,1] neg_hi:[0,0,1]
	v_pk_fma_f32 v[40:41], v[84:85], v[52:53], v[80:81] op_sel_hi:[0,1,1] neg_lo:[0,0,1] neg_hi:[0,0,1]
	v_cvt_pk_bf16_f32 v38, v38, v39
	v_cvt_pk_bf16_f32 v39, v40, v41
	v_pk_add_f32 v[40:41], v[74:75], v[54:55] neg_lo:[0,1] neg_hi:[0,1]
	v_lshlrev_b32_e32 v70, 16, v42
	v_pk_add_f32 v[54:55], v[40:41], v[82:83]
	v_and_b32_e32 v71, 0xffff0000, v42
	v_pk_fma_f32 v[40:41], v[84:85], v[54:55], v[82:83] op_sel_hi:[0,1,1] neg_lo:[0,0,1] neg_hi:[0,0,1]
	v_cvt_pk_bf16_f32 v40, v40, v41


; DEV float bflo(unsigned u) { return __uint_as_float(u << 16); }
; DEV float bfhi(unsigned u) { return __uint_as_float(u & 0xffff0000u); }
; template <int WIN>
; DEV void pool_d_prompt8(const bf16_t* __restrict__ proj, bf16_t* __restrict__ dpl, int row0, int c8) {
;     ...
;         const uint4 x = u[j + WIN - 1];
;         const float xs[8] = {bflo(x.x), bfhi(x.x), bflo(x.y), bfhi(x.y), bflo(x.z), bfhi(x.z), bflo(x.w), bfhi(x.w)};
	v_lshlrev_b32_e32 v74, 16, v43
	v_and_b32_e32 v75, 0xffff0000, v43
	v_lshlrev_b32_e32 v86, 16, v44


; DEV unsigned cvt_pk_bf16(float lo, float hi) { const f32x2_t v = {lo, hi}; const bf16x2_t b = __builtin_convertvector(v, bf16x2_t); return __builtin_bit_cast(unsigned, b); }
; DEV float bflo(unsigned u) { return __uint_as_float(u << 16); }
; DEV float bfhi(unsigned u) { return __uint_as_float(u & 0xffff0000u); }
; template <int WIN>
; DEV void pool_d_prompt8(const bf16_t* __restrict__ proj, bf16_t* __restrict__ dpl, int row0, int c8) {
;     ...
;         const uint4 x = u[j + WIN - 1];
;         const float xs[8] = {bflo(x.x), bfhi(x.x), bflo(x.y), bfhi(x.y), bflo(x.z), bfhi(x.z), bflo(x.w), bfhi(x.w)};
; #pragma unroll
;         for (int e_ = 0; e_ < 8; ++e_) acc[e_] += xs[e_];
;         const float ic = 1.f / (float)min(WIN, t0 + j + 1);
;         uint4 o;
;         o.x = cvt_pk_bf16(acc[0] * ic - xs[0], acc[1] * ic - xs[1]); o.y = cvt_pk_bf16(acc[2] * ic - xs[2], acc[3] * ic - xs[3]);
;         o.z = cvt_pk_bf16(acc[4] * ic - xs[4], acc[5] * ic - xs[5]); o.w = cvt_pk_bf16(acc[6] * ic - xs[6], acc[7] * ic - xs[7]);
;         *(uint4*)(dpl + (size_t)(row0 + j) * LDP + c8) = o;
;         const uint4 y = u[j];
;         acc[0] -= bflo(y.x); acc[1] -= bfhi(y.x); acc[2] -= bflo(y.y); acc[3] -= bfhi(y.y); acc[4] -= bflo(y.z); acc[5] -= bfhi(y.z); acc[6] -= bflo(y.w); acc[7] -= bfhi(y.w);
	v_pk_add_f32 v[28:29], v[50:51], v[28:29] neg_lo:[0,1] neg_hi:[0,1]
	v_pk_add_f32 v[44:45], v[52:53], v[56:57] neg_lo:[0,1] neg_hi:[0,1]
	v_rcp_f32_e32 v41, v33
	s_nop 0
	v_mul_f32_e32 v90, 1.0, v41
	v_pk_add_f32 v[28:29], v[28:29], v[70:71]
	v_pk_add_f32 v[50:51], v[44:45], v[74:75]
	v_pk_fma_f32 v[42:43], v[90:91], v[28:29], v[70:71] op_sel_hi:[0,1,1] neg_lo:[0,0,1] neg_hi:[0,0,1]
	v_pk_fma_f32 v[44:45], v[90:91], v[50:51], v[74:75] op_sel_hi:[0,1,1] neg_lo:[0,0,1] neg_hi:[0,0,1]
	v_cvt_pk_bf16_f32 v42, v42, v43
	v_cvt_pk_bf16_f32 v43, v44, v45
	v_pk_add_f32 v[44:45], v[54:55], v[58:59] neg_lo:[0,1] neg_hi:[0,1]
	s_waitcnt vmcnt(4)
	v_lshlrev_b32_e32 v56, 16, v46
	v_and_b32_e32 v57, 0xffff0000, v46
	v_lshlrev_b32_e32 v58, 16, v47
	v_and_b32_e32 v59, 0xffff0000, v47
	v_lshlrev_b32_e32 v92, 16, v48
	v_and_b32_e32 v93, 0xffff0000, v48
	v_lshlrev_b32_e32 v98, 16, v49
	v_and_b32_e32 v99, 0xffff0000, v49
	v_pk_add_f32 v[28:29], v[28:29], v[64:65] neg_lo:[0,1] neg_hi:[0,1]
	v_pk_add_f32 v[48:49], v[50:51], v[68:69] neg_lo:[0,1] neg_hi:[0,1]
	v_pk_add_f32 v[28:29], v[28:29], v[56:57]
	v_pk_add_f32 v[50:51], v[48:49], v[58:59]
	v_pk_add_f32 v[52:53], v[44:45], v[86:87]
	v_pk_fma_f32 v[46:47], v[28:29], s[12:13], v[56:57] op_sel_hi:[1,0,1] neg_lo:[0,0,1] neg_hi:[0,0,1]
	v_pk_fma_f32 v[48:49], v[50:51], s[12:13], v[58:59] op_sel_hi:[1,0,1] neg_lo:[0,0,1] neg_hi:[0,0,1]
	v_cvt_pk_bf16_f32 v46, v46, v47
	v_cvt_pk_bf16_f32 v47, v48, v49
	v_pk_add_f32 v[48:49], v[52:53], v[72:73] neg_lo:[0,1] neg_hi:[0,1]
	v_mad_i64_i32 v[64:65], s[4:5], v100, s27, v[26:27]
	s_waitcnt vmcnt(3)
	v_lshlrev_b32_e32 v68, 16, v18
	v_and_b32_e32 v69, 0xffff0000, v18
	v_lshlrev_b32_e32 v72, 16, v19
	v_and_b32_e32 v73, 0xffff0000, v19
	v_lshlrev_b32_e32 v100, 16, v20
	v_and_b32_e32 v101, 0xffff0000, v20
	v_lshlrev_b32_e32 v102, 16, v21
	v_and_b32_e32 v103, 0xffff0000, v21
	v_pk_add_f32 v[18:19], v[28:29], v[60:61] neg_lo:[0,1] neg_hi:[0,1]
	v_pk_add_f32 v[20:21], v[50:51], v[34:35] neg_lo:[0,1] neg_hi:[0,1]
	v_pk_add_f32 v[28:29], v[18:19], v[68:69]
	v_pk_add_f32 v[34:35], v[20:21], v[72:73]
	v_pk_fma_f32 v[44:45], v[90:91], v[52:53], v[86:87] op_sel_hi:[0,1,1] neg_lo:[0,0,1] neg_hi:[0,0,1]
	v_pk_add_f32 v[52:53], v[48:49], v[92:93]
	v_pk_fma_f32 v[18:19], v[28:29], s[12:13], v[68:69] op_sel_hi:[1,0,1] neg_lo:[0,0,1] neg_hi:[0,0,1]
	v_pk_fma_f32 v[20:21], v[34:35], s[12:13], v[72:73] op_sel_hi:[1,0,1] neg_lo:[0,0,1] neg_hi:[0,0,1]
	v_cvt_pk_bf16_f32 v18, v18, v19
	v_cvt_pk_bf16_f32 v19, v20, v21
	v_pk_add_f32 v[20:21], v[52:53], v[62:63] neg_lo:[0,1] neg_hi:[0,1]
	s_waitcnt vmcnt(2)
	v_lshlrev_b32_e32 v60, 16, v14
	v_and_b32_e32 v61, 0xffff0000, v14
	v_lshlrev_b32_e32 v62, 16, v15
	v_and_b32_e32 v63, 0xffff0000, v15
	v_lshlrev_b32_e32 v68, 16, v16
	v_and_b32_e32 v69, 0xffff0000, v16
	v_lshlrev_b32_e32 v72, 16, v17
	v_and_b32_e32 v73, 0xffff0000, v17
	v_pk_add_f32 v[14:15], v[28:29], v[78:79] neg_lo:[0,1] neg_hi:[0,1]
	v_pk_add_f32 v[16:17], v[34:35], v[80:81] neg_lo:[0,1] neg_hi:[0,1]
	v_pk_add_f32 v[28:29], v[14:15], v[60:61]
	v_pk_add_f32 v[34:35], v[16:17], v[62:63]
	v_pk_add_f32 v[50:51], v[20:21], v[100:101]
	v_pk_fma_f32 v[14:15], v[28:29], s[12:13], v[60:61] op_sel_hi:[1,0,1] neg_lo:[0,0,1] neg_hi:[0,0,1]
	v_pk_fma_f32 v[16:17], v[34:35], s[12:13], v[62:63] op_sel_hi:[1,0,1] neg_lo:[0,0,1] neg_hi:[0,0,1]
	v_cvt_pk_bf16_f32 v14, v14, v15
	v_cvt_pk_bf16_f32 v15, v16, v17
	v_pk_add_f32 v[16:17], v[50:51], v[82:83] neg_lo:[0,1] neg_hi:[0,1]
	v_pk_fma_f32 v[20:21], v[50:51], s[12:13], v[100:101] op_sel_hi:[1,0,1] neg_lo:[0,0,1] neg_hi:[0,0,1]
	v_pk_add_f32 v[50:51], v[16:17], v[68:69]
	s_waitcnt vmcnt(1)
	v_lshlrev_b32_e32 v62, 16, v10
	v_pk_fma_f32 v[16:17], v[50:51], s[12:13], v[68:69] op_sel_hi:[1,0,1] neg_lo:[0,0,1] neg_hi:[0,0,1]
	v_and_b32_e32 v63, 0xffff0000, v10
	v_lshlrev_b32_e32 v68, 16, v11
	v_and_b32_e32 v69, 0xffff0000, v11
	v_pk_add_f32 v[10:11], v[28:29], v[70:71] neg_lo:[0,1] neg_hi:[0,1]
	v_lshlrev_b32_e32 v78, 16, v12
	v_and_b32_e32 v79, 0xffff0000, v12
	v_lshlrev_b32_e32 v80, 16, v13
	v_and_b32_e32 v81, 0xffff0000, v13
	v_pk_add_f32 v[28:29], v[10:11], v[62:63]
	v_pk_add_f32 v[12:13], v[34:35], v[74:75] neg_lo:[0,1] neg_hi:[0,1]
	v_mad_i64_i32 v[66:67], s[4:5], v85, s27, v[26:27]
	v_mad_i64_i32 v[54:55], s[4:5], v91, s27, v[26:27]
	v_pk_fma_f32 v[48:49], v[52:53], s[12:13], v[92:93] op_sel_hi:[1,0,1] neg_lo:[0,0,1] neg_hi:[0,0,1]
	v_mad_i64_i32 v[52:53], s[4:5], v104, s27, v[26:27]
	v_mad_i64_i32 v[60:61], s[4:5], v105, s27, v[26:27]
	v_pk_fma_f32 v[10:11], v[28:29], s[12:13], v[62:63] op_sel_hi:[1,0,1] neg_lo:[0,0,1] neg_hi:[0,0,1]
	v_pk_add_f32 v[34:35], v[12:13], v[68:69]
	v_mad_i64_i32 v[62:63], s[4:5], v106, s27, v[26:27]
	s_waitcnt vmcnt(0)
; DEV unsigned cvt_pk_bf16(float lo, float hi) { const f32x2_t v = {lo, hi}; const bf16x2_t b = __builtin_convertvector(v, bf16x2_t); return __builtin_bit_cast(unsigned, b); }
; DEV float bflo(unsigned u) { return __uint_as_float(u << 16); }
; DEV float bfhi(unsigned u) { return __uint_as_float(u & 0xffff0000u); }
; template <int WIN>
; DEV void pool_d_prompt8(const bf16_t* __restrict__ proj, bf16_t* __restrict__ dpl, int row0, int c8) {
;     ...
;         for (int e_ = 0; e_ < 8; ++e_) acc[e_] += xs[e_];
;         const float ic = 1.f / (float)min(WIN, t0 + j + 1);
;         uint4 o;
;         o.x = cvt_pk_bf16(acc[0] * ic - xs[0], acc[1] * ic - xs[1]); o.y = cvt_pk_bf16(acc[2] * ic - xs[2], acc[3] * ic - xs[3]);
;         o.z = cvt_pk_bf16(acc[4] * ic - xs[4], acc[5] * ic - xs[5]); o.w = cvt_pk_bf16(acc[6] * ic - xs[6], acc[7] * ic - xs[7]);
;         *(uint4*)(dpl + (size_t)(row0 + j) * LDP + c8) = o;
;         const uint4 y = u[j];
;         acc[0] -= bflo(y.x); acc[1] -= bfhi(y.x); acc[2] -= bflo(y.y); acc[3] -= bfhi(y.y); acc[4] -= bflo(y.z); acc[5] -= bfhi(y.z); acc[6] -= bflo(y.w); acc[7] -= bfhi(y.w);
;     }
	v_lshlrev_b32_e32 v26, 16, v6
	v_and_b32_e32 v27, 0xffff0000, v6
	v_pk_add_f32 v[28:29], v[28:29], v[56:57] neg_lo:[0,1] neg_hi:[0,1]
	v_pk_fma_f32 v[12:13], v[34:35], s[12:13], v[68:69] op_sel_hi:[1,0,1] neg_lo:[0,0,1] neg_hi:[0,0,1]
	v_pk_add_f32 v[28:29], v[28:29], v[26:27]
	v_cvt_pk_bf16_f32 v10, v10, v11
	v_cvt_pk_bf16_f32 v11, v12, v13
	v_pk_add_f32 v[12:13], v[50:51], v[86:87] neg_lo:[0,1] neg_hi:[0,1]
	v_lshlrev_b32_e32 v6, 16, v7
	v_and_b32_e32 v7, 0xffff0000, v7
	v_pk_fma_f32 v[26:27], v[28:29], s[12:13], v[26:27] op_sel_hi:[1,0,1] neg_lo:[0,0,1] neg_hi:[0,0,1]
	v_pk_add_f32 v[28:29], v[34:35], v[58:59] neg_lo:[0,1] neg_hi:[0,1]
	v_pk_add_f32 v[50:51], v[12:13], v[78:79]
	v_pk_add_f32 v[28:29], v[28:29], v[6:7]
	v_lshlrev_b32_e32 v68, 16, v8
	v_and_b32_e32 v69, 0xffff0000, v8
	v_pk_fma_f32 v[28:29], v[28:29], s[12:13], v[6:7] op_sel_hi:[1,0,1] neg_lo:[0,0,1] neg_hi:[0,0,1]
	v_pk_add_f32 v[6:7], v[50:51], v[92:93] neg_lo:[0,1] neg_hi:[0,1]
	v_and_b32_e32 v25, 0xffff0000, v25
	v_pk_add_f32 v[6:7], v[6:7], v[68:69]
	v_pk_fma_f32 v[12:13], v[50:51], s[12:13], v[78:79] op_sel_hi:[1,0,1] neg_lo:[0,0,1] neg_hi:[0,0,1]
	v_pk_fma_f32 v[34:35], v[6:7], s[12:13], v[68:69] op_sel_hi:[1,0,1] neg_lo:[0,0,1] neg_hi:[0,0,1]
	v_pk_add_f32 v[6:7], v[30:31], 0 op_sel_hi:[1,0]
	v_lshlrev_b32_e32 v50, 16, v5
	v_pk_add_f32 v[6:7], v[6:7], v[24:25]
	v_and_b32_e32 v51, 0xffff0000, v5
	v_pk_add_f32 v[6:7], v[6:7], v[50:51]
	v_cvt_pk_bf16_f32 v44, v44, v45
	v_pk_add_f32 v[6:7], v[6:7], v[22:23]
	v_cvt_pk_bf16_f32 v48, v48, v49
	v_pk_fma_f32 v[32:33], v[32:33], v[6:7], v[22:23] op_sel_hi:[0,1,1] neg_lo:[0,0,1] neg_hi:[0,0,1]
	v_cvt_pk_bf16_f32 v5, v32, v33
	global_store_dwordx4 v[76:77], v[2:5], off sc1
	v_cvt_pk_bf16_f32 v20, v20, v21
	v_cvt_pk_bf16_f32 v16, v16, v17
	v_pk_add_f32 v[2:3], v[6:7], v[30:31] neg_lo:[0,1] neg_hi:[0,1]
	v_lshlrev_b32_e32 v8, 16, v9
	v_pk_add_f32 v[2:3], v[2:3], v[36:37]
	v_and_b32_e32 v9, 0xffff0000, v9
	v_pk_fma_f32 v[4:5], v[84:85], v[2:3], v[36:37] op_sel_hi:[0,1,1] neg_lo:[0,0,1] neg_hi:[0,0,1]
	v_pk_add_f32 v[2:3], v[2:3], v[24:25] neg_lo:[0,1] neg_hi:[0,1]
	v_cvt_pk_bf16_f32 v41, v4, v5
	v_pk_add_f32 v[2:3], v[2:3], v[88:89]
	v_ashrrev_i32_e32 v97, 31, v96
	v_pk_fma_f32 v[4:5], v[90:91], v[2:3], v[88:89] op_sel_hi:[0,1,1] neg_lo:[0,0,1] neg_hi:[0,0,1]
	v_pk_add_f32 v[2:3], v[2:3], v[50:51] neg_lo:[0,1] neg_hi:[0,1]
	v_cvt_pk_bf16_f32 v45, v4, v5
	v_pk_add_f32 v[2:3], v[2:3], v[98:99]
	v_cvt_pk_bf16_f32 v12, v12, v13
	v_pk_fma_f32 v[4:5], v[2:3], s[12:13], v[98:99] op_sel_hi:[1,0,1] neg_lo:[0,0,1] neg_hi:[0,0,1]
	v_pk_add_f32 v[2:3], v[2:3], v[22:23] neg_lo:[0,1] neg_hi:[0,1]
	v_cvt_pk_bf16_f32 v49, v4, v5
	v_pk_add_f32 v[2:3], v[2:3], v[102:103]
	global_store_dwordx4 v[66:67], v[38:41], off sc1
	v_pk_fma_f32 v[4:5], v[2:3], s[12:13], v[102:103] op_sel_hi:[1,0,1] neg_lo:[0,0,1] neg_hi:[0,0,1]
	v_pk_add_f32 v[2:3], v[2:3], v[36:37] neg_lo:[0,1] neg_hi:[0,1]
	v_cvt_pk_bf16_f32 v21, v4, v5
	v_pk_add_f32 v[2:3], v[2:3], v[72:73]
	global_store_dwordx4 v[54:55], v[42:45], off sc1
	v_pk_fma_f32 v[4:5], v[2:3], s[12:13], v[72:73] op_sel_hi:[1,0,1] neg_lo:[0,0,1] neg_hi:[0,0,1]
	v_pk_add_f32 v[2:3], v[2:3], v[88:89] neg_lo:[0,1] neg_hi:[0,1]
	v_cvt_pk_bf16_f32 v17, v4, v5
	v_pk_add_f32 v[2:3], v[2:3], v[80:81]
	global_store_dwordx4 v[64:65], v[46:49], off sc1
	v_pk_fma_f32 v[4:5], v[2:3], s[12:13], v[80:81] op_sel_hi:[1,0,1] neg_lo:[0,0,1] neg_hi:[0,0,1]
	v_pk_add_f32 v[2:3], v[2:3], v[98:99] neg_lo:[0,1] neg_hi:[0,1]
	v_cvt_pk_bf16_f32 v13, v4, v5
	v_pk_add_f32 v[2:3], v[2:3], v[8:9]
	global_store_dwordx4 v[52:53], v[18:21], off sc1
	v_pk_fma_f32 v[2:3], v[2:3], s[12:13], v[8:9] op_sel_hi:[1,0,1] neg_lo:[0,0,1] neg_hi:[0,0,1]
	global_store_dwordx4 v[60:61], v[14:17], off sc1
	global_store_dwordx4 v[62:63], v[10:13], off sc1

; __global__ void __launch_bounds__(512) hymba_fwd(Params p) {
;     ...
;             const float ic = 1.f / (float)win;
.LBB0_748:
	s_or_b64 exec, exec, s[12:13]
	v_cvt_f32_ubyte0_e32 v10, v40


; __global__ void __launch_bounds__(512) hymba_fwd(Params p) {
;     ...
;         for (int i = TP * 128 + bid * 512 + tid; i < TT * 128; i += G * 512) {
	v_add_u32_e32 v23, s18, v23


; DEV unsigned cvt_pk_bf16(float lo, float hi) { const f32x2_t v = {lo, hi}; const bf16x2_t b = __builtin_convertvector(v, bf16x2_t); return __builtin_bit_cast(unsigned, b); }
; __global__ void __launch_bounds__(512) hymba_fwd(Params p) {
;     ...
;             const float ic = 1.f / (float)win;
;             uint4 o; o.x = cvt_pk_bf16(acc[0] * ic - self[0], acc[1] * ic - self[1]); o.y = cvt_pk_bf16(acc[2] * ic - self[2], acc[3] * ic - self[3]);
;             o.z = cvt_pk_bf16(acc[4] * ic - self[4], acc[5] * ic - self[5]); o.w = cvt_pk_bf16(acc[6] * ic - self[6], acc[7] * ic - self[7]);
;             *(uint4*)(dpl + (size_t)row * LDP + c8) = o;
	v_rcp_f32_e32 v11, v10
	s_nop 0
	v_mul_f32_e32 v10, 1.0, v11
	v_pk_fma_f32 v[2:3], v[10:11], v[2:3], v[34:35] op_sel_hi:[0,1,1] neg_lo:[0,0,1] neg_hi:[0,0,1]
	v_pk_fma_f32 v[4:5], v[10:11], v[4:5], v[32:33] op_sel_hi:[0,1,1] neg_lo:[0,0,1] neg_hi:[0,0,1]
	v_cvt_pk_bf16_f32 v2, v2, v3
	v_cvt_pk_bf16_f32 v3, v4, v5
	v_pk_fma_f32 v[4:5], v[10:11], v[6:7], v[30:31] op_sel_hi:[0,1,1] neg_lo:[0,0,1] neg_hi:[0,0,1]
	v_pk_fma_f32 v[6:7], v[10:11], v[8:9], v[28:29] op_sel_hi:[0,1,1] neg_lo:[0,0,1] neg_hi:[0,0,1]
	v_cvt_pk_bf16_f32 v4, v4, v5
	v_cvt_pk_bf16_f32 v5, v6, v7
	v_mad_i64_i32 v[6:7], s[12:13], v22, s23, v[140:141]
	v_lshlrev_b32_e32 v20, 1, v24
	v_cmp_lt_i32_e32 vcc, s24, v23
	v_lshl_add_u64 v[6:7], v[6:7], 0, v[20:21]
	s_or_b64 s[8:9], vcc, s[8:9]
	v_add_u32_e32 v25, s19, v25
	global_store_dwordx4 v[6:7], v[2:5], off sc1
	s_andn2_b64 exec, exec, s[8:9]
	s_cbranch_execz .LBB0_755

; __global__ void __launch_bounds__(512) hymba_fwd(Params p) {
;     ...
;         for (int i = bid * 512 + tid; i < SB * 11 * 256; i += G * 512) {
;             const int c4 = (i & 255) * 4, rr = (i >> 8) % 11, sb = (i >> 8) / 11;
;             *(f32x4*)(p.out + O_PS + ((size_t)sb * 15 + rr) * 1024 + c4) = *(const f32x4*)(p.in[7] + ((size_t)sb * 15 + rr + 4) * 1024 + c4);
;         }
.LBB0_764:
	v_ashrrev_i32_e32 v4, 8, v136
	v_mul_hi_i32 v5, v4, s16
	v_lshrrev_b32_e32 v6, 31, v5
	v_ashrrev_i32_e32 v5, 1, v5
	v_add_u32_e32 v5, v5, v6
	v_mul_lo_u32 v6, v5, 11
	v_sub_u32_e32 v4, v4, v6
	v_mad_u64_u32 v[4:5], s[18:19], v5, 15, v[4:5]
	v_ashrrev_i32_e32 v5, 31, v4
	v_and_b32_e32 v2, 0x3fc, v1
	v_lshlrev_b64 v[8:9], 12, v[4:5]
	v_lshlrev_b32_e32 v2, 2, v2
	v_lshl_add_u64 v[4:5], s[6:7], 0, v[8:9]
	v_lshl_add_u64 v[4:5], v[4:5], 0, v[2:3]
	v_add_co_u32_e32 v4, vcc, 0x4000, v4
	v_add_u32_e32 v136, s12, v136
	s_nop 0
	v_addc_co_u32_e32 v5, vcc, 0, v5, vcc
	global_load_dwordx4 v[4:7], v[4:5], off
	v_cmp_lt_i32_e32 vcc, s17, v136
	v_lshl_add_u64 v[8:9], s[8:9], 0, v[8:9]
	v_add_u32_e32 v1, s13, v1
	s_or_b64 s[10:11], vcc, s[10:11]
	v_lshl_add_u64 v[8:9], v[8:9], 0, v[2:3]
	s_waitcnt vmcnt(0)
	global_store_dwordx4 v[8:9], v[4:7], off sc1
	s_andn2_b64 exec, exec, s[10:11]
	s_cbranch_execnz .LBB0_764

; #define LAS __attribute__((address_space(3)))
; template <int WT, class Epi>
; DEV void gemm_tile(const bf16_t* __restrict__ A, int lda, const bf16_t* __restrict__ Bt, int ldb, int K, unsigned char* lds, const Epi& epi) {
;     ...
;     const int lrow = tid >> 3, lcs = (tid & 7) ^ (lrow & 7);
;     const bf16_t* ap = A + (size_t)lrow * lda + lcs * 8;
;     const bf16_t* bp = Bt + (size_t)lrow * ldb + lcs * 8;
;     const unsigned l3a = (unsigned)(size_t)(LAS unsigned char*)lds;
;     const int nk = K >> 6;
;     ...
;     constexpr int NSTG = 65536 / STB;
; #pragma unroll
;     for (int s_ = 0; s_ < NSTG - 1; ++s_) if (s_ < nk) GLDS_STAGE(s_ * STB, s_);
;     const int aoff = (wr * WT + fr) * 128, boff = OPB + (wc * WT + fr) * 128, sw = fr & 7;
;     int cur = 0, nxt = (NSTG - 1) * STB;
;     for (int kt = 0; kt < nk; ++kt) {
;         if (NSTG == 4 && kt + 2 < nk) { if (FI == 2) asm volatile("s_waitcnt vmcnt(8)" ::: "memory"); else asm volatile("s_waitcnt vmcnt(0)" ::: "memory"); }
;         else asm volatile("s_waitcnt vmcnt(0)" ::: "memory");
;         __syncthreads();
;         if (kt + NSTG - 1 < nk) GLDS_STAGE(nxt, kt + NSTG - 1);
; #pragma unroll
;         for (int kh = 0; kh < 2; ++kh) {
;             bf16x8 af[FI], bfr[FI];
;             const int ch = ((kh * 4 + fq) ^ sw) << 4;
; #pragma unroll
;             for (int i = 0; i < FI; ++i) { af[i] = *(const bf16x8*)(lds + cur + aoff + i * 2048 + ch); bfr[i] = *(const bf16x8*)(lds + cur + boff + i * 2048 + ch); }
; #pragma unroll
;             for (int mi = 0; mi < FI; ++mi)
; #pragma unroll
;                 for (int ni = 0; ni < FI; ++ni) acc[mi][ni] = __builtin_amdgcn_mfma_f32_16x16x32_bf16(bfr[ni], af[mi], acc[mi][ni], 0, 0, 0);
; __global__ void __launch_bounds__(512) hymba_fwd(Params p) {
;     ...
;             for (int t0 = 2 * ob; t0 < NPL; t0 += 2 * no) { const int t = min(t0 + vb, NPL - 1); int nt, mt; tile_map(t, 68, 8, mt, nt); const int g = nt >> 1;
;                 EpiPoolS e{mt * 128, nt * 128, proj, p.in[15], mix + (size_t)mt * 128 * LDB + 1024 + nt * 128, LDB};
;                 gemm_tile<64>(dpl + (size_t)mt * 128 * LDP + g * 256, LDP, Wt_pool + (size_t)nt * 128 * LDM, LDM, 256, vlds, e);
.LBB0_870:
	s_add_i32 s14, s71, s72
	s_min_i32 s14, s14, 0x21f
	s_and_b32 s15, s14, 7
	s_mulk_i32 s15, 0x44
	s_ashr_i32 s14, s14, 3
	s_add_i32 s14, s15, s14
	s_ashr_i32 s15, s14, 31
	s_lshr_b32 s15, s15, 26
	s_add_i32 s15, s14, s15
	s_ashr_i32 s68, s15, 6
	s_lshl_b32 s81, s68, 3
	s_sub_i32 s68, 0x44, s81
	s_andn2_b32 s15, s15, 63
	s_min_u32 s82, s68, 8
	s_sub_i32 s14, s14, s15
	s_sext_i32_i8 s15, s14
	v_cvt_f32_ubyte0_e32 v3, s82
	v_cvt_f32_i32_e32 v2, s15
	v_rcp_iflag_f32_e32 v4, v3
	s_ashr_i32 s68, s15, 30
	s_or_b32 s83, s68, 1
	v_mov_b32_e32 v137, v1
	v_mul_f32_e32 v4, v2, v4
	v_trunc_f32_e32 v4, v4
	v_fma_f32 v2, -v4, v3, v2
	v_cvt_i32_f32_e32 v4, v4
	v_cmp_ge_f32_e64 s[68:69], |v2|, v3
	s_and_b64 s[68:69], s[68:69], exec
	s_cselect_b32 s15, s83, 0
	v_readfirstlane_b32 s68, v4
	s_add_i32 s15, s68, s15
	s_sext_i32_i8 s84, s15
	s_mul_i32 s15, s15, s82
	s_sub_i32 s14, s14, s15
	s_sext_i32_i8 s14, s14
	s_add_i32 s14, s81, s14
	s_lshl_b32 s68, s84, 7
	v_mad_i64_i32 v[2:3], s[82:83], s14, v134, v[174:175]
	s_ashr_i32 s69, s68, 31
	v_lshl_add_u64 v[132:133], s[68:69], 1, v[2:3]
	v_mad_i64_i32 v[2:3], s[82:83], s14, v135, v[140:141]
	s_and_b32 s82, s68, 0xffffff00
	s_ashr_i32 s83, s82, 31
	v_ashrrev_i32_e32 v6, 3, v137
	v_xor_b32_e32 v7, v6, v137
	v_lshl_add_u64 v[2:3], s[82:83], 1, v[2:3]
	v_mad_i64_i32 v[4:5], s[82:83], s84, v136, v[138:139]
	v_lshlrev_b32_e32 v7, 4, v7
	v_lshlrev_b32_e32 v9, 4, v137
	v_mad_i64_i32 v[2:3], s[82:83], v6, s77, v[2:3]
	v_and_b32_e32 v130, 0x70, v7
	v_mad_i64_i32 v[4:5], s[82:83], v6, s78, v[4:5]
	v_add_u32_e32 v6, s70, v9
	s_lshl_b32 s81, s14, 7
	v_lshl_add_u64 v[2:3], v[2:3], 0, v[130:131]
	v_add_u32_e32 v7, 0x4000, v6
	v_readfirstlane_b32 s14, v6
	s_mov_b32 s15, m0
	s_mov_b32 m0, s14
	s_nop 0
	global_load_lds_dwordx4 v[2:3], off
	s_mov_b32 m0, s15
	v_lshl_add_u64 v[4:5], v[4:5], 0, v[130:131]
	v_readfirstlane_b32 s15, v7
	s_mov_b32 s82, m0
	s_mov_b32 m0, s15
	s_nop 0
	global_load_lds_dwordx4 v[4:5], off
	s_mov_b32 m0, s82
	v_lshl_add_u64 v[6:7], v[2:3], 0, s[6:7]
	s_add_i32 s82, s14, 0x1000
	s_mov_b32 s83, m0
	s_mov_b32 m0, s82
	s_nop 0
	global_load_lds_dwordx4 v[6:7], off
	s_mov_b32 m0, s83
	v_lshl_add_u64 v[6:7], v[4:5], 0, s[8:9]
	s_add_i32 s83, s15, 0x1000
	s_mov_b32 s84, m0
	s_mov_b32 m0, s83
	s_nop 0
	global_load_lds_dwordx4 v[6:7], off
	s_mov_b32 m0, s84
	v_lshl_add_u64 v[6:7], v[2:3], 0, s[10:11]
	s_add_i32 s83, s14, 0x2000
	s_mov_b32 s84, m0
	s_mov_b32 m0, s83
	s_nop 0
	global_load_lds_dwordx4 v[6:7], off
	s_mov_b32 m0, s84
	v_lshl_add_u64 v[6:7], v[4:5], 0, s[12:13]
	s_add_i32 s84, s15, 0x2000
	s_mov_b32 s85, m0
	s_mov_b32 m0, s84
	s_nop 0
	global_load_lds_dwordx4 v[6:7], off
	s_mov_b32 m0, s85
	v_lshl_add_u64 v[6:7], v[2:3], 0, s[16:17]
	s_add_i32 s84, s14, 0x3000
	s_mov_b32 s85, m0
	s_mov_b32 m0, s84
	s_nop 0
	global_load_lds_dwordx4 v[6:7], off
	s_mov_b32 m0, s85
	v_lshl_add_u64 v[6:7], v[4:5], 0, s[18:19]
	v_and_b32_e32 v8, 15, v137
	s_addk_i32 s15, 0x3000
	s_mov_b32 s85, m0
	s_mov_b32 m0, s15
	s_nop 0
	global_load_lds_dwordx4 v[6:7], off
	s_mov_b32 m0, s85
	v_ashrrev_i32_e32 v6, 1, v137
	v_and_or_b32 v130, v6, s76, v8
	v_lshlrev_b32_e32 v6, 7, v137
	v_add_u32_e32 v102, 0x4000, v9
	v_add_u32_e32 v12, s73, v9
	v_and_b32_e32 v11, 0x2780, v6
	s_waitcnt vmcnt(0)
	s_waitcnt lgkmcnt(0)
	s_barrier
	v_lshl_add_u64 v[6:7], v[2:3], 0, s[20:21]
	v_add_u32_e32 v13, s73, v102
	v_readfirstlane_b32 s15, v12
	s_mov_b32 s85, m0
	s_mov_b32 m0, s15
	s_nop 0
	global_load_lds_dwordx4 v[6:7], off
	s_mov_b32 m0, s85
	v_lshl_add_u64 v[8:9], v[4:5], 0, s[20:21]
	v_readfirstlane_b32 s85, v13
	s_mov_b32 s86, m0
	s_mov_b32 m0, s85
	s_nop 0
	global_load_lds_dwordx4 v[8:9], off
	s_mov_b32 m0, s86
	v_lshl_add_u64 v[6:7], v[2:3], 0, s[22:23]
	s_add_i32 s86, s15, 0x1000
	s_mov_b32 s87, m0
	s_mov_b32 m0, s86
	s_nop 0
	global_load_lds_dwordx4 v[6:7], off
	s_mov_b32 m0, s87
	v_lshl_add_u64 v[6:7], v[4:5], 0, s[24:25]
	s_add_i32 s87, s85, 0x1000
	s_mov_b32 s88, m0
	s_mov_b32 m0, s87
	s_nop 0
	global_load_lds_dwordx4 v[6:7], off
	s_mov_b32 m0, s88
	v_lshl_add_u64 v[6:7], v[2:3], 0, s[26:27]
	s_add_i32 s88, s15, 0x2000
	s_mov_b32 s89, m0
	s_mov_b32 m0, s88
	s_nop 0
	global_load_lds_dwordx4 v[6:7], off
	s_mov_b32 m0, s89
	v_lshl_add_u64 v[6:7], v[4:5], 0, s[30:31]
	s_add_i32 s89, s85, 0x2000
	s_mov_b32 s90, m0
	s_mov_b32 m0, s89
	s_nop 0
	global_load_lds_dwordx4 v[6:7], off
	s_mov_b32 m0, s90
	v_lshl_add_u64 v[6:7], v[2:3], 0, s[34:35]
	v_lshrrev_b32_e32 v10, 4, v137
	v_and_b32_e32 v74, 7, v137
	s_add_i32 s90, s15, 0x3000
	s_mov_b32 s91, m0
	s_mov_b32 m0, s90
	s_nop 0
	global_load_lds_dwordx4 v[6:7], off
	s_mov_b32 m0, s91
	v_lshl_add_u64 v[6:7], v[4:5], 0, s[36:37]
	s_add_i32 s91, s85, 0x3000
	s_mov_b32 s92, m0
	s_mov_b32 m0, s91
	s_nop 0
	global_load_lds_dwordx4 v[6:7], off
	s_mov_b32 m0, s92
	v_bitop3_b32 v6, v10, v74, 3 bitop3:0x6c
	v_lshl_add_u32 v75, v130, 7, s70
	v_lshlrev_b32_e32 v6, 4, v6
	v_add_u32_e32 v76, s70, v11
	v_add_u32_e32 v126, v75, v6
	v_add_u32_e32 v118, v76, v6
	ds_read_b128 v[6:9], v126
	ds_read_b128 v[10:13], v118 offset:16384
	ds_read_b128 v[14:17], v126 offset:2048
	ds_read_b128 v[18:21], v118 offset:18432
	ds_read_b128 v[22:25], v126 offset:4096
	ds_read_b128 v[26:29], v118 offset:20480
	ds_read_b128 v[30:33], v126 offset:6144
	ds_read_b128 v[34:37], v118 offset:22528
	v_bfe_u32 v142, v137, 4, 2
	s_waitcnt lgkmcnt(6)
	v_mfma_f32_16x16x32_bf16 v[38:41], v[10:13], v[6:9], 0
	v_and_b32_e32 v143, 64, v137
	s_add_i32 s72, s72, s74
	s_waitcnt lgkmcnt(4)
	v_mfma_f32_16x16x32_bf16 v[42:45], v[18:21], v[6:9], 0
	s_waitcnt lgkmcnt(2)
	v_mfma_f32_16x16x32_bf16 v[46:49], v[26:29], v[6:9], 0
	s_waitcnt lgkmcnt(0)
	v_mfma_f32_16x16x32_bf16 v[6:9], v[34:37], v[6:9], 0
	v_mfma_f32_16x16x32_bf16 v[50:53], v[10:13], v[14:17], 0
	v_mfma_f32_16x16x32_bf16 v[54:57], v[18:21], v[14:17], 0
	v_mfma_f32_16x16x32_bf16 v[58:61], v[26:29], v[14:17], 0
	v_mfma_f32_16x16x32_bf16 v[14:17], v[34:37], v[14:17], 0
	v_mfma_f32_16x16x32_bf16 v[62:65], v[10:13], v[22:25], 0
	v_mfma_f32_16x16x32_bf16 v[66:69], v[18:21], v[22:25], 0
	v_mfma_f32_16x16x32_bf16 v[70:73], v[26:29], v[22:25], 0
	v_mfma_f32_16x16x32_bf16 v[22:25], v[34:37], v[22:25], 0
	v_mfma_f32_16x16x32_bf16 v[10:13], v[10:13], v[30:33], 0
	v_mfma_f32_16x16x32_bf16 v[18:21], v[18:21], v[30:33], 0
	v_mfma_f32_16x16x32_bf16 v[26:29], v[26:29], v[30:33], 0
	v_mfma_f32_16x16x32_bf16 v[30:33], v[34:37], v[30:33], 0
	v_bitop3_b32 v34, v142, v74, 4 bitop3:0x36
	v_lshlrev_b32_e32 v34, 4, v34
	v_add_u32_e32 v114, v75, v34
	v_add_u32_e32 v115, v76, v34
	ds_read_b128 v[34:37], v114
	ds_read_b128 v[74:77], v115 offset:16384
	ds_read_b128 v[78:81], v114 offset:2048
	ds_read_b128 v[82:85], v115 offset:18432
	ds_read_b128 v[86:89], v114 offset:4096
	ds_read_b128 v[90:93], v115 offset:20480
	ds_read_b128 v[94:97], v114 offset:6144
	ds_read_b128 v[98:101], v115 offset:22528
	s_waitcnt lgkmcnt(6)
	v_mfma_f32_16x16x32_bf16 v[38:41], v[74:77], v[34:37], v[38:41]
	s_waitcnt vmcnt(0)
	s_waitcnt lgkmcnt(0)
	s_barrier
; #define GLDS_STAGE(st, kt_) do { \
;         _Pragma("unroll") for (int i_ = 0; i_ < FI; ++i_) { \
;             glds16(ap + (size_t)(32 * i_) * lda + (kt_) * 64, l3a + (st) + tid * 16 + i_ * 4096); \
;             glds16(bp + (size_t)(32 * i_) * ldb + (kt_) * 64, l3a + (st) + OPB + tid * 16 + i_ * 4096); } } while (0)
; #define GLDS_STAGE(st, kt_) do { \
;         _Pragma("unroll") for (int i_ = 0; i_ < 4; ++i_) { \
;             glds16(ap + (size_t)(64 * i_) * lda + (kt_) * 64, l3a + (st) + tid * 16 + i_ * 8192); \
;             glds16(bp + (size_t)(64 * i_) * ldb + (kt_) * 64, l3a + (st) + 32768 + tid * 16 + i_ * 8192); } } while (0)
; template <int WT, class Epi>
; DEV void gemm_tile(const bf16_t* __restrict__ A, int lda, const bf16_t* __restrict__ Bt, int ldb, int K, unsigned char* lds, const Epi& epi) {
;     ...
;     for (int kt = 0; kt < nk; ++kt) {
;         if (NSTG == 4 && kt + 2 < nk) { if (FI == 2) asm volatile("s_waitcnt vmcnt(8)" ::: "memory"); else asm volatile("s_waitcnt vmcnt(0)" ::: "memory"); }
;         else asm volatile("s_waitcnt vmcnt(0)" ::: "memory");
;         __syncthreads();
;         if (kt + NSTG - 1 < nk) GLDS_STAGE(nxt, kt + NSTG - 1);
; #pragma unroll
;         for (int kh = 0; kh < 2; ++kh) {
;             bf16x8 af[FI], bfr[FI];
;             const int ch = ((kh * 4 + fq) ^ sw) << 4;
; #pragma unroll
;             for (int i = 0; i < FI; ++i) { af[i] = *(const bf16x8*)(lds + cur + aoff + i * 2048 + ch); bfr[i] = *(const bf16x8*)(lds + cur + boff + i * 2048 + ch); }
; #pragma unroll
;             for (int mi = 0; mi < FI; ++mi)
; #pragma unroll
;                 for (int ni = 0; ni < FI; ++ni) acc[mi][ni] = __builtin_amdgcn_mfma_f32_16x16x32_bf16(bfr[ni], af[mi], acc[mi][ni], 0, 0, 0);
;         }
	v_mfma_f32_16x16x32_bf16 v[42:45], v[82:85], v[34:37], v[42:45]
	v_mfma_f32_16x16x32_bf16 v[46:49], v[90:93], v[34:37], v[46:49]
	v_mfma_f32_16x16x32_bf16 v[6:9], v[98:101], v[34:37], v[6:9]
	v_mfma_f32_16x16x32_bf16 v[34:37], v[74:77], v[78:81], v[50:53]
	v_mfma_f32_16x16x32_bf16 v[50:53], v[82:85], v[78:81], v[54:57]
	v_mfma_f32_16x16x32_bf16 v[54:57], v[90:93], v[78:81], v[58:61]
	v_mfma_f32_16x16x32_bf16 v[58:61], v[74:77], v[86:89], v[62:65]
	v_mfma_f32_16x16x32_bf16 v[62:65], v[82:85], v[86:89], v[66:69]
	v_mfma_f32_16x16x32_bf16 v[66:69], v[90:93], v[86:89], v[70:73]
	v_mfma_f32_16x16x32_bf16 v[10:13], v[74:77], v[94:97], v[10:13]
	s_nop 1
	v_lshl_add_u64 v[70:71], v[2:3], 0, s[38:39]
	v_add_u32_e32 v74, s70, v102
	s_mov_b32 s92, m0
	s_mov_b32 m0, s14
	s_nop 0
	global_load_lds_dwordx4 v[70:71], off
	s_mov_b32 m0, s92
	v_lshl_add_u64 v[72:73], v[4:5], 0, s[38:39]
	v_readfirstlane_b32 s14, v74
	s_mov_b32 s92, m0
	s_mov_b32 m0, s14
	s_nop 0
	global_load_lds_dwordx4 v[72:73], off
	s_mov_b32 m0, s92
	v_lshl_add_u64 v[70:71], v[2:3], 0, s[40:41]
	s_mov_b32 s92, m0
	s_mov_b32 m0, s82
	s_nop 0
	global_load_lds_dwordx4 v[70:71], off
	s_mov_b32 m0, s92
	v_lshl_add_u64 v[70:71], v[4:5], 0, s[42:43]
	s_add_i32 s82, s14, 0x1000
	s_mov_b32 s92, m0
	s_mov_b32 m0, s82
	s_nop 0
	global_load_lds_dwordx4 v[70:71], off
	s_mov_b32 m0, s92
	v_lshl_add_u64 v[70:71], v[2:3], 0, s[44:45]
	s_mov_b32 s82, m0
	s_mov_b32 m0, s83
	s_nop 0
	global_load_lds_dwordx4 v[70:71], off
	s_mov_b32 m0, s82
	v_lshl_add_u64 v[70:71], v[4:5], 0, s[46:47]
	s_add_i32 s82, s14, 0x2000
	s_mov_b32 s83, m0
	s_mov_b32 m0, s82
	s_nop 0
	global_load_lds_dwordx4 v[70:71], off
	s_mov_b32 m0, s83
	v_lshl_add_u64 v[70:71], v[2:3], 0, s[48:49]
	s_mov_b32 s82, m0
	s_mov_b32 m0, s84
	s_nop 0
	global_load_lds_dwordx4 v[70:71], off
	s_mov_b32 m0, s82
	v_lshl_add_u64 v[70:71], v[4:5], 0, s[50:51]
	s_addk_i32 s14, 0x3000
	s_mov_b32 s82, m0
	s_mov_b32 m0, s14
	s_nop 0
	global_load_lds_dwordx4 v[70:71], off
	s_mov_b32 m0, s82
	v_mfma_f32_16x16x32_bf16 v[14:17], v[98:101], v[78:81], v[14:17]
	s_cmpk_lt_i32 s72, 0x220
	v_mfma_f32_16x16x32_bf16 v[22:25], v[98:101], v[86:89], v[22:25]
	v_mfma_f32_16x16x32_bf16 v[18:21], v[82:85], v[94:97], v[18:21]
	v_mfma_f32_16x16x32_bf16 v[26:29], v[90:93], v[94:97], v[26:29]
	v_mfma_f32_16x16x32_bf16 v[30:33], v[98:101], v[94:97], v[30:33]
	ds_read_b128 v[70:73], v126 offset:32768
	ds_read_b128 v[74:77], v118 offset:49152
	ds_read_b128 v[78:81], v126 offset:34816
	ds_read_b128 v[82:85], v118 offset:51200
	ds_read_b128 v[86:89], v126 offset:36864
	ds_read_b128 v[90:93], v118 offset:53248
	ds_read_b128 v[94:97], v126 offset:38912
	ds_read_b128 v[98:101], v118 offset:55296
	s_waitcnt lgkmcnt(6)
	v_mfma_f32_16x16x32_bf16 v[38:41], v[74:77], v[70:73], v[38:41]
	s_waitcnt lgkmcnt(4)
	v_mfma_f32_16x16x32_bf16 v[42:45], v[82:85], v[70:73], v[42:45]
	s_waitcnt lgkmcnt(2)
	v_mfma_f32_16x16x32_bf16 v[46:49], v[90:93], v[70:73], v[46:49]
	s_waitcnt lgkmcnt(0)
	v_mfma_f32_16x16x32_bf16 v[6:9], v[98:101], v[70:73], v[6:9]
	v_mfma_f32_16x16x32_bf16 v[34:37], v[74:77], v[78:81], v[34:37]
	v_mfma_f32_16x16x32_bf16 v[50:53], v[82:85], v[78:81], v[50:53]
	v_mfma_f32_16x16x32_bf16 v[54:57], v[90:93], v[78:81], v[54:57]
	v_mfma_f32_16x16x32_bf16 v[14:17], v[98:101], v[78:81], v[14:17]
	v_mfma_f32_16x16x32_bf16 v[58:61], v[74:77], v[86:89], v[58:61]
	v_mfma_f32_16x16x32_bf16 v[62:65], v[82:85], v[86:89], v[62:65]
	v_mfma_f32_16x16x32_bf16 v[66:69], v[90:93], v[86:89], v[66:69]
	v_mfma_f32_16x16x32_bf16 v[22:25], v[98:101], v[86:89], v[22:25]
	v_mfma_f32_16x16x32_bf16 v[10:13], v[74:77], v[94:97], v[10:13]
	v_mfma_f32_16x16x32_bf16 v[18:21], v[82:85], v[94:97], v[18:21]
	v_mfma_f32_16x16x32_bf16 v[26:29], v[90:93], v[94:97], v[26:29]
	v_mfma_f32_16x16x32_bf16 v[30:33], v[98:101], v[94:97], v[30:33]
	ds_read_b128 v[70:73], v114 offset:32768
	ds_read_b128 v[74:77], v115 offset:49152
	ds_read_b128 v[78:81], v114 offset:34816
	ds_read_b128 v[82:85], v115 offset:51200
	ds_read_b128 v[86:89], v114 offset:36864
	ds_read_b128 v[90:93], v115 offset:53248
	ds_read_b128 v[94:97], v114 offset:38912
	ds_read_b128 v[98:101], v115 offset:55296
	s_waitcnt vmcnt(0)
	s_waitcnt lgkmcnt(0)
	v_mfma_f32_16x16x32_bf16 v[38:41], v[74:77], v[70:73], v[38:41]
	s_barrier
; #define GLDS_STAGE(st, kt_) do { \
;         _Pragma("unroll") for (int i_ = 0; i_ < FI; ++i_) { \
;             glds16(ap + (size_t)(32 * i_) * lda + (kt_) * 64, l3a + (st) + tid * 16 + i_ * 4096); \
;             glds16(bp + (size_t)(32 * i_) * ldb + (kt_) * 64, l3a + (st) + OPB + tid * 16 + i_ * 4096); } } while (0)
; #define GLDS_STAGE(st, kt_) do { \
;         _Pragma("unroll") for (int i_ = 0; i_ < 4; ++i_) { \
;             glds16(ap + (size_t)(64 * i_) * lda + (kt_) * 64, l3a + (st) + tid * 16 + i_ * 8192); \
;             glds16(bp + (size_t)(64 * i_) * ldb + (kt_) * 64, l3a + (st) + 32768 + tid * 16 + i_ * 8192); } } while (0)
; template <int WT, class Epi>
; DEV void gemm_tile(const bf16_t* __restrict__ A, int lda, const bf16_t* __restrict__ Bt, int ldb, int K, unsigned char* lds, const Epi& epi) {
;     ...
;     for (int kt = 0; kt < nk; ++kt) {
;         if (NSTG == 4 && kt + 2 < nk) { if (FI == 2) asm volatile("s_waitcnt vmcnt(8)" ::: "memory"); else asm volatile("s_waitcnt vmcnt(0)" ::: "memory"); }
;         else asm volatile("s_waitcnt vmcnt(0)" ::: "memory");
;         __syncthreads();
;         if (kt + NSTG - 1 < nk) GLDS_STAGE(nxt, kt + NSTG - 1);
; #pragma unroll
;         for (int kh = 0; kh < 2; ++kh) {
;             bf16x8 af[FI], bfr[FI];
;             const int ch = ((kh * 4 + fq) ^ sw) << 4;
; #pragma unroll
;             for (int i = 0; i < FI; ++i) { af[i] = *(const bf16x8*)(lds + cur + aoff + i * 2048 + ch); bfr[i] = *(const bf16x8*)(lds + cur + boff + i * 2048 + ch); }
; #pragma unroll
;             for (int mi = 0; mi < FI; ++mi)
; #pragma unroll
;                 for (int ni = 0; ni < FI; ++ni) acc[mi][ni] = __builtin_amdgcn_mfma_f32_16x16x32_bf16(bfr[ni], af[mi], acc[mi][ni], 0, 0, 0);
;         }
	v_mfma_f32_16x16x32_bf16 v[42:45], v[82:85], v[70:73], v[42:45]
	v_mfma_f32_16x16x32_bf16 v[46:49], v[90:93], v[70:73], v[46:49]
	v_mfma_f32_16x16x32_bf16 v[6:9], v[98:101], v[70:73], v[6:9]
	v_lshl_add_u64 v[70:71], v[2:3], 0, s[52:53]
	s_mov_b32 s14, m0
	s_mov_b32 m0, s15
	s_nop 0
	global_load_lds_dwordx4 v[70:71], off
	s_mov_b32 m0, s14
	v_lshl_add_u64 v[72:73], v[4:5], 0, s[52:53]
	s_mov_b32 s14, m0
	s_mov_b32 m0, s85
	s_nop 0
	global_load_lds_dwordx4 v[72:73], off
	s_mov_b32 m0, s14
	v_lshl_add_u64 v[70:71], v[2:3], 0, s[54:55]
	s_mov_b32 s14, m0
	s_mov_b32 m0, s86
	s_nop 0
	global_load_lds_dwordx4 v[70:71], off
	s_mov_b32 m0, s14
	v_lshl_add_u64 v[70:71], v[4:5], 0, s[56:57]
	s_mov_b32 s14, m0
	s_mov_b32 m0, s87
	s_nop 0
	global_load_lds_dwordx4 v[70:71], off
	s_mov_b32 m0, s14
	v_lshl_add_u64 v[70:71], v[2:3], 0, s[58:59]
	s_mov_b32 s14, m0
	s_mov_b32 m0, s88
	s_nop 0
	global_load_lds_dwordx4 v[70:71], off
	s_mov_b32 m0, s14
	v_lshl_add_u64 v[70:71], v[4:5], 0, s[60:61]
	s_mov_b32 s14, m0
	s_mov_b32 m0, s89
	s_nop 0
	global_load_lds_dwordx4 v[70:71], off
	s_mov_b32 m0, s14
	v_lshl_add_u64 v[2:3], v[2:3], 0, s[62:63]
	s_mov_b32 s14, m0
	s_mov_b32 m0, s90
	s_nop 0
	global_load_lds_dwordx4 v[2:3], off
	s_mov_b32 m0, s14
	v_lshl_add_u64 v[2:3], v[4:5], 0, s[64:65]
	s_mov_b32 s14, m0
	s_mov_b32 m0, s91
	s_nop 0
	global_load_lds_dwordx4 v[2:3], off
	s_mov_b32 m0, s14
	v_mfma_f32_16x16x32_bf16 v[34:37], v[74:77], v[78:81], v[34:37]
	v_mfma_f32_16x16x32_bf16 v[50:53], v[82:85], v[78:81], v[50:53]
	v_mfma_f32_16x16x32_bf16 v[54:57], v[90:93], v[78:81], v[54:57]
	v_mfma_f32_16x16x32_bf16 v[14:17], v[98:101], v[78:81], v[14:17]
	v_mfma_f32_16x16x32_bf16 v[58:61], v[74:77], v[86:89], v[58:61]
	v_mfma_f32_16x16x32_bf16 v[62:65], v[82:85], v[86:89], v[62:65]
	v_mfma_f32_16x16x32_bf16 v[66:69], v[90:93], v[86:89], v[66:69]
	v_mfma_f32_16x16x32_bf16 v[22:25], v[98:101], v[86:89], v[22:25]
	v_mfma_f32_16x16x32_bf16 v[10:13], v[74:77], v[94:97], v[10:13]
	v_mfma_f32_16x16x32_bf16 v[18:21], v[82:85], v[94:97], v[18:21]
	v_mfma_f32_16x16x32_bf16 v[26:29], v[90:93], v[94:97], v[26:29]
	v_mfma_f32_16x16x32_bf16 v[30:33], v[98:101], v[94:97], v[30:33]
	ds_read_b128 v[2:5], v126
	ds_read_b128 v[70:73], v118 offset:16384
	ds_read_b128 v[74:77], v126 offset:2048
	ds_read_b128 v[78:81], v118 offset:18432
	ds_read_b128 v[82:85], v126 offset:4096
	ds_read_b128 v[86:89], v118 offset:20480
	ds_read_b128 v[90:93], v126 offset:6144
	ds_read_b128 v[94:97], v118 offset:22528
	s_waitcnt lgkmcnt(6)
	v_mfma_f32_16x16x32_bf16 v[38:41], v[70:73], v[2:5], v[38:41]
	s_waitcnt lgkmcnt(4)
	v_mfma_f32_16x16x32_bf16 v[42:45], v[78:81], v[2:5], v[42:45]
	s_waitcnt lgkmcnt(2)
	v_mfma_f32_16x16x32_bf16 v[46:49], v[86:89], v[2:5], v[46:49]
	s_waitcnt lgkmcnt(0)
	v_mfma_f32_16x16x32_bf16 v[2:5], v[94:97], v[2:5], v[6:9]
	v_mfma_f32_16x16x32_bf16 v[6:9], v[70:73], v[74:77], v[34:37]
	v_mfma_f32_16x16x32_bf16 v[50:53], v[78:81], v[74:77], v[50:53]
	v_mfma_f32_16x16x32_bf16 v[54:57], v[86:89], v[74:77], v[54:57]
	v_mfma_f32_16x16x32_bf16 v[14:17], v[94:97], v[74:77], v[14:17]
	v_mfma_f32_16x16x32_bf16 v[58:61], v[70:73], v[82:85], v[58:61]
	v_mfma_f32_16x16x32_bf16 v[62:65], v[78:81], v[82:85], v[62:65]
	v_mfma_f32_16x16x32_bf16 v[66:69], v[86:89], v[82:85], v[66:69]
	v_mfma_f32_16x16x32_bf16 v[74:77], v[94:97], v[82:85], v[22:25]
	v_mfma_f32_16x16x32_bf16 v[10:13], v[70:73], v[90:93], v[10:13]
	v_mfma_f32_16x16x32_bf16 v[78:81], v[78:81], v[90:93], v[18:21]
	v_mfma_f32_16x16x32_bf16 v[82:85], v[86:89], v[90:93], v[26:29]
	v_mfma_f32_16x16x32_bf16 v[86:89], v[94:97], v[90:93], v[30:33]
	s_nop 2
	ds_read_b128 v[30:33], v114
	ds_read_b128 v[90:93], v115 offset:16384
	ds_read_b128 v[70:73], v114 offset:2048
	ds_read_b128 v[94:97], v115 offset:18432
	ds_read_b128 v[98:101], v114 offset:4096
	ds_read_b128 v[102:105], v115 offset:20480
	ds_read_b128 v[106:109], v114 offset:6144
	ds_read_b128 v[110:113], v115 offset:22528
	s_waitcnt vmcnt(0)
	s_waitcnt lgkmcnt(0)
	v_mfma_f32_16x16x32_bf16 v[18:21], v[90:93], v[30:33], v[38:41]
	s_barrier
; template <int WT, class Epi>
; DEV void gemm_tile(const bf16_t* __restrict__ A, int lda, const bf16_t* __restrict__ Bt, int ldb, int K, unsigned char* lds, const Epi& epi) {
;     ...
;             for (int i = 0; i < FI; ++i) { af[i] = *(const bf16x8*)(lds + cur + aoff + i * 2048 + ch); bfr[i] = *(const bf16x8*)(lds + cur + boff + i * 2048 + ch); }
; #pragma unroll
;             for (int mi = 0; mi < FI; ++mi)
; #pragma unroll
;                 for (int ni = 0; ni < FI; ++ni) acc[mi][ni] = __builtin_amdgcn_mfma_f32_16x16x32_bf16(bfr[ni], af[mi], acc[mi][ni], 0, 0, 0);
;     DEV f32x4 xform(int r, int c, f32x4 v) const {
;         const int row = m0 + r, col = n0 + c;
;         const uint2 z = *(const uint2*)(proj + (size_t)row * NPJ + C_ZB + col);
;         const f32x4 s = *(const f32x4*)(scale + col);
	v_mfma_f32_16x16x32_bf16 v[22:25], v[94:97], v[30:33], v[42:45]
	v_mfma_f32_16x16x32_bf16 v[26:29], v[102:105], v[30:33], v[46:49]
	v_mfma_f32_16x16x32_bf16 v[30:33], v[110:113], v[30:33], v[2:5]
	v_mfma_f32_16x16x32_bf16 v[34:37], v[90:93], v[70:73], v[6:9]
	v_mfma_f32_16x16x32_bf16 v[38:41], v[94:97], v[70:73], v[50:53]
	v_mfma_f32_16x16x32_bf16 v[50:53], v[102:105], v[70:73], v[54:57]
	v_mfma_f32_16x16x32_bf16 v[54:57], v[110:113], v[70:73], v[14:17]
	v_mfma_f32_16x16x32_bf16 v[58:61], v[90:93], v[98:101], v[58:61]
	v_mfma_f32_16x16x32_bf16 v[62:65], v[94:97], v[98:101], v[62:65]
	v_mfma_f32_16x16x32_bf16 v[66:69], v[102:105], v[98:101], v[66:69]
	v_mfma_f32_16x16x32_bf16 v[70:73], v[110:113], v[98:101], v[74:77]
	v_mfma_f32_16x16x32_bf16 v[74:77], v[90:93], v[106:109], v[10:13]
	v_mfma_f32_16x16x32_bf16 v[78:81], v[94:97], v[106:109], v[78:81]
	v_mfma_f32_16x16x32_bf16 v[82:85], v[102:105], v[106:109], v[82:85]
	v_mfma_f32_16x16x32_bf16 v[86:89], v[110:113], v[106:109], v[86:89]
	ds_read_b128 v[2:5], v115 offset:55296
	ds_read_b128 v[42:45], v114 offset:38912
	ds_read_b128 v[6:9], v115 offset:53248
	ds_read_b128 v[14:17], v114 offset:36864
	ds_read_b128 v[10:13], v115 offset:51200
	ds_read_b128 v[90:93], v114 offset:34816
	ds_read_b128 v[46:49], v115 offset:49152
	ds_read_b128 v[94:97], v114 offset:32768
	ds_read_b128 v[98:101], v118 offset:55296
	ds_read_b128 v[102:105], v126 offset:38912
	ds_read_b128 v[106:109], v118 offset:53248
	ds_read_b128 v[114:117], v126 offset:36864
	ds_read_b128 v[110:113], v118 offset:51200
	ds_read_b128 v[122:125], v126 offset:34816
	ds_read_b128 v[118:121], v118 offset:49152
	ds_read_b128 v[126:129], v126 offset:32768
	s_waitcnt lgkmcnt(0)
	s_barrier
	v_mfma_f32_16x16x32_bf16 v[18:21], v[118:121], v[126:129], v[18:21]
	v_mfma_f32_16x16x32_bf16 v[22:25], v[110:113], v[126:129], v[22:25]
	v_mfma_f32_16x16x32_bf16 v[26:29], v[106:109], v[126:129], v[26:29]
	v_mfma_f32_16x16x32_bf16 v[30:33], v[98:101], v[126:129], v[30:33]
	v_mfma_f32_16x16x32_bf16 v[34:37], v[118:121], v[122:125], v[34:37]
	v_mfma_f32_16x16x32_bf16 v[38:41], v[110:113], v[122:125], v[38:41]
	v_mfma_f32_16x16x32_bf16 v[126:129], v[106:109], v[122:125], v[50:53]
	v_mfma_f32_16x16x32_bf16 v[122:125], v[98:101], v[122:125], v[54:57]
	v_mfma_f32_16x16x32_bf16 v[144:147], v[118:121], v[114:117], v[58:61]
	v_mfma_f32_16x16x32_bf16 v[148:151], v[110:113], v[114:117], v[62:65]
	v_mfma_f32_16x16x32_bf16 v[66:69], v[106:109], v[114:117], v[66:69]
	v_mfma_f32_16x16x32_bf16 v[70:73], v[98:101], v[114:117], v[70:73]
	v_mfma_f32_16x16x32_bf16 v[74:77], v[118:121], v[102:105], v[74:77]
	v_mfma_f32_16x16x32_bf16 v[78:81], v[110:113], v[102:105], v[78:81]
	v_mfma_f32_16x16x32_bf16 v[82:85], v[106:109], v[102:105], v[82:85]
	v_mfma_f32_16x16x32_bf16 v[86:89], v[98:101], v[102:105], v[86:89]
	v_mfma_f32_16x16x32_bf16 v[98:101], v[46:49], v[94:97], v[18:21]
	v_mfma_f32_16x16x32_bf16 v[102:105], v[10:13], v[94:97], v[22:25]
	v_mfma_f32_16x16x32_bf16 v[62:65], v[6:9], v[94:97], v[26:29]
	v_mfma_f32_16x16x32_bf16 v[58:61], v[2:5], v[94:97], v[30:33]
	v_mfma_f32_16x16x32_bf16 v[54:57], v[46:49], v[90:93], v[34:37]
	v_mfma_f32_16x16x32_bf16 v[50:53], v[10:13], v[90:93], v[38:41]
	v_mfma_f32_16x16x32_bf16 v[38:41], v[6:9], v[90:93], v[126:129]
	v_mfma_f32_16x16x32_bf16 v[34:37], v[2:5], v[90:93], v[122:125]
	v_lshl_add_u32 v90, v130, 8, s70
	v_mfma_f32_16x16x32_bf16 v[30:33], v[46:49], v[14:17], v[144:147]
	v_mfma_f32_16x16x32_bf16 v[26:29], v[10:13], v[14:17], v[148:151]
	v_mfma_f32_16x16x32_bf16 v[22:25], v[6:9], v[14:17], v[66:69]
	v_mfma_f32_16x16x32_bf16 v[18:21], v[2:5], v[14:17], v[70:73]
	v_mfma_f32_16x16x32_bf16 v[14:17], v[46:49], v[42:45], v[74:77]
	v_mfma_f32_16x16x32_bf16 v[10:13], v[10:13], v[42:45], v[78:81]
	v_mfma_f32_16x16x32_bf16 v[6:9], v[6:9], v[42:45], v[82:85]
	v_mfma_f32_16x16x32_bf16 v[2:5], v[2:5], v[42:45], v[86:89]
	v_lshrrev_b32_e32 v42, 1, v137
	s_nop 1
	v_lshl_or_b32 v88, v142, 2, v143
	v_and_b32_e32 v89, 8, v42
	v_add_u32_e32 v42, s81, v130
	v_or_b32_e32 v46, s68, v88
	v_mad_i64_i32 v[42:43], s[82:83], v42, s79, v[172:173]
	v_ashrrev_i32_e32 v47, 31, v46
	v_lshl_add_u64 v[82:83], v[42:43], 0, s[66:67]
	v_lshlrev_b64 v[68:69], 1, v[46:47]
	v_lshl_add_u64 v[42:43], v[82:83], 0, v[68:69]
	global_load_dwordx2 v[48:49], v[42:43], off
	v_lshl_add_u64 v[70:71], v[46:47], 2, s[4:5]
	global_load_dwordx4 v[42:45], v[70:71], off
	s_waitcnt vmcnt(1)
	v_lshlrev_b32_e32 v47, 16, v48
	v_and_b32_e32 v48, 0xffff0000, v48
	v_mul_f32_e32 v66, 0xbfb8aa3b, v47
	v_mul_f32_e32 v67, 0xbfb8aa3b, v48
	v_exp_f32_e32 v66, v66
	v_exp_f32_e32 v67, v67
	s_waitcnt vmcnt(0)
	v_pk_mul_f32 v[74:75], v[98:99], v[42:43]
	v_pk_mul_f32 v[72:73], v[100:101], v[44:45]
	v_pk_mul_f32 v[42:43], v[54:55], v[42:43]
	v_pk_add_f32 v[66:67], v[66:67], 1.0 op_sel_hi:[1,0]
	v_pk_mul_f32 v[44:45], v[56:57], v[44:45]


; DEV float silu_f(float x) { return x / (1.f + __expf(-x)); }
	s_nop 0


; DEV float silu_f(float x) { return x / (1.f + __expf(-x)); }
	v_rcp_f32_e32 v76, v67
	s_nop 0
	v_mul_f32_e32 v67, v48, v76


; DEV float silu_f(float x) { return x / (1.f + __expf(-x)); }
	s_nop 0


; DEV float bflo(unsigned u) { return __uint_as_float(u << 16); }
; DEV float bfhi(unsigned u) { return __uint_as_float(u & 0xffff0000u); }
; DEV float silu_f(float x) { return x / (1.f + __expf(-x)); }
;     DEV f32x4 xform(int r, int c, f32x4 v) const {
;     ...
;         o[0] = v[0] * s[0] * silu_f(bflo(z.x)); o[1] = v[1] * s[1] * silu_f(bfhi(z.x));
;         o[2] = v[2] * s[2] * silu_f(bflo(z.y)); o[3] = v[3] * s[3] * silu_f(bfhi(z.y));
	v_rcp_f32_e32 v48, v66
	s_nop 0
	v_mul_f32_e32 v66, v47, v48
	v_pk_mul_f32 v[66:67], v[74:75], v[66:67]
	v_lshlrev_b32_e32 v47, 16, v49
	v_and_b32_e32 v74, 0xffff0000, v49
	v_mul_f32_e32 v48, 0xbfb8aa3b, v47
	v_mul_f32_e32 v49, 0xbfb8aa3b, v74
	v_exp_f32_e32 v48, v48
	v_exp_f32_e32 v49, v49
	v_cvt_pk_bf16_f32 v66, v66, v67
	v_pk_add_f32 v[48:49], v[48:49], 1.0 op_sel_hi:[1,0]
	s_nop 0


; DEV float silu_f(float x) { return x / (1.f + __expf(-x)); }
	s_nop 0


; DEV float silu_f(float x) { return x / (1.f + __expf(-x)); }
	v_rcp_f32_e32 v75, v49
	s_nop 0
	v_mul_f32_e32 v49, v74, v75


; DEV float silu_f(float x) { return x / (1.f + __expf(-x)); }
	s_nop 0


; DEV float bflo(unsigned u) { return __uint_as_float(u << 16); }
; DEV float bfhi(unsigned u) { return __uint_as_float(u & 0xffff0000u); }
; DEV float silu_f(float x) { return x / (1.f + __expf(-x)); }
; template <int WT, class Epi>
; DEV void gemm_tile(const bf16_t* __restrict__ A, int lda, const bf16_t* __restrict__ Bt, int ldb, int K, unsigned char* lds, const Epi& epi) {
;     ...
;                 *(uint2*)(lds + row * RB + ((((col >> 3) ^ (row & (CPR - 1))) << 4) | (((col >> 2) & 1) << 3))) = w;
;     DEV f32x4 xform(int r, int c, f32x4 v) const {
;     ...
;         const uint2 z = *(const uint2*)(proj + (size_t)row * NPJ + C_ZB + col);
;         const f32x4 s = *(const f32x4*)(scale + col);
;     ...
;         o[0] = v[0] * s[0] * silu_f(bflo(z.x)); o[1] = v[1] * s[1] * silu_f(bfhi(z.x));
;         o[2] = v[2] * s[2] * silu_f(bflo(z.y)); o[3] = v[3] * s[3] * silu_f(bfhi(z.y));
	v_rcp_f32_e32 v74, v48
	s_nop 0
	v_mul_f32_e32 v48, v47, v74
	v_pk_mul_f32 v[48:49], v[72:73], v[48:49]
	v_or_b32_e32 v77, 16, v88
	v_cvt_pk_bf16_f32 v67, v48, v49
	v_or_b32_e32 v48, s68, v77
	v_ashrrev_i32_e32 v49, 31, v48
	v_lshlrev_b64 v[72:73], 1, v[48:49]
	v_lshl_add_u64 v[48:49], v[82:83], 0, v[72:73]
	global_load_dwordx2 v[74:75], v[48:49], off
	v_lshrrev_b32_e32 v47, 3, v88
	v_bitop3_b32 v47, v47, v137, 15 bitop3:0x78
	v_lshl_or_b32 v76, v47, 4, v89
	v_add_u32_e32 v47, v90, v76
	ds_write_b64 v47, v[66:67]
	v_mov_b32_e32 v47, s69
	v_lshl_add_u64 v[66:67], v[46:47], 2, s[4:5]
	global_load_dwordx4 v[46:49], v[66:67], off offset:64
	s_waitcnt vmcnt(1)
	v_lshlrev_b32_e32 v86, 16, v74
	v_and_b32_e32 v74, 0xffff0000, v74
	v_mul_f32_e32 v78, 0xbfb8aa3b, v86
	v_mul_f32_e32 v79, 0xbfb8aa3b, v74
	v_exp_f32_e32 v78, v78
	v_exp_f32_e32 v79, v79
	s_waitcnt vmcnt(0)
	v_pk_mul_f32 v[84:85], v[102:103], v[46:47]
	v_pk_add_f32 v[78:79], v[78:79], 1.0 op_sel_hi:[1,0]
	v_pk_mul_f32 v[80:81], v[104:105], v[48:49]


; DEV float bflo(unsigned u) { return __uint_as_float(u << 16); }
; DEV float bfhi(unsigned u) { return __uint_as_float(u & 0xffff0000u); }
; DEV float silu_f(float x) { return x / (1.f + __expf(-x)); }
;     DEV f32x4 xform(int r, int c, f32x4 v) const {
;     ...
;         o[0] = v[0] * s[0] * silu_f(bflo(z.x)); o[1] = v[1] * s[1] * silu_f(bfhi(z.x));
	v_pk_mul_f32 v[46:47], v[50:51], v[46:47]
	v_pk_mul_f32 v[48:49], v[52:53], v[48:49]


; DEV float silu_f(float x) { return x / (1.f + __expf(-x)); }
	v_rcp_f32_e32 v87, v79
	s_nop 0
	v_mul_f32_e32 v79, v74, v87


; DEV float silu_f(float x) { return x / (1.f + __expf(-x)); }
	s_nop 0


; DEV float bflo(unsigned u) { return __uint_as_float(u << 16); }
; DEV float bfhi(unsigned u) { return __uint_as_float(u & 0xffff0000u); }
; DEV float silu_f(float x) { return x / (1.f + __expf(-x)); }
;     DEV f32x4 xform(int r, int c, f32x4 v) const {
;     ...
;         o[0] = v[0] * s[0] * silu_f(bflo(z.x)); o[1] = v[1] * s[1] * silu_f(bfhi(z.x));
;         o[2] = v[2] * s[2] * silu_f(bflo(z.y)); o[3] = v[3] * s[3] * silu_f(bfhi(z.y));
	v_rcp_f32_e32 v74, v78
	s_nop 0
	v_mul_f32_e32 v78, v86, v74
	v_pk_mul_f32 v[78:79], v[84:85], v[78:79]
	v_lshlrev_b32_e32 v84, 16, v75
	v_and_b32_e32 v85, 0xffff0000, v75
	v_mul_f32_e32 v74, 0xbfb8aa3b, v84
	v_mul_f32_e32 v75, 0xbfb8aa3b, v85
	v_exp_f32_e32 v74, v74
	v_exp_f32_e32 v75, v75
	v_cvt_pk_bf16_f32 v78, v78, v79
	v_pk_add_f32 v[74:75], v[74:75], 1.0 op_sel_hi:[1,0]
	s_nop 0


; DEV float silu_f(float x) { return x / (1.f + __expf(-x)); }
	s_nop 0


; DEV float silu_f(float x) { return x / (1.f + __expf(-x)); }
	v_rcp_f32_e32 v86, v75
	s_nop 0
	v_mul_f32_e32 v75, v85, v86


; DEV float silu_f(float x) { return x / (1.f + __expf(-x)); }
	s_nop 0


; DEV unsigned cvt_pk_bf16(float lo, float hi) { const f32x2_t v = {lo, hi}; const bf16x2_t b = __builtin_convertvector(v, bf16x2_t); return __builtin_bit_cast(unsigned, b); }
; DEV float bflo(unsigned u) { return __uint_as_float(u << 16); }
; DEV float bfhi(unsigned u) { return __uint_as_float(u & 0xffff0000u); }
; DEV float silu_f(float x) { return x / (1.f + __expf(-x)); }
; template <int WT, class Epi>
; DEV void gemm_tile(const bf16_t* __restrict__ A, int lda, const bf16_t* __restrict__ Bt, int ldb, int K, unsigned char* lds, const Epi& epi) {
;     ...
;                 const int row = wr * WT + mi * 16 + fr, col = wc * WT + ni * 16 + fq * 4;
;                 const f32x4 v = epi.xform(row, col, acc[mi][ni]);
;                 uint2 w; w.x = cvt_pk_bf16(v[0], v[1]); w.y = cvt_pk_bf16(v[2], v[3]);
;                 *(uint2*)(lds + row * RB + ((((col >> 3) ^ (row & (CPR - 1))) << 4) | (((col >> 2) & 1) << 3))) = w;
;     DEV f32x4 xform(int r, int c, f32x4 v) const {
;         const int row = m0 + r, col = n0 + c;
;         const uint2 z = *(const uint2*)(proj + (size_t)row * NPJ + C_ZB + col);
;         const f32x4 s = *(const f32x4*)(scale + col);
;         f32x4 o;
;         o[0] = v[0] * s[0] * silu_f(bflo(z.x)); o[1] = v[1] * s[1] * silu_f(bfhi(z.x));
;         o[2] = v[2] * s[2] * silu_f(bflo(z.y)); o[3] = v[3] * s[3] * silu_f(bfhi(z.y));
;         return o;
;     }
	v_rcp_f32_e32 v85, v74
	s_nop 0
	v_mul_f32_e32 v74, v84, v85
	v_pk_mul_f32 v[74:75], v[80:81], v[74:75]
	v_or_b32_e32 v91, 32, v88
	v_cvt_pk_bf16_f32 v79, v74, v75
	v_lshrrev_b32_e32 v74, 3, v77
	v_bitop3_b32 v74, v74, v137, 15 bitop3:0x78
	v_lshl_or_b32 v77, v74, 4, v89
	v_add_u32_e32 v74, v90, v77
	ds_write_b64 v74, v[78:79]
	v_or_b32_e32 v74, s68, v91
	v_ashrrev_i32_e32 v75, 31, v74
	v_lshlrev_b64 v[74:75], 1, v[74:75]
	v_lshl_add_u64 v[78:79], v[82:83], 0, v[74:75]
	global_load_dwordx2 v[84:85], v[78:79], off
	s_nop 0
	global_load_dwordx4 v[78:81], v[66:67], off offset:128
	s_waitcnt vmcnt(1)
	v_lshlrev_b32_e32 v92, 16, v84
	v_and_b32_e32 v84, 0xffff0000, v84
	v_mul_f32_e32 v86, 0xbfb8aa3b, v92
	s_waitcnt vmcnt(0)
	v_pk_mul_f32 v[62:63], v[62:63], v[78:79]
	v_mul_f32_e32 v78, 0xbfb8aa3b, v84
	v_exp_f32_e32 v86, v86
	v_exp_f32_e32 v87, v78
	v_pk_mul_f32 v[64:65], v[64:65], v[80:81]
	v_pk_add_f32 v[78:79], v[86:87], 1.0 op_sel_hi:[1,0]
	s_nop 0


; DEV float silu_f(float x) { return x / (1.f + __expf(-x)); }
	s_nop 0


; DEV float silu_f(float x) { return x / (1.f + __expf(-x)); }
	v_rcp_f32_e32 v80, v79
	s_nop 0
	v_mul_f32_e32 v79, v84, v80


; DEV float silu_f(float x) { return x / (1.f + __expf(-x)); }
	s_nop 0


; DEV float bflo(unsigned u) { return __uint_as_float(u << 16); }
; DEV float bfhi(unsigned u) { return __uint_as_float(u & 0xffff0000u); }
; DEV float silu_f(float x) { return x / (1.f + __expf(-x)); }
;     DEV f32x4 xform(int r, int c, f32x4 v) const {
;     ...
;         o[0] = v[0] * s[0] * silu_f(bflo(z.x)); o[1] = v[1] * s[1] * silu_f(bfhi(z.x));
;         o[2] = v[2] * s[2] * silu_f(bflo(z.y)); o[3] = v[3] * s[3] * silu_f(bfhi(z.y));
	v_rcp_f32_e32 v80, v78
	s_nop 0
	v_mul_f32_e32 v78, v92, v80
	v_lshlrev_b32_e32 v80, 16, v85
	v_and_b32_e32 v81, 0xffff0000, v85
	v_pk_mul_f32 v[62:63], v[62:63], v[78:79]
	v_mul_f32_e32 v78, 0xbfb8aa3b, v80
	v_mul_f32_e32 v79, 0xbfb8aa3b, v81
	v_exp_f32_e32 v78, v78
	v_exp_f32_e32 v79, v79
	v_cvt_pk_bf16_f32 v62, v62, v63
	v_pk_add_f32 v[78:79], v[78:79], 1.0 op_sel_hi:[1,0]
	s_nop 0


; DEV float silu_f(float x) { return x / (1.f + __expf(-x)); }
	s_nop 0


; DEV float silu_f(float x) { return x / (1.f + __expf(-x)); }
	v_rcp_f32_e32 v84, v79
	s_nop 0
	v_mul_f32_e32 v79, v81, v84


; DEV float silu_f(float x) { return x / (1.f + __expf(-x)); }
	s_nop 0


; DEV unsigned cvt_pk_bf16(float lo, float hi) { const f32x2_t v = {lo, hi}; const bf16x2_t b = __builtin_convertvector(v, bf16x2_t); return __builtin_bit_cast(unsigned, b); }
; DEV float bflo(unsigned u) { return __uint_as_float(u << 16); }
; DEV float bfhi(unsigned u) { return __uint_as_float(u & 0xffff0000u); }
; DEV float silu_f(float x) { return x / (1.f + __expf(-x)); }
; template <int WT, class Epi>
; DEV void gemm_tile(const bf16_t* __restrict__ A, int lda, const bf16_t* __restrict__ Bt, int ldb, int K, unsigned char* lds, const Epi& epi) {
;     ...
;                 const int row = wr * WT + mi * 16 + fr, col = wc * WT + ni * 16 + fq * 4;
;                 const f32x4 v = epi.xform(row, col, acc[mi][ni]);
;                 uint2 w; w.x = cvt_pk_bf16(v[0], v[1]); w.y = cvt_pk_bf16(v[2], v[3]);
;                 *(uint2*)(lds + row * RB + ((((col >> 3) ^ (row & (CPR - 1))) << 4) | (((col >> 2) & 1) << 3))) = w;
;     DEV f32x4 xform(int r, int c, f32x4 v) const {
;         const int row = m0 + r, col = n0 + c;
;         const uint2 z = *(const uint2*)(proj + (size_t)row * NPJ + C_ZB + col);
;         const f32x4 s = *(const f32x4*)(scale + col);
;         f32x4 o;
;         o[0] = v[0] * s[0] * silu_f(bflo(z.x)); o[1] = v[1] * s[1] * silu_f(bfhi(z.x));
;         o[2] = v[2] * s[2] * silu_f(bflo(z.y)); o[3] = v[3] * s[3] * silu_f(bfhi(z.y));
;         return o;
;     }
	v_rcp_f32_e32 v81, v78
	s_nop 0
	v_mul_f32_e32 v78, v80, v81
	v_pk_mul_f32 v[64:65], v[64:65], v[78:79]
	s_nop 0
	v_cvt_pk_bf16_f32 v63, v64, v65
	v_lshrrev_b32_e32 v64, 3, v91
	v_bitop3_b32 v64, v64, v137, 15 bitop3:0x78
	v_lshl_or_b32 v64, v64, 4, v89
	v_add_u32_e32 v65, v90, v64
	ds_write_b64 v65, v[62:63]
	v_or_b32_e32 v65, 48, v88
	v_or_b32_e32 v62, s68, v65
	v_ashrrev_i32_e32 v63, 31, v62
	v_lshlrev_b64 v[62:63], 1, v[62:63]
	v_lshl_add_u64 v[78:79], v[82:83], 0, v[62:63]
	global_load_dwordx2 v[82:83], v[78:79], off
	s_nop 0
	global_load_dwordx4 v[78:81], v[66:67], off offset:192
	s_waitcnt vmcnt(1)
	v_lshlrev_b32_e32 v86, 16, v82
	v_and_b32_e32 v82, 0xffff0000, v82
	v_mul_f32_e32 v84, 0xbfb8aa3b, v86
	s_waitcnt vmcnt(0)
	v_pk_mul_f32 v[58:59], v[58:59], v[78:79]
	v_mul_f32_e32 v78, 0xbfb8aa3b, v82
	v_exp_f32_e32 v84, v84
	v_exp_f32_e32 v85, v78
	v_pk_mul_f32 v[60:61], v[60:61], v[80:81]
	v_pk_add_f32 v[78:79], v[84:85], 1.0 op_sel_hi:[1,0]
	s_nop 0


; DEV float silu_f(float x) { return x / (1.f + __expf(-x)); }
	s_nop 0


; DEV float silu_f(float x) { return x / (1.f + __expf(-x)); }
	v_rcp_f32_e32 v80, v79
	s_nop 0
	v_mul_f32_e32 v79, v82, v80


; DEV float silu_f(float x) { return x / (1.f + __expf(-x)); }
	s_nop 0


; DEV float bflo(unsigned u) { return __uint_as_float(u << 16); }
; DEV float bfhi(unsigned u) { return __uint_as_float(u & 0xffff0000u); }
; DEV float silu_f(float x) { return x / (1.f + __expf(-x)); }
;     DEV f32x4 xform(int r, int c, f32x4 v) const {
;     ...
;         o[0] = v[0] * s[0] * silu_f(bflo(z.x)); o[1] = v[1] * s[1] * silu_f(bfhi(z.x));
;         o[2] = v[2] * s[2] * silu_f(bflo(z.y)); o[3] = v[3] * s[3] * silu_f(bfhi(z.y));
	v_rcp_f32_e32 v80, v78
	s_nop 0
	v_mul_f32_e32 v78, v86, v80
	v_lshlrev_b32_e32 v80, 16, v83
	v_and_b32_e32 v81, 0xffff0000, v83
	v_pk_mul_f32 v[58:59], v[58:59], v[78:79]
	v_mul_f32_e32 v78, 0xbfb8aa3b, v80
	v_mul_f32_e32 v79, 0xbfb8aa3b, v81
	v_exp_f32_e32 v78, v78
	v_exp_f32_e32 v79, v79
	s_nop 0
	v_pk_add_f32 v[78:79], v[78:79], 1.0 op_sel_hi:[1,0]
	s_nop 0


; DEV float silu_f(float x) { return x / (1.f + __expf(-x)); }
	s_nop 0


; DEV float silu_f(float x) { return x / (1.f + __expf(-x)); }
	v_rcp_f32_e32 v82, v79
	s_nop 0
	v_mul_f32_e32 v79, v81, v82


; DEV float silu_f(float x) { return x / (1.f + __expf(-x)); }
	s_nop 0


; DEV unsigned cvt_pk_bf16(float lo, float hi) { const f32x2_t v = {lo, hi}; const bf16x2_t b = __builtin_convertvector(v, bf16x2_t); return __builtin_bit_cast(unsigned, b); }
; DEV float bflo(unsigned u) { return __uint_as_float(u << 16); }
; DEV float bfhi(unsigned u) { return __uint_as_float(u & 0xffff0000u); }
; DEV float silu_f(float x) { return x / (1.f + __expf(-x)); }
; template <int WT, class Epi>
; DEV void gemm_tile(const bf16_t* __restrict__ A, int lda, const bf16_t* __restrict__ Bt, int ldb, int K, unsigned char* lds, const Epi& epi) {
;     ...
;                 const int row = wr * WT + mi * 16 + fr, col = wc * WT + ni * 16 + fq * 4;
;                 const f32x4 v = epi.xform(row, col, acc[mi][ni]);
;                 uint2 w; w.x = cvt_pk_bf16(v[0], v[1]); w.y = cvt_pk_bf16(v[2], v[3]);
;                 *(uint2*)(lds + row * RB + ((((col >> 3) ^ (row & (CPR - 1))) << 4) | (((col >> 2) & 1) << 3))) = w;
;     DEV f32x4 xform(int r, int c, f32x4 v) const {
;         const int row = m0 + r, col = n0 + c;
;         const uint2 z = *(const uint2*)(proj + (size_t)row * NPJ + C_ZB + col);
;         const f32x4 s = *(const f32x4*)(scale + col);
;         f32x4 o;
;         o[0] = v[0] * s[0] * silu_f(bflo(z.x)); o[1] = v[1] * s[1] * silu_f(bfhi(z.x));
;         o[2] = v[2] * s[2] * silu_f(bflo(z.y)); o[3] = v[3] * s[3] * silu_f(bfhi(z.y));
;         return o;
;     }
	v_rcp_f32_e32 v81, v78
	s_nop 0
	v_mul_f32_e32 v78, v80, v81
	v_pk_mul_f32 v[60:61], v[60:61], v[78:79]
	v_cvt_pk_bf16_f32 v78, v58, v59
	v_lshrrev_b32_e32 v58, 3, v65
	v_bitop3_b32 v58, v58, v137, 15 bitop3:0x78
	v_lshl_or_b32 v58, v58, 4, v89
	v_cvt_pk_bf16_f32 v79, v60, v61
	v_add_u32_e32 v59, v90, v58
	ds_write_b64 v59, v[78:79]
	v_or_b32_e32 v59, 16, v130
	v_lshl_add_u32 v65, v59, 8, s70
	v_add_u32_e32 v59, s81, v59
	v_mad_i64_i32 v[60:61], s[68:69], v59, s79, v[172:173]
	v_lshl_add_u64 v[60:61], v[60:61], 0, s[66:67]
	v_lshl_add_u64 v[78:79], v[60:61], 0, v[68:69]
	global_load_dwordx2 v[78:79], v[78:79], off
	s_waitcnt vmcnt(0)
	v_lshlrev_b32_e32 v59, 16, v78
	v_and_b32_e32 v78, 0xffff0000, v78
	v_mul_f32_e32 v80, 0xbfb8aa3b, v59
	v_mul_f32_e32 v54, 0xbfb8aa3b, v78
	v_exp_f32_e32 v80, v80
	v_exp_f32_e32 v81, v54
	s_nop 0
	v_pk_add_f32 v[54:55], v[80:81], 1.0 op_sel_hi:[1,0]
	s_nop 0


; DEV float silu_f(float x) { return x / (1.f + __expf(-x)); }
	s_nop 0


; DEV float silu_f(float x) { return x / (1.f + __expf(-x)); }
	v_rcp_f32_e32 v56, v55
	s_nop 0
	v_mul_f32_e32 v55, v78, v56


; DEV float silu_f(float x) { return x / (1.f + __expf(-x)); }
	s_nop 0


; DEV float bflo(unsigned u) { return __uint_as_float(u << 16); }
; DEV float bfhi(unsigned u) { return __uint_as_float(u & 0xffff0000u); }
; DEV float silu_f(float x) { return x / (1.f + __expf(-x)); }
;     DEV f32x4 xform(int r, int c, f32x4 v) const {
;     ...
;         o[0] = v[0] * s[0] * silu_f(bflo(z.x)); o[1] = v[1] * s[1] * silu_f(bfhi(z.x));
;         o[2] = v[2] * s[2] * silu_f(bflo(z.y)); o[3] = v[3] * s[3] * silu_f(bfhi(z.y));
	v_rcp_f32_e32 v56, v54
	s_nop 0
	v_mul_f32_e32 v54, v59, v56
	v_lshlrev_b32_e32 v56, 16, v79
	v_and_b32_e32 v57, 0xffff0000, v79
	v_pk_mul_f32 v[42:43], v[42:43], v[54:55]
	v_mul_f32_e32 v54, 0xbfb8aa3b, v56
	v_mul_f32_e32 v55, 0xbfb8aa3b, v57
	v_exp_f32_e32 v54, v54
	v_exp_f32_e32 v55, v55
	v_cvt_pk_bf16_f32 v42, v42, v43
	v_pk_add_f32 v[54:55], v[54:55], 1.0 op_sel_hi:[1,0]
	s_nop 0


; DEV float silu_f(float x) { return x / (1.f + __expf(-x)); }
	s_nop 0


; DEV float silu_f(float x) { return x / (1.f + __expf(-x)); }
	v_rcp_f32_e32 v59, v55
	s_nop 0
	v_mul_f32_e32 v55, v57, v59


; DEV float silu_f(float x) { return x / (1.f + __expf(-x)); }
	s_nop 0


; DEV unsigned cvt_pk_bf16(float lo, float hi) { const f32x2_t v = {lo, hi}; const bf16x2_t b = __builtin_convertvector(v, bf16x2_t); return __builtin_bit_cast(unsigned, b); }
; DEV float bflo(unsigned u) { return __uint_as_float(u << 16); }
; DEV float bfhi(unsigned u) { return __uint_as_float(u & 0xffff0000u); }
; DEV float silu_f(float x) { return x / (1.f + __expf(-x)); }
; template <int WT, class Epi>
; DEV void gemm_tile(const bf16_t* __restrict__ A, int lda, const bf16_t* __restrict__ Bt, int ldb, int K, unsigned char* lds, const Epi& epi) {
;     ...
;                 const int row = wr * WT + mi * 16 + fr, col = wc * WT + ni * 16 + fq * 4;
;                 const f32x4 v = epi.xform(row, col, acc[mi][ni]);
;                 uint2 w; w.x = cvt_pk_bf16(v[0], v[1]); w.y = cvt_pk_bf16(v[2], v[3]);
;                 *(uint2*)(lds + row * RB + ((((col >> 3) ^ (row & (CPR - 1))) << 4) | (((col >> 2) & 1) << 3))) = w;
;     DEV f32x4 xform(int r, int c, f32x4 v) const {
;         const int row = m0 + r, col = n0 + c;
;         const uint2 z = *(const uint2*)(proj + (size_t)row * NPJ + C_ZB + col);
;         const f32x4 s = *(const f32x4*)(scale + col);
;         f32x4 o;
;         o[0] = v[0] * s[0] * silu_f(bflo(z.x)); o[1] = v[1] * s[1] * silu_f(bfhi(z.x));
;         o[2] = v[2] * s[2] * silu_f(bflo(z.y)); o[3] = v[3] * s[3] * silu_f(bfhi(z.y));
;         return o;
;     }
	v_rcp_f32_e32 v57, v54
	s_nop 0
	v_mul_f32_e32 v54, v56, v57
	v_pk_mul_f32 v[44:45], v[44:45], v[54:55]
	s_nop 0
	v_cvt_pk_bf16_f32 v43, v44, v45
	v_add_u32_e32 v44, v65, v76
	ds_write_b64 v44, v[42:43]
	v_lshl_add_u64 v[42:43], v[60:61], 0, v[72:73]
	global_load_dwordx2 v[42:43], v[42:43], off
	s_waitcnt vmcnt(0)
	v_lshlrev_b32_e32 v54, 16, v42
	v_and_b32_e32 v42, 0xffff0000, v42
	v_mul_f32_e32 v44, 0xbfb8aa3b, v54
	v_mul_f32_e32 v45, 0xbfb8aa3b, v42
	v_exp_f32_e32 v44, v44
	v_exp_f32_e32 v45, v45
	s_nop 0
	v_pk_add_f32 v[44:45], v[44:45], 1.0 op_sel_hi:[1,0]
	s_nop 0


; DEV float silu_f(float x) { return x / (1.f + __expf(-x)); }
	s_nop 0


; DEV float silu_f(float x) { return x / (1.f + __expf(-x)); }
	v_rcp_f32_e32 v50, v45
	s_nop 0
	v_mul_f32_e32 v45, v42, v50


; DEV float silu_f(float x) { return x / (1.f + __expf(-x)); }
	s_nop 0


; DEV float bflo(unsigned u) { return __uint_as_float(u << 16); }
; DEV float bfhi(unsigned u) { return __uint_as_float(u & 0xffff0000u); }
; DEV float silu_f(float x) { return x / (1.f + __expf(-x)); }
;     DEV f32x4 xform(int r, int c, f32x4 v) const {
;     ...
;         o[0] = v[0] * s[0] * silu_f(bflo(z.x)); o[1] = v[1] * s[1] * silu_f(bfhi(z.x));
;         o[2] = v[2] * s[2] * silu_f(bflo(z.y)); o[3] = v[3] * s[3] * silu_f(bfhi(z.y));
	v_rcp_f32_e32 v42, v44
	s_nop 0
	v_mul_f32_e32 v44, v54, v42
	v_pk_mul_f32 v[44:45], v[46:47], v[44:45]
	v_lshlrev_b32_e32 v46, 16, v43
	v_and_b32_e32 v47, 0xffff0000, v43
	v_mul_f32_e32 v42, 0xbfb8aa3b, v46
	v_mul_f32_e32 v43, 0xbfb8aa3b, v47
	v_exp_f32_e32 v42, v42
	v_exp_f32_e32 v43, v43
	v_cvt_pk_bf16_f32 v44, v44, v45
	v_pk_add_f32 v[42:43], v[42:43], 1.0 op_sel_hi:[1,0]
	s_nop 0


; DEV float silu_f(float x) { return x / (1.f + __expf(-x)); }
	s_nop 0


; DEV float silu_f(float x) { return x / (1.f + __expf(-x)); }
	v_rcp_f32_e32 v50, v43
	s_nop 0
	v_mul_f32_e32 v43, v47, v50


; DEV float silu_f(float x) { return x / (1.f + __expf(-x)); }
	s_nop 0


; DEV unsigned cvt_pk_bf16(float lo, float hi) { const f32x2_t v = {lo, hi}; const bf16x2_t b = __builtin_convertvector(v, bf16x2_t); return __builtin_bit_cast(unsigned, b); }
; DEV float bflo(unsigned u) { return __uint_as_float(u << 16); }
; DEV float bfhi(unsigned u) { return __uint_as_float(u & 0xffff0000u); }
; DEV float silu_f(float x) { return x / (1.f + __expf(-x)); }
; template <int WT, class Epi>
; DEV void gemm_tile(const bf16_t* __restrict__ A, int lda, const bf16_t* __restrict__ Bt, int ldb, int K, unsigned char* lds, const Epi& epi) {
;     ...
;                 const int row = wr * WT + mi * 16 + fr, col = wc * WT + ni * 16 + fq * 4;
;                 const f32x4 v = epi.xform(row, col, acc[mi][ni]);
;                 uint2 w; w.x = cvt_pk_bf16(v[0], v[1]); w.y = cvt_pk_bf16(v[2], v[3]);
;                 *(uint2*)(lds + row * RB + ((((col >> 3) ^ (row & (CPR - 1))) << 4) | (((col >> 2) & 1) << 3))) = w;
;     DEV f32x4 xform(int r, int c, f32x4 v) const {
;         const int row = m0 + r, col = n0 + c;
;         const uint2 z = *(const uint2*)(proj + (size_t)row * NPJ + C_ZB + col);
;         const f32x4 s = *(const f32x4*)(scale + col);
;         f32x4 o;
;         o[0] = v[0] * s[0] * silu_f(bflo(z.x)); o[1] = v[1] * s[1] * silu_f(bfhi(z.x));
;         o[2] = v[2] * s[2] * silu_f(bflo(z.y)); o[3] = v[3] * s[3] * silu_f(bfhi(z.y));
;         return o;
;     }
	v_rcp_f32_e32 v47, v42
	s_nop 0
	v_mul_f32_e32 v42, v46, v47
	v_pk_mul_f32 v[42:43], v[48:49], v[42:43]
	s_nop 0
	v_cvt_pk_bf16_f32 v45, v42, v43
	v_add_u32_e32 v42, v65, v77
	ds_write_b64 v42, v[44:45]
	v_lshl_add_u64 v[42:43], v[60:61], 0, v[74:75]
	global_load_dwordx2 v[46:47], v[42:43], off
	s_nop 0
	global_load_dwordx4 v[42:45], v[66:67], off offset:128
	s_waitcnt vmcnt(1)
	v_lshlrev_b32_e32 v50, 16, v46
	v_and_b32_e32 v46, 0xffff0000, v46
	v_mul_f32_e32 v48, 0xbfb8aa3b, v50
	s_waitcnt vmcnt(0)
	v_pk_mul_f32 v[38:39], v[38:39], v[42:43]
	v_mul_f32_e32 v42, 0xbfb8aa3b, v46
	v_exp_f32_e32 v48, v48
	v_exp_f32_e32 v49, v42
	v_pk_mul_f32 v[40:41], v[40:41], v[44:45]
	v_pk_add_f32 v[42:43], v[48:49], 1.0 op_sel_hi:[1,0]
	s_nop 0


; DEV float silu_f(float x) { return x / (1.f + __expf(-x)); }
	s_nop 0


; DEV float silu_f(float x) { return x / (1.f + __expf(-x)); }
	v_rcp_f32_e32 v44, v43
	s_nop 0
	v_mul_f32_e32 v43, v46, v44


; DEV float silu_f(float x) { return x / (1.f + __expf(-x)); }
	s_nop 0


; DEV float bflo(unsigned u) { return __uint_as_float(u << 16); }
; DEV float bfhi(unsigned u) { return __uint_as_float(u & 0xffff0000u); }
; DEV float silu_f(float x) { return x / (1.f + __expf(-x)); }
;     DEV f32x4 xform(int r, int c, f32x4 v) const {
;     ...
;         o[0] = v[0] * s[0] * silu_f(bflo(z.x)); o[1] = v[1] * s[1] * silu_f(bfhi(z.x));
;         o[2] = v[2] * s[2] * silu_f(bflo(z.y)); o[3] = v[3] * s[3] * silu_f(bfhi(z.y));
	v_rcp_f32_e32 v44, v42
	s_nop 0
	v_mul_f32_e32 v42, v50, v44
	v_lshlrev_b32_e32 v44, 16, v47
	v_and_b32_e32 v45, 0xffff0000, v47
	v_pk_mul_f32 v[38:39], v[38:39], v[42:43]
	v_mul_f32_e32 v42, 0xbfb8aa3b, v44
	v_mul_f32_e32 v43, 0xbfb8aa3b, v45
	v_exp_f32_e32 v42, v42
	v_exp_f32_e32 v43, v43
	v_cvt_pk_bf16_f32 v38, v38, v39
	v_pk_add_f32 v[42:43], v[42:43], 1.0 op_sel_hi:[1,0]
	s_nop 0


; DEV float silu_f(float x) { return x / (1.f + __expf(-x)); }
	s_nop 0


; DEV float silu_f(float x) { return x / (1.f + __expf(-x)); }
	v_rcp_f32_e32 v46, v43
	s_nop 0
	v_mul_f32_e32 v43, v45, v46


; DEV float silu_f(float x) { return x / (1.f + __expf(-x)); }
	s_nop 0


; DEV unsigned cvt_pk_bf16(float lo, float hi) { const f32x2_t v = {lo, hi}; const bf16x2_t b = __builtin_convertvector(v, bf16x2_t); return __builtin_bit_cast(unsigned, b); }
; DEV float bflo(unsigned u) { return __uint_as_float(u << 16); }
; DEV float bfhi(unsigned u) { return __uint_as_float(u & 0xffff0000u); }
; DEV float silu_f(float x) { return x / (1.f + __expf(-x)); }
; template <int WT, class Epi>
; DEV void gemm_tile(const bf16_t* __restrict__ A, int lda, const bf16_t* __restrict__ Bt, int ldb, int K, unsigned char* lds, const Epi& epi) {
;     ...
;                 const int row = wr * WT + mi * 16 + fr, col = wc * WT + ni * 16 + fq * 4;
;                 const f32x4 v = epi.xform(row, col, acc[mi][ni]);
;                 uint2 w; w.x = cvt_pk_bf16(v[0], v[1]); w.y = cvt_pk_bf16(v[2], v[3]);
;                 *(uint2*)(lds + row * RB + ((((col >> 3) ^ (row & (CPR - 1))) << 4) | (((col >> 2) & 1) << 3))) = w;
;     DEV f32x4 xform(int r, int c, f32x4 v) const {
;         const int row = m0 + r, col = n0 + c;
;         const uint2 z = *(const uint2*)(proj + (size_t)row * NPJ + C_ZB + col);
;         const f32x4 s = *(const f32x4*)(scale + col);
;         f32x4 o;
;         o[0] = v[0] * s[0] * silu_f(bflo(z.x)); o[1] = v[1] * s[1] * silu_f(bfhi(z.x));
;         o[2] = v[2] * s[2] * silu_f(bflo(z.y)); o[3] = v[3] * s[3] * silu_f(bfhi(z.y));
;         return o;
;     }
	v_rcp_f32_e32 v45, v42
	s_nop 0
	v_mul_f32_e32 v42, v44, v45
	v_pk_mul_f32 v[40:41], v[40:41], v[42:43]
	s_nop 0
	v_cvt_pk_bf16_f32 v39, v40, v41
	v_add_u32_e32 v40, v65, v64
	ds_write_b64 v40, v[38:39]
	v_lshl_add_u64 v[38:39], v[60:61], 0, v[62:63]
	global_load_dwordx2 v[42:43], v[38:39], off
	s_nop 0
	global_load_dwordx4 v[38:41], v[66:67], off offset:192
	s_waitcnt vmcnt(1)
	v_lshlrev_b32_e32 v46, 16, v42
	v_and_b32_e32 v42, 0xffff0000, v42
	v_mul_f32_e32 v44, 0xbfb8aa3b, v46
	s_waitcnt vmcnt(0)
	v_pk_mul_f32 v[34:35], v[34:35], v[38:39]
	v_mul_f32_e32 v38, 0xbfb8aa3b, v42
	v_exp_f32_e32 v44, v44
	v_exp_f32_e32 v45, v38
	v_pk_mul_f32 v[36:37], v[36:37], v[40:41]
	v_pk_add_f32 v[38:39], v[44:45], 1.0 op_sel_hi:[1,0]
	s_nop 0


; DEV float silu_f(float x) { return x / (1.f + __expf(-x)); }
	s_nop 0


; DEV float silu_f(float x) { return x / (1.f + __expf(-x)); }
	v_rcp_f32_e32 v40, v39
	s_nop 0
	v_mul_f32_e32 v39, v42, v40


; DEV float silu_f(float x) { return x / (1.f + __expf(-x)); }
	s_nop 0


; DEV float bflo(unsigned u) { return __uint_as_float(u << 16); }
; DEV float bfhi(unsigned u) { return __uint_as_float(u & 0xffff0000u); }
; DEV float silu_f(float x) { return x / (1.f + __expf(-x)); }
;     DEV f32x4 xform(int r, int c, f32x4 v) const {
;     ...
;         o[0] = v[0] * s[0] * silu_f(bflo(z.x)); o[1] = v[1] * s[1] * silu_f(bfhi(z.x));
;         o[2] = v[2] * s[2] * silu_f(bflo(z.y)); o[3] = v[3] * s[3] * silu_f(bfhi(z.y));
	v_rcp_f32_e32 v40, v38
	s_nop 0
	v_mul_f32_e32 v38, v46, v40
	v_lshlrev_b32_e32 v40, 16, v43
	v_and_b32_e32 v41, 0xffff0000, v43
	v_pk_mul_f32 v[34:35], v[34:35], v[38:39]
	v_mul_f32_e32 v38, 0xbfb8aa3b, v40
	v_mul_f32_e32 v39, 0xbfb8aa3b, v41
	v_exp_f32_e32 v38, v38
	v_exp_f32_e32 v39, v39
	v_cvt_pk_bf16_f32 v34, v34, v35
	v_pk_add_f32 v[38:39], v[38:39], 1.0 op_sel_hi:[1,0]
	s_nop 0


; DEV float silu_f(float x) { return x / (1.f + __expf(-x)); }
	s_nop 0


; DEV float silu_f(float x) { return x / (1.f + __expf(-x)); }
	v_rcp_f32_e32 v42, v39
	s_nop 0
	v_mul_f32_e32 v39, v41, v42


; DEV float silu_f(float x) { return x / (1.f + __expf(-x)); }
	s_nop 0


; DEV unsigned cvt_pk_bf16(float lo, float hi) { const f32x2_t v = {lo, hi}; const bf16x2_t b = __builtin_convertvector(v, bf16x2_t); return __builtin_bit_cast(unsigned, b); }
; DEV float bflo(unsigned u) { return __uint_as_float(u << 16); }
; DEV float bfhi(unsigned u) { return __uint_as_float(u & 0xffff0000u); }
; DEV float silu_f(float x) { return x / (1.f + __expf(-x)); }
; template <int WT, class Epi>
; DEV void gemm_tile(const bf16_t* __restrict__ A, int lda, const bf16_t* __restrict__ Bt, int ldb, int K, unsigned char* lds, const Epi& epi) {
;     ...
;                 const int row = wr * WT + mi * 16 + fr, col = wc * WT + ni * 16 + fq * 4;
;                 const f32x4 v = epi.xform(row, col, acc[mi][ni]);
;                 uint2 w; w.x = cvt_pk_bf16(v[0], v[1]); w.y = cvt_pk_bf16(v[2], v[3]);
;                 *(uint2*)(lds + row * RB + ((((col >> 3) ^ (row & (CPR - 1))) << 4) | (((col >> 2) & 1) << 3))) = w;
;     DEV f32x4 xform(int r, int c, f32x4 v) const {
;         const int row = m0 + r, col = n0 + c;
;         const uint2 z = *(const uint2*)(proj + (size_t)row * NPJ + C_ZB + col);
;         const f32x4 s = *(const f32x4*)(scale + col);
;         f32x4 o;
;         o[0] = v[0] * s[0] * silu_f(bflo(z.x)); o[1] = v[1] * s[1] * silu_f(bfhi(z.x));
;         o[2] = v[2] * s[2] * silu_f(bflo(z.y)); o[3] = v[3] * s[3] * silu_f(bfhi(z.y));
;         return o;
;     }
	v_rcp_f32_e32 v41, v38
	s_nop 0
	v_mul_f32_e32 v38, v40, v41
	v_pk_mul_f32 v[36:37], v[36:37], v[38:39]
	s_nop 0
	v_cvt_pk_bf16_f32 v35, v36, v37
	v_add_u32_e32 v36, v65, v58
	ds_write_b64 v36, v[34:35]
	v_or_b32_e32 v34, 32, v130
	v_lshl_add_u32 v44, v34, 8, s70
	v_add_u32_e32 v34, s81, v34
	v_mad_i64_i32 v[34:35], s[68:69], v34, s79, v[172:173]
	v_lshl_add_u64 v[38:39], v[34:35], 0, s[66:67]
	v_lshl_add_u64 v[34:35], v[38:39], 0, v[68:69]
	global_load_dwordx2 v[40:41], v[34:35], off
	s_nop 0
	global_load_dwordx4 v[34:37], v[70:71], off
	s_waitcnt vmcnt(1)
	v_lshlrev_b32_e32 v45, 16, v40
	v_and_b32_e32 v40, 0xffff0000, v40
	v_mul_f32_e32 v42, 0xbfb8aa3b, v45
	s_waitcnt vmcnt(0)
	v_pk_mul_f32 v[30:31], v[30:31], v[34:35]
	v_mul_f32_e32 v34, 0xbfb8aa3b, v40
	v_exp_f32_e32 v42, v42
	v_exp_f32_e32 v43, v34
	v_pk_mul_f32 v[32:33], v[32:33], v[36:37]
	v_pk_add_f32 v[34:35], v[42:43], 1.0 op_sel_hi:[1,0]
	s_nop 0


; DEV float silu_f(float x) { return x / (1.f + __expf(-x)); }
	s_nop 0


; DEV float silu_f(float x) { return x / (1.f + __expf(-x)); }
	v_rcp_f32_e32 v36, v35
	s_nop 0
	v_mul_f32_e32 v35, v40, v36


; DEV float silu_f(float x) { return x / (1.f + __expf(-x)); }
	s_nop 0


; DEV float bflo(unsigned u) { return __uint_as_float(u << 16); }
; DEV float bfhi(unsigned u) { return __uint_as_float(u & 0xffff0000u); }
; DEV float silu_f(float x) { return x / (1.f + __expf(-x)); }
;     DEV f32x4 xform(int r, int c, f32x4 v) const {
;     ...
;         o[0] = v[0] * s[0] * silu_f(bflo(z.x)); o[1] = v[1] * s[1] * silu_f(bfhi(z.x));
;         o[2] = v[2] * s[2] * silu_f(bflo(z.y)); o[3] = v[3] * s[3] * silu_f(bfhi(z.y));
	v_rcp_f32_e32 v36, v34
	s_nop 0
	v_mul_f32_e32 v34, v45, v36
	v_lshlrev_b32_e32 v36, 16, v41
	v_and_b32_e32 v37, 0xffff0000, v41
	v_pk_mul_f32 v[30:31], v[30:31], v[34:35]
	v_mul_f32_e32 v34, 0xbfb8aa3b, v36
	v_mul_f32_e32 v35, 0xbfb8aa3b, v37
	v_exp_f32_e32 v34, v34
	v_exp_f32_e32 v35, v35
	v_cvt_pk_bf16_f32 v30, v30, v31
	v_pk_add_f32 v[34:35], v[34:35], 1.0 op_sel_hi:[1,0]
	s_nop 0


; DEV float silu_f(float x) { return x / (1.f + __expf(-x)); }
	s_nop 0


; DEV float silu_f(float x) { return x / (1.f + __expf(-x)); }
	v_rcp_f32_e32 v40, v35
	s_nop 0
	v_mul_f32_e32 v35, v37, v40


; DEV float silu_f(float x) { return x / (1.f + __expf(-x)); }
	s_nop 0


; DEV unsigned cvt_pk_bf16(float lo, float hi) { const f32x2_t v = {lo, hi}; const bf16x2_t b = __builtin_convertvector(v, bf16x2_t); return __builtin_bit_cast(unsigned, b); }
; DEV float bflo(unsigned u) { return __uint_as_float(u << 16); }
; DEV float bfhi(unsigned u) { return __uint_as_float(u & 0xffff0000u); }
; DEV float silu_f(float x) { return x / (1.f + __expf(-x)); }
; template <int WT, class Epi>
; DEV void gemm_tile(const bf16_t* __restrict__ A, int lda, const bf16_t* __restrict__ Bt, int ldb, int K, unsigned char* lds, const Epi& epi) {
;     ...
;                 const int row = wr * WT + mi * 16 + fr, col = wc * WT + ni * 16 + fq * 4;
;                 const f32x4 v = epi.xform(row, col, acc[mi][ni]);
;                 uint2 w; w.x = cvt_pk_bf16(v[0], v[1]); w.y = cvt_pk_bf16(v[2], v[3]);
;                 *(uint2*)(lds + row * RB + ((((col >> 3) ^ (row & (CPR - 1))) << 4) | (((col >> 2) & 1) << 3))) = w;
;     DEV f32x4 xform(int r, int c, f32x4 v) const {
;         const int row = m0 + r, col = n0 + c;
;         const uint2 z = *(const uint2*)(proj + (size_t)row * NPJ + C_ZB + col);
;         const f32x4 s = *(const f32x4*)(scale + col);
;         f32x4 o;
;         o[0] = v[0] * s[0] * silu_f(bflo(z.x)); o[1] = v[1] * s[1] * silu_f(bfhi(z.x));
;         o[2] = v[2] * s[2] * silu_f(bflo(z.y)); o[3] = v[3] * s[3] * silu_f(bfhi(z.y));
;         return o;
;     }
	v_rcp_f32_e32 v37, v34
	s_nop 0
	v_mul_f32_e32 v34, v36, v37
	v_pk_mul_f32 v[32:33], v[32:33], v[34:35]
	s_nop 0
	v_cvt_pk_bf16_f32 v31, v32, v33
	v_add_u32_e32 v32, v44, v76
	ds_write_b64 v32, v[30:31]
	v_lshl_add_u64 v[30:31], v[38:39], 0, v[72:73]
	global_load_dwordx2 v[34:35], v[30:31], off
	s_nop 0
	global_load_dwordx4 v[30:33], v[66:67], off offset:64
	s_waitcnt vmcnt(1)
	v_lshlrev_b32_e32 v40, 16, v34
	v_and_b32_e32 v34, 0xffff0000, v34
	v_mul_f32_e32 v36, 0xbfb8aa3b, v40
	s_waitcnt vmcnt(0)
	v_pk_mul_f32 v[26:27], v[26:27], v[30:31]
	v_mul_f32_e32 v30, 0xbfb8aa3b, v34
	v_exp_f32_e32 v36, v36
	v_exp_f32_e32 v37, v30
	v_pk_mul_f32 v[28:29], v[28:29], v[32:33]
	v_pk_add_f32 v[30:31], v[36:37], 1.0 op_sel_hi:[1,0]
	s_nop 0


; DEV float silu_f(float x) { return x / (1.f + __expf(-x)); }
	s_nop 0


; DEV float silu_f(float x) { return x / (1.f + __expf(-x)); }
	v_rcp_f32_e32 v32, v31
	s_nop 0
	v_mul_f32_e32 v31, v34, v32


; DEV float silu_f(float x) { return x / (1.f + __expf(-x)); }
	s_nop 0


; DEV unsigned cvt_pk_bf16(float lo, float hi) { const f32x2_t v = {lo, hi}; const bf16x2_t b = __builtin_convertvector(v, bf16x2_t); return __builtin_bit_cast(unsigned, b); }
; DEV float bflo(unsigned u) { return __uint_as_float(u << 16); }
; DEV float bfhi(unsigned u) { return __uint_as_float(u & 0xffff0000u); }
; DEV float silu_f(float x) { return x / (1.f + __expf(-x)); }
; template <int WT, class Epi>
; DEV void gemm_tile(const bf16_t* __restrict__ A, int lda, const bf16_t* __restrict__ Bt, int ldb, int K, unsigned char* lds, const Epi& epi) {
;     ...
;                 const int row = wr * WT + mi * 16 + fr, col = wc * WT + ni * 16 + fq * 4;
;                 const f32x4 v = epi.xform(row, col, acc[mi][ni]);
;                 uint2 w; w.x = cvt_pk_bf16(v[0], v[1]); w.y = cvt_pk_bf16(v[2], v[3]);
;     DEV f32x4 xform(int r, int c, f32x4 v) const {
;         const int row = m0 + r, col = n0 + c;
;         const uint2 z = *(const uint2*)(proj + (size_t)row * NPJ + C_ZB + col);
;         const f32x4 s = *(const f32x4*)(scale + col);
;         f32x4 o;
;         o[0] = v[0] * s[0] * silu_f(bflo(z.x)); o[1] = v[1] * s[1] * silu_f(bfhi(z.x));
;         o[2] = v[2] * s[2] * silu_f(bflo(z.y)); o[3] = v[3] * s[3] * silu_f(bfhi(z.y));
	v_rcp_f32_e32 v32, v30
	s_nop 0
	v_mul_f32_e32 v30, v40, v32
	v_lshlrev_b32_e32 v32, 16, v35
	v_and_b32_e32 v33, 0xffff0000, v35
	v_pk_mul_f32 v[26:27], v[26:27], v[30:31]
	v_mul_f32_e32 v30, 0xbfb8aa3b, v32
	v_mul_f32_e32 v31, 0xbfb8aa3b, v33
	v_exp_f32_e32 v30, v30
	v_exp_f32_e32 v31, v31
	v_cvt_pk_bf16_f32 v26, v26, v27
	v_pk_add_f32 v[30:31], v[30:31], 1.0 op_sel_hi:[1,0]
	s_nop 0


; DEV float bflo(unsigned u) { return __uint_as_float(u << 16); }
; DEV float bfhi(unsigned u) { return __uint_as_float(u & 0xffff0000u); }
; DEV float silu_f(float x) { return x / (1.f + __expf(-x)); }
;     DEV f32x4 xform(int r, int c, f32x4 v) const {
;     ...
;         o[0] = v[0] * s[0] * silu_f(bflo(z.x)); o[1] = v[1] * s[1] * silu_f(bfhi(z.x));
	s_nop 0


; DEV float bflo(unsigned u) { return __uint_as_float(u << 16); }
; DEV float bfhi(unsigned u) { return __uint_as_float(u & 0xffff0000u); }
; DEV float silu_f(float x) { return x / (1.f + __expf(-x)); }
;     DEV f32x4 xform(int r, int c, f32x4 v) const {
;     ...
;         o[0] = v[0] * s[0] * silu_f(bflo(z.x)); o[1] = v[1] * s[1] * silu_f(bfhi(z.x));
	v_rcp_f32_e32 v34, v31
	s_nop 0
	v_mul_f32_e32 v31, v33, v34


; DEV float bflo(unsigned u) { return __uint_as_float(u << 16); }
; DEV float bfhi(unsigned u) { return __uint_as_float(u & 0xffff0000u); }
; DEV float silu_f(float x) { return x / (1.f + __expf(-x)); }
;     DEV f32x4 xform(int r, int c, f32x4 v) const {
;     ...
;         o[0] = v[0] * s[0] * silu_f(bflo(z.x)); o[1] = v[1] * s[1] * silu_f(bfhi(z.x));
	s_nop 0


; DEV unsigned cvt_pk_bf16(float lo, float hi) { const f32x2_t v = {lo, hi}; const bf16x2_t b = __builtin_convertvector(v, bf16x2_t); return __builtin_bit_cast(unsigned, b); }
; DEV float bflo(unsigned u) { return __uint_as_float(u << 16); }
; DEV float bfhi(unsigned u) { return __uint_as_float(u & 0xffff0000u); }
; DEV float silu_f(float x) { return x / (1.f + __expf(-x)); }
; template <int WT, class Epi>
; DEV void gemm_tile(const bf16_t* __restrict__ A, int lda, const bf16_t* __restrict__ Bt, int ldb, int K, unsigned char* lds, const Epi& epi) {
;     ...
;                 const int row = wr * WT + mi * 16 + fr, col = wc * WT + ni * 16 + fq * 4;
;                 const f32x4 v = epi.xform(row, col, acc[mi][ni]);
;                 uint2 w; w.x = cvt_pk_bf16(v[0], v[1]); w.y = cvt_pk_bf16(v[2], v[3]);
;                 *(uint2*)(lds + row * RB + ((((col >> 3) ^ (row & (CPR - 1))) << 4) | (((col >> 2) & 1) << 3))) = w;
;     DEV f32x4 xform(int r, int c, f32x4 v) const {
;     ...
;         const uint2 z = *(const uint2*)(proj + (size_t)row * NPJ + C_ZB + col);
;         const f32x4 s = *(const f32x4*)(scale + col);
;         f32x4 o;
;         o[0] = v[0] * s[0] * silu_f(bflo(z.x)); o[1] = v[1] * s[1] * silu_f(bfhi(z.x));
;         o[2] = v[2] * s[2] * silu_f(bflo(z.y)); o[3] = v[3] * s[3] * silu_f(bfhi(z.y));
	v_rcp_f32_e32 v33, v30
	s_nop 0
	v_mul_f32_e32 v30, v32, v33
	v_pk_mul_f32 v[28:29], v[28:29], v[30:31]
	s_nop 0
	v_cvt_pk_bf16_f32 v27, v28, v29
	v_add_u32_e32 v28, v44, v77
	ds_write_b64 v28, v[26:27]
	v_lshl_add_u64 v[26:27], v[38:39], 0, v[74:75]
	global_load_dwordx2 v[30:31], v[26:27], off
	s_nop 0
	global_load_dwordx4 v[26:29], v[66:67], off offset:128
	s_waitcnt vmcnt(1)
	v_lshlrev_b32_e32 v34, 16, v30
	v_and_b32_e32 v30, 0xffff0000, v30
	v_mul_f32_e32 v32, 0xbfb8aa3b, v34
	s_waitcnt vmcnt(0)
	v_pk_mul_f32 v[22:23], v[22:23], v[26:27]
	v_mul_f32_e32 v26, 0xbfb8aa3b, v30
	v_exp_f32_e32 v32, v32
	v_exp_f32_e32 v33, v26
	v_pk_mul_f32 v[24:25], v[24:25], v[28:29]
	v_pk_add_f32 v[26:27], v[32:33], 1.0 op_sel_hi:[1,0]
	s_nop 0


; DEV float bflo(unsigned u) { return __uint_as_float(u << 16); }
; DEV float bfhi(unsigned u) { return __uint_as_float(u & 0xffff0000u); }
; DEV float silu_f(float x) { return x / (1.f + __expf(-x)); }
;     DEV f32x4 xform(int r, int c, f32x4 v) const {
;     ...
;         o[0] = v[0] * s[0] * silu_f(bflo(z.x)); o[1] = v[1] * s[1] * silu_f(bfhi(z.x));
	s_nop 0


; DEV float bflo(unsigned u) { return __uint_as_float(u << 16); }
; DEV float bfhi(unsigned u) { return __uint_as_float(u & 0xffff0000u); }
; DEV float silu_f(float x) { return x / (1.f + __expf(-x)); }
;     DEV f32x4 xform(int r, int c, f32x4 v) const {
;     ...
;         o[0] = v[0] * s[0] * silu_f(bflo(z.x)); o[1] = v[1] * s[1] * silu_f(bfhi(z.x));
	v_rcp_f32_e32 v28, v27
	s_nop 0
	v_mul_f32_e32 v27, v30, v28


; DEV float bflo(unsigned u) { return __uint_as_float(u << 16); }
; DEV float bfhi(unsigned u) { return __uint_as_float(u & 0xffff0000u); }
; DEV float silu_f(float x) { return x / (1.f + __expf(-x)); }
;     DEV f32x4 xform(int r, int c, f32x4 v) const {
;     ...
;         o[0] = v[0] * s[0] * silu_f(bflo(z.x)); o[1] = v[1] * s[1] * silu_f(bfhi(z.x));
	s_nop 0


; DEV unsigned cvt_pk_bf16(float lo, float hi) { const f32x2_t v = {lo, hi}; const bf16x2_t b = __builtin_convertvector(v, bf16x2_t); return __builtin_bit_cast(unsigned, b); }
; DEV float bflo(unsigned u) { return __uint_as_float(u << 16); }
; DEV float bfhi(unsigned u) { return __uint_as_float(u & 0xffff0000u); }
; DEV float silu_f(float x) { return x / (1.f + __expf(-x)); }
; template <int WT, class Epi>
; DEV void gemm_tile(const bf16_t* __restrict__ A, int lda, const bf16_t* __restrict__ Bt, int ldb, int K, unsigned char* lds, const Epi& epi) {
;     ...
;                 uint2 w; w.x = cvt_pk_bf16(v[0], v[1]); w.y = cvt_pk_bf16(v[2], v[3]);
;     DEV f32x4 xform(int r, int c, f32x4 v) const {
;     ...
;         o[0] = v[0] * s[0] * silu_f(bflo(z.x)); o[1] = v[1] * s[1] * silu_f(bfhi(z.x));
;         o[2] = v[2] * s[2] * silu_f(bflo(z.y)); o[3] = v[3] * s[3] * silu_f(bfhi(z.y));
	v_rcp_f32_e32 v28, v26
	s_nop 0
	v_mul_f32_e32 v26, v34, v28
	v_lshlrev_b32_e32 v28, 16, v31
	v_and_b32_e32 v29, 0xffff0000, v31
	v_pk_mul_f32 v[22:23], v[22:23], v[26:27]
	v_mul_f32_e32 v26, 0xbfb8aa3b, v28
	v_mul_f32_e32 v27, 0xbfb8aa3b, v29
	v_exp_f32_e32 v26, v26
	v_exp_f32_e32 v27, v27
	v_cvt_pk_bf16_f32 v22, v22, v23
	v_pk_add_f32 v[26:27], v[26:27], 1.0 op_sel_hi:[1,0]
	s_nop 0


; DEV float bflo(unsigned u) { return __uint_as_float(u << 16); }
; DEV float bfhi(unsigned u) { return __uint_as_float(u & 0xffff0000u); }
; DEV float silu_f(float x) { return x / (1.f + __expf(-x)); }
;     DEV f32x4 xform(int r, int c, f32x4 v) const {
;     ...
;         o[2] = v[2] * s[2] * silu_f(bflo(z.y)); o[3] = v[3] * s[3] * silu_f(bfhi(z.y));
	s_nop 0


; DEV float bflo(unsigned u) { return __uint_as_float(u << 16); }
; DEV float bfhi(unsigned u) { return __uint_as_float(u & 0xffff0000u); }
; DEV float silu_f(float x) { return x / (1.f + __expf(-x)); }
;     DEV f32x4 xform(int r, int c, f32x4 v) const {
;     ...
;         o[2] = v[2] * s[2] * silu_f(bflo(z.y)); o[3] = v[3] * s[3] * silu_f(bfhi(z.y));
	v_rcp_f32_e32 v30, v27
	s_nop 0
	v_mul_f32_e32 v27, v29, v30


; DEV float bflo(unsigned u) { return __uint_as_float(u << 16); }
; DEV float bfhi(unsigned u) { return __uint_as_float(u & 0xffff0000u); }
; DEV float silu_f(float x) { return x / (1.f + __expf(-x)); }
;     DEV f32x4 xform(int r, int c, f32x4 v) const {
;     ...
;         o[2] = v[2] * s[2] * silu_f(bflo(z.y)); o[3] = v[3] * s[3] * silu_f(bfhi(z.y));
	s_nop 0


; DEV unsigned cvt_pk_bf16(float lo, float hi) { const f32x2_t v = {lo, hi}; const bf16x2_t b = __builtin_convertvector(v, bf16x2_t); return __builtin_bit_cast(unsigned, b); }
; DEV float bflo(unsigned u) { return __uint_as_float(u << 16); }
; DEV float bfhi(unsigned u) { return __uint_as_float(u & 0xffff0000u); }
; DEV float silu_f(float x) { return x / (1.f + __expf(-x)); }
; template <int WT, class Epi>
; DEV void gemm_tile(const bf16_t* __restrict__ A, int lda, const bf16_t* __restrict__ Bt, int ldb, int K, unsigned char* lds, const Epi& epi) {
;     ...
;                 const int row = wr * WT + mi * 16 + fr, col = wc * WT + ni * 16 + fq * 4;
;                 const f32x4 v = epi.xform(row, col, acc[mi][ni]);
;                 uint2 w; w.x = cvt_pk_bf16(v[0], v[1]); w.y = cvt_pk_bf16(v[2], v[3]);
;                 *(uint2*)(lds + row * RB + ((((col >> 3) ^ (row & (CPR - 1))) << 4) | (((col >> 2) & 1) << 3))) = w;
;     DEV f32x4 xform(int r, int c, f32x4 v) const {
;     ...
;         const uint2 z = *(const uint2*)(proj + (size_t)row * NPJ + C_ZB + col);
;         const f32x4 s = *(const f32x4*)(scale + col);
;         f32x4 o;
;         o[0] = v[0] * s[0] * silu_f(bflo(z.x)); o[1] = v[1] * s[1] * silu_f(bfhi(z.x));
;         o[2] = v[2] * s[2] * silu_f(bflo(z.y)); o[3] = v[3] * s[3] * silu_f(bfhi(z.y));
	v_rcp_f32_e32 v29, v26
	s_nop 0
	v_mul_f32_e32 v26, v28, v29
	v_pk_mul_f32 v[24:25], v[24:25], v[26:27]
	s_nop 0
	v_cvt_pk_bf16_f32 v23, v24, v25
	v_add_u32_e32 v24, v44, v64
	ds_write_b64 v24, v[22:23]
	v_lshl_add_u64 v[22:23], v[38:39], 0, v[62:63]
	global_load_dwordx2 v[26:27], v[22:23], off
	s_nop 0
	global_load_dwordx4 v[22:25], v[66:67], off offset:192
	s_waitcnt vmcnt(1)
	v_lshlrev_b32_e32 v30, 16, v26
	v_and_b32_e32 v26, 0xffff0000, v26
	v_mul_f32_e32 v28, 0xbfb8aa3b, v30
	s_waitcnt vmcnt(0)
	v_pk_mul_f32 v[18:19], v[18:19], v[22:23]
	v_mul_f32_e32 v22, 0xbfb8aa3b, v26
	v_exp_f32_e32 v28, v28
	v_exp_f32_e32 v29, v22
	v_pk_mul_f32 v[20:21], v[20:21], v[24:25]
	v_pk_add_f32 v[22:23], v[28:29], 1.0 op_sel_hi:[1,0]
	s_nop 0


; DEV float bflo(unsigned u) { return __uint_as_float(u << 16); }
; DEV float bfhi(unsigned u) { return __uint_as_float(u & 0xffff0000u); }
; DEV float silu_f(float x) { return x / (1.f + __expf(-x)); }
;     DEV f32x4 xform(int r, int c, f32x4 v) const {
;     ...
;         o[0] = v[0] * s[0] * silu_f(bflo(z.x)); o[1] = v[1] * s[1] * silu_f(bfhi(z.x));
	s_nop 0


; DEV float bflo(unsigned u) { return __uint_as_float(u << 16); }
; DEV float bfhi(unsigned u) { return __uint_as_float(u & 0xffff0000u); }
; DEV float silu_f(float x) { return x / (1.f + __expf(-x)); }
;     DEV f32x4 xform(int r, int c, f32x4 v) const {
;     ...
;         o[0] = v[0] * s[0] * silu_f(bflo(z.x)); o[1] = v[1] * s[1] * silu_f(bfhi(z.x));
	v_rcp_f32_e32 v24, v23
	s_nop 0
	v_mul_f32_e32 v23, v26, v24


; DEV float bflo(unsigned u) { return __uint_as_float(u << 16); }
; DEV float bfhi(unsigned u) { return __uint_as_float(u & 0xffff0000u); }
; DEV float silu_f(float x) { return x / (1.f + __expf(-x)); }
;     DEV f32x4 xform(int r, int c, f32x4 v) const {
;     ...
;         o[0] = v[0] * s[0] * silu_f(bflo(z.x)); o[1] = v[1] * s[1] * silu_f(bfhi(z.x));
	s_nop 0


; DEV unsigned cvt_pk_bf16(float lo, float hi) { const f32x2_t v = {lo, hi}; const bf16x2_t b = __builtin_convertvector(v, bf16x2_t); return __builtin_bit_cast(unsigned, b); }
; DEV float bflo(unsigned u) { return __uint_as_float(u << 16); }
; DEV float bfhi(unsigned u) { return __uint_as_float(u & 0xffff0000u); }
; DEV float silu_f(float x) { return x / (1.f + __expf(-x)); }
; template <int WT, class Epi>
; DEV void gemm_tile(const bf16_t* __restrict__ A, int lda, const bf16_t* __restrict__ Bt, int ldb, int K, unsigned char* lds, const Epi& epi) {
;     ...
;                 uint2 w; w.x = cvt_pk_bf16(v[0], v[1]); w.y = cvt_pk_bf16(v[2], v[3]);
;     DEV f32x4 xform(int r, int c, f32x4 v) const {
;     ...
;         o[0] = v[0] * s[0] * silu_f(bflo(z.x)); o[1] = v[1] * s[1] * silu_f(bfhi(z.x));
;         o[2] = v[2] * s[2] * silu_f(bflo(z.y)); o[3] = v[3] * s[3] * silu_f(bfhi(z.y));
	v_rcp_f32_e32 v24, v22
	s_nop 0
	v_mul_f32_e32 v22, v30, v24
	v_lshlrev_b32_e32 v24, 16, v27
	v_and_b32_e32 v25, 0xffff0000, v27
	v_pk_mul_f32 v[18:19], v[18:19], v[22:23]
	v_mul_f32_e32 v22, 0xbfb8aa3b, v24
	v_mul_f32_e32 v23, 0xbfb8aa3b, v25
	v_exp_f32_e32 v22, v22
	v_exp_f32_e32 v23, v23
	v_cvt_pk_bf16_f32 v18, v18, v19
	v_pk_add_f32 v[22:23], v[22:23], 1.0 op_sel_hi:[1,0]
	s_nop 0


; DEV float bflo(unsigned u) { return __uint_as_float(u << 16); }
; DEV float bfhi(unsigned u) { return __uint_as_float(u & 0xffff0000u); }
; DEV float silu_f(float x) { return x / (1.f + __expf(-x)); }
;     DEV f32x4 xform(int r, int c, f32x4 v) const {
;     ...
;         o[2] = v[2] * s[2] * silu_f(bflo(z.y)); o[3] = v[3] * s[3] * silu_f(bfhi(z.y));
	s_nop 0


; DEV float bflo(unsigned u) { return __uint_as_float(u << 16); }
; DEV float bfhi(unsigned u) { return __uint_as_float(u & 0xffff0000u); }
; DEV float silu_f(float x) { return x / (1.f + __expf(-x)); }
;     DEV f32x4 xform(int r, int c, f32x4 v) const {
;     ...
;         o[2] = v[2] * s[2] * silu_f(bflo(z.y)); o[3] = v[3] * s[3] * silu_f(bfhi(z.y));
	v_rcp_f32_e32 v26, v23
	s_nop 0
	v_mul_f32_e32 v23, v25, v26


; DEV float bflo(unsigned u) { return __uint_as_float(u << 16); }
; DEV float bfhi(unsigned u) { return __uint_as_float(u & 0xffff0000u); }
; DEV float silu_f(float x) { return x / (1.f + __expf(-x)); }
;     DEV f32x4 xform(int r, int c, f32x4 v) const {
;     ...
;         o[2] = v[2] * s[2] * silu_f(bflo(z.y)); o[3] = v[3] * s[3] * silu_f(bfhi(z.y));
	s_nop 0


; DEV unsigned cvt_pk_bf16(float lo, float hi) { const f32x2_t v = {lo, hi}; const bf16x2_t b = __builtin_convertvector(v, bf16x2_t); return __builtin_bit_cast(unsigned, b); }
; DEV float bflo(unsigned u) { return __uint_as_float(u << 16); }
; DEV float bfhi(unsigned u) { return __uint_as_float(u & 0xffff0000u); }
; DEV float silu_f(float x) { return x / (1.f + __expf(-x)); }
; template <int WT, class Epi>
; DEV void gemm_tile(const bf16_t* __restrict__ A, int lda, const bf16_t* __restrict__ Bt, int ldb, int K, unsigned char* lds, const Epi& epi) {
;     ...
;                 const int row = wr * WT + mi * 16 + fr, col = wc * WT + ni * 16 + fq * 4;
;                 const f32x4 v = epi.xform(row, col, acc[mi][ni]);
;                 uint2 w; w.x = cvt_pk_bf16(v[0], v[1]); w.y = cvt_pk_bf16(v[2], v[3]);
;                 *(uint2*)(lds + row * RB + ((((col >> 3) ^ (row & (CPR - 1))) << 4) | (((col >> 2) & 1) << 3))) = w;
;     DEV f32x4 xform(int r, int c, f32x4 v) const {
;         const int row = m0 + r, col = n0 + c;
;         const uint2 z = *(const uint2*)(proj + (size_t)row * NPJ + C_ZB + col);
;         const f32x4 s = *(const f32x4*)(scale + col);
;         f32x4 o;
;         o[0] = v[0] * s[0] * silu_f(bflo(z.x)); o[1] = v[1] * s[1] * silu_f(bfhi(z.x));
;         o[2] = v[2] * s[2] * silu_f(bflo(z.y)); o[3] = v[3] * s[3] * silu_f(bfhi(z.y));
	v_rcp_f32_e32 v25, v22
	s_nop 0
	v_mul_f32_e32 v22, v24, v25
	v_pk_mul_f32 v[20:21], v[20:21], v[22:23]
	s_nop 0
	v_cvt_pk_bf16_f32 v19, v20, v21
	v_add_u32_e32 v20, v44, v58
	ds_write_b64 v20, v[18:19]
	v_or_b32_e32 v18, 48, v130
	v_lshl_add_u32 v28, v18, 8, s70
	v_add_u32_e32 v18, s81, v18
	v_mad_i64_i32 v[18:19], s[68:69], v18, s79, v[172:173]
	v_lshl_add_u64 v[22:23], v[18:19], 0, s[66:67]
	v_lshl_add_u64 v[18:19], v[22:23], 0, v[68:69]
	global_load_dwordx2 v[24:25], v[18:19], off
	s_nop 0
	global_load_dwordx4 v[18:21], v[70:71], off
	s_waitcnt vmcnt(1)
	v_lshlrev_b32_e32 v29, 16, v24
	v_and_b32_e32 v24, 0xffff0000, v24
	v_mul_f32_e32 v26, 0xbfb8aa3b, v29
	s_waitcnt vmcnt(0)
	v_pk_mul_f32 v[14:15], v[14:15], v[18:19]
	v_mul_f32_e32 v18, 0xbfb8aa3b, v24
	v_exp_f32_e32 v26, v26
	v_exp_f32_e32 v27, v18
	v_pk_mul_f32 v[16:17], v[16:17], v[20:21]
	v_pk_add_f32 v[18:19], v[26:27], 1.0 op_sel_hi:[1,0]
	s_nop 0


; DEV float bflo(unsigned u) { return __uint_as_float(u << 16); }
; DEV float bfhi(unsigned u) { return __uint_as_float(u & 0xffff0000u); }
; DEV float silu_f(float x) { return x / (1.f + __expf(-x)); }
;     DEV f32x4 xform(int r, int c, f32x4 v) const {
;     ...
;         o[0] = v[0] * s[0] * silu_f(bflo(z.x)); o[1] = v[1] * s[1] * silu_f(bfhi(z.x));
	s_nop 0


; DEV float bflo(unsigned u) { return __uint_as_float(u << 16); }
; DEV float bfhi(unsigned u) { return __uint_as_float(u & 0xffff0000u); }
; DEV float silu_f(float x) { return x / (1.f + __expf(-x)); }
;     DEV f32x4 xform(int r, int c, f32x4 v) const {
;     ...
;         o[0] = v[0] * s[0] * silu_f(bflo(z.x)); o[1] = v[1] * s[1] * silu_f(bfhi(z.x));
	v_rcp_f32_e32 v20, v19
	s_nop 0
	v_mul_f32_e32 v19, v24, v20


; DEV float bflo(unsigned u) { return __uint_as_float(u << 16); }
; DEV float bfhi(unsigned u) { return __uint_as_float(u & 0xffff0000u); }
; DEV float silu_f(float x) { return x / (1.f + __expf(-x)); }
;     DEV f32x4 xform(int r, int c, f32x4 v) const {
;     ...
;         o[0] = v[0] * s[0] * silu_f(bflo(z.x)); o[1] = v[1] * s[1] * silu_f(bfhi(z.x));
	s_nop 0


; DEV unsigned cvt_pk_bf16(float lo, float hi) { const f32x2_t v = {lo, hi}; const bf16x2_t b = __builtin_convertvector(v, bf16x2_t); return __builtin_bit_cast(unsigned, b); }
; DEV float bflo(unsigned u) { return __uint_as_float(u << 16); }
; DEV float bfhi(unsigned u) { return __uint_as_float(u & 0xffff0000u); }
; DEV float silu_f(float x) { return x / (1.f + __expf(-x)); }
; template <int WT, class Epi>
; DEV void gemm_tile(const bf16_t* __restrict__ A, int lda, const bf16_t* __restrict__ Bt, int ldb, int K, unsigned char* lds, const Epi& epi) {
;     ...
;                 uint2 w; w.x = cvt_pk_bf16(v[0], v[1]); w.y = cvt_pk_bf16(v[2], v[3]);
;     DEV f32x4 xform(int r, int c, f32x4 v) const {
;     ...
;         o[0] = v[0] * s[0] * silu_f(bflo(z.x)); o[1] = v[1] * s[1] * silu_f(bfhi(z.x));
;         o[2] = v[2] * s[2] * silu_f(bflo(z.y)); o[3] = v[3] * s[3] * silu_f(bfhi(z.y));
	v_rcp_f32_e32 v20, v18
	s_nop 0
	v_mul_f32_e32 v18, v29, v20
	v_lshlrev_b32_e32 v20, 16, v25
	v_and_b32_e32 v21, 0xffff0000, v25
	v_pk_mul_f32 v[14:15], v[14:15], v[18:19]
	v_mul_f32_e32 v18, 0xbfb8aa3b, v20
	v_mul_f32_e32 v19, 0xbfb8aa3b, v21
	v_exp_f32_e32 v18, v18
	v_exp_f32_e32 v19, v19
	v_cvt_pk_bf16_f32 v14, v14, v15
	v_pk_add_f32 v[18:19], v[18:19], 1.0 op_sel_hi:[1,0]
	s_nop 0


; DEV float bflo(unsigned u) { return __uint_as_float(u << 16); }
; DEV float bfhi(unsigned u) { return __uint_as_float(u & 0xffff0000u); }
; DEV float silu_f(float x) { return x / (1.f + __expf(-x)); }
;     DEV f32x4 xform(int r, int c, f32x4 v) const {
;     ...
;         o[2] = v[2] * s[2] * silu_f(bflo(z.y)); o[3] = v[3] * s[3] * silu_f(bfhi(z.y));
	s_nop 0


; DEV float bflo(unsigned u) { return __uint_as_float(u << 16); }
; DEV float bfhi(unsigned u) { return __uint_as_float(u & 0xffff0000u); }
; DEV float silu_f(float x) { return x / (1.f + __expf(-x)); }
;     DEV f32x4 xform(int r, int c, f32x4 v) const {
;     ...
;         o[2] = v[2] * s[2] * silu_f(bflo(z.y)); o[3] = v[3] * s[3] * silu_f(bfhi(z.y));
	v_rcp_f32_e32 v24, v19
	s_nop 0
	v_mul_f32_e32 v19, v21, v24


; DEV float bflo(unsigned u) { return __uint_as_float(u << 16); }
; DEV float bfhi(unsigned u) { return __uint_as_float(u & 0xffff0000u); }
; DEV float silu_f(float x) { return x / (1.f + __expf(-x)); }
;     DEV f32x4 xform(int r, int c, f32x4 v) const {
;     ...
;         o[2] = v[2] * s[2] * silu_f(bflo(z.y)); o[3] = v[3] * s[3] * silu_f(bfhi(z.y));
	s_nop 0


; DEV unsigned cvt_pk_bf16(float lo, float hi) { const f32x2_t v = {lo, hi}; const bf16x2_t b = __builtin_convertvector(v, bf16x2_t); return __builtin_bit_cast(unsigned, b); }
; DEV float bflo(unsigned u) { return __uint_as_float(u << 16); }
; DEV float bfhi(unsigned u) { return __uint_as_float(u & 0xffff0000u); }
; DEV float silu_f(float x) { return x / (1.f + __expf(-x)); }
; template <int WT, class Epi>
; DEV void gemm_tile(const bf16_t* __restrict__ A, int lda, const bf16_t* __restrict__ Bt, int ldb, int K, unsigned char* lds, const Epi& epi) {
;     ...
;                 const int row = wr * WT + mi * 16 + fr, col = wc * WT + ni * 16 + fq * 4;
;                 const f32x4 v = epi.xform(row, col, acc[mi][ni]);
;                 uint2 w; w.x = cvt_pk_bf16(v[0], v[1]); w.y = cvt_pk_bf16(v[2], v[3]);
;                 *(uint2*)(lds + row * RB + ((((col >> 3) ^ (row & (CPR - 1))) << 4) | (((col >> 2) & 1) << 3))) = w;
;     DEV f32x4 xform(int r, int c, f32x4 v) const {
;     ...
;         const uint2 z = *(const uint2*)(proj + (size_t)row * NPJ + C_ZB + col);
;         const f32x4 s = *(const f32x4*)(scale + col);
;         f32x4 o;
;         o[0] = v[0] * s[0] * silu_f(bflo(z.x)); o[1] = v[1] * s[1] * silu_f(bfhi(z.x));
;         o[2] = v[2] * s[2] * silu_f(bflo(z.y)); o[3] = v[3] * s[3] * silu_f(bfhi(z.y));
	v_rcp_f32_e32 v21, v18
	s_nop 0
	v_mul_f32_e32 v18, v20, v21
	v_pk_mul_f32 v[16:17], v[16:17], v[18:19]
	s_nop 0
	v_cvt_pk_bf16_f32 v15, v16, v17
	v_add_u32_e32 v16, v28, v76
	ds_write_b64 v16, v[14:15]
	v_lshl_add_u64 v[14:15], v[22:23], 0, v[72:73]
	global_load_dwordx2 v[18:19], v[14:15], off
	s_nop 0
	global_load_dwordx4 v[14:17], v[66:67], off offset:64
	s_waitcnt vmcnt(1)
	v_lshlrev_b32_e32 v24, 16, v18
	v_and_b32_e32 v18, 0xffff0000, v18
	v_mul_f32_e32 v20, 0xbfb8aa3b, v24
	s_waitcnt vmcnt(0)
	v_pk_mul_f32 v[10:11], v[10:11], v[14:15]
	v_mul_f32_e32 v14, 0xbfb8aa3b, v18
	v_exp_f32_e32 v20, v20
	v_exp_f32_e32 v21, v14
	v_pk_mul_f32 v[12:13], v[12:13], v[16:17]
	v_pk_add_f32 v[14:15], v[20:21], 1.0 op_sel_hi:[1,0]
	s_nop 0


; DEV float bflo(unsigned u) { return __uint_as_float(u << 16); }
; DEV float bfhi(unsigned u) { return __uint_as_float(u & 0xffff0000u); }
; DEV float silu_f(float x) { return x / (1.f + __expf(-x)); }
;     DEV f32x4 xform(int r, int c, f32x4 v) const {
;     ...
;         o[0] = v[0] * s[0] * silu_f(bflo(z.x)); o[1] = v[1] * s[1] * silu_f(bfhi(z.x));
	s_nop 0


; DEV float bflo(unsigned u) { return __uint_as_float(u << 16); }
; DEV float bfhi(unsigned u) { return __uint_as_float(u & 0xffff0000u); }
; DEV float silu_f(float x) { return x / (1.f + __expf(-x)); }
;     DEV f32x4 xform(int r, int c, f32x4 v) const {
;     ...
;         o[0] = v[0] * s[0] * silu_f(bflo(z.x)); o[1] = v[1] * s[1] * silu_f(bfhi(z.x));
	v_rcp_f32_e32 v16, v15
	s_nop 0
	v_mul_f32_e32 v15, v18, v16


; DEV float bflo(unsigned u) { return __uint_as_float(u << 16); }
; DEV float bfhi(unsigned u) { return __uint_as_float(u & 0xffff0000u); }
; DEV float silu_f(float x) { return x / (1.f + __expf(-x)); }
;     DEV f32x4 xform(int r, int c, f32x4 v) const {
;     ...
;         o[0] = v[0] * s[0] * silu_f(bflo(z.x)); o[1] = v[1] * s[1] * silu_f(bfhi(z.x));
	s_nop 0


; DEV unsigned cvt_pk_bf16(float lo, float hi) { const f32x2_t v = {lo, hi}; const bf16x2_t b = __builtin_convertvector(v, bf16x2_t); return __builtin_bit_cast(unsigned, b); }
; DEV float bflo(unsigned u) { return __uint_as_float(u << 16); }
; DEV float bfhi(unsigned u) { return __uint_as_float(u & 0xffff0000u); }
; DEV float silu_f(float x) { return x / (1.f + __expf(-x)); }
; template <int WT, class Epi>
; DEV void gemm_tile(const bf16_t* __restrict__ A, int lda, const bf16_t* __restrict__ Bt, int ldb, int K, unsigned char* lds, const Epi& epi) {
;     ...
;                 uint2 w; w.x = cvt_pk_bf16(v[0], v[1]); w.y = cvt_pk_bf16(v[2], v[3]);
;     DEV f32x4 xform(int r, int c, f32x4 v) const {
;     ...
;         o[0] = v[0] * s[0] * silu_f(bflo(z.x)); o[1] = v[1] * s[1] * silu_f(bfhi(z.x));
;         o[2] = v[2] * s[2] * silu_f(bflo(z.y)); o[3] = v[3] * s[3] * silu_f(bfhi(z.y));
	v_rcp_f32_e32 v16, v14
	s_nop 0
	v_mul_f32_e32 v14, v24, v16
	v_lshlrev_b32_e32 v16, 16, v19
	v_and_b32_e32 v17, 0xffff0000, v19
	v_pk_mul_f32 v[10:11], v[10:11], v[14:15]
	v_mul_f32_e32 v14, 0xbfb8aa3b, v16
	v_mul_f32_e32 v15, 0xbfb8aa3b, v17
	v_exp_f32_e32 v14, v14
	v_exp_f32_e32 v15, v15
	v_cvt_pk_bf16_f32 v10, v10, v11
	v_pk_add_f32 v[14:15], v[14:15], 1.0 op_sel_hi:[1,0]
	s_nop 0


; DEV float bflo(unsigned u) { return __uint_as_float(u << 16); }
; DEV float bfhi(unsigned u) { return __uint_as_float(u & 0xffff0000u); }
; DEV float silu_f(float x) { return x / (1.f + __expf(-x)); }
;     DEV f32x4 xform(int r, int c, f32x4 v) const {
;     ...
;         o[2] = v[2] * s[2] * silu_f(bflo(z.y)); o[3] = v[3] * s[3] * silu_f(bfhi(z.y));
	s_nop 0


; DEV float bflo(unsigned u) { return __uint_as_float(u << 16); }
; DEV float bfhi(unsigned u) { return __uint_as_float(u & 0xffff0000u); }
; DEV float silu_f(float x) { return x / (1.f + __expf(-x)); }
;     DEV f32x4 xform(int r, int c, f32x4 v) const {
;     ...
;         o[2] = v[2] * s[2] * silu_f(bflo(z.y)); o[3] = v[3] * s[3] * silu_f(bfhi(z.y));
	v_rcp_f32_e32 v18, v15
	s_nop 0
	v_mul_f32_e32 v15, v17, v18


; DEV float bflo(unsigned u) { return __uint_as_float(u << 16); }
; DEV float bfhi(unsigned u) { return __uint_as_float(u & 0xffff0000u); }
; DEV float silu_f(float x) { return x / (1.f + __expf(-x)); }
;     DEV f32x4 xform(int r, int c, f32x4 v) const {
;     ...
;         o[2] = v[2] * s[2] * silu_f(bflo(z.y)); o[3] = v[3] * s[3] * silu_f(bfhi(z.y));
	s_nop 0


; DEV unsigned cvt_pk_bf16(float lo, float hi) { const f32x2_t v = {lo, hi}; const bf16x2_t b = __builtin_convertvector(v, bf16x2_t); return __builtin_bit_cast(unsigned, b); }
; DEV float bflo(unsigned u) { return __uint_as_float(u << 16); }
; DEV float bfhi(unsigned u) { return __uint_as_float(u & 0xffff0000u); }
; DEV float silu_f(float x) { return x / (1.f + __expf(-x)); }
; template <int WT, class Epi>
; DEV void gemm_tile(const bf16_t* __restrict__ A, int lda, const bf16_t* __restrict__ Bt, int ldb, int K, unsigned char* lds, const Epi& epi) {
;     ...
;                 const int row = wr * WT + mi * 16 + fr, col = wc * WT + ni * 16 + fq * 4;
;                 const f32x4 v = epi.xform(row, col, acc[mi][ni]);
;                 uint2 w; w.x = cvt_pk_bf16(v[0], v[1]); w.y = cvt_pk_bf16(v[2], v[3]);
;                 *(uint2*)(lds + row * RB + ((((col >> 3) ^ (row & (CPR - 1))) << 4) | (((col >> 2) & 1) << 3))) = w;
;     DEV f32x4 xform(int r, int c, f32x4 v) const {
;     ...
;         const uint2 z = *(const uint2*)(proj + (size_t)row * NPJ + C_ZB + col);
;         const f32x4 s = *(const f32x4*)(scale + col);
;         f32x4 o;
;         o[0] = v[0] * s[0] * silu_f(bflo(z.x)); o[1] = v[1] * s[1] * silu_f(bfhi(z.x));
;         o[2] = v[2] * s[2] * silu_f(bflo(z.y)); o[3] = v[3] * s[3] * silu_f(bfhi(z.y));
	v_rcp_f32_e32 v17, v14
	s_nop 0
	v_mul_f32_e32 v14, v16, v17
	v_pk_mul_f32 v[12:13], v[12:13], v[14:15]
	s_nop 0
	v_cvt_pk_bf16_f32 v11, v12, v13
	v_add_u32_e32 v12, v28, v77
	ds_write_b64 v12, v[10:11]
	v_lshl_add_u64 v[10:11], v[22:23], 0, v[74:75]
	global_load_dwordx2 v[14:15], v[10:11], off
	s_nop 0
	global_load_dwordx4 v[10:13], v[66:67], off offset:128
	s_waitcnt vmcnt(1)
	v_lshlrev_b32_e32 v18, 16, v14
	v_and_b32_e32 v14, 0xffff0000, v14
	v_mul_f32_e32 v16, 0xbfb8aa3b, v18
	s_waitcnt vmcnt(0)
	v_pk_mul_f32 v[6:7], v[6:7], v[10:11]
	v_mul_f32_e32 v10, 0xbfb8aa3b, v14
	v_exp_f32_e32 v16, v16
	v_exp_f32_e32 v17, v10
	v_pk_mul_f32 v[8:9], v[8:9], v[12:13]
	v_pk_add_f32 v[10:11], v[16:17], 1.0 op_sel_hi:[1,0]
	s_nop 0


; DEV float bflo(unsigned u) { return __uint_as_float(u << 16); }
; DEV float bfhi(unsigned u) { return __uint_as_float(u & 0xffff0000u); }
; DEV float silu_f(float x) { return x / (1.f + __expf(-x)); }
;     DEV f32x4 xform(int r, int c, f32x4 v) const {
;     ...
;         o[0] = v[0] * s[0] * silu_f(bflo(z.x)); o[1] = v[1] * s[1] * silu_f(bfhi(z.x));
	s_nop 0


; DEV float bflo(unsigned u) { return __uint_as_float(u << 16); }
; DEV float bfhi(unsigned u) { return __uint_as_float(u & 0xffff0000u); }
; DEV float silu_f(float x) { return x / (1.f + __expf(-x)); }
;     DEV f32x4 xform(int r, int c, f32x4 v) const {
;     ...
;         o[0] = v[0] * s[0] * silu_f(bflo(z.x)); o[1] = v[1] * s[1] * silu_f(bfhi(z.x));
	v_rcp_f32_e32 v12, v11
	s_nop 0
	v_mul_f32_e32 v11, v14, v12


; DEV float bflo(unsigned u) { return __uint_as_float(u << 16); }
; DEV float bfhi(unsigned u) { return __uint_as_float(u & 0xffff0000u); }
; DEV float silu_f(float x) { return x / (1.f + __expf(-x)); }
;     DEV f32x4 xform(int r, int c, f32x4 v) const {
;     ...
;         o[0] = v[0] * s[0] * silu_f(bflo(z.x)); o[1] = v[1] * s[1] * silu_f(bfhi(z.x));
	s_nop 0


; DEV unsigned cvt_pk_bf16(float lo, float hi) { const f32x2_t v = {lo, hi}; const bf16x2_t b = __builtin_convertvector(v, bf16x2_t); return __builtin_bit_cast(unsigned, b); }
; DEV float bflo(unsigned u) { return __uint_as_float(u << 16); }
; DEV float bfhi(unsigned u) { return __uint_as_float(u & 0xffff0000u); }
; DEV float silu_f(float x) { return x / (1.f + __expf(-x)); }
; template <int WT, class Epi>
; DEV void gemm_tile(const bf16_t* __restrict__ A, int lda, const bf16_t* __restrict__ Bt, int ldb, int K, unsigned char* lds, const Epi& epi) {
;     ...
;                 uint2 w; w.x = cvt_pk_bf16(v[0], v[1]); w.y = cvt_pk_bf16(v[2], v[3]);
;     DEV f32x4 xform(int r, int c, f32x4 v) const {
;     ...
;         o[0] = v[0] * s[0] * silu_f(bflo(z.x)); o[1] = v[1] * s[1] * silu_f(bfhi(z.x));
;         o[2] = v[2] * s[2] * silu_f(bflo(z.y)); o[3] = v[3] * s[3] * silu_f(bfhi(z.y));
	v_rcp_f32_e32 v12, v10
	s_nop 0
	v_mul_f32_e32 v10, v18, v12
	v_lshlrev_b32_e32 v12, 16, v15
	v_and_b32_e32 v13, 0xffff0000, v15
	v_pk_mul_f32 v[6:7], v[6:7], v[10:11]
	v_mul_f32_e32 v10, 0xbfb8aa3b, v12
	v_mul_f32_e32 v11, 0xbfb8aa3b, v13
	v_exp_f32_e32 v10, v10
	v_exp_f32_e32 v11, v11
	v_cvt_pk_bf16_f32 v6, v6, v7
	v_pk_add_f32 v[10:11], v[10:11], 1.0 op_sel_hi:[1,0]
	s_nop 0


; DEV float bflo(unsigned u) { return __uint_as_float(u << 16); }
; DEV float bfhi(unsigned u) { return __uint_as_float(u & 0xffff0000u); }
; DEV float silu_f(float x) { return x / (1.f + __expf(-x)); }
;     DEV f32x4 xform(int r, int c, f32x4 v) const {
;     ...
;         o[2] = v[2] * s[2] * silu_f(bflo(z.y)); o[3] = v[3] * s[3] * silu_f(bfhi(z.y));
	s_nop 0


; DEV float bflo(unsigned u) { return __uint_as_float(u << 16); }
; DEV float bfhi(unsigned u) { return __uint_as_float(u & 0xffff0000u); }
; DEV float silu_f(float x) { return x / (1.f + __expf(-x)); }
;     DEV f32x4 xform(int r, int c, f32x4 v) const {
;     ...
;         o[2] = v[2] * s[2] * silu_f(bflo(z.y)); o[3] = v[3] * s[3] * silu_f(bfhi(z.y));
	v_rcp_f32_e32 v14, v11
	s_nop 0
	v_mul_f32_e32 v11, v13, v14


; DEV float bflo(unsigned u) { return __uint_as_float(u << 16); }
; DEV float bfhi(unsigned u) { return __uint_as_float(u & 0xffff0000u); }
; DEV float silu_f(float x) { return x / (1.f + __expf(-x)); }
;     DEV f32x4 xform(int r, int c, f32x4 v) const {
;     ...
;         o[2] = v[2] * s[2] * silu_f(bflo(z.y)); o[3] = v[3] * s[3] * silu_f(bfhi(z.y));
	s_nop 0


; DEV unsigned cvt_pk_bf16(float lo, float hi) { const f32x2_t v = {lo, hi}; const bf16x2_t b = __builtin_convertvector(v, bf16x2_t); return __builtin_bit_cast(unsigned, b); }
; DEV float bflo(unsigned u) { return __uint_as_float(u << 16); }
; DEV float bfhi(unsigned u) { return __uint_as_float(u & 0xffff0000u); }
; DEV float silu_f(float x) { return x / (1.f + __expf(-x)); }
; template <int WT, class Epi>
; DEV void gemm_tile(const bf16_t* __restrict__ A, int lda, const bf16_t* __restrict__ Bt, int ldb, int K, unsigned char* lds, const Epi& epi) {
;     ...
;                 const int row = wr * WT + mi * 16 + fr, col = wc * WT + ni * 16 + fq * 4;
;                 const f32x4 v = epi.xform(row, col, acc[mi][ni]);
;                 uint2 w; w.x = cvt_pk_bf16(v[0], v[1]); w.y = cvt_pk_bf16(v[2], v[3]);
;                 *(uint2*)(lds + row * RB + ((((col >> 3) ^ (row & (CPR - 1))) << 4) | (((col >> 2) & 1) << 3))) = w;
;     DEV f32x4 xform(int r, int c, f32x4 v) const {
;     ...
;         const uint2 z = *(const uint2*)(proj + (size_t)row * NPJ + C_ZB + col);
;         const f32x4 s = *(const f32x4*)(scale + col);
;         f32x4 o;
;         o[0] = v[0] * s[0] * silu_f(bflo(z.x)); o[1] = v[1] * s[1] * silu_f(bfhi(z.x));
;         o[2] = v[2] * s[2] * silu_f(bflo(z.y)); o[3] = v[3] * s[3] * silu_f(bfhi(z.y));
	v_rcp_f32_e32 v13, v10
	s_nop 0
	v_mul_f32_e32 v10, v12, v13
	v_pk_mul_f32 v[8:9], v[8:9], v[10:11]
	s_nop 0
	v_cvt_pk_bf16_f32 v7, v8, v9
	v_add_u32_e32 v8, v28, v64
	ds_write_b64 v8, v[6:7]
	v_lshl_add_u64 v[6:7], v[22:23], 0, v[62:63]
	global_load_dwordx2 v[10:11], v[6:7], off
	s_nop 0
	global_load_dwordx4 v[6:9], v[66:67], off offset:192
	s_waitcnt vmcnt(1)
	v_lshlrev_b32_e32 v14, 16, v10
	v_and_b32_e32 v10, 0xffff0000, v10
	v_mul_f32_e32 v12, 0xbfb8aa3b, v14
	s_waitcnt vmcnt(0)
	v_pk_mul_f32 v[2:3], v[2:3], v[6:7]
	v_mul_f32_e32 v6, 0xbfb8aa3b, v10
	v_exp_f32_e32 v12, v12
	v_exp_f32_e32 v13, v6
	v_pk_mul_f32 v[4:5], v[4:5], v[8:9]
	v_pk_add_f32 v[6:7], v[12:13], 1.0 op_sel_hi:[1,0]
	s_nop 0


; DEV float bflo(unsigned u) { return __uint_as_float(u << 16); }
; DEV float bfhi(unsigned u) { return __uint_as_float(u & 0xffff0000u); }
; DEV float silu_f(float x) { return x / (1.f + __expf(-x)); }
;     DEV f32x4 xform(int r, int c, f32x4 v) const {
;     ...
;         o[0] = v[0] * s[0] * silu_f(bflo(z.x)); o[1] = v[1] * s[1] * silu_f(bfhi(z.x));
	s_nop 0


; DEV float bflo(unsigned u) { return __uint_as_float(u << 16); }
; DEV float bfhi(unsigned u) { return __uint_as_float(u & 0xffff0000u); }
; DEV float silu_f(float x) { return x / (1.f + __expf(-x)); }
;     DEV f32x4 xform(int r, int c, f32x4 v) const {
;     ...
;         o[0] = v[0] * s[0] * silu_f(bflo(z.x)); o[1] = v[1] * s[1] * silu_f(bfhi(z.x));
	v_rcp_f32_e32 v8, v7
	s_nop 0
	v_mul_f32_e32 v7, v10, v8


; DEV float bflo(unsigned u) { return __uint_as_float(u << 16); }
; DEV float bfhi(unsigned u) { return __uint_as_float(u & 0xffff0000u); }
; DEV float silu_f(float x) { return x / (1.f + __expf(-x)); }
;     DEV f32x4 xform(int r, int c, f32x4 v) const {
;     ...
;         o[0] = v[0] * s[0] * silu_f(bflo(z.x)); o[1] = v[1] * s[1] * silu_f(bfhi(z.x));
	s_nop 0


; DEV unsigned cvt_pk_bf16(float lo, float hi) { const f32x2_t v = {lo, hi}; const bf16x2_t b = __builtin_convertvector(v, bf16x2_t); return __builtin_bit_cast(unsigned, b); }
; DEV float bflo(unsigned u) { return __uint_as_float(u << 16); }
; DEV float bfhi(unsigned u) { return __uint_as_float(u & 0xffff0000u); }
; DEV float silu_f(float x) { return x / (1.f + __expf(-x)); }
; template <int WT, class Epi>
; DEV void gemm_tile(const bf16_t* __restrict__ A, int lda, const bf16_t* __restrict__ Bt, int ldb, int K, unsigned char* lds, const Epi& epi) {
;     ...
;                 uint2 w; w.x = cvt_pk_bf16(v[0], v[1]); w.y = cvt_pk_bf16(v[2], v[3]);
;     DEV f32x4 xform(int r, int c, f32x4 v) const {
;     ...
;         o[0] = v[0] * s[0] * silu_f(bflo(z.x)); o[1] = v[1] * s[1] * silu_f(bfhi(z.x));
;         o[2] = v[2] * s[2] * silu_f(bflo(z.y)); o[3] = v[3] * s[3] * silu_f(bfhi(z.y));
	v_rcp_f32_e32 v8, v6
	s_nop 0
	v_mul_f32_e32 v6, v14, v8
	v_lshlrev_b32_e32 v8, 16, v11
	v_and_b32_e32 v9, 0xffff0000, v11
	v_pk_mul_f32 v[2:3], v[2:3], v[6:7]
	v_mul_f32_e32 v6, 0xbfb8aa3b, v8
	v_mul_f32_e32 v7, 0xbfb8aa3b, v9
	v_exp_f32_e32 v6, v6
	v_exp_f32_e32 v7, v7
	v_cvt_pk_bf16_f32 v2, v2, v3
	v_pk_add_f32 v[6:7], v[6:7], 1.0 op_sel_hi:[1,0]
	s_nop 0


; DEV float bflo(unsigned u) { return __uint_as_float(u << 16); }
; DEV float bfhi(unsigned u) { return __uint_as_float(u & 0xffff0000u); }
; DEV float silu_f(float x) { return x / (1.f + __expf(-x)); }
;     DEV f32x4 xform(int r, int c, f32x4 v) const {
;     ...
;         o[2] = v[2] * s[2] * silu_f(bflo(z.y)); o[3] = v[3] * s[3] * silu_f(bfhi(z.y));
	s_nop 0


; DEV float bflo(unsigned u) { return __uint_as_float(u << 16); }
; DEV float bfhi(unsigned u) { return __uint_as_float(u & 0xffff0000u); }
; DEV float silu_f(float x) { return x / (1.f + __expf(-x)); }
;     DEV f32x4 xform(int r, int c, f32x4 v) const {
;     ...
;         o[2] = v[2] * s[2] * silu_f(bflo(z.y)); o[3] = v[3] * s[3] * silu_f(bfhi(z.y));
	v_rcp_f32_e32 v10, v7
	s_nop 0
	v_mul_f32_e32 v7, v9, v10


; DEV float bflo(unsigned u) { return __uint_as_float(u << 16); }
; DEV float bfhi(unsigned u) { return __uint_as_float(u & 0xffff0000u); }
; DEV float silu_f(float x) { return x / (1.f + __expf(-x)); }
;     DEV f32x4 xform(int r, int c, f32x4 v) const {
;     ...
;         o[2] = v[2] * s[2] * silu_f(bflo(z.y)); o[3] = v[3] * s[3] * silu_f(bfhi(z.y));
	s_nop 0


; DEV float bflo(unsigned u) { return __uint_as_float(u << 16); }
; DEV float bfhi(unsigned u) { return __uint_as_float(u & 0xffff0000u); }
; DEV float silu_f(float x) { return x / (1.f + __expf(-x)); }
; template <int WT, class Epi>
; DEV void gemm_tile(const bf16_t* __restrict__ A, int lda, const bf16_t* __restrict__ Bt, int ldb, int K, unsigned char* lds, const Epi& epi) {
;     ...
; #pragma unroll
;         for (int i = 0; i < (2 * WT * CPR) / 256; ++i) {
;             const int idx = tid + 256 * i, row = idx / CPR, cp = idx % CPR, c = cp ^ (row & (CPR - 1));
;             const uint4 d = *(const uint4*)(lds + row * RB + (cp << 4));
;             *(uint4*)(epi.obase + (size_t)row * epi.old + c * 8) = epi.finish(row, c * 8, d);
;         }
;         __syncthreads();
;     DEV f32x4 xform(int r, int c, f32x4 v) const {
;     ...
;         o[2] = v[2] * s[2] * silu_f(bflo(z.y)); o[3] = v[3] * s[3] * silu_f(bfhi(z.y));
	v_rcp_f32_e32 v9, v6
	s_nop 0
	v_mul_f32_e32 v6, v8, v9
	v_pk_mul_f32 v[4:5], v[4:5], v[6:7]
	s_nop 0
	v_cvt_pk_bf16_f32 v3, v4, v5
	v_add_u32_e32 v4, v28, v58
	ds_write_b64 v4, v[2:3]
	v_ashrrev_i32_e32 v2, 31, v137
	v_lshrrev_b32_e32 v2, 28, v2
	v_add_u32_e32 v2, v137, v2
	v_ashrrev_i32_e32 v3, 4, v2
	v_and_b32_e32 v2, -16, v2
	v_sub_u32_e32 v2, v137, v2
	v_bitop3_b32 v4, v3, v2, 15 bitop3:0x6c
	v_lshlrev_b32_e32 v5, 8, v3
	v_lshlrev_b32_e32 v2, 4, v2
	v_add3_u32 v8, s70, v5, v2
	v_lshlrev_b32_e32 v2, 3, v4
	v_mad_i64_i32 v[4:5], s[68:69], v3, s80, v[132:133]
	v_ashrrev_i32_e32 v3, 31, v2
	s_waitcnt lgkmcnt(0)
	s_barrier
	v_lshl_add_u64 v[6:7], v[2:3], 1, v[4:5]
	ds_read_b128 v[2:5], v8
	s_waitcnt lgkmcnt(0)
	global_store_dwordx4 v[6:7], v[2:5], off offset:2048 sc1
	s_nop 1
	v_add_u32_e32 v2, 0x100, v137
	v_ashrrev_i32_e32 v3, 31, v2
	v_lshrrev_b32_e32 v3, 28, v3
	v_add_u32_e32 v3, v2, v3
	v_ashrrev_i32_e32 v4, 4, v3
	v_and_b32_e32 v3, -16, v3
	v_sub_u32_e32 v2, v2, v3
	v_bitop3_b32 v3, v4, v2, 15 bitop3:0x6c
	v_lshlrev_b32_e32 v5, 8, v4
	v_lshlrev_b32_e32 v2, 4, v2
	v_add3_u32 v8, s70, v5, v2
	v_lshlrev_b32_e32 v2, 3, v3
	v_mad_i64_i32 v[4:5], s[68:69], v4, s80, v[132:133]
	v_ashrrev_i32_e32 v3, 31, v2
	v_lshl_add_u64 v[6:7], v[2:3], 1, v[4:5]
	ds_read_b128 v[2:5], v8
	s_waitcnt lgkmcnt(0)
	global_store_dwordx4 v[6:7], v[2:5], off offset:2048 sc1
	s_nop 1
	v_add_u32_e32 v2, 0x200, v137
	v_ashrrev_i32_e32 v3, 31, v2
	v_lshrrev_b32_e32 v3, 28, v3
	v_add_u32_e32 v3, v2, v3
	v_ashrrev_i32_e32 v4, 4, v3
	v_and_b32_e32 v3, -16, v3
	v_sub_u32_e32 v2, v2, v3
	v_bitop3_b32 v3, v4, v2, 15 bitop3:0x6c
	v_lshlrev_b32_e32 v5, 8, v4
	v_lshlrev_b32_e32 v2, 4, v2
	v_add3_u32 v8, s70, v5, v2
	v_lshlrev_b32_e32 v2, 3, v3
	v_mad_i64_i32 v[4:5], s[68:69], v4, s80, v[132:133]
	v_ashrrev_i32_e32 v3, 31, v2
	v_lshl_add_u64 v[6:7], v[2:3], 1, v[4:5]
	ds_read_b128 v[2:5], v8
	s_waitcnt lgkmcnt(0)
	global_store_dwordx4 v[6:7], v[2:5], off offset:2048 sc1
	s_nop 1
	v_add_u32_e32 v2, 0x300, v137
	v_ashrrev_i32_e32 v3, 31, v2
	v_lshrrev_b32_e32 v3, 28, v3
	v_add_u32_e32 v3, v2, v3
	v_ashrrev_i32_e32 v4, 4, v3
	v_and_b32_e32 v3, -16, v3
	v_sub_u32_e32 v2, v2, v3
	v_bitop3_b32 v3, v4, v2, 15 bitop3:0x6c
	v_lshlrev_b32_e32 v5, 8, v4
	v_lshlrev_b32_e32 v2, 4, v2
	v_add3_u32 v8, s70, v5, v2
	v_lshlrev_b32_e32 v2, 3, v3
	v_mad_i64_i32 v[4:5], s[68:69], v4, s80, v[132:133]
	v_ashrrev_i32_e32 v3, 31, v2
	v_lshl_add_u64 v[6:7], v[2:3], 1, v[4:5]
	ds_read_b128 v[2:5], v8
	s_waitcnt lgkmcnt(0)
	global_store_dwordx4 v[6:7], v[2:5], off offset:2048 sc1
	s_nop 1
	v_add_u32_e32 v2, 0x400, v137
	v_ashrrev_i32_e32 v3, 31, v2
	v_lshrrev_b32_e32 v3, 28, v3
	v_add_u32_e32 v3, v2, v3
	v_ashrrev_i32_e32 v4, 4, v3
	v_and_b32_e32 v3, -16, v3
	v_sub_u32_e32 v2, v2, v3
	v_bitop3_b32 v3, v4, v2, 15 bitop3:0x6c
	v_lshlrev_b32_e32 v5, 8, v4
	v_lshlrev_b32_e32 v2, 4, v2
	v_add3_u32 v8, s70, v5, v2
	v_lshlrev_b32_e32 v2, 3, v3
	v_mad_i64_i32 v[4:5], s[68:69], v4, s80, v[132:133]
	v_ashrrev_i32_e32 v3, 31, v2
	v_lshl_add_u64 v[6:7], v[2:3], 1, v[4:5]
	ds_read_b128 v[2:5], v8
	s_waitcnt lgkmcnt(0)
	global_store_dwordx4 v[6:7], v[2:5], off offset:2048 sc1
	s_nop 1
	v_add_u32_e32 v2, 0x500, v137
	v_ashrrev_i32_e32 v3, 31, v2
	v_lshrrev_b32_e32 v3, 28, v3
	v_add_u32_e32 v3, v2, v3
	v_ashrrev_i32_e32 v4, 4, v3
	v_and_b32_e32 v3, -16, v3
	v_sub_u32_e32 v2, v2, v3
	v_bitop3_b32 v3, v4, v2, 15 bitop3:0x6c
	v_lshlrev_b32_e32 v5, 8, v4
	v_lshlrev_b32_e32 v2, 4, v2
	v_add3_u32 v8, s70, v5, v2
	v_lshlrev_b32_e32 v2, 3, v3
	v_mad_i64_i32 v[4:5], s[68:69], v4, s80, v[132:133]
	v_ashrrev_i32_e32 v3, 31, v2
	v_lshl_add_u64 v[6:7], v[2:3], 1, v[4:5]
	ds_read_b128 v[2:5], v8
	s_waitcnt lgkmcnt(0)
	global_store_dwordx4 v[6:7], v[2:5], off offset:2048 sc1
	s_nop 1
	v_add_u32_e32 v2, 0x600, v137
	v_ashrrev_i32_e32 v3, 31, v2
	v_lshrrev_b32_e32 v3, 28, v3
	v_add_u32_e32 v3, v2, v3
	v_ashrrev_i32_e32 v4, 4, v3
	v_and_b32_e32 v3, -16, v3
	v_sub_u32_e32 v2, v2, v3
	v_bitop3_b32 v3, v4, v2, 15 bitop3:0x6c
	v_lshlrev_b32_e32 v5, 8, v4
	v_lshlrev_b32_e32 v2, 4, v2
	v_add3_u32 v8, s70, v5, v2
	v_lshlrev_b32_e32 v2, 3, v3
	v_mad_i64_i32 v[4:5], s[68:69], v4, s80, v[132:133]
	v_ashrrev_i32_e32 v3, 31, v2
	v_lshl_add_u64 v[6:7], v[2:3], 1, v[4:5]
	ds_read_b128 v[2:5], v8
	s_waitcnt lgkmcnt(0)
	global_store_dwordx4 v[6:7], v[2:5], off offset:2048 sc1
	s_nop 1
	v_add_u32_e32 v2, 0x700, v137
	v_ashrrev_i32_e32 v3, 31, v2
	v_lshrrev_b32_e32 v3, 28, v3
	v_add_u32_e32 v3, v2, v3
	v_ashrrev_i32_e32 v4, 4, v3
	v_and_b32_e32 v3, -16, v3
	v_sub_u32_e32 v2, v2, v3
	v_bitop3_b32 v3, v4, v2, 15 bitop3:0x6c
	v_lshlrev_b32_e32 v5, 8, v4
	v_lshlrev_b32_e32 v2, 4, v2
	v_add3_u32 v8, s70, v5, v2
	v_lshlrev_b32_e32 v2, 3, v3
	v_mad_i64_i32 v[4:5], s[68:69], v4, s80, v[132:133]
	v_ashrrev_i32_e32 v3, 31, v2
	v_lshl_add_u64 v[6:7], v[2:3], 1, v[4:5]
	ds_read_b128 v[2:5], v8
	s_waitcnt lgkmcnt(0)
	global_store_dwordx4 v[6:7], v[2:5], off offset:2048 sc1
	s_barrier
	s_cbranch_scc1 .LBB0_870

; DEV unsigned cvt_pk_bf16(float lo, float hi) { const f32x2_t v = {lo, hi}; const bf16x2_t b = __builtin_convertvector(v, bf16x2_t); return __builtin_bit_cast(unsigned, b); }
; DEV float bflo(unsigned u) { return __uint_as_float(u << 16); }
; DEV float bfhi(unsigned u) { return __uint_as_float(u & 0xffff0000u); }
; DEV float silu_f(float x) { return x / (1.f + __expf(-x)); }
; __global__ void __launch_bounds__(512) hymba_fwd(Params p) {
;     ...
;         for (int i = bid * 512 + tid; i < TP * 8 * 16; i += G * 512) {
;             const int l16 = i & 15, rh = i >> 4, h = rh & 7, row = rh >> 3;
;             const float* op = obuf + (size_t)row * 1024 + h * 128 + l16 * 8;
;             const f32x4 a = __builtin_nontemporal_load((const f32x4*)op), b4 = __builtin_nontemporal_load((const f32x4*)(op + 4));
;             float ss = a[0] * a[0] + a[1] * a[1] + a[2] * a[2] + a[3] * a[3] + b4[0] * b4[0] + b4[1] * b4[1] + b4[2] * b4[2] + b4[3] * b4[3];
;             ss += __shfl_xor(ss, 1); ss += __shfl_xor(ss, 2); ss += __shfl_xor(ss, 4); ss += __shfl_xor(ss, 8);
;             const float rs = rsqrtf(ss * (1.f / 128.f) + EPS);
;             const f32x4 g0 = *(const f32x4*)(p.in[13] + l16 * 8), g1 = *(const f32x4*)(p.in[13] + l16 * 8 + 4);
;             const uint4 z = *(const uint4*)(proj + (size_t)row * NPJ + C_ZA + h * 128 + l16 * 8);
;             uint4 o;
;             o.x = cvt_pk_bf16(a[0] * rs * g0[0] * silu_f(bflo(z.x)), a[1] * rs * g0[1] * silu_f(bfhi(z.x)));
.LBB0_945:
	v_ashrrev_i32_e32 v6, 7, v1
	v_ashrrev_i32_e32 v7, 31, v6
	v_and_b32_e32 v22, 0x380, v12
	v_mad_i64_i32 v[32:33], s[4:5], v6, s31, v[172:173]
	v_mad_i64_i32 v[34:35], s[4:5], v6, s35, v[174:175]
	v_lshlrev_b64 v[6:7], 12, v[6:7]
	v_and_b32_e32 v14, 0x78, v12
	v_lshlrev_b32_e32 v4, 2, v22
	v_lshl_add_u64 v[6:7], v[2:3], 0, v[6:7]
	v_lshl_add_u64 v[6:7], v[6:7], 0, v[4:5]
	v_lshlrev_b32_e32 v4, 2, v14
	v_lshl_add_u64 v[6:7], v[6:7], 0, v[4:5]
	v_lshlrev_b32_e32 v30, 1, v14
	s_waitcnt lgkmcnt(0)
	global_load_dwordx4 v[14:17], v4, s[22:23] offset:16
	global_load_dwordx4 v[18:21], v4, s[22:23]
	v_lshlrev_b32_e32 v4, 1, v22
	global_load_dwordx4 v[22:25], v[6:7], off offset:16 nt
	global_load_dwordx4 v[26:29], v[6:7], off nt
	v_mov_b32_e32 v31, v5
	v_add_u32_e32 v1, s26, v1
	v_lshl_add_u64 v[6:7], v[32:33], 0, v[4:5]
	v_cmp_lt_i32_e32 vcc, s36, v1
	v_lshl_add_u64 v[6:7], v[6:7], 0, v[30:31]
	s_or_b64 s[24:25], vcc, s[24:25]
	v_add_co_u32_e32 v6, vcc, s34, v6
	v_lshl_add_u64 v[32:33], v[34:35], 0, v[4:5]
	s_nop 0
	v_addc_co_u32_e32 v7, vcc, 0, v7, vcc
	v_lshl_add_u64 v[34:35], v[32:33], 0, v[30:31]
	global_load_dwordx4 v[30:33], v[6:7], off offset:2048
	v_add_u32_e32 v12, s27, v12
	s_waitcnt vmcnt(2)
	v_pk_mul_f32 v[38:39], v[22:23], v[22:23]
	s_waitcnt vmcnt(1)
	v_mul_f32_e32 v4, v27, v27
	v_pk_mul_f32 v[6:7], v[28:29], v[28:29]
	v_fmac_f32_e32 v4, v26, v26
	v_add_f32_e32 v4, v6, v4
	v_add_f32_e32 v4, v7, v4
	v_add_f32_e32 v4, v38, v4
	v_pk_mul_f32 v[36:37], v[24:25], v[24:25]
	v_add_f32_e32 v4, v39, v4
	v_add_f32_e32 v4, v36, v4
	v_add_f32_e32 v4, v37, v4
	s_waitcnt vmcnt(0)
	v_and_b32_e32 v47, 0xffff0000, v33
	v_lshlrev_b32_e32 v40, 16, v30
	v_and_b32_e32 v41, 0xffff0000, v30
	v_mul_f32_e32 v48, 0xbfb8aa3b, v47
	v_lshlrev_b32_e32 v46, 16, v33
	v_mul_f32_e32 v6, 0xbfb8aa3b, v40
	v_mul_f32_e32 v7, 0xbfb8aa3b, v41
	v_exp_f32_e32 v39, v48
	ds_bpermute_b32 v48, v8, v4
	v_lshlrev_b32_e32 v42, 16, v31
	v_and_b32_e32 v43, 0xffff0000, v31
	v_mul_f32_e32 v38, 0xbfb8aa3b, v46
	v_exp_f32_e32 v6, v6
	v_exp_f32_e32 v7, v7
	v_mul_f32_e32 v30, 0xbfb8aa3b, v42
	v_mul_f32_e32 v31, 0xbfb8aa3b, v43
	v_exp_f32_e32 v38, v38
	v_lshlrev_b32_e32 v44, 16, v32
	v_and_b32_e32 v45, 0xffff0000, v32
	v_exp_f32_e32 v30, v30
	v_exp_f32_e32 v31, v31
	v_mul_f32_e32 v32, 0xbfb8aa3b, v44
	v_mul_f32_e32 v33, 0xbfb8aa3b, v45
	v_exp_f32_e32 v32, v32
	v_exp_f32_e32 v33, v33
	v_pk_add_f32 v[6:7], v[6:7], 1.0 op_sel_hi:[1,0]
	s_waitcnt lgkmcnt(0)
	v_add_f32_e32 v4, v4, v48
	v_pk_add_f32 v[36:37], v[38:39], 1.0 op_sel_hi:[1,0]

; DEV unsigned cvt_pk_bf16(float lo, float hi) { const f32x2_t v = {lo, hi}; const bf16x2_t b = __builtin_convertvector(v, bf16x2_t); return __builtin_bit_cast(unsigned, b); }
; DEV float bflo(unsigned u) { return __uint_as_float(u << 16); }
; DEV float bfhi(unsigned u) { return __uint_as_float(u & 0xffff0000u); }
; DEV float silu_f(float x) { return x / (1.f + __expf(-x)); }
; __global__ void __launch_bounds__(512) hymba_fwd(Params p) {
;     ...
;             ss += __shfl_xor(ss, 1); ss += __shfl_xor(ss, 2); ss += __shfl_xor(ss, 4); ss += __shfl_xor(ss, 8);
;     ...
;             o.x = cvt_pk_bf16(a[0] * rs * g0[0] * silu_f(bflo(z.x)), a[1] * rs * g0[1] * silu_f(bfhi(z.x)));
;             o.y = cvt_pk_bf16(a[2] * rs * g0[2] * silu_f(bflo(z.y)), a[3] * rs * g0[3] * silu_f(bfhi(z.y)));
	ds_bpermute_b32 v48, v9, v4
	v_pk_add_f32 v[30:31], v[30:31], 1.0 op_sel_hi:[1,0]


; DEV unsigned cvt_pk_bf16(float lo, float hi) { const f32x2_t v = {lo, hi}; const bf16x2_t b = __builtin_convertvector(v, bf16x2_t); return __builtin_bit_cast(unsigned, b); }
; DEV float bflo(unsigned u) { return __uint_as_float(u << 16); }
; DEV float bfhi(unsigned u) { return __uint_as_float(u & 0xffff0000u); }
; DEV float silu_f(float x) { return x / (1.f + __expf(-x)); }
; __global__ void __launch_bounds__(512) hymba_fwd(Params p) {
;     ...
;             o.z = cvt_pk_bf16(b4[0] * rs * g1[0] * silu_f(bflo(z.z)), b4[1] * rs * g1[1] * silu_f(bfhi(z.z)));
	v_pk_add_f32 v[32:33], v[32:33], 1.0 op_sel_hi:[1,0]


; __global__ void __launch_bounds__(512) hymba_fwd(Params p) {
;     ...
;             ss += __shfl_xor(ss, 1); ss += __shfl_xor(ss, 2); ss += __shfl_xor(ss, 4); ss += __shfl_xor(ss, 8);
	s_waitcnt lgkmcnt(0)
	v_add_f32_e32 v4, v4, v48


; __global__ void __launch_bounds__(512) hymba_fwd(Params p) {
;     ...
;             ss += __shfl_xor(ss, 1); ss += __shfl_xor(ss, 2); ss += __shfl_xor(ss, 4); ss += __shfl_xor(ss, 8);
	ds_bpermute_b32 v48, v10, v4


; __global__ void __launch_bounds__(512) hymba_fwd(Params p) {
;     ...
;             ss += __shfl_xor(ss, 1); ss += __shfl_xor(ss, 2); ss += __shfl_xor(ss, 4); ss += __shfl_xor(ss, 8);
	s_mov_b64 vcc, s[4:5]
	s_waitcnt lgkmcnt(0)
	v_add_f32_e32 v4, v4, v48


; DEV unsigned cvt_pk_bf16(float lo, float hi) { const f32x2_t v = {lo, hi}; const bf16x2_t b = __builtin_convertvector(v, bf16x2_t); return __builtin_bit_cast(unsigned, b); }
; DEV float bflo(unsigned u) { return __uint_as_float(u << 16); }
; DEV float bfhi(unsigned u) { return __uint_as_float(u & 0xffff0000u); }
; DEV float silu_f(float x) { return x / (1.f + __expf(-x)); }
; __global__ void __launch_bounds__(512) hymba_fwd(Params p) {
;     ...
;             o.x = cvt_pk_bf16(a[0] * rs * g0[0] * silu_f(bflo(z.x)), a[1] * rs * g0[1] * silu_f(bfhi(z.x)));
	v_rcp_f32_e32 v38, v7
	s_nop 0
	v_mul_f32_e32 v7, v41, v38

; DEV unsigned cvt_pk_bf16(float lo, float hi) { const f32x2_t v = {lo, hi}; const bf16x2_t b = __builtin_convertvector(v, bf16x2_t); return __builtin_bit_cast(unsigned, b); }
; DEV float bflo(unsigned u) { return __uint_as_float(u << 16); }
; DEV float bfhi(unsigned u) { return __uint_as_float(u & 0xffff0000u); }
; DEV float silu_f(float x) { return x / (1.f + __expf(-x)); }
; __global__ void __launch_bounds__(512) hymba_fwd(Params p) {
;     ...
;             ss += __shfl_xor(ss, 1); ss += __shfl_xor(ss, 2); ss += __shfl_xor(ss, 4); ss += __shfl_xor(ss, 8);
;             const float rs = rsqrtf(ss * (1.f / 128.f) + EPS);
;             const f32x4 g0 = *(const f32x4*)(p.in[13] + l16 * 8), g1 = *(const f32x4*)(p.in[13] + l16 * 8 + 4);
;             const uint4 z = *(const uint4*)(proj + (size_t)row * NPJ + C_ZA + h * 128 + l16 * 8);
;             uint4 o;
;             o.x = cvt_pk_bf16(a[0] * rs * g0[0] * silu_f(bflo(z.x)), a[1] * rs * g0[1] * silu_f(bfhi(z.x)));
;             o.y = cvt_pk_bf16(a[2] * rs * g0[2] * silu_f(bflo(z.y)), a[3] * rs * g0[3] * silu_f(bfhi(z.y)));
;             o.z = cvt_pk_bf16(b4[0] * rs * g1[0] * silu_f(bflo(z.z)), b4[1] * rs * g1[1] * silu_f(bfhi(z.z)));
;             o.w = cvt_pk_bf16(b4[2] * rs * g1[2] * silu_f(bflo(z.w)), b4[3] * rs * g1[3] * silu_f(bfhi(z.w)));
	s_mov_b64 vcc, s[6:7]
	ds_bpermute_b32 v39, v11, v4


; DEV unsigned cvt_pk_bf16(float lo, float hi) { const f32x2_t v = {lo, hi}; const bf16x2_t b = __builtin_convertvector(v, bf16x2_t); return __builtin_bit_cast(unsigned, b); }
; DEV float bflo(unsigned u) { return __uint_as_float(u << 16); }
; DEV float bfhi(unsigned u) { return __uint_as_float(u & 0xffff0000u); }
; DEV float silu_f(float x) { return x / (1.f + __expf(-x)); }
; __global__ void __launch_bounds__(512) hymba_fwd(Params p) {
;     ...
;             ss += __shfl_xor(ss, 1); ss += __shfl_xor(ss, 2); ss += __shfl_xor(ss, 4); ss += __shfl_xor(ss, 8);
;             const float rs = rsqrtf(ss * (1.f / 128.f) + EPS);
;             const f32x4 g0 = *(const f32x4*)(p.in[13] + l16 * 8), g1 = *(const f32x4*)(p.in[13] + l16 * 8 + 4);
;             const uint4 z = *(const uint4*)(proj + (size_t)row * NPJ + C_ZA + h * 128 + l16 * 8);
;             uint4 o;
;             o.x = cvt_pk_bf16(a[0] * rs * g0[0] * silu_f(bflo(z.x)), a[1] * rs * g0[1] * silu_f(bfhi(z.x)));
;             o.y = cvt_pk_bf16(a[2] * rs * g0[2] * silu_f(bflo(z.y)), a[3] * rs * g0[3] * silu_f(bfhi(z.y)));
;             o.z = cvt_pk_bf16(b4[0] * rs * g1[0] * silu_f(bflo(z.z)), b4[1] * rs * g1[1] * silu_f(bfhi(z.z)));
;             o.w = cvt_pk_bf16(b4[2] * rs * g1[2] * silu_f(bflo(z.w)), b4[3] * rs * g1[3] * silu_f(bfhi(z.w)));
	v_rcp_f32_e32 v38, v6
	s_nop 0
	v_mul_f32_e32 v6, v40, v38

; DEV unsigned cvt_pk_bf16(float lo, float hi) { const f32x2_t v = {lo, hi}; const bf16x2_t b = __builtin_convertvector(v, bf16x2_t); return __builtin_bit_cast(unsigned, b); }
; DEV float bflo(unsigned u) { return __uint_as_float(u << 16); }
; DEV float bfhi(unsigned u) { return __uint_as_float(u & 0xffff0000u); }
; DEV float silu_f(float x) { return x / (1.f + __expf(-x)); }
; __global__ void __launch_bounds__(512) hymba_fwd(Params p) {
;     ...
;             ss += __shfl_xor(ss, 1); ss += __shfl_xor(ss, 2); ss += __shfl_xor(ss, 4); ss += __shfl_xor(ss, 8);
;             const float rs = rsqrtf(ss * (1.f / 128.f) + EPS);
;             const f32x4 g0 = *(const f32x4*)(p.in[13] + l16 * 8), g1 = *(const f32x4*)(p.in[13] + l16 * 8 + 4);
;             const uint4 z = *(const uint4*)(proj + (size_t)row * NPJ + C_ZA + h * 128 + l16 * 8);
;             uint4 o;
;             o.x = cvt_pk_bf16(a[0] * rs * g0[0] * silu_f(bflo(z.x)), a[1] * rs * g0[1] * silu_f(bfhi(z.x)));
;             o.y = cvt_pk_bf16(a[2] * rs * g0[2] * silu_f(bflo(z.y)), a[3] * rs * g0[3] * silu_f(bfhi(z.y)));
;             o.z = cvt_pk_bf16(b4[0] * rs * g1[0] * silu_f(bflo(z.z)), b4[1] * rs * g1[1] * silu_f(bfhi(z.z)));
;             o.w = cvt_pk_bf16(b4[2] * rs * g1[2] * silu_f(bflo(z.w)), b4[3] * rs * g1[3] * silu_f(bfhi(z.w)));
	s_mov_b64 vcc, s[8:9]


; DEV unsigned cvt_pk_bf16(float lo, float hi) { const f32x2_t v = {lo, hi}; const bf16x2_t b = __builtin_convertvector(v, bf16x2_t); return __builtin_bit_cast(unsigned, b); }
; DEV float bflo(unsigned u) { return __uint_as_float(u << 16); }
; DEV float bfhi(unsigned u) { return __uint_as_float(u & 0xffff0000u); }
; DEV float silu_f(float x) { return x / (1.f + __expf(-x)); }
; __global__ void __launch_bounds__(512) hymba_fwd(Params p) {
;     ...
;             ss += __shfl_xor(ss, 1); ss += __shfl_xor(ss, 2); ss += __shfl_xor(ss, 4); ss += __shfl_xor(ss, 8);
;             const float rs = rsqrtf(ss * (1.f / 128.f) + EPS);
;             const f32x4 g0 = *(const f32x4*)(p.in[13] + l16 * 8), g1 = *(const f32x4*)(p.in[13] + l16 * 8 + 4);
;             const uint4 z = *(const uint4*)(proj + (size_t)row * NPJ + C_ZA + h * 128 + l16 * 8);
;             uint4 o;
;             o.x = cvt_pk_bf16(a[0] * rs * g0[0] * silu_f(bflo(z.x)), a[1] * rs * g0[1] * silu_f(bfhi(z.x)));
;             o.y = cvt_pk_bf16(a[2] * rs * g0[2] * silu_f(bflo(z.y)), a[3] * rs * g0[3] * silu_f(bfhi(z.y)));
;             o.z = cvt_pk_bf16(b4[0] * rs * g1[0] * silu_f(bflo(z.z)), b4[1] * rs * g1[1] * silu_f(bfhi(z.z)));
;             o.w = cvt_pk_bf16(b4[2] * rs * g1[2] * silu_f(bflo(z.w)), b4[3] * rs * g1[3] * silu_f(bfhi(z.w)));
	v_rcp_f32_e32 v38, v31
	s_nop 0
	v_mul_f32_e32 v31, v43, v38

; DEV unsigned cvt_pk_bf16(float lo, float hi) { const f32x2_t v = {lo, hi}; const bf16x2_t b = __builtin_convertvector(v, bf16x2_t); return __builtin_bit_cast(unsigned, b); }
; DEV float bflo(unsigned u) { return __uint_as_float(u << 16); }
; DEV float bfhi(unsigned u) { return __uint_as_float(u & 0xffff0000u); }
; DEV float silu_f(float x) { return x / (1.f + __expf(-x)); }
; __global__ void __launch_bounds__(512) hymba_fwd(Params p) {
;     ...
;             ss += __shfl_xor(ss, 1); ss += __shfl_xor(ss, 2); ss += __shfl_xor(ss, 4); ss += __shfl_xor(ss, 8);
;             const float rs = rsqrtf(ss * (1.f / 128.f) + EPS);
;             const f32x4 g0 = *(const f32x4*)(p.in[13] + l16 * 8), g1 = *(const f32x4*)(p.in[13] + l16 * 8 + 4);
;             const uint4 z = *(const uint4*)(proj + (size_t)row * NPJ + C_ZA + h * 128 + l16 * 8);
;             uint4 o;
;             o.x = cvt_pk_bf16(a[0] * rs * g0[0] * silu_f(bflo(z.x)), a[1] * rs * g0[1] * silu_f(bfhi(z.x)));
;             o.y = cvt_pk_bf16(a[2] * rs * g0[2] * silu_f(bflo(z.y)), a[3] * rs * g0[3] * silu_f(bfhi(z.y)));
;             o.z = cvt_pk_bf16(b4[0] * rs * g1[0] * silu_f(bflo(z.z)), b4[1] * rs * g1[1] * silu_f(bfhi(z.z)));
;             o.w = cvt_pk_bf16(b4[2] * rs * g1[2] * silu_f(bflo(z.w)), b4[3] * rs * g1[3] * silu_f(bfhi(z.w)));
	s_mov_b64 vcc, s[10:11]


; DEV unsigned cvt_pk_bf16(float lo, float hi) { const f32x2_t v = {lo, hi}; const bf16x2_t b = __builtin_convertvector(v, bf16x2_t); return __builtin_bit_cast(unsigned, b); }
; DEV float bflo(unsigned u) { return __uint_as_float(u << 16); }
; DEV float bfhi(unsigned u) { return __uint_as_float(u & 0xffff0000u); }
; DEV float silu_f(float x) { return x / (1.f + __expf(-x)); }
; __global__ void __launch_bounds__(512) hymba_fwd(Params p) {
;     ...
;             ss += __shfl_xor(ss, 1); ss += __shfl_xor(ss, 2); ss += __shfl_xor(ss, 4); ss += __shfl_xor(ss, 8);
;             const float rs = rsqrtf(ss * (1.f / 128.f) + EPS);
;             const f32x4 g0 = *(const f32x4*)(p.in[13] + l16 * 8), g1 = *(const f32x4*)(p.in[13] + l16 * 8 + 4);
;             const uint4 z = *(const uint4*)(proj + (size_t)row * NPJ + C_ZA + h * 128 + l16 * 8);
;             uint4 o;
;             o.x = cvt_pk_bf16(a[0] * rs * g0[0] * silu_f(bflo(z.x)), a[1] * rs * g0[1] * silu_f(bfhi(z.x)));
;             o.y = cvt_pk_bf16(a[2] * rs * g0[2] * silu_f(bflo(z.y)), a[3] * rs * g0[3] * silu_f(bfhi(z.y)));
;             o.z = cvt_pk_bf16(b4[0] * rs * g1[0] * silu_f(bflo(z.z)), b4[1] * rs * g1[1] * silu_f(bfhi(z.z)));
;             o.w = cvt_pk_bf16(b4[2] * rs * g1[2] * silu_f(bflo(z.w)), b4[3] * rs * g1[3] * silu_f(bfhi(z.w)));
	v_rcp_f32_e32 v38, v30
	s_nop 0
	v_mul_f32_e32 v30, v42, v38

; DEV unsigned cvt_pk_bf16(float lo, float hi) { const f32x2_t v = {lo, hi}; const bf16x2_t b = __builtin_convertvector(v, bf16x2_t); return __builtin_bit_cast(unsigned, b); }
; DEV float bflo(unsigned u) { return __uint_as_float(u << 16); }
; DEV float bfhi(unsigned u) { return __uint_as_float(u & 0xffff0000u); }
; DEV float silu_f(float x) { return x / (1.f + __expf(-x)); }
; __global__ void __launch_bounds__(512) hymba_fwd(Params p) {
;     ...
;             ss += __shfl_xor(ss, 1); ss += __shfl_xor(ss, 2); ss += __shfl_xor(ss, 4); ss += __shfl_xor(ss, 8);
;             const float rs = rsqrtf(ss * (1.f / 128.f) + EPS);
;             const f32x4 g0 = *(const f32x4*)(p.in[13] + l16 * 8), g1 = *(const f32x4*)(p.in[13] + l16 * 8 + 4);
;             const uint4 z = *(const uint4*)(proj + (size_t)row * NPJ + C_ZA + h * 128 + l16 * 8);
;             uint4 o;
;             o.x = cvt_pk_bf16(a[0] * rs * g0[0] * silu_f(bflo(z.x)), a[1] * rs * g0[1] * silu_f(bfhi(z.x)));
;             o.y = cvt_pk_bf16(a[2] * rs * g0[2] * silu_f(bflo(z.y)), a[3] * rs * g0[3] * silu_f(bfhi(z.y)));
;             o.z = cvt_pk_bf16(b4[0] * rs * g1[0] * silu_f(bflo(z.z)), b4[1] * rs * g1[1] * silu_f(bfhi(z.z)));
;             o.w = cvt_pk_bf16(b4[2] * rs * g1[2] * silu_f(bflo(z.w)), b4[3] * rs * g1[3] * silu_f(bfhi(z.w)));
	s_mov_b64 vcc, s[12:13]


; DEV unsigned cvt_pk_bf16(float lo, float hi) { const f32x2_t v = {lo, hi}; const bf16x2_t b = __builtin_convertvector(v, bf16x2_t); return __builtin_bit_cast(unsigned, b); }
; DEV float bflo(unsigned u) { return __uint_as_float(u << 16); }
; DEV float bfhi(unsigned u) { return __uint_as_float(u & 0xffff0000u); }
; DEV float silu_f(float x) { return x / (1.f + __expf(-x)); }
; __global__ void __launch_bounds__(512) hymba_fwd(Params p) {
;     ...
;             ss += __shfl_xor(ss, 1); ss += __shfl_xor(ss, 2); ss += __shfl_xor(ss, 4); ss += __shfl_xor(ss, 8);
;             const float rs = rsqrtf(ss * (1.f / 128.f) + EPS);
;             const f32x4 g0 = *(const f32x4*)(p.in[13] + l16 * 8), g1 = *(const f32x4*)(p.in[13] + l16 * 8 + 4);
;             const uint4 z = *(const uint4*)(proj + (size_t)row * NPJ + C_ZA + h * 128 + l16 * 8);
;             uint4 o;
;             o.x = cvt_pk_bf16(a[0] * rs * g0[0] * silu_f(bflo(z.x)), a[1] * rs * g0[1] * silu_f(bfhi(z.x)));
;             o.y = cvt_pk_bf16(a[2] * rs * g0[2] * silu_f(bflo(z.y)), a[3] * rs * g0[3] * silu_f(bfhi(z.y)));
;             o.z = cvt_pk_bf16(b4[0] * rs * g1[0] * silu_f(bflo(z.z)), b4[1] * rs * g1[1] * silu_f(bfhi(z.z)));
;             o.w = cvt_pk_bf16(b4[2] * rs * g1[2] * silu_f(bflo(z.w)), b4[3] * rs * g1[3] * silu_f(bfhi(z.w)));
	v_rcp_f32_e32 v38, v33
	s_nop 0
	v_mul_f32_e32 v33, v45, v38

; DEV unsigned cvt_pk_bf16(float lo, float hi) { const f32x2_t v = {lo, hi}; const bf16x2_t b = __builtin_convertvector(v, bf16x2_t); return __builtin_bit_cast(unsigned, b); }
; DEV float bflo(unsigned u) { return __uint_as_float(u << 16); }
; DEV float bfhi(unsigned u) { return __uint_as_float(u & 0xffff0000u); }
; DEV float silu_f(float x) { return x / (1.f + __expf(-x)); }
; __global__ void __launch_bounds__(512) hymba_fwd(Params p) {
;     ...
;             ss += __shfl_xor(ss, 1); ss += __shfl_xor(ss, 2); ss += __shfl_xor(ss, 4); ss += __shfl_xor(ss, 8);
;             const float rs = rsqrtf(ss * (1.f / 128.f) + EPS);
;             const f32x4 g0 = *(const f32x4*)(p.in[13] + l16 * 8), g1 = *(const f32x4*)(p.in[13] + l16 * 8 + 4);
;             const uint4 z = *(const uint4*)(proj + (size_t)row * NPJ + C_ZA + h * 128 + l16 * 8);
;             uint4 o;
;             o.x = cvt_pk_bf16(a[0] * rs * g0[0] * silu_f(bflo(z.x)), a[1] * rs * g0[1] * silu_f(bfhi(z.x)));
;             o.y = cvt_pk_bf16(a[2] * rs * g0[2] * silu_f(bflo(z.y)), a[3] * rs * g0[3] * silu_f(bfhi(z.y)));
;             o.z = cvt_pk_bf16(b4[0] * rs * g1[0] * silu_f(bflo(z.z)), b4[1] * rs * g1[1] * silu_f(bfhi(z.z)));
;             o.w = cvt_pk_bf16(b4[2] * rs * g1[2] * silu_f(bflo(z.w)), b4[3] * rs * g1[3] * silu_f(bfhi(z.w)));
	s_mov_b64 vcc, s[16:17]

; DEV unsigned cvt_pk_bf16(float lo, float hi) { const f32x2_t v = {lo, hi}; const bf16x2_t b = __builtin_convertvector(v, bf16x2_t); return __builtin_bit_cast(unsigned, b); }
; DEV float bflo(unsigned u) { return __uint_as_float(u << 16); }
; DEV float bfhi(unsigned u) { return __uint_as_float(u & 0xffff0000u); }
; DEV float silu_f(float x) { return x / (1.f + __expf(-x)); }
; __global__ void __launch_bounds__(512) hymba_fwd(Params p) {
;     ...
;             ss += __shfl_xor(ss, 1); ss += __shfl_xor(ss, 2); ss += __shfl_xor(ss, 4); ss += __shfl_xor(ss, 8);
;             const float rs = rsqrtf(ss * (1.f / 128.f) + EPS);
;             const f32x4 g0 = *(const f32x4*)(p.in[13] + l16 * 8), g1 = *(const f32x4*)(p.in[13] + l16 * 8 + 4);
;             const uint4 z = *(const uint4*)(proj + (size_t)row * NPJ + C_ZA + h * 128 + l16 * 8);
;             uint4 o;
;             o.x = cvt_pk_bf16(a[0] * rs * g0[0] * silu_f(bflo(z.x)), a[1] * rs * g0[1] * silu_f(bfhi(z.x)));
;             o.y = cvt_pk_bf16(a[2] * rs * g0[2] * silu_f(bflo(z.y)), a[3] * rs * g0[3] * silu_f(bfhi(z.y)));
;             o.z = cvt_pk_bf16(b4[0] * rs * g1[0] * silu_f(bflo(z.z)), b4[1] * rs * g1[1] * silu_f(bfhi(z.z)));
;             o.w = cvt_pk_bf16(b4[2] * rs * g1[2] * silu_f(bflo(z.w)), b4[3] * rs * g1[3] * silu_f(bfhi(z.w)));
	v_rcp_f32_e32 v38, v32
	s_nop 0
	v_mul_f32_e32 v32, v44, v38

; DEV unsigned cvt_pk_bf16(float lo, float hi) { const f32x2_t v = {lo, hi}; const bf16x2_t b = __builtin_convertvector(v, bf16x2_t); return __builtin_bit_cast(unsigned, b); }
; DEV float bflo(unsigned u) { return __uint_as_float(u << 16); }
; DEV float bfhi(unsigned u) { return __uint_as_float(u & 0xffff0000u); }
; DEV float silu_f(float x) { return x / (1.f + __expf(-x)); }
; __global__ void __launch_bounds__(512) hymba_fwd(Params p) {
;     ...
;             ss += __shfl_xor(ss, 1); ss += __shfl_xor(ss, 2); ss += __shfl_xor(ss, 4); ss += __shfl_xor(ss, 8);
;             const float rs = rsqrtf(ss * (1.f / 128.f) + EPS);
;             const f32x4 g0 = *(const f32x4*)(p.in[13] + l16 * 8), g1 = *(const f32x4*)(p.in[13] + l16 * 8 + 4);
;             const uint4 z = *(const uint4*)(proj + (size_t)row * NPJ + C_ZA + h * 128 + l16 * 8);
;             uint4 o;
;             o.x = cvt_pk_bf16(a[0] * rs * g0[0] * silu_f(bflo(z.x)), a[1] * rs * g0[1] * silu_f(bfhi(z.x)));
;             o.y = cvt_pk_bf16(a[2] * rs * g0[2] * silu_f(bflo(z.y)), a[3] * rs * g0[3] * silu_f(bfhi(z.y)));
;             o.z = cvt_pk_bf16(b4[0] * rs * g1[0] * silu_f(bflo(z.z)), b4[1] * rs * g1[1] * silu_f(bfhi(z.z)));
;             o.w = cvt_pk_bf16(b4[2] * rs * g1[2] * silu_f(bflo(z.w)), b4[3] * rs * g1[3] * silu_f(bfhi(z.w)));
	s_mov_b64 vcc, s[18:19]
	s_waitcnt lgkmcnt(0)
	v_add_f32_e32 v4, v4, v39
	v_rcp_f32_e32 v38, v37
	s_nop 0
	v_mul_f32_e32 v37, v47, v38

; DEV unsigned cvt_pk_bf16(float lo, float hi) { const f32x2_t v = {lo, hi}; const bf16x2_t b = __builtin_convertvector(v, bf16x2_t); return __builtin_bit_cast(unsigned, b); }
; DEV float bflo(unsigned u) { return __uint_as_float(u << 16); }
; DEV float bfhi(unsigned u) { return __uint_as_float(u & 0xffff0000u); }
; DEV float silu_f(float x) { return x / (1.f + __expf(-x)); }
; __global__ void __launch_bounds__(512) hymba_fwd(Params p) {
;     ...
;             const float rs = rsqrtf(ss * (1.f / 128.f) + EPS);
;             const f32x4 g0 = *(const f32x4*)(p.in[13] + l16 * 8), g1 = *(const f32x4*)(p.in[13] + l16 * 8 + 4);
;             const uint4 z = *(const uint4*)(proj + (size_t)row * NPJ + C_ZA + h * 128 + l16 * 8);
;             uint4 o;
;             o.x = cvt_pk_bf16(a[0] * rs * g0[0] * silu_f(bflo(z.x)), a[1] * rs * g0[1] * silu_f(bfhi(z.x)));
;             o.y = cvt_pk_bf16(a[2] * rs * g0[2] * silu_f(bflo(z.y)), a[3] * rs * g0[3] * silu_f(bfhi(z.y)));
;             o.z = cvt_pk_bf16(b4[0] * rs * g1[0] * silu_f(bflo(z.z)), b4[1] * rs * g1[1] * silu_f(bfhi(z.z)));
;             o.w = cvt_pk_bf16(b4[2] * rs * g1[2] * silu_f(bflo(z.w)), b4[3] * rs * g1[3] * silu_f(bfhi(z.w)));
;             *(uint4*)(mix + (size_t)row * LDB + h * 128 + l16 * 8) = o;
	v_fmamk_f32 v4, v4, 0x3c000000, v13
	v_rcp_f32_e32 v38, v36
	s_nop 0
	v_mul_f32_e32 v36, v46, v38
	v_mul_f32_e32 v38, 0x4b800000, v4
	v_cmp_gt_f32_e32 vcc, s30, v4
	s_nop 1
	v_cndmask_b32_e32 v4, v4, v38, vcc
	v_rsq_f32_e32 v4, v4
	s_nop 0
	v_mul_f32_e32 v38, 0x45800000, v4
	v_cndmask_b32_e32 v4, v4, v38, vcc
	v_pk_mul_f32 v[26:27], v[26:27], v[4:5] op_sel_hi:[1,0]
	v_pk_mul_f32 v[28:29], v[28:29], v[4:5] op_sel_hi:[1,0]
	v_pk_mul_f32 v[22:23], v[22:23], v[4:5] op_sel_hi:[1,0]
	v_pk_mul_f32 v[24:25], v[24:25], v[4:5] op_sel_hi:[1,0]
	v_pk_mul_f32 v[18:19], v[18:19], v[26:27]
	v_pk_mul_f32 v[20:21], v[20:21], v[28:29]
	v_pk_mul_f32 v[14:15], v[14:15], v[22:23]
	v_pk_mul_f32 v[16:17], v[16:17], v[24:25]
	v_pk_mul_f32 v[6:7], v[6:7], v[18:19]
	v_pk_mul_f32 v[18:19], v[30:31], v[20:21]
	v_pk_mul_f32 v[20:21], v[32:33], v[14:15]
	v_pk_mul_f32 v[22:23], v[36:37], v[16:17]
	v_cvt_pk_bf16_f32 v14, v6, v7
	v_cvt_pk_bf16_f32 v15, v18, v19
	v_cvt_pk_bf16_f32 v16, v20, v21
	v_cvt_pk_bf16_f32 v17, v22, v23
	global_store_dwordx4 v[34:35], v[14:17], off sc1
	s_andn2_b64 exec, exec, s[24:25]
	s_cbranch_execnz .LBB0_945

; template <class Epi>
; DEV void gemm256_tile(const bf16_t* __restrict__ A, int lda, const bf16_t* __restrict__ Bt, int ldb, int K, unsigned char* lds, const Epi& epi) {
;     ...
; #pragma unroll 4
;         for (int i = 0; i < 16; ++i) {
;             const int idx = tid + 512 * i, row = idx >> 5, cp = idx & 31, c = cp ^ (row & 31);
;             const uint4 d = *(const uint4*)(lds + row * 512 + (cp << 4));
;             *(uint4*)(epi.obase + (size_t)row * epi.old + c * 8) = epi.finish(row, c * 8, d);
;         }
;     DEV uint4 finish(int r, int c, uint4 d) const {
;         const f32x4 a = __builtin_nontemporal_load((const f32x4*)(res + (size_t)r * D + c)), b = __builtin_nontemporal_load((const f32x4*)(res + (size_t)r * D + c + 4));
;         const float r8[8] = {a[0], a[1], a[2], a[3], b[0], b[1], b[2], b[3]};
;         return add8_bf16(d, r8);
;     }
.LBB0_1005:
	v_add_u32_e32 v3, s18, v142
	v_ashrrev_i32_e32 v12, 5, v3
	v_xor_b32_e32 v4, v12, v142
	v_ashrrev_i32_e32 v13, 31, v12
	v_lshlrev_b32_e32 v6, 3, v4
	v_lshlrev_b64 v[4:5], 13, v[12:13]
	v_and_b32_e32 v22, 0xf8, v6
	v_lshl_add_u64 v[4:5], s[16:17], 0, v[4:5]
	v_lshlrev_b32_e32 v136, 2, v22
	v_lshl_add_u64 v[14:15], v[4:5], 0, v[136:137]
	global_load_dwordx4 v[4:7], v[14:15], off nt
	global_load_dwordx4 v[8:11], v[14:15], off offset:16 nt
	v_add_u32_e32 v13, 0x200, v3
	v_lshl_or_b32 v14, v12, 9, v2
	v_mad_i64_i32 v[16:17], s[24:25], v12, s21, v[26:27]
	v_ashrrev_i32_e32 v18, 5, v13
	ds_read_b128 v[12:15], v14
	v_xor_b32_e32 v20, v18, v142
	v_lshlrev_b32_e32 v23, 3, v20
	v_ashrrev_i32_e32 v19, 31, v18
	v_and_b32_e32 v28, 0xf8, v23
	v_lshlrev_b32_e32 v136, 1, v22
	s_waitcnt lgkmcnt(0)
	v_lshlrev_b32_e32 v22, 16, v12
	v_and_b32_e32 v23, 0xffff0000, v12
	v_lshlrev_b32_e32 v12, 16, v13
	v_and_b32_e32 v13, 0xffff0000, v13
	v_lshlrev_b32_e32 v24, 16, v14
	v_and_b32_e32 v25, 0xffff0000, v14
	v_lshlrev_b32_e32 v14, 16, v15
	v_and_b32_e32 v15, 0xffff0000, v15
	v_lshlrev_b64 v[20:21], 13, v[18:19]
	v_lshl_add_u64 v[20:21], s[16:17], 0, v[20:21]
	v_lshl_add_u64 v[16:17], v[16:17], 0, v[136:137]
	v_lshlrev_b32_e32 v136, 2, v28
	v_lshl_add_u64 v[20:21], v[20:21], 0, v[136:137]
	v_lshlrev_b32_e32 v136, 1, v28
	s_addk_i32 s18, 0x800
	s_cmpk_lg_i32 s18, 0x2000
	s_waitcnt vmcnt(1)
	v_pk_add_f32 v[4:5], v[4:5], v[22:23]
	v_pk_add_f32 v[6:7], v[6:7], v[12:13]
	s_waitcnt vmcnt(0)
	v_pk_add_f32 v[8:9], v[8:9], v[24:25]
	v_pk_add_f32 v[10:11], v[10:11], v[14:15]
	v_cvt_pk_bf16_f32 v4, v4, v5
	v_cvt_pk_bf16_f32 v5, v6, v7
	v_cvt_pk_bf16_f32 v6, v8, v9
	v_cvt_pk_bf16_f32 v7, v10, v11
	global_store_dwordx4 v[16:17], v[4:7], off sc1
	global_load_dwordx4 v[4:7], v[20:21], off nt
	s_nop 0
	global_load_dwordx4 v[8:11], v[20:21], off offset:16 nt
	v_add_u32_e32 v12, 0x400, v3
	v_ashrrev_i32_e32 v16, 5, v12
	v_lshl_or_b32 v12, v18, 9, v2
	ds_read_b128 v[12:15], v12
	v_xor_b32_e32 v20, v16, v142
	v_lshlrev_b32_e32 v22, 3, v20
	v_ashrrev_i32_e32 v17, 31, v16
	v_and_b32_e32 v29, 0xf8, v22
	s_waitcnt lgkmcnt(0)
	v_lshlrev_b32_e32 v22, 16, v12
	v_and_b32_e32 v23, 0xffff0000, v12
	v_lshlrev_b32_e32 v12, 16, v13
	v_and_b32_e32 v13, 0xffff0000, v13
	v_lshlrev_b32_e32 v24, 16, v14
	v_and_b32_e32 v25, 0xffff0000, v14
	v_lshlrev_b32_e32 v14, 16, v15
	v_and_b32_e32 v15, 0xffff0000, v15
	v_mad_i64_i32 v[18:19], s[24:25], v18, s21, v[26:27]
	v_lshlrev_b64 v[20:21], 13, v[16:17]
	v_lshl_add_u64 v[20:21], s[16:17], 0, v[20:21]
	v_lshl_add_u64 v[18:19], v[18:19], 0, v[136:137]
	v_lshlrev_b32_e32 v136, 2, v29
	v_lshl_add_u64 v[20:21], v[20:21], 0, v[136:137]
	v_add_u32_e32 v3, 0x600, v3
	v_lshlrev_b32_e32 v136, 1, v29
	s_waitcnt vmcnt(1)
	v_pk_add_f32 v[4:5], v[4:5], v[22:23]
	v_pk_add_f32 v[6:7], v[6:7], v[12:13]
	s_waitcnt vmcnt(0)
	v_pk_add_f32 v[8:9], v[8:9], v[24:25]
	v_pk_add_f32 v[10:11], v[10:11], v[14:15]
	v_cvt_pk_bf16_f32 v4, v4, v5
	v_cvt_pk_bf16_f32 v5, v6, v7
	v_cvt_pk_bf16_f32 v6, v8, v9
	v_cvt_pk_bf16_f32 v7, v10, v11
	global_store_dwordx4 v[18:19], v[4:7], off sc1
	global_load_dwordx4 v[4:7], v[20:21], off nt
	s_nop 0
	global_load_dwordx4 v[8:11], v[20:21], off offset:16 nt
	v_ashrrev_i32_e32 v18, 5, v3
	v_lshl_or_b32 v3, v16, 9, v2
	ds_read_b128 v[12:15], v3
	v_xor_b32_e32 v20, v18, v142
	v_ashrrev_i32_e32 v19, 31, v18
	v_lshlrev_b32_e32 v3, 3, v20
	v_mad_i64_i32 v[16:17], s[24:25], v16, s21, v[26:27]
	s_waitcnt lgkmcnt(0)
	v_lshlrev_b32_e32 v22, 16, v12
	v_and_b32_e32 v23, 0xffff0000, v12
	v_lshlrev_b32_e32 v12, 16, v13
	v_and_b32_e32 v13, 0xffff0000, v13
	v_lshlrev_b32_e32 v24, 16, v14
	v_and_b32_e32 v25, 0xffff0000, v14
	v_lshlrev_b32_e32 v14, 16, v15
	v_and_b32_e32 v15, 0xffff0000, v15
	v_lshlrev_b64 v[20:21], 13, v[18:19]
	v_and_b32_e32 v3, 0xf8, v3
	v_lshl_add_u64 v[20:21], s[16:17], 0, v[20:21]
	v_lshl_add_u64 v[16:17], v[16:17], 0, v[136:137]
	v_lshlrev_b32_e32 v136, 2, v3
	v_lshl_add_u64 v[20:21], v[20:21], 0, v[136:137]
	v_lshlrev_b32_e32 v136, 1, v3
	s_waitcnt vmcnt(1)
	v_pk_add_f32 v[4:5], v[4:5], v[22:23]
	v_pk_add_f32 v[6:7], v[6:7], v[12:13]
	s_waitcnt vmcnt(0)
	v_pk_add_f32 v[8:9], v[8:9], v[24:25]
	v_pk_add_f32 v[10:11], v[10:11], v[14:15]
	v_cvt_pk_bf16_f32 v4, v4, v5
	v_cvt_pk_bf16_f32 v5, v6, v7
	v_cvt_pk_bf16_f32 v6, v8, v9
	v_cvt_pk_bf16_f32 v7, v10, v11
	global_store_dwordx4 v[16:17], v[4:7], off sc1
	global_load_dwordx4 v[4:7], v[20:21], off nt
	s_nop 0
	global_load_dwordx4 v[8:11], v[20:21], off offset:16 nt
	v_lshl_or_b32 v12, v18, 9, v2
	ds_read_b128 v[12:15], v12
	v_mad_i64_i32 v[16:17], s[24:25], v18, s21, v[26:27]
	v_lshl_add_u64 v[16:17], v[16:17], 0, v[136:137]
	s_waitcnt lgkmcnt(0)
	v_lshlrev_b32_e32 v18, 16, v12
	v_and_b32_e32 v19, 0xffff0000, v12
	v_lshlrev_b32_e32 v12, 16, v13
	v_and_b32_e32 v13, 0xffff0000, v13
	v_lshlrev_b32_e32 v20, 16, v14
	v_and_b32_e32 v21, 0xffff0000, v14
	v_lshlrev_b32_e32 v14, 16, v15
	v_and_b32_e32 v15, 0xffff0000, v15
	s_waitcnt vmcnt(1)
	v_pk_add_f32 v[4:5], v[4:5], v[18:19]
	v_pk_add_f32 v[6:7], v[6:7], v[12:13]
	s_waitcnt vmcnt(0)
	v_pk_add_f32 v[8:9], v[8:9], v[20:21]
	v_pk_add_f32 v[10:11], v[10:11], v[14:15]
	v_cvt_pk_bf16_f32 v4, v4, v5
	v_cvt_pk_bf16_f32 v5, v6, v7
	v_cvt_pk_bf16_f32 v6, v8, v9
	v_cvt_pk_bf16_f32 v7, v10, v11
	global_store_dwordx4 v[16:17], v[4:7], off sc1
	s_cbranch_scc1 .LBB0_1005
	s_add_i32 s23, s23, s33
	s_cmpk_gt_i32 s23, 0xff
	s_barrier
	s_cbranch_scc0 .LBB0_1002

; DEV unsigned cvt_pk_bf16(float lo, float hi) { const f32x2_t v = {lo, hi}; const bf16x2_t b = __builtin_convertvector(v, bf16x2_t); return __builtin_bit_cast(unsigned, b); }
; template <int WT, class Epi>
; DEV void gemm_tile(const bf16_t* __restrict__ A, int lda, const bf16_t* __restrict__ Bt, int ldb, int K, unsigned char* lds, const Epi& epi) {
;     ...
;     if constexpr (Epi::STAGE) {
;         constexpr int RB = 4 * WT, CPR = RB / 16;
; #pragma unroll
;         for (int mi = 0; mi < FI; ++mi)
; #pragma unroll
;             for (int ni = 0; ni < FI; ++ni) {
;                 const int row = wr * WT + mi * 16 + fr, col = wc * WT + ni * 16 + fq * 4;
;                 const f32x4 v = epi.xform(row, col, acc[mi][ni]);
;                 uint2 w; w.x = cvt_pk_bf16(v[0], v[1]); w.y = cvt_pk_bf16(v[2], v[3]);
;                 *(uint2*)(lds + row * RB + ((((col >> 3) ^ (row & (CPR - 1))) << 4) | (((col >> 2) & 1) << 3))) = w;
;             }
;         __syncthreads();
; #pragma unroll
;         for (int i = 0; i < (2 * WT * CPR) / 256; ++i) {
;             const int idx = tid + 256 * i, row = idx / CPR, cp = idx % CPR, c = cp ^ (row & (CPR - 1));
;             const uint4 d = *(const uint4*)(lds + row * RB + (cp << 4));
;             *(uint4*)(epi.obase + (size_t)row * epi.old + c * 8) = epi.finish(row, c * 8, d);
;         }
;         __syncthreads();
;     DEV uint4 finish(int r, int c, uint4 d) const {
;         const f32x4 a = __builtin_nontemporal_load((const f32x4*)(res + (size_t)r * D + c)), b = __builtin_nontemporal_load((const f32x4*)(res + (size_t)r * D + c + 4));
;         const float r8[8] = {a[0], a[1], a[2], a[3], b[0], b[1], b[2], b[3]};
;         return add8_bf16(d, r8);
;     }
.Lsk5_nox:
	v_lshl_or_b32 v18, v30, 2, v32
	v_lshlrev_b32_e32 v20, 3, v26
	s_nop 0
	v_cvt_pk_bf16_f32 v14, v14, v15
	v_cvt_pk_bf16_f32 v15, v16, v17
	v_lshrrev_b32_e32 v16, 3, v18
	v_and_b32_e32 v20, 8, v20
	v_xor_b32_e32 v17, v16, v29
	v_cvt_pk_bf16_f32 v10, v10, v11
	v_cvt_pk_bf16_f32 v11, v12, v13
	v_bitop3_b32 v12, v16, v29, 2 bitop3:0x36
	v_add_u32_e32 v21, s45, v31
	v_lshl_or_b32 v17, v17, 4, v20
	v_lshl_or_b32 v12, v12, 4, v20
	v_add_u32_e32 v17, v21, v17
	v_add_u32_e32 v12, v21, v12
	v_cvt_pk_bf16_f32 v2, v2, v3
	v_cvt_pk_bf16_f32 v3, v4, v5
	s_barrier
	ds_write_b64 v17, v[14:15]
	ds_write_b64 v12, v[10:11]
	ds_write_b64 v17, v[2:3] offset:2048
	v_cvt_pk_bf16_f32 v2, v6, v7
	v_cvt_pk_bf16_f32 v3, v8, v9
	ds_write_b64 v12, v[2:3] offset:2048
	v_ashrrev_i32_e32 v2, 31, v25
	s_lshl_b32 s42, s53, 6
	v_lshrrev_b32_e32 v2, 29, v2
	s_ashr_i32 s43, s42, 31
	s_lshl_b32 s6, s52, 1
	s_lshl_b32 s14, s51, 19
	v_add_u32_e32 v2, v25, v2
	s_add_u32 s14, s4, s14
	v_ashrrev_i32_e32 v10, 3, v2
	v_and_b32_e32 v2, -8, v2
	s_addc_u32 s15, s5, 0
	s_lshl_b64 s[40:41], s[42:43], 2
	v_sub_u32_e32 v18, v25, v2
	s_add_u32 s40, s14, s40
	v_bitop3_b32 v2, v10, v18, 7 bitop3:0x6c
	v_ashrrev_i32_e32 v11, 31, v10
	s_addc_u32 s41, s15, s41
	v_lshlrev_b32_e32 v14, 3, v2
	v_lshlrev_b64 v[2:3], 13, v[10:11]
	v_lshl_add_u64 v[2:3], s[40:41], 0, v[2:3]
	v_ashrrev_i32_e32 v15, 31, v14
	v_lshl_add_u64 v[6:7], v[14:15], 2, v[2:3]
	s_waitcnt lgkmcnt(0)
	s_barrier
	global_load_dwordx4 v[2:5], v[6:7], off nt
	s_nop 0
	global_load_dwordx4 v[6:9], v[6:7], off offset:16 nt
	v_add_u32_e32 v11, 0x100, v25
	v_lshl_add_u64 v[12:13], v[130:131], 0, s[6:7]
	v_ashrrev_i32_e32 v20, 31, v11
	v_lshl_add_u64 v[16:17], s[42:43], 1, v[12:13]
	v_lshrrev_b32_e32 v12, 29, v20
	v_add_u32_e32 v12, v11, v12
	v_lshlrev_b32_e32 v13, 7, v10
	v_mad_i64_i32 v[20:21], s[42:43], v10, s49, v[16:17]
	v_ashrrev_i32_e32 v22, 3, v12
	v_and_b32_e32 v10, -8, v12
	v_lshlrev_b32_e32 v12, 4, v18
	v_sub_u32_e32 v18, v11, v10
	v_add3_u32 v10, s45, v13, v12
	ds_read_b128 v[10:13], v10
	v_ashrrev_i32_e32 v23, 31, v22
	v_bitop3_b32 v25, v22, v18, 7 bitop3:0x6c
	v_lshl_add_u64 v[14:15], v[14:15], 1, v[20:21]
	v_lshlrev_b64 v[26:27], 13, v[22:23]
	s_waitcnt lgkmcnt(0)
	v_lshlrev_b32_e32 v20, 16, v10
	v_and_b32_e32 v21, 0xffff0000, v10
	v_lshlrev_b32_e32 v10, 16, v11
	v_and_b32_e32 v11, 0xffff0000, v11
	v_lshlrev_b32_e32 v30, 16, v12
	v_and_b32_e32 v31, 0xffff0000, v12
	v_lshlrev_b32_e32 v12, 16, v13
	v_and_b32_e32 v13, 0xffff0000, v13
	v_lshlrev_b32_e32 v28, 3, v25
	v_lshl_add_u64 v[26:27], s[40:41], 0, v[26:27]
	v_ashrrev_i32_e32 v29, 31, v28
	s_add_i32 s46, s46, s75
	s_add_i32 s6, s46, s44
	s_min_i32 s6, s6, 0xff
	s_cmpk_lt_i32 s46, 0x100
	s_waitcnt vmcnt(1)
	v_pk_add_f32 v[2:3], v[2:3], v[20:21]
	v_pk_add_f32 v[4:5], v[4:5], v[10:11]
	s_waitcnt vmcnt(0)
	v_pk_add_f32 v[6:7], v[6:7], v[30:31]
	v_pk_add_f32 v[8:9], v[8:9], v[12:13]
	v_cvt_pk_bf16_f32 v2, v2, v3
	v_cvt_pk_bf16_f32 v3, v4, v5
	v_cvt_pk_bf16_f32 v4, v6, v7
	v_cvt_pk_bf16_f32 v5, v8, v9
	global_store_dwordx4 v[14:15], v[2:5], off sc1
	v_lshl_add_u64 v[6:7], v[28:29], 2, v[26:27]
	global_load_dwordx4 v[2:5], v[6:7], off nt
	s_nop 0
	global_load_dwordx4 v[6:9], v[6:7], off offset:16 nt
	v_lshlrev_b32_e32 v10, 7, v22
	v_lshlrev_b32_e32 v11, 4, v18
	v_add3_u32 v10, s45, v10, v11
	ds_read_b128 v[10:13], v10
	v_mad_i64_i32 v[14:15], s[40:41], v22, s49, v[16:17]
	v_lshl_add_u64 v[14:15], v[28:29], 1, v[14:15]
	s_waitcnt lgkmcnt(0)
	v_lshlrev_b32_e32 v16, 16, v10
	v_and_b32_e32 v17, 0xffff0000, v10
	v_lshlrev_b32_e32 v10, 16, v11
	v_and_b32_e32 v11, 0xffff0000, v11
	v_lshlrev_b32_e32 v20, 16, v12
	v_and_b32_e32 v21, 0xffff0000, v12
	v_lshlrev_b32_e32 v12, 16, v13
	v_and_b32_e32 v13, 0xffff0000, v13
	s_waitcnt vmcnt(1)
	v_pk_add_f32 v[2:3], v[2:3], v[16:17]
	v_pk_add_f32 v[4:5], v[4:5], v[10:11]
	s_waitcnt vmcnt(0)
	v_pk_add_f32 v[6:7], v[6:7], v[20:21]
	v_pk_add_f32 v[8:9], v[8:9], v[12:13]
	v_cvt_pk_bf16_f32 v2, v2, v3
	v_cvt_pk_bf16_f32 v3, v4, v5
	v_cvt_pk_bf16_f32 v4, v6, v7
	v_cvt_pk_bf16_f32 v5, v8, v9
	global_store_dwordx4 v[14:15], v[2:5], off sc1
	s_barrier
	s_cbranch_scc0 .LBB0_1024

; DEV unsigned cvt_pk_bf16(float lo, float hi) { const f32x2_t v = {lo, hi}; const bf16x2_t b = __builtin_convertvector(v, bf16x2_t); return __builtin_bit_cast(unsigned, b); }
; DEV float bflo(unsigned u) { return __uint_as_float(u << 16); }
; DEV float bfhi(unsigned u) { return __uint_as_float(u & 0xffff0000u); }
; template <bool OUT_F32>
; DEV void rmsnorm_row_from_bf16(const bf16_t* __restrict__ x, const float* __restrict__ g, void* __restrict__ y, int lane) {
;     float v[4][8]; float ss = 0.f;
; #pragma unroll
;     for (int i = 0; i < 4; ++i) { uint4 u; if (OUT_F32) { const u32x4 t_ = __builtin_nontemporal_load((const u32x4*)x + i * 64 + lane); u = make_uint4(t_[0], t_[1], t_[2], t_[3]); } else u = ((const uint4*)x)[i * 64 + lane];
;         v[i][0] = bflo(u.x); v[i][1] = bfhi(u.x); v[i][2] = bflo(u.y); v[i][3] = bfhi(u.y); v[i][4] = bflo(u.z); v[i][5] = bfhi(u.z); v[i][6] = bflo(u.w); v[i][7] = bfhi(u.w);
; #pragma unroll
;         for (int e = 0; e < 8; ++e) ss += v[i][e] * v[i][e]; }
;     ss = wave_sum(ss);
;     const float rs = rsqrtf(ss * (1.f / 2048.f) + EPS);
; #pragma unroll
;     for (int i = 0; i < 4; ++i) {
;         const f32x4 g0 = ((const f32x4*)g)[(i * 64 + lane) * 2], g1 = ((const f32x4*)g)[(i * 64 + lane) * 2 + 1];
;         const f32x4 o0 = (f32x4){v[i][0], v[i][1], v[i][2], v[i][3]} * rs * g0, o1 = (f32x4){v[i][4], v[i][5], v[i][6], v[i][7]} * rs * g1;
;         if (OUT_F32) { __builtin_nontemporal_store(o0, (f32x4*)y + (i * 64 + lane) * 2); __builtin_nontemporal_store(o1, (f32x4*)y + (i * 64 + lane) * 2 + 1); }
;         else { uint4 w; w.x = cvt_pk_bf16(o0[0], o0[1]); w.y = cvt_pk_bf16(o0[2], o0[3]); w.z = cvt_pk_bf16(o1[0], o1[1]); w.w = cvt_pk_bf16(o1[2], o1[3]); ((uint4*)y)[i * 64 + lane] = w; }
;     }
; }
.LBB0_1079:
	global_load_dwordx4 v[44:47], v[34:35], off
	global_load_dwordx4 v[48:51], v[34:35], off offset:1024
	global_load_dwordx4 v[52:55], v[34:35], off offset:2048
	global_load_dwordx4 v[56:59], v[34:35], off offset:3072
	v_add_co_u32_e32 v60, vcc, s12, v34
	v_add_u32_e32 v1, s10, v1
	s_nop 0
	v_addc_co_u32_e32 v61, vcc, -1, v35, vcc
	v_add_co_u32_e32 v62, vcc, s13, v34
	s_waitcnt vmcnt(3)
	v_lshlrev_b32_e32 v64, 16, v44
	v_and_b32_e32 v65, 0xffff0000, v44
	v_lshlrev_b32_e32 v44, 16, v45
	v_and_b32_e32 v45, 0xffff0000, v45
	v_pk_mul_f32 v[80:81], v[64:65], v[64:65]
	v_pk_mul_f32 v[82:83], v[44:45], v[44:45]
	v_add_f32_e32 v43, v80, v81
	v_lshlrev_b32_e32 v66, 16, v46
	v_and_b32_e32 v67, 0xffff0000, v46
	v_add_f32_e32 v43, v43, v82
	v_pk_mul_f32 v[84:85], v[66:67], v[66:67]
	v_add_f32_e32 v43, v83, v43
	v_lshlrev_b32_e32 v46, 16, v47
	v_and_b32_e32 v47, 0xffff0000, v47
	v_add_f32_e32 v43, v84, v43
	v_pk_mul_f32 v[86:87], v[46:47], v[46:47]
	v_add_f32_e32 v43, v85, v43
	s_waitcnt vmcnt(2)
	v_lshlrev_b32_e32 v68, 16, v48
	v_and_b32_e32 v69, 0xffff0000, v48
	v_add_f32_e32 v43, v86, v43
	v_pk_mul_f32 v[88:89], v[68:69], v[68:69]
	v_add_f32_e32 v43, v87, v43
	v_lshlrev_b32_e32 v48, 16, v49
	v_and_b32_e32 v49, 0xffff0000, v49
	v_add_f32_e32 v43, v88, v43
	v_pk_mul_f32 v[90:91], v[48:49], v[48:49]
	v_add_f32_e32 v43, v89, v43
	v_lshlrev_b32_e32 v70, 16, v50
	v_and_b32_e32 v71, 0xffff0000, v50
	v_add_f32_e32 v43, v90, v43
	v_pk_mul_f32 v[92:93], v[70:71], v[70:71]
	v_add_f32_e32 v43, v91, v43
	v_lshlrev_b32_e32 v50, 16, v51
	v_and_b32_e32 v51, 0xffff0000, v51
	v_add_f32_e32 v43, v92, v43
	v_pk_mul_f32 v[94:95], v[50:51], v[50:51]
	v_add_f32_e32 v43, v93, v43
	s_waitcnt vmcnt(1)
	v_lshlrev_b32_e32 v72, 16, v52
	v_and_b32_e32 v73, 0xffff0000, v52
	v_add_f32_e32 v43, v94, v43
	v_pk_mul_f32 v[96:97], v[72:73], v[72:73]
	v_add_f32_e32 v43, v95, v43
	v_lshlrev_b32_e32 v52, 16, v53
	v_and_b32_e32 v53, 0xffff0000, v53
	v_add_f32_e32 v43, v96, v43
	v_pk_mul_f32 v[98:99], v[52:53], v[52:53]
	v_add_f32_e32 v43, v97, v43
	v_lshlrev_b32_e32 v74, 16, v54
	v_and_b32_e32 v75, 0xffff0000, v54
	v_add_f32_e32 v43, v98, v43
	v_pk_mul_f32 v[100:101], v[74:75], v[74:75]
	v_add_f32_e32 v43, v99, v43
	v_lshlrev_b32_e32 v54, 16, v55
	v_and_b32_e32 v55, 0xffff0000, v55
	v_add_f32_e32 v43, v100, v43
	v_pk_mul_f32 v[102:103], v[54:55], v[54:55]
	v_add_f32_e32 v43, v101, v43
	s_waitcnt vmcnt(0)
	v_lshlrev_b32_e32 v76, 16, v56
	v_and_b32_e32 v77, 0xffff0000, v56
	v_add_f32_e32 v43, v102, v43
	v_pk_mul_f32 v[104:105], v[76:77], v[76:77]
	v_add_f32_e32 v43, v103, v43
	v_lshlrev_b32_e32 v56, 16, v57
	v_and_b32_e32 v57, 0xffff0000, v57
	v_add_f32_e32 v43, v104, v43
	v_pk_mul_f32 v[106:107], v[56:57], v[56:57]
	v_add_f32_e32 v43, v105, v43
	v_lshlrev_b32_e32 v78, 16, v58
	v_and_b32_e32 v79, 0xffff0000, v58
	v_add_f32_e32 v43, v106, v43
	v_pk_mul_f32 v[108:109], v[78:79], v[78:79]
	v_add_f32_e32 v43, v107, v43
	v_lshlrev_b32_e32 v58, 16, v59
	v_and_b32_e32 v59, 0xffff0000, v59
	v_add_f32_e32 v43, v108, v43
	v_pk_mul_f32 v[110:111], v[58:59], v[58:59]
	v_add_f32_e32 v43, v109, v43
	v_add_f32_e32 v43, v110, v43
	v_add_f32_e32 v43, v111, v43
	ds_bpermute_b32 v80, v36, v43
	v_addc_co_u32_e32 v63, vcc, -1, v35, vcc
	v_cmp_lt_i32_e32 vcc, s16, v1
	s_or_b64 s[8:9], vcc, s[8:9]
	s_waitcnt lgkmcnt(0)
	v_add_f32_e32 v43, v43, v80
	ds_bpermute_b32 v80, v37, v43
	v_lshl_add_u64 v[34:35], v[34:35], 0, s[6:7]
	s_waitcnt lgkmcnt(0)
	v_add_f32_e32 v43, v43, v80
	ds_bpermute_b32 v80, v38, v43
	s_waitcnt lgkmcnt(0)
	v_add_f32_e32 v43, v43, v80
	ds_bpermute_b32 v80, v39, v43
	s_waitcnt lgkmcnt(0)
	v_add_f32_e32 v43, v43, v80
	ds_bpermute_b32 v80, v40, v43
	s_waitcnt lgkmcnt(0)
	v_add_f32_e32 v43, v43, v80
	ds_bpermute_b32 v80, v41, v43
	s_waitcnt lgkmcnt(0)
	v_add_f32_e32 v43, v43, v80
	v_fmamk_f32 v43, v43, 0x3a000000, v42
	v_mul_f32_e32 v80, 0x4b800000, v43
	v_cmp_gt_f32_e32 vcc, s11, v43
	s_nop 1
	v_cndmask_b32_e32 v43, v43, v80, vcc
	v_rsq_f32_e32 v43, v43
	s_nop 0
	v_mul_f32_e32 v80, 0x45800000, v43
	v_cndmask_b32_e32 v80, v43, v80, vcc
	v_pk_mul_f32 v[64:65], v[80:81], v[64:65] op_sel_hi:[0,1]
	v_pk_mul_f32 v[44:45], v[80:81], v[44:45] op_sel_hi:[0,1]
	v_pk_mul_f32 v[66:67], v[80:81], v[66:67] op_sel_hi:[0,1]
	v_pk_mul_f32 v[46:47], v[80:81], v[46:47] op_sel_hi:[0,1]
	v_pk_mul_f32 v[68:69], v[80:81], v[68:69] op_sel_hi:[0,1]
	v_pk_mul_f32 v[48:49], v[80:81], v[48:49] op_sel_hi:[0,1]
	v_pk_mul_f32 v[70:71], v[80:81], v[70:71] op_sel_hi:[0,1]
	v_pk_mul_f32 v[50:51], v[80:81], v[50:51] op_sel_hi:[0,1]
	v_pk_mul_f32 v[72:73], v[80:81], v[72:73] op_sel_hi:[0,1]
	v_pk_mul_f32 v[52:53], v[80:81], v[52:53] op_sel_hi:[0,1]
	v_pk_mul_f32 v[74:75], v[80:81], v[74:75] op_sel_hi:[0,1]
	v_pk_mul_f32 v[54:55], v[80:81], v[54:55] op_sel_hi:[0,1]
	v_pk_mul_f32 v[76:77], v[80:81], v[76:77] op_sel_hi:[0,1]
	v_pk_mul_f32 v[56:57], v[80:81], v[56:57] op_sel_hi:[0,1]
	v_pk_mul_f32 v[78:79], v[80:81], v[78:79] op_sel_hi:[0,1]
	v_pk_mul_f32 v[58:59], v[80:81], v[58:59] op_sel_hi:[0,1]
	v_pk_mul_f32 v[80:81], v[8:9], v[44:45]
	v_pk_mul_f32 v[44:45], v[6:7], v[64:65]
	v_pk_mul_f32 v[64:65], v[4:5], v[46:47]
	v_pk_mul_f32 v[46:47], v[2:3], v[66:67]
	v_pk_mul_f32 v[66:67], v[16:17], v[48:49]
	v_pk_mul_f32 v[48:49], v[14:15], v[68:69]
	v_pk_mul_f32 v[68:69], v[12:13], v[50:51]
	v_pk_mul_f32 v[50:51], v[10:11], v[70:71]
	v_pk_mul_f32 v[70:71], v[24:25], v[52:53]
	v_pk_mul_f32 v[52:53], v[22:23], v[72:73]
	v_pk_mul_f32 v[72:73], v[20:21], v[54:55]
	v_pk_mul_f32 v[54:55], v[18:19], v[74:75]
	v_pk_mul_f32 v[74:75], v[32:33], v[56:57]
	v_pk_mul_f32 v[56:57], v[30:31], v[76:77]
	v_pk_mul_f32 v[76:77], v[28:29], v[58:59]
	v_pk_mul_f32 v[58:59], v[26:27], v[78:79]
	v_cvt_pk_bf16_f32 v44, v44, v45
	v_cvt_pk_bf16_f32 v45, v80, v81
	v_cvt_pk_bf16_f32 v46, v46, v47
	v_cvt_pk_bf16_f32 v47, v64, v65
	v_cvt_pk_bf16_f32 v48, v48, v49
	v_cvt_pk_bf16_f32 v49, v66, v67
	v_cvt_pk_bf16_f32 v50, v50, v51
	v_cvt_pk_bf16_f32 v51, v68, v69
	v_cvt_pk_bf16_f32 v52, v52, v53
	v_cvt_pk_bf16_f32 v53, v70, v71
	v_cvt_pk_bf16_f32 v54, v54, v55
	v_cvt_pk_bf16_f32 v55, v72, v73
	v_cvt_pk_bf16_f32 v56, v56, v57
	v_cvt_pk_bf16_f32 v57, v74, v75
	v_cvt_pk_bf16_f32 v58, v58, v59
	v_cvt_pk_bf16_f32 v59, v76, v77
	global_store_dwordx4 v[60:61], v[44:47], off sc1
	global_store_dwordx4 v[62:63], v[48:51], off offset:-3072 sc1
	global_store_dwordx4 v[62:63], v[52:55], off offset:-2048 sc1
	global_store_dwordx4 v[62:63], v[56:59], off offset:-1024 sc1
	s_andn2_b64 exec, exec, s[8:9]
	s_cbranch_execnz .LBB0_1079

; DEV unsigned cvt_pk_bf16(float lo, float hi) { const f32x2_t v = {lo, hi}; const bf16x2_t b = __builtin_convertvector(v, bf16x2_t); return __builtin_bit_cast(unsigned, b); }
; template <int WT, class Epi>
; DEV void gemm_tile(const bf16_t* __restrict__ A, int lda, const bf16_t* __restrict__ Bt, int ldb, int K, unsigned char* lds, const Epi& epi) {
;     ...
;     if constexpr (Epi::STAGE) {
;         constexpr int RB = 4 * WT, CPR = RB / 16;
; #pragma unroll
;         for (int mi = 0; mi < FI; ++mi)
; #pragma unroll
;             for (int ni = 0; ni < FI; ++ni) {
;                 const int row = wr * WT + mi * 16 + fr, col = wc * WT + ni * 16 + fq * 4;
;                 const f32x4 v = epi.xform(row, col, acc[mi][ni]);
;                 uint2 w; w.x = cvt_pk_bf16(v[0], v[1]); w.y = cvt_pk_bf16(v[2], v[3]);
;                 *(uint2*)(lds + row * RB + ((((col >> 3) ^ (row & (CPR - 1))) << 4) | (((col >> 2) & 1) << 3))) = w;
;             }
;         __syncthreads();
; #pragma unroll
;         for (int i = 0; i < (2 * WT * CPR) / 256; ++i) {
;             const int idx = tid + 256 * i, row = idx / CPR, cp = idx % CPR, c = cp ^ (row & (CPR - 1));
;             const uint4 d = *(const uint4*)(lds + row * RB + (cp << 4));
;             *(uint4*)(epi.obase + (size_t)row * epi.old + c * 8) = epi.finish(row, c * 8, d);
;         }
;         __syncthreads();
.Lsk7a_nox:
	v_lshl_or_b32 v18, v30, 2, v32
	v_lshlrev_b32_e32 v22, 3, v26
	s_nop 0
	v_cvt_pk_bf16_f32 v14, v14, v15
	v_cvt_pk_bf16_f32 v15, v16, v17
	v_lshrrev_b32_e32 v16, 3, v18
	v_and_b32_e32 v22, 8, v22
	v_xor_b32_e32 v17, v16, v29
	v_cvt_pk_bf16_f32 v10, v10, v11
	v_cvt_pk_bf16_f32 v11, v12, v13
	v_bitop3_b32 v12, v16, v29, 2 bitop3:0x36
	v_add_u32_e32 v23, s43, v31
	v_lshl_or_b32 v17, v17, 4, v22
	v_lshl_or_b32 v12, v12, 4, v22
	v_add_u32_e32 v17, v23, v17
	v_add_u32_e32 v12, v23, v12
	v_cvt_pk_bf16_f32 v2, v2, v3
	v_cvt_pk_bf16_f32 v3, v4, v5
	s_barrier
	ds_write_b64 v17, v[14:15]
	ds_write_b64 v12, v[10:11]
	ds_write_b64 v17, v[2:3] offset:2048
	v_cvt_pk_bf16_f32 v2, v6, v7
	v_cvt_pk_bf16_f32 v3, v8, v9
	ds_write_b64 v12, v[2:3] offset:2048
	v_ashrrev_i32_e32 v2, 31, v25
	v_lshrrev_b32_e32 v2, 29, v2
	v_add_u32_e32 v2, v25, v2
	v_ashrrev_i32_e32 v3, 3, v2
	v_and_b32_e32 v2, -8, v2
	s_lshl_b32 s38, s49, 6
	s_lshl_b32 s4, s50, 1
	v_sub_u32_e32 v2, v25, v2
	s_ashr_i32 s39, s38, 31
	v_lshl_add_u64 v[20:21], v[132:133], 0, s[4:5]
	v_bitop3_b32 v4, v3, v2, 7 bitop3:0x6c
	v_lshlrev_b32_e32 v5, 7, v3
	v_lshlrev_b32_e32 v2, 4, v2
	v_lshl_add_u64 v[20:21], s[38:39], 1, v[20:21]
	v_add3_u32 v6, s43, v5, v2
	v_lshlrev_b32_e32 v2, 3, v4
	v_mad_i64_i32 v[4:5], s[38:39], v3, s47, v[20:21]
	v_ashrrev_i32_e32 v3, 31, v2
	s_waitcnt lgkmcnt(0)
	s_barrier
	v_lshl_add_u64 v[10:11], v[2:3], 1, v[4:5]
	ds_read_b128 v[2:5], v6
	v_add_u32_e32 v6, 0x100, v25
	v_ashrrev_i32_e32 v7, 31, v6
	v_lshrrev_b32_e32 v7, 29, v7
	v_add_u32_e32 v7, v6, v7
	v_ashrrev_i32_e32 v12, 3, v7
	v_and_b32_e32 v7, -8, v7
	v_sub_u32_e32 v13, v6, v7
	v_lshlrev_b32_e32 v6, 7, v12
	v_lshlrev_b32_e32 v7, 4, v13
	v_add3_u32 v6, s43, v6, v7
	ds_read_b128 v[6:9], v6
	s_waitcnt lgkmcnt(1)
	global_store_dwordx4 v[10:11], v[2:5], off sc1
	s_add_i32 s44, s44, s75
	s_add_i32 s4, s44, s42
	v_bitop3_b32 v2, v12, v13, 7 bitop3:0x6c
	v_lshlrev_b32_e32 v2, 3, v2
	v_mad_i64_i32 v[4:5], s[38:39], v12, s47, v[20:21]
	v_ashrrev_i32_e32 v3, 31, v2
	s_min_i32 s38, s4, 0xff
	v_lshl_add_u64 v[2:3], v[2:3], 1, v[4:5]
	s_cmpk_lt_i32 s44, 0x100
	s_waitcnt lgkmcnt(0)
	global_store_dwordx4 v[2:3], v[6:9], off sc1
	s_waitcnt vmcnt(63) expcnt(7) lgkmcnt(15)
	s_barrier
	s_cbranch_scc0 .LBB0_1151

; template <class Epi>
; DEV void gemm256_tile(const bf16_t* __restrict__ A, int lda, const bf16_t* __restrict__ Bt, int ldb, int K, unsigned char* lds, const Epi& epi) {
;     ...
; #pragma unroll 4
;         for (int i = 0; i < 16; ++i) {
;             const int idx = tid + 512 * i, row = idx >> 5, cp = idx & 31, c = cp ^ (row & 31);
;             const uint4 d = *(const uint4*)(lds + row * 512 + (cp << 4));
;             *(uint4*)(epi.obase + (size_t)row * epi.old + c * 8) = epi.finish(row, c * 8, d);
;         }
.LBB0_1238:
	v_add_u32_e32 v3, s12, v144
	v_ashrrev_i32_e32 v4, 5, v3
	v_add_u32_e32 v5, 0x200, v3
	v_add_u32_e32 v6, 0x400, v3
	v_add_u32_e32 v3, 0x600, v3
	v_xor_b32_e32 v7, v4, v144
	v_lshl_or_b32 v8, v4, 9, v2
	v_ashrrev_i32_e32 v9, 5, v5
	v_ashrrev_i32_e32 v10, 5, v6
	v_ashrrev_i32_e32 v3, 5, v3
	v_mad_i64_i32 v[20:21], s[20:21], v4, s16, v[26:27]
	v_lshlrev_b32_e32 v11, 4, v7
	ds_read_b128 v[4:7], v8
	v_xor_b32_e32 v8, v9, v144
	v_lshl_or_b32 v12, v9, 9, v2
	v_xor_b32_e32 v13, v10, v144
	v_lshl_or_b32 v14, v10, 9, v2
	v_xor_b32_e32 v15, v3, v144
	v_lshl_or_b32 v16, v3, 9, v2
	v_mad_i64_i32 v[22:23], s[20:21], v9, s16, v[26:27]
	v_mad_i64_i32 v[24:25], s[20:21], v10, s16, v[26:27]
	v_mad_i64_i32 v[28:29], s[20:21], v3, s16, v[26:27]
	v_and_b32_e32 v138, 0x1f0, v11
	v_lshlrev_b32_e32 v3, 4, v8
	ds_read_b128 v[8:11], v12
	v_lshlrev_b32_e32 v30, 4, v13
	v_lshlrev_b32_e32 v31, 4, v15
	ds_read_b128 v[12:15], v14
	ds_read_b128 v[16:19], v16
	v_lshl_add_u64 v[20:21], v[20:21], 0, v[138:139]
	v_and_b32_e32 v138, 0x1f0, v3
	s_addk_i32 s12, 0x800
	v_lshl_add_u64 v[22:23], v[22:23], 0, v[138:139]
	v_and_b32_e32 v138, 0x1f0, v30
	s_cmpk_lg_i32 s12, 0x2000
	v_lshl_add_u64 v[24:25], v[24:25], 0, v[138:139]
	v_and_b32_e32 v138, 0x1f0, v31
	s_waitcnt lgkmcnt(3)
	global_store_dwordx4 v[20:21], v[4:7], off sc1
	s_nop 1
	v_lshl_add_u64 v[4:5], v[28:29], 0, v[138:139]
	s_waitcnt lgkmcnt(2)
	global_store_dwordx4 v[22:23], v[8:11], off sc1
	s_waitcnt lgkmcnt(1)
	global_store_dwordx4 v[24:25], v[12:15], off sc1
	s_waitcnt lgkmcnt(0)
	global_store_dwordx4 v[4:5], v[16:19], off sc1
	s_cbranch_scc1 .LBB0_1238
	s_add_i32 s19, s19, s17
	s_cmpk_gt_i32 s19, 0xff
	s_waitcnt vmcnt(63) expcnt(7) lgkmcnt(15)
	s_barrier
	s_cbranch_scc0 .LBB0_1235

; #define LAS __attribute__((address_space(3)))
; #define VLOOP(t, N) for (int t##0_ = 2 * bid, t = min(t##0_ + vb, (N) - 1); t##0_ < (N); t##0_ += VG, t = min(t##0_ + vb, (N) - 1))
; template <int WT, class Epi>
; DEV void gemm_tile(const bf16_t* __restrict__ A, int lda, const bf16_t* __restrict__ Bt, int ldb, int K, unsigned char* lds, const Epi& epi) {
;     ...
;     const int lrow = tid >> 3, lcs = (tid & 7) ^ (lrow & 7);
;     const bf16_t* ap = A + (size_t)lrow * lda + lcs * 8;
;     const bf16_t* bp = Bt + (size_t)lrow * ldb + lcs * 8;
;     const unsigned l3a = (unsigned)(size_t)(LAS unsigned char*)lds;
;     const int nk = K >> 6;
;     ...
;     constexpr int NSTG = 65536 / STB;
; #pragma unroll
;     for (int s_ = 0; s_ < NSTG - 1; ++s_) if (s_ < nk) GLDS_STAGE(s_ * STB, s_);
;     const int aoff = (wr * WT + fr) * 128, boff = OPB + (wc * WT + fr) * 128, sw = fr & 7;
;     int cur = 0, nxt = (NSTG - 1) * STB;
;     for (int kt = 0; kt < nk; ++kt) {
;         if (NSTG == 4 && kt + 2 < nk) { if (FI == 2) asm volatile("s_waitcnt vmcnt(8)" ::: "memory"); else asm volatile("s_waitcnt vmcnt(0)" ::: "memory"); }
;         else asm volatile("s_waitcnt vmcnt(0)" ::: "memory");
;         __syncthreads();
;         if (kt + NSTG - 1 < nk) GLDS_STAGE(nxt, kt + NSTG - 1);
; #pragma unroll
;         for (int kh = 0; kh < 2; ++kh) {
;             bf16x8 af[FI], bfr[FI];
;             const int ch = ((kh * 4 + fq) ^ sw) << 4;
; #pragma unroll
;             for (int i = 0; i < FI; ++i) { af[i] = *(const bf16x8*)(lds + cur + aoff + i * 2048 + ch); bfr[i] = *(const bf16x8*)(lds + cur + boff + i * 2048 + ch); }
; #pragma unroll
;             for (int mi = 0; mi < FI; ++mi)
; #pragma unroll
;                 for (int ni = 0; ni < FI; ++ni) acc[mi][ni] = __builtin_amdgcn_mfma_f32_16x16x32_bf16(bfr[ni], af[mi], acc[mi][ni], 0, 0, 0);
; __global__ void __launch_bounds__(512) hymba_fwd(Params p) {
;     ...
;         VLOOP(t, 16 * 16 * 4) { const int bhd = t >> 6, v = t & 63, mt = v >> 2, nt = v & 3, b = bhd >> 2, hd = bhd & 3;
;             EpiBfS e{ctx + (size_t)(b * SEQ + mt * 128) * LDB + hd * 512 + nt * 128, LDB};
;             gemm_tile<64>(pb + (size_t)(b * SEQ + mt * 128) * LDP + hd * 256, LDP, mvt + ((size_t)b * D + hd * 512 + nt * 128) * LDM, LDM, 256, vlds, e);
.LBB0_1409:
	s_ashr_i32 s68, s88, 8
	s_bfe_u32 s66, s88, 0x20006
	s_lshl_b32 s4, s88, 5
	s_ashr_i32 s69, s68, 31
	s_lshl_b32 s14, s88, 7
	v_mov_b32_e32 v97, v1
	s_lshl_b32 s15, s68, 11
	s_and_b32 s67, s4, 0x780
	s_lshl_b32 s4, s66, 9
	s_lshl_b64 s[68:69], s[68:69], 11
	s_and_b32 s80, s14, 0x180
	s_or_b32 s79, s15, s67
	v_lshrrev_b32_e32 v4, 4, v97
	v_and_b32_e32 v99, 15, v97
	v_ashrrev_i32_e32 v6, 3, v97
	v_lshlrev_b32_e32 v5, 4, v97
	v_ashrrev_i32_e32 v7, 1, v97
	v_lshlrev_b32_e32 v8, 7, v97
	v_and_b32_e32 v74, 7, v97
	s_or_b32 s14, s68, s4
	v_mad_i64_i32 v[2:3], s[82:83], s79, v95, v[86:87]
	v_xor_b32_e32 v9, v6, v97
	v_add_u32_e32 v10, s70, v5
	v_and_or_b32 v102, v7, s78, v99
	v_and_b32_e32 v7, 0x2780, v8
	v_add_u32_e32 v128, 0x4000, v5
	v_add_u32_e32 v5, s71, v5
	v_bitop3_b32 v4, v4, v74, 3 bitop3:0x6c
	s_or_b32 s14, s14, s80
	s_mul_i32 s15, s69, 0x240
	v_lshl_add_u64 v[2:3], v[2:3], 0, s[4:5]
	v_lshlrev_b32_e32 v8, 4, v9
	v_readfirstlane_b32 s4, v5
	v_add_u32_e32 v79, s70, v7
	v_lshlrev_b32_e32 v7, 4, v4
	v_mad_u64_u32 v[4:5], s[68:69], s14, v96, v[162:163]
	v_mad_i64_i32 v[2:3], s[68:69], v6, s76, v[2:3]
	v_and_b32_e32 v88, 0x70, v8
	v_add_u32_e32 v5, s15, v5
	v_add_u32_e32 v9, 0x4000, v10
	v_readfirstlane_b32 s67, v10
	v_lshl_add_u64 v[90:91], v[2:3], 0, v[88:89]
	v_mad_i64_i32 v[2:3], s[68:69], v6, s77, v[4:5]
	s_mov_b32 s68, m0
	s_mov_b32 m0, s67
	s_nop 0
	global_load_lds_dwordx4 v[90:91], off
	s_mov_b32 m0, s68
	v_readfirstlane_b32 s14, v9
	v_lshl_add_u64 v[92:93], v[2:3], 0, v[88:89]
	s_mov_b32 s68, m0
	s_mov_b32 m0, s14
	s_nop 0
	global_load_lds_dwordx4 v[92:93], off
	s_mov_b32 m0, s68
	s_add_i32 s88, s67, 0x1000
	s_add_i32 s15, s14, 0x1000
	s_add_i32 s91, s14, 0x2000
	s_add_i32 s92, s14, 0x3000
	v_lshl_add_u64 v[4:5], v[90:91], 0, s[6:7]
	s_mov_b32 s14, m0
	s_mov_b32 m0, s88
	s_nop 0
	global_load_lds_dwordx4 v[4:5], off
	s_mov_b32 m0, s14
	v_lshl_add_u32 v78, v102, 7, s70
	v_lshl_add_u64 v[2:3], v[92:93], 0, s[8:9]
	s_mov_b32 s14, m0
	s_mov_b32 m0, s15
	s_nop 0
	global_load_lds_dwordx4 v[2:3], off
	s_mov_b32 m0, s14
	s_add_i32 s89, s67, 0x2000
	v_add_u32_e32 v98, v78, v7
	v_add_u32_e32 v100, v79, v7
	v_lshl_add_u64 v[6:7], v[90:91], 0, s[10:11]
	s_mov_b32 s14, m0
	s_mov_b32 m0, s89
	s_nop 0
	global_load_lds_dwordx4 v[6:7], off
	s_mov_b32 m0, s14
	v_lshl_add_u64 v[18:19], v[92:93], 0, s[12:13]
	s_mov_b32 s14, m0
	s_mov_b32 m0, s91
	s_nop 0
	global_load_lds_dwordx4 v[18:19], off
	s_mov_b32 m0, s14
	s_add_i32 s90, s67, 0x3000
	v_lshl_add_u64 v[8:9], v[90:91], 0, s[16:17]
	s_mov_b32 s14, m0
	s_mov_b32 m0, s90
	s_nop 0
	global_load_lds_dwordx4 v[8:9], off
	s_mov_b32 m0, s14
	v_add_u32_e32 v10, s71, v128
	v_lshl_add_u64 v[20:21], v[92:93], 0, s[18:19]
	s_mov_b32 s14, m0
	s_mov_b32 m0, s92
	s_nop 0
	global_load_lds_dwordx4 v[20:21], off
	s_mov_b32 m0, s14
	v_readfirstlane_b32 s84, v10
	v_lshl_add_u64 v[10:11], v[90:91], 0, s[20:21]
	s_waitcnt vmcnt(0)
	s_barrier
	s_mov_b32 s14, m0
	s_mov_b32 m0, s4
	s_nop 0
	global_load_lds_dwordx4 v[10:11], off
	s_mov_b32 m0, s14
	v_lshl_add_u64 v[22:23], v[92:93], 0, s[20:21]
	s_mov_b32 s14, m0
	s_mov_b32 m0, s84
	s_nop 0
	global_load_lds_dwordx4 v[22:23], off
	s_mov_b32 m0, s14
	s_add_i32 s83, s4, 0x1000
	v_lshl_add_u64 v[12:13], v[90:91], 0, s[22:23]
	s_mov_b32 s14, m0
	s_mov_b32 m0, s83
	s_nop 0
	global_load_lds_dwordx4 v[12:13], off
	s_mov_b32 m0, s14
	s_add_i32 s87, s84, 0x1000
	v_lshl_add_u64 v[24:25], v[92:93], 0, s[24:25]
	s_mov_b32 s14, m0
	s_mov_b32 m0, s87
	s_nop 0
	global_load_lds_dwordx4 v[24:25], off
	s_mov_b32 m0, s14
	s_add_i32 s82, s4, 0x2000
	v_lshl_add_u64 v[14:15], v[90:91], 0, s[26:27]
	s_mov_b32 s14, m0
	s_mov_b32 m0, s82
	s_nop 0
	global_load_lds_dwordx4 v[14:15], off
	s_mov_b32 m0, s14
	s_add_i32 s86, s84, 0x2000
	v_lshl_add_u64 v[26:27], v[92:93], 0, s[30:31]
	s_mov_b32 s14, m0
	s_mov_b32 m0, s86
	s_nop 0
	global_load_lds_dwordx4 v[26:27], off
	s_mov_b32 m0, s14
	s_add_i32 s81, s4, 0x3000
	v_lshl_add_u64 v[16:17], v[90:91], 0, s[34:35]
	s_mov_b32 s14, m0
	s_mov_b32 m0, s81
	s_nop 0
	global_load_lds_dwordx4 v[16:17], off
	s_mov_b32 m0, s14
	s_add_i32 s85, s84, 0x3000
	v_lshl_add_u64 v[28:29], v[92:93], 0, s[36:37]
	s_mov_b32 s14, m0
	s_mov_b32 m0, s85
	s_nop 0
	global_load_lds_dwordx4 v[28:29], off
	s_mov_b32 m0, s14
	ds_read_b128 v[2:5], v100 offset:16384
	ds_read_b128 v[6:9], v100 offset:18432
	ds_read_b128 v[10:13], v98
	ds_read_b128 v[14:17], v98 offset:2048
	ds_read_b128 v[22:25], v100 offset:20480
	ds_read_b128 v[30:33], v100 offset:22528
	ds_read_b128 v[50:53], v98 offset:4096
	ds_read_b128 v[54:57], v98 offset:6144
	v_bfe_u32 v103, v97, 4, 2
	s_waitcnt lgkmcnt(5)
	v_mfma_f32_16x16x32_bf16 v[18:21], v[2:5], v[10:13], 0
	s_waitcnt lgkmcnt(4)
	v_mfma_f32_16x16x32_bf16 v[38:41], v[2:5], v[14:17], 0
	s_waitcnt lgkmcnt(1)
	v_mfma_f32_16x16x32_bf16 v[58:61], v[2:5], v[50:53], 0
	s_waitcnt lgkmcnt(0)
	v_mfma_f32_16x16x32_bf16 v[70:73], v[2:5], v[54:57], 0
	v_bitop3_b32 v2, v103, v74, 4 bitop3:0x36
	v_lshlrev_b32_e32 v2, 4, v2
	v_add_u32_e32 v88, v78, v2
	v_add_u32_e32 v101, v79, v2
	v_mfma_f32_16x16x32_bf16 v[34:37], v[22:25], v[10:13], 0
	ds_read_b128 v[82:85], v101 offset:16384
	ds_read_b128 v[104:107], v101 offset:18432
	v_mfma_f32_16x16x32_bf16 v[46:49], v[22:25], v[14:17], 0
	v_mfma_f32_16x16x32_bf16 v[66:69], v[22:25], v[50:53], 0
	v_mfma_f32_16x16x32_bf16 v[78:81], v[22:25], v[54:57], 0
	ds_read_b128 v[2:5], v88
	ds_read_b128 v[22:25], v88 offset:2048
	ds_read_b128 v[112:115], v101 offset:20480
	ds_read_b128 v[120:123], v101 offset:22528
	v_mfma_f32_16x16x32_bf16 v[26:29], v[6:9], v[10:13], 0
	v_mfma_f32_16x16x32_bf16 v[10:13], v[30:33], v[10:13], 0
	v_mfma_f32_16x16x32_bf16 v[42:45], v[6:9], v[14:17], 0
	s_waitcnt lgkmcnt(0)
	v_mfma_f32_16x16x32_bf16 v[134:137], v[120:123], v[2:5], v[10:13]
	s_nop 4
	v_add_u32_e32 v10, s70, v128
	v_mfma_f32_16x16x32_bf16 v[14:17], v[30:33], v[14:17], 0
	v_readfirstlane_b32 s14, v10
	s_add_i32 s15, s14, 0x1000
	s_add_i32 s68, s14, 0x2000
	v_mfma_f32_16x16x32_bf16 v[62:65], v[6:9], v[50:53], 0
	s_add_i32 s69, s14, 0x3000
	v_lshl_add_u32 v128, v102, 8, s70
	v_mfma_f32_16x16x32_bf16 v[50:53], v[30:33], v[50:53], 0
	v_mfma_f32_16x16x32_bf16 v[74:77], v[6:9], v[54:57], 0
	v_mfma_f32_16x16x32_bf16 v[54:57], v[30:33], v[54:57], 0
	v_mfma_f32_16x16x32_bf16 v[124:127], v[112:115], v[2:5], v[34:37]
	v_mfma_f32_16x16x32_bf16 v[10:13], v[112:115], v[22:25], v[46:49]
	s_nop 1
	v_lshl_add_u64 v[34:35], v[90:91], 0, s[38:39]
	ds_read_b128 v[30:33], v88 offset:4096
	ds_read_b128 v[46:49], v88 offset:6144
	s_waitcnt vmcnt(0)
	s_waitcnt lgkmcnt(0)
	s_barrier
; #define GLDS_STAGE(st, kt_) do { \
;         _Pragma("unroll") for (int i_ = 0; i_ < FI; ++i_) { \
;             glds16(ap + (size_t)(32 * i_) * lda + (kt_) * 64, l3a + (st) + tid * 16 + i_ * 4096); \
;             glds16(bp + (size_t)(32 * i_) * ldb + (kt_) * 64, l3a + (st) + OPB + tid * 16 + i_ * 4096); } } while (0)
; #define GLDS_STAGE(st, kt_) do { \
;         _Pragma("unroll") for (int i_ = 0; i_ < 4; ++i_) { \
;             glds16(ap + (size_t)(64 * i_) * lda + (kt_) * 64, l3a + (st) + tid * 16 + i_ * 8192); \
;             glds16(bp + (size_t)(64 * i_) * ldb + (kt_) * 64, l3a + (st) + 32768 + tid * 16 + i_ * 8192); } } while (0)
; template <int WT, class Epi>
; DEV void gemm_tile(const bf16_t* __restrict__ A, int lda, const bf16_t* __restrict__ Bt, int ldb, int K, unsigned char* lds, const Epi& epi) {
;     ...
;     for (int kt = 0; kt < nk; ++kt) {
;         if (NSTG == 4 && kt + 2 < nk) { if (FI == 2) asm volatile("s_waitcnt vmcnt(8)" ::: "memory"); else asm volatile("s_waitcnt vmcnt(0)" ::: "memory"); }
;         else asm volatile("s_waitcnt vmcnt(0)" ::: "memory");
;         __syncthreads();
;         if (kt + NSTG - 1 < nk) GLDS_STAGE(nxt, kt + NSTG - 1);
; #pragma unroll
;         for (int kh = 0; kh < 2; ++kh) {
;             bf16x8 af[FI], bfr[FI];
;             const int ch = ((kh * 4 + fq) ^ sw) << 4;
; #pragma unroll
;             for (int i = 0; i < FI; ++i) { af[i] = *(const bf16x8*)(lds + cur + aoff + i * 2048 + ch); bfr[i] = *(const bf16x8*)(lds + cur + boff + i * 2048 + ch); }
; #pragma unroll
;             for (int mi = 0; mi < FI; ++mi)
; #pragma unroll
;                 for (int ni = 0; ni < FI; ++ni) acc[mi][ni] = __builtin_amdgcn_mfma_f32_16x16x32_bf16(bfr[ni], af[mi], acc[mi][ni], 0, 0, 0);
;         }
;         nxt = cur; cur += STB; if (cur == NSTG * STB) cur = 0;
	s_mov_b32 s91, m0
	s_mov_b32 m0, s67
	s_nop 0
	global_load_lds_dwordx4 v[34:35], off
	s_mov_b32 m0, s91
	v_lshl_add_u64 v[36:37], v[92:93], 0, s[38:39]
	s_mov_b32 s67, m0
	s_mov_b32 m0, s14
	s_nop 0
	global_load_lds_dwordx4 v[36:37], off
	s_mov_b32 m0, s67
	v_mfma_f32_16x16x32_bf16 v[108:111], v[82:85], v[2:5], v[18:21]
	s_mov_b32 s67, s5
	v_mfma_f32_16x16x32_bf16 v[116:119], v[104:107], v[2:5], v[26:29]
	v_mfma_f32_16x16x32_bf16 v[2:5], v[82:85], v[22:25], v[38:41]
	s_nop 2
	v_lshl_add_u64 v[38:39], v[90:91], 0, s[40:41]
	s_mov_b32 s14, m0
	s_mov_b32 m0, s88
	s_nop 0
	global_load_lds_dwordx4 v[38:39], off
	s_mov_b32 m0, s14
	v_mfma_f32_16x16x32_bf16 v[6:9], v[104:107], v[22:25], v[42:45]
	v_lshl_add_u64 v[40:41], v[90:91], 0, s[44:45]
	s_nop 1
	v_lshl_add_u64 v[44:45], v[92:93], 0, s[42:43]
	s_mov_b32 s14, m0
	s_mov_b32 m0, s15
	s_nop 0
	global_load_lds_dwordx4 v[44:45], off
	s_mov_b32 m0, s14
	v_mfma_f32_16x16x32_bf16 v[18:21], v[82:85], v[30:33], v[58:61]
	s_mov_b32 s14, m0
	s_mov_b32 m0, s89
	s_nop 0
	global_load_lds_dwordx4 v[40:41], off
	s_mov_b32 m0, s14
	v_lshl_add_u64 v[42:43], v[90:91], 0, s[48:49]
	s_add_i32 s89, s74, s97
	v_mfma_f32_16x16x32_bf16 v[14:17], v[120:123], v[22:25], v[14:17]
	v_lshl_add_u64 v[58:59], v[92:93], 0, s[46:47]
	s_mov_b32 s14, m0
	s_mov_b32 m0, s68
	s_nop 0
	global_load_lds_dwordx4 v[58:59], off
	s_mov_b32 m0, s14
	v_lshl_add_u64 v[60:61], v[92:93], 0, s[50:51]
	s_mov_b32 s14, m0
	s_mov_b32 m0, s90
	s_nop 0
	global_load_lds_dwordx4 v[42:43], off
	s_mov_b32 m0, s14
	v_mfma_f32_16x16x32_bf16 v[22:25], v[104:107], v[30:33], v[62:65]
	s_mov_b32 s14, m0
	s_mov_b32 m0, s69
	s_nop 0
	global_load_lds_dwordx4 v[60:61], off
	s_mov_b32 m0, s14
	s_mov_b32 s69, s5
	s_lshl_b32 s68, s66, 10
	v_mfma_f32_16x16x32_bf16 v[26:29], v[112:115], v[30:33], v[66:69]
	s_add_i32 s14, s72, s74
	s_lshl_b32 s66, s80, 1
	s_min_i32 s88, s14, 0x3ff
	v_mfma_f32_16x16x32_bf16 v[30:33], v[120:123], v[30:33], v[50:53]
	s_mov_b32 s74, s89
	s_cmp_lt_i32 s89, s96
	v_mfma_f32_16x16x32_bf16 v[34:37], v[82:85], v[46:49], v[70:73]
	s_nop 2
	ds_read_b128 v[70:73], v100 offset:49152
	ds_read_b128 v[66:69], v100 offset:51200
	ds_read_b128 v[50:53], v98 offset:32768
	ds_read_b128 v[82:85], v98 offset:34816
	v_mfma_f32_16x16x32_bf16 v[38:41], v[104:107], v[46:49], v[74:77]
	v_mfma_f32_16x16x32_bf16 v[42:45], v[112:115], v[46:49], v[78:81]
	s_nop 1
	ds_read_b128 v[74:77], v100 offset:55296
	v_ashrrev_i32_e32 v112, 31, v97
	ds_read_b128 v[78:81], v100 offset:53248
	s_waitcnt lgkmcnt(2)
	v_mfma_f32_16x16x32_bf16 v[2:5], v[70:73], v[82:85], v[2:5]
	v_mfma_f32_16x16x32_bf16 v[6:9], v[66:69], v[82:85], v[6:9]
	s_waitcnt lgkmcnt(0)
	v_mfma_f32_16x16x32_bf16 v[10:13], v[78:81], v[82:85], v[10:13]
	v_mfma_f32_16x16x32_bf16 v[14:17], v[74:77], v[82:85], v[14:17]
	ds_read_b128 v[82:85], v98 offset:36864
	ds_read_b128 v[104:107], v98 offset:38912
	v_mfma_f32_16x16x32_bf16 v[46:49], v[120:123], v[46:49], v[54:57]
	v_add_u32_e32 v123, 0x400, v97
	v_add_u32_e32 v120, 0x100, v97
	v_ashrrev_i32_e32 v114, 31, v123
	v_mfma_f32_16x16x32_bf16 v[54:57], v[70:73], v[50:53], v[108:111]
	v_lshrrev_b32_e32 v138, 28, v114
	v_add_u32_e32 v121, 0x200, v97
	v_add_u32_e32 v122, 0x300, v97
	v_mfma_f32_16x16x32_bf16 v[58:61], v[66:69], v[50:53], v[116:119]
	v_and_b32_e32 v110, 64, v97
	v_mad_i64_i32 v[108:109], s[90:91], s79, v94, v[132:133]
	v_mfma_f32_16x16x32_bf16 v[62:65], v[78:81], v[50:53], v[124:127]
	v_lshl_or_b32 v103, v103, 2, v110
	v_lshl_add_u64 v[108:109], v[108:109], 0, s[68:69]
	v_lshrrev_b32_e32 v111, 1, v97
	v_mfma_f32_16x16x32_bf16 v[50:53], v[74:77], v[50:53], v[134:137]
	v_add_u32_e32 v124, 0x500, v97
	v_ashrrev_i32_e32 v115, 31, v124
	v_lshrrev_b32_e32 v129, 3, v103
	s_waitcnt lgkmcnt(1)
	v_mfma_f32_16x16x32_bf16 v[18:21], v[70:73], v[82:85], v[18:21]
	v_lshl_add_u64 v[102:103], v[108:109], 0, s[66:67]
	v_lshl_add_u64 v[108:109], v[90:91], 0, s[52:53]
	v_add_u32_e32 v125, 0x600, v97
	v_mfma_f32_16x16x32_bf16 v[22:25], v[66:69], v[82:85], v[22:25]
	v_add_u32_e32 v126, 0x700, v97
	v_and_b32_e32 v127, 8, v111
	v_lshrrev_b32_e32 v110, 28, v112
	v_mfma_f32_16x16x32_bf16 v[26:29], v[78:81], v[82:85], v[26:29]
	v_ashrrev_i32_e32 v111, 31, v120
	v_lshrrev_b32_e32 v139, 28, v115
	v_lshl_add_u64 v[114:115], v[92:93], 0, s[52:53]
	v_mfma_f32_16x16x32_bf16 v[30:33], v[74:77], v[82:85], v[30:33]
	v_ashrrev_i32_e32 v116, 31, v125
	v_ashrrev_i32_e32 v117, 31, v126
	v_add_u32_e32 v134, v97, v110
	s_waitcnt lgkmcnt(0)
	v_mfma_f32_16x16x32_bf16 v[34:37], v[70:73], v[104:107], v[34:37]
	v_lshrrev_b32_e32 v135, 28, v111
	v_lshl_add_u64 v[110:111], v[90:91], 0, s[54:55]
	v_ashrrev_i32_e32 v112, 31, v121
	v_mfma_f32_16x16x32_bf16 v[38:41], v[66:69], v[104:107], v[38:41]
	ds_read_b128 v[66:69], v101 offset:49152
	ds_read_b128 v[70:73], v101 offset:51200
	v_ashrrev_i32_e32 v113, 31, v122
	v_lshrrev_b32_e32 v140, 28, v116
	v_mfma_f32_16x16x32_bf16 v[42:45], v[78:81], v[104:107], v[42:45]
	v_lshrrev_b32_e32 v141, 28, v117
	v_lshl_add_u64 v[116:117], v[92:93], 0, s[56:57]
	v_lshrrev_b32_e32 v136, 28, v112
	v_mfma_f32_16x16x32_bf16 v[46:49], v[74:77], v[104:107], v[46:49]
	ds_read_b128 v[74:77], v88 offset:32768
	ds_read_b128 v[78:81], v88 offset:34816
	ds_read_b128 v[82:85], v101 offset:53248
	ds_read_b128 v[104:107], v101 offset:55296
	s_waitcnt lgkmcnt(3)
	v_mfma_f32_16x16x32_bf16 v[54:57], v[66:69], v[74:77], v[54:57]
	v_lshrrev_b32_e32 v137, 28, v113
	v_lshl_add_u64 v[112:113], v[90:91], 0, s[58:59]
	v_lshl_add_u64 v[118:119], v[92:93], 0, s[60:61]
	v_mfma_f32_16x16x32_bf16 v[58:61], v[70:73], v[74:77], v[58:61]
	v_lshl_add_u64 v[90:91], v[90:91], 0, s[62:63]
	v_lshl_add_u64 v[92:93], v[92:93], 0, s[64:65]
	v_bitop3_b32 v142, v129, v97, 15 bitop3:0x78
	s_waitcnt lgkmcnt(1)
	v_mfma_f32_16x16x32_bf16 v[62:65], v[82:85], v[74:77], v[62:65]
	s_waitcnt lgkmcnt(0)
	v_mfma_f32_16x16x32_bf16 v[50:53], v[104:107], v[74:77], v[50:53]
	v_mfma_f32_16x16x32_bf16 v[2:5], v[66:69], v[78:81], v[2:5]
	v_mfma_f32_16x16x32_bf16 v[6:9], v[70:73], v[78:81], v[6:9]
	v_mfma_f32_16x16x32_bf16 v[10:13], v[82:85], v[78:81], v[10:13]
	v_mfma_f32_16x16x32_bf16 v[14:17], v[104:107], v[78:81], v[14:17]
	ds_read_b128 v[74:77], v88 offset:36864
	ds_read_b128 v[78:81], v88 offset:38912
	s_waitcnt vmcnt(0)
	s_waitcnt lgkmcnt(0)
	s_barrier
; #define GLDS_STAGE(st, kt_) do { \
;         _Pragma("unroll") for (int i_ = 0; i_ < FI; ++i_) { \
;             glds16(ap + (size_t)(32 * i_) * lda + (kt_) * 64, l3a + (st) + tid * 16 + i_ * 4096); \
;             glds16(bp + (size_t)(32 * i_) * ldb + (kt_) * 64, l3a + (st) + OPB + tid * 16 + i_ * 4096); } } while (0)
; #define GLDS_STAGE(st, kt_) do { \
;         _Pragma("unroll") for (int i_ = 0; i_ < 4; ++i_) { \
;             glds16(ap + (size_t)(64 * i_) * lda + (kt_) * 64, l3a + (st) + tid * 16 + i_ * 8192); \
;             glds16(bp + (size_t)(64 * i_) * ldb + (kt_) * 64, l3a + (st) + 32768 + tid * 16 + i_ * 8192); } } while (0)
; template <int WT, class Epi>
; DEV void gemm_tile(const bf16_t* __restrict__ A, int lda, const bf16_t* __restrict__ Bt, int ldb, int K, unsigned char* lds, const Epi& epi) {
;     ...
;     for (int kt = 0; kt < nk; ++kt) {
;         if (NSTG == 4 && kt + 2 < nk) { if (FI == 2) asm volatile("s_waitcnt vmcnt(8)" ::: "memory"); else asm volatile("s_waitcnt vmcnt(0)" ::: "memory"); }
;         else asm volatile("s_waitcnt vmcnt(0)" ::: "memory");
;         __syncthreads();
;         if (kt + NSTG - 1 < nk) GLDS_STAGE(nxt, kt + NSTG - 1);
; #pragma unroll
;         for (int kh = 0; kh < 2; ++kh) {
;             bf16x8 af[FI], bfr[FI];
;             const int ch = ((kh * 4 + fq) ^ sw) << 4;
; #pragma unroll
;             for (int i = 0; i < FI; ++i) { af[i] = *(const bf16x8*)(lds + cur + aoff + i * 2048 + ch); bfr[i] = *(const bf16x8*)(lds + cur + boff + i * 2048 + ch); }
; #pragma unroll
;             for (int mi = 0; mi < FI; ++mi)
; #pragma unroll
;                 for (int ni = 0; ni < FI; ++ni) acc[mi][ni] = __builtin_amdgcn_mfma_f32_16x16x32_bf16(bfr[ni], af[mi], acc[mi][ni], 0, 0, 0);
;         }
;         nxt = cur; cur += STB; if (cur == NSTG * STB) cur = 0;
	s_mov_b32 s14, m0
	s_mov_b32 m0, s4
	s_nop 0
	global_load_lds_dwordx4 v[108:109], off
	s_mov_b32 m0, s14
	s_mov_b32 s4, m0
	s_mov_b32 m0, s84
	s_nop 0
	global_load_lds_dwordx4 v[114:115], off
	s_mov_b32 m0, s4
	v_mfma_f32_16x16x32_bf16 v[18:21], v[66:69], v[74:77], v[18:21]
	s_mov_b32 s4, m0
	s_mov_b32 m0, s83
	s_nop 0
	global_load_lds_dwordx4 v[110:111], off
	s_mov_b32 m0, s4
	v_add_u32_e32 v108, v120, v135
	s_mov_b32 s4, m0
	s_mov_b32 m0, s87
	s_nop 0
	global_load_lds_dwordx4 v[116:117], off
	s_mov_b32 m0, s4
	v_mfma_f32_16x16x32_bf16 v[22:25], v[70:73], v[74:77], v[22:25]
	s_mov_b32 s4, m0
	s_mov_b32 m0, s82
	s_nop 0
	global_load_lds_dwordx4 v[112:113], off
	s_mov_b32 m0, s4
	v_add_u32_e32 v109, v121, v136
	s_mov_b32 s4, m0
	s_mov_b32 m0, s86
	s_nop 0
	global_load_lds_dwordx4 v[118:119], off
	s_mov_b32 m0, s4
	v_mfma_f32_16x16x32_bf16 v[26:29], v[82:85], v[74:77], v[26:29]
	s_mov_b32 s4, m0
	s_mov_b32 m0, s81
	s_nop 0
	global_load_lds_dwordx4 v[90:91], off
	s_mov_b32 m0, s4
	v_add_u32_e32 v110, v122, v137
	s_mov_b32 s4, m0
	s_mov_b32 m0, s85
	s_nop 0
	global_load_lds_dwordx4 v[92:93], off
	s_mov_b32 m0, s4
	v_mfma_f32_16x16x32_bf16 v[30:33], v[104:107], v[74:77], v[30:33]
	v_add_u32_e32 v111, v123, v138
	v_add_u32_e32 v112, v124, v139
	v_add_u32_e32 v113, v125, v140
	v_mfma_f32_16x16x32_bf16 v[34:37], v[66:69], v[78:81], v[34:37]
	v_add_u32_e32 v114, v126, v141
	v_lshl_or_b32 v115, v142, 4, v127
	v_ashrrev_i32_e32 v119, 4, v108
	v_mfma_f32_16x16x32_bf16 v[38:41], v[70:73], v[78:81], v[38:41]
	ds_read_b128 v[66:69], v100 offset:16384
	ds_read_b128 v[70:73], v100 offset:18432
	v_and_b32_e32 v135, -16, v111
	v_and_b32_e32 v137, -16, v112
	v_mfma_f32_16x16x32_bf16 v[42:45], v[82:85], v[78:81], v[42:45]
	v_and_b32_e32 v139, -16, v113
	v_and_b32_e32 v141, -16, v114
	v_ashrrev_i32_e32 v136, 4, v112
	v_mfma_f32_16x16x32_bf16 v[46:49], v[104:107], v[78:81], v[46:49]
	ds_read_b128 v[74:77], v98
	ds_read_b128 v[78:81], v98 offset:2048
	ds_read_b128 v[82:85], v100 offset:20480
	ds_read_b128 v[90:93], v100 offset:22528
	s_waitcnt lgkmcnt(3)
	v_mfma_f32_16x16x32_bf16 v[54:57], v[66:69], v[74:77], v[54:57]
	v_bitop3_b32 v104, v129, v99, 2 bitop3:0x36
	v_bitop3_b32 v105, v129, v99, 4 bitop3:0x36
	v_bitop3_b32 v99, v129, v99, 6 bitop3:0x36
	v_mfma_f32_16x16x32_bf16 v[58:61], v[70:73], v[74:77], v[58:61]
	v_and_b32_e32 v107, -16, v134
	v_ashrrev_i32_e32 v106, 4, v134
	v_lshl_or_b32 v116, v104, 4, v127
	s_waitcnt lgkmcnt(1)
	v_mfma_f32_16x16x32_bf16 v[62:65], v[82:85], v[74:77], v[62:65]
	v_lshl_or_b32 v117, v105, 4, v127
	v_lshl_or_b32 v99, v99, 4, v127
	v_sub_u32_e32 v97, v97, v107
	s_waitcnt lgkmcnt(0)
	v_mfma_f32_16x16x32_bf16 v[50:53], v[90:93], v[74:77], v[50:53]
	v_and_b32_e32 v107, -16, v108
	v_and_b32_e32 v108, -16, v109
	v_ashrrev_i32_e32 v129, 4, v110
	v_mfma_f32_16x16x32_bf16 v[2:5], v[66:69], v[78:81], v[2:5]
	v_and_b32_e32 v110, -16, v110
	v_lshlrev_b32_e32 v118, 8, v106
	v_ashrrev_i32_e32 v127, 4, v109
	v_mfma_f32_16x16x32_bf16 v[6:9], v[70:73], v[78:81], v[6:9]
	v_ashrrev_i32_e32 v134, 4, v111
	v_ashrrev_i32_e32 v138, 4, v113
	v_ashrrev_i32_e32 v140, 4, v114
	v_mfma_f32_16x16x32_bf16 v[10:13], v[82:85], v[78:81], v[10:13]
	v_add_u32_e32 v142, v128, v115
	v_add_u32_e32 v143, v128, v116
	v_add_u32_e32 v144, v128, v117
	v_mfma_f32_16x16x32_bf16 v[14:17], v[90:93], v[78:81], v[14:17]
	ds_read_b128 v[74:77], v98 offset:4096
	ds_read_b128 v[78:81], v98 offset:6144
	v_add_u32_e32 v128, v128, v99
	v_bitop3_b32 v99, v106, v97, 15 bitop3:0x6c
	s_waitcnt lgkmcnt(1)
	v_mfma_f32_16x16x32_bf16 v[18:21], v[66:69], v[74:77], v[18:21]
	v_lshlrev_b32_e32 v97, 4, v97
	v_sub_u32_e32 v120, v120, v107
	v_sub_u32_e32 v121, v121, v108
	v_mfma_f32_16x16x32_bf16 v[22:25], v[70:73], v[74:77], v[22:25]
	v_sub_u32_e32 v122, v122, v110
	v_sub_u32_e32 v123, v123, v135
	v_sub_u32_e32 v124, v124, v137
	v_mfma_f32_16x16x32_bf16 v[26:29], v[82:85], v[74:77], v[26:29]
	v_sub_u32_e32 v125, v125, v139
	v_sub_u32_e32 v126, v126, v141
	v_mad_i64_i32 v[104:105], s[66:67], v106, s73, v[102:103]
	v_mfma_f32_16x16x32_bf16 v[30:33], v[90:93], v[74:77], v[30:33]
	v_lshlrev_b32_e32 v145, 8, v119
	v_mad_i64_i32 v[106:107], s[66:67], v119, s73, v[102:103]
	s_waitcnt lgkmcnt(0)
	v_mfma_f32_16x16x32_bf16 v[34:37], v[66:69], v[78:81], v[34:37]
	v_lshlrev_b32_e32 v146, 8, v127
	v_mad_i64_i32 v[108:109], s[66:67], v127, s73, v[102:103]
	v_mfma_f32_16x16x32_bf16 v[38:41], v[70:73], v[78:81], v[38:41]
	ds_read_b128 v[66:69], v101 offset:16384
	ds_read_b128 v[70:73], v101 offset:18432
	v_lshlrev_b32_e32 v147, 8, v129
	v_mad_i64_i32 v[110:111], s[66:67], v129, s73, v[102:103]
	v_mfma_f32_16x16x32_bf16 v[42:45], v[82:85], v[78:81], v[42:45]
	v_lshlrev_b32_e32 v135, 8, v134
	v_mad_i64_i32 v[112:113], s[66:67], v134, s73, v[102:103]
	v_mfma_f32_16x16x32_bf16 v[46:49], v[90:93], v[78:81], v[46:49]
	ds_read_b128 v[74:77], v88
	ds_read_b128 v[78:81], v88 offset:2048
	ds_read_b128 v[82:85], v101 offset:20480
	ds_read_b128 v[90:93], v101 offset:22528
	s_waitcnt lgkmcnt(3)
	v_mfma_f32_16x16x32_bf16 v[54:57], v[66:69], v[74:77], v[54:57]
	v_lshlrev_b32_e32 v137, 8, v136
	v_mad_i64_i32 v[114:115], s[66:67], v136, s73, v[102:103]
	v_mfma_f32_16x16x32_bf16 v[58:61], v[70:73], v[74:77], v[58:61]
	v_lshlrev_b32_e32 v139, 8, v138
	v_mad_i64_i32 v[116:117], s[66:67], v138, s73, v[102:103]
	s_waitcnt lgkmcnt(1)
	v_mfma_f32_16x16x32_bf16 v[62:65], v[82:85], v[74:77], v[62:65]
	v_lshlrev_b32_e32 v141, 8, v140
	v_add3_u32 v97, s70, v118, v97
	v_bitop3_b32 v118, v129, v122, 15 bitop3:0x6c
	s_waitcnt lgkmcnt(0)
	v_mfma_f32_16x16x32_bf16 v[50:53], v[90:93], v[74:77], v[50:53]
	v_mfma_f32_16x16x32_bf16 v[2:5], v[66:69], v[78:81], v[2:5]
	v_mfma_f32_16x16x32_bf16 v[6:9], v[70:73], v[78:81], v[6:9]
	v_mfma_f32_16x16x32_bf16 v[10:13], v[82:85], v[78:81], v[10:13]
	v_mfma_f32_16x16x32_bf16 v[14:17], v[90:93], v[78:81], v[14:17]
	ds_read_b128 v[74:77], v88 offset:4096
	ds_read_b128 v[78:81], v88 offset:6144
	s_waitcnt vmcnt(0)
	s_waitcnt lgkmcnt(0)
	v_mfma_f32_16x16x32_bf16 v[18:21], v[66:69], v[74:77], v[18:21]
	s_barrier
; DEV unsigned cvt_pk_bf16(float lo, float hi) { const f32x2_t v = {lo, hi}; const bf16x2_t b = __builtin_convertvector(v, bf16x2_t); return __builtin_bit_cast(unsigned, b); }
; #define GLDS_STAGE(st, kt_) do { \
;         _Pragma("unroll") for (int i_ = 0; i_ < FI; ++i_) { \
;             glds16(ap + (size_t)(32 * i_) * lda + (kt_) * 64, l3a + (st) + tid * 16 + i_ * 4096); \
;             glds16(bp + (size_t)(32 * i_) * ldb + (kt_) * 64, l3a + (st) + OPB + tid * 16 + i_ * 4096); } } while (0)
; template <int WT, class Epi>
; DEV void gemm_tile(const bf16_t* __restrict__ A, int lda, const bf16_t* __restrict__ Bt, int ldb, int K, unsigned char* lds, const Epi& epi) {
;     ...
;     for (int kt = 0; kt < nk; ++kt) {
;         if (NSTG == 4 && kt + 2 < nk) { if (FI == 2) asm volatile("s_waitcnt vmcnt(8)" ::: "memory"); else asm volatile("s_waitcnt vmcnt(0)" ::: "memory"); }
;         else asm volatile("s_waitcnt vmcnt(0)" ::: "memory");
;         __syncthreads();
;         if (kt + NSTG - 1 < nk) GLDS_STAGE(nxt, kt + NSTG - 1);
; #pragma unroll
;         for (int kh = 0; kh < 2; ++kh) {
;             bf16x8 af[FI], bfr[FI];
;             const int ch = ((kh * 4 + fq) ^ sw) << 4;
; #pragma unroll
;             for (int i = 0; i < FI; ++i) { af[i] = *(const bf16x8*)(lds + cur + aoff + i * 2048 + ch); bfr[i] = *(const bf16x8*)(lds + cur + boff + i * 2048 + ch); }
; #pragma unroll
;             for (int mi = 0; mi < FI; ++mi)
; #pragma unroll
;                 for (int ni = 0; ni < FI; ++ni) acc[mi][ni] = __builtin_amdgcn_mfma_f32_16x16x32_bf16(bfr[ni], af[mi], acc[mi][ni], 0, 0, 0);
;         }
;         nxt = cur; cur += STB; if (cur == NSTG * STB) cur = 0;
;     }
;     ...
;     __syncthreads();
;     if constexpr (Epi::STAGE) {
;         constexpr int RB = 4 * WT, CPR = RB / 16;
; #pragma unroll
;         for (int mi = 0; mi < FI; ++mi)
; #pragma unroll
;             for (int ni = 0; ni < FI; ++ni) {
;                 const int row = wr * WT + mi * 16 + fr, col = wc * WT + ni * 16 + fq * 4;
;                 const f32x4 v = epi.xform(row, col, acc[mi][ni]);
;                 uint2 w; w.x = cvt_pk_bf16(v[0], v[1]); w.y = cvt_pk_bf16(v[2], v[3]);
;                 *(uint2*)(lds + row * RB + ((((col >> 3) ^ (row & (CPR - 1))) << 4) | (((col >> 2) & 1) << 3))) = w;
	v_mfma_f32_16x16x32_bf16 v[22:25], v[70:73], v[74:77], v[22:25]
	v_mfma_f32_16x16x32_bf16 v[26:29], v[82:85], v[74:77], v[26:29]
	v_mfma_f32_16x16x32_bf16 v[30:33], v[90:93], v[74:77], v[30:33]
	ds_read_b128 v[74:77], v100 offset:51200
	v_mfma_f32_16x16x32_bf16 v[34:37], v[66:69], v[78:81], v[34:37]
	ds_read_b128 v[66:69], v100 offset:49152
	v_mfma_f32_16x16x32_bf16 v[38:41], v[70:73], v[78:81], v[38:41]
	ds_read_b128 v[70:73], v98 offset:32768
	v_mfma_f32_16x16x32_bf16 v[42:45], v[82:85], v[78:81], v[42:45]
	ds_read_b128 v[82:85], v100 offset:55296
	v_mfma_f32_16x16x32_bf16 v[46:49], v[90:93], v[78:81], v[46:49]
	ds_read_b128 v[78:81], v100 offset:53248
	v_mad_i64_i32 v[90:91], s[66:67], v140, s73, v[102:103]
	s_waitcnt lgkmcnt(2)
	v_mfma_f32_16x16x32_bf16 v[54:57], v[66:69], v[70:73], v[54:57]
	v_lshlrev_b32_e32 v92, 3, v99
	v_bitop3_b32 v99, v119, v120, 15 bitop3:0x6c
	v_lshlrev_b32_e32 v100, 4, v120
	v_mfma_f32_16x16x32_bf16 v[58:61], v[74:77], v[70:73], v[58:61]
	v_bitop3_b32 v102, v127, v121, 15 bitop3:0x6c
	v_lshlrev_b32_e32 v103, 4, v121
	v_lshlrev_b32_e32 v119, 4, v122
	s_waitcnt lgkmcnt(0)
	v_mfma_f32_16x16x32_bf16 v[62:65], v[78:81], v[70:73], v[62:65]
	v_bitop3_b32 v120, v134, v123, 15 bitop3:0x6c
	v_lshlrev_b32_e32 v121, 4, v123
	v_bitop3_b32 v122, v136, v124, 15 bitop3:0x6c
	v_mfma_f32_16x16x32_bf16 v[50:53], v[82:85], v[70:73], v[50:53]
	ds_read_b128 v[70:73], v98 offset:34816
	v_lshlrev_b32_e32 v123, 4, v124
	v_bitop3_b32 v124, v138, v125, 15 bitop3:0x6c
	s_waitcnt lgkmcnt(0)
	v_mfma_f32_16x16x32_bf16 v[2:5], v[66:69], v[70:73], v[2:5]
	v_lshlrev_b32_e32 v125, 4, v125
	v_bitop3_b32 v127, v140, v126, 15 bitop3:0x6c
	v_lshlrev_b32_e32 v126, 4, v126
	v_mfma_f32_16x16x32_bf16 v[6:9], v[74:77], v[70:73], v[6:9]
	v_add3_u32 v129, s70, v145, v100
	v_add3_u32 v134, s70, v146, v103
	v_add3_u32 v136, s70, v147, v119
	v_mfma_f32_16x16x32_bf16 v[10:13], v[78:81], v[70:73], v[10:13]
	v_add3_u32 v135, s70, v135, v121
	v_add3_u32 v137, s70, v137, v123
	v_add3_u32 v138, s70, v139, v125
	v_mfma_f32_16x16x32_bf16 v[14:17], v[82:85], v[70:73], v[14:17]
	ds_read_b128 v[70:73], v98 offset:36864
	v_add3_u32 v126, s70, v141, v126
	v_ashrrev_i32_e32 v93, 31, v92
	s_waitcnt lgkmcnt(0)
	v_mfma_f32_16x16x32_bf16 v[18:21], v[66:69], v[70:73], v[18:21]
	v_lshlrev_b32_e32 v100, 3, v102
	v_lshlrev_b32_e32 v102, 3, v118
	v_lshlrev_b32_e32 v118, 3, v120
	v_mfma_f32_16x16x32_bf16 v[22:25], v[74:77], v[70:73], v[22:25]
	v_lshlrev_b32_e32 v120, 3, v122
	v_lshlrev_b32_e32 v122, 3, v124
	v_lshlrev_b32_e32 v124, 3, v127
	v_mfma_f32_16x16x32_bf16 v[26:29], v[78:81], v[70:73], v[26:29]
	v_lshl_add_u64 v[92:93], v[92:93], 1, v[104:105]
	v_ashrrev_i32_e32 v103, 31, v102
	v_ashrrev_i32_e32 v119, 31, v118
	v_mfma_f32_16x16x32_bf16 v[30:33], v[82:85], v[70:73], v[30:33]
	ds_read_b128 v[70:73], v98 offset:38912
	v_lshlrev_b32_e32 v98, 3, v99
	v_ashrrev_i32_e32 v99, 31, v98
	s_waitcnt lgkmcnt(0)
	v_mfma_f32_16x16x32_bf16 v[34:37], v[66:69], v[70:73], v[34:37]
	ds_read_b128 v[66:69], v101 offset:49152
	v_ashrrev_i32_e32 v121, 31, v120
	v_ashrrev_i32_e32 v123, 31, v122
	v_mfma_f32_16x16x32_bf16 v[38:41], v[74:77], v[70:73], v[38:41]
	ds_read_b128 v[74:77], v101 offset:51200
	v_ashrrev_i32_e32 v125, 31, v124
	v_lshl_add_u64 v[98:99], v[98:99], 1, v[106:107]
	v_mfma_f32_16x16x32_bf16 v[42:45], v[78:81], v[70:73], v[42:45]
	ds_read_b128 v[78:81], v101 offset:53248
	v_lshl_add_u64 v[90:91], v[124:125], 1, v[90:91]
	v_mfma_f32_16x16x32_bf16 v[46:49], v[82:85], v[70:73], v[46:49]
	ds_read_b128 v[82:85], v101 offset:55296
	ds_read_b128 v[70:73], v88 offset:32768
	v_ashrrev_i32_e32 v101, 31, v100
	s_waitcnt lgkmcnt(0)
	v_mfma_f32_16x16x32_bf16 v[54:57], v[66:69], v[70:73], v[54:57]
	v_mfma_f32_16x16x32_bf16 v[58:61], v[74:77], v[70:73], v[58:61]
	s_nop 6
	v_cvt_pk_bf16_f32 v54, v54, v55
	v_cvt_pk_bf16_f32 v55, v56, v57
	v_mfma_f32_16x16x32_bf16 v[62:65], v[78:81], v[70:73], v[62:65]
	v_mfma_f32_16x16x32_bf16 v[50:53], v[82:85], v[70:73], v[50:53]
	ds_read_b128 v[70:73], v88 offset:34816
	v_cvt_pk_bf16_f32 v56, v58, v59
	v_cvt_pk_bf16_f32 v57, v60, v61
	s_waitcnt lgkmcnt(0)
	v_mfma_f32_16x16x32_bf16 v[2:5], v[66:69], v[70:73], v[2:5]
	s_nop 1
	v_cvt_pk_bf16_f32 v58, v62, v63
	v_cvt_pk_bf16_f32 v59, v64, v65
	v_cvt_pk_bf16_f32 v50, v50, v51
	v_mfma_f32_16x16x32_bf16 v[6:9], v[74:77], v[70:73], v[6:9]
	s_nop 1
	v_cvt_pk_bf16_f32 v2, v2, v3
	v_cvt_pk_bf16_f32 v3, v4, v5
	v_cvt_pk_bf16_f32 v51, v52, v53
	v_mfma_f32_16x16x32_bf16 v[10:13], v[78:81], v[70:73], v[10:13]
	v_mfma_f32_16x16x32_bf16 v[14:17], v[82:85], v[70:73], v[14:17]
	ds_read_b128 v[70:73], v88 offset:36864
	v_cvt_pk_bf16_f32 v4, v6, v7
	v_cvt_pk_bf16_f32 v5, v8, v9
	s_waitcnt lgkmcnt(0)
	v_mfma_f32_16x16x32_bf16 v[18:21], v[66:69], v[70:73], v[18:21]
	s_nop 1
	v_cvt_pk_bf16_f32 v6, v10, v11
	v_cvt_pk_bf16_f32 v7, v12, v13
	v_cvt_pk_bf16_f32 v8, v14, v15
	v_mfma_f32_16x16x32_bf16 v[22:25], v[74:77], v[70:73], v[22:25]
	v_cvt_pk_bf16_f32 v9, v16, v17
	s_nop 0
	v_cvt_pk_bf16_f32 v10, v18, v19
	v_cvt_pk_bf16_f32 v11, v20, v21
	v_mfma_f32_16x16x32_bf16 v[26:29], v[78:81], v[70:73], v[26:29]
	v_mfma_f32_16x16x32_bf16 v[30:33], v[82:85], v[70:73], v[30:33]
	ds_read_b128 v[70:73], v88 offset:38912
	s_nop 0
	v_cvt_pk_bf16_f32 v12, v22, v23
	v_cvt_pk_bf16_f32 v13, v24, v25
	s_waitcnt lgkmcnt(0)
	v_mfma_f32_16x16x32_bf16 v[34:37], v[66:69], v[70:73], v[34:37]
	s_nop 0
	v_cvt_pk_bf16_f32 v14, v26, v27
	v_cvt_pk_bf16_f32 v15, v28, v29
	v_cvt_pk_bf16_f32 v16, v30, v31
	v_mfma_f32_16x16x32_bf16 v[38:41], v[74:77], v[70:73], v[38:41]
	v_cvt_pk_bf16_f32 v17, v32, v33
	s_nop 1
	v_cvt_pk_bf16_f32 v18, v34, v35
	v_cvt_pk_bf16_f32 v19, v36, v37
	v_mfma_f32_16x16x32_bf16 v[42:45], v[78:81], v[70:73], v[42:45]
	s_nop 1
	v_cvt_pk_bf16_f32 v20, v38, v39
	v_cvt_pk_bf16_f32 v21, v40, v41
	v_mfma_f32_16x16x32_bf16 v[46:49], v[82:85], v[70:73], v[46:49]
	s_barrier
; DEV unsigned cvt_pk_bf16(float lo, float hi) { const f32x2_t v = {lo, hi}; const bf16x2_t b = __builtin_convertvector(v, bf16x2_t); return __builtin_bit_cast(unsigned, b); }
; template <int WT, class Epi>
; DEV void gemm_tile(const bf16_t* __restrict__ A, int lda, const bf16_t* __restrict__ Bt, int ldb, int K, unsigned char* lds, const Epi& epi) {
;     ...
;     if constexpr (Epi::STAGE) {
;         constexpr int RB = 4 * WT, CPR = RB / 16;
; #pragma unroll
;         for (int mi = 0; mi < FI; ++mi)
; #pragma unroll
;             for (int ni = 0; ni < FI; ++ni) {
;                 const int row = wr * WT + mi * 16 + fr, col = wc * WT + ni * 16 + fq * 4;
;                 const f32x4 v = epi.xform(row, col, acc[mi][ni]);
;                 uint2 w; w.x = cvt_pk_bf16(v[0], v[1]); w.y = cvt_pk_bf16(v[2], v[3]);
;                 *(uint2*)(lds + row * RB + ((((col >> 3) ^ (row & (CPR - 1))) << 4) | (((col >> 2) & 1) << 3))) = w;
;             }
;         __syncthreads();
; #pragma unroll
;         for (int i = 0; i < (2 * WT * CPR) / 256; ++i) {
;             const int idx = tid + 256 * i, row = idx / CPR, cp = idx % CPR, c = cp ^ (row & (CPR - 1));
;             const uint4 d = *(const uint4*)(lds + row * RB + (cp << 4));
;             *(uint4*)(epi.obase + (size_t)row * epi.old + c * 8) = epi.finish(row, c * 8, d);
;         }
;         __syncthreads();
	s_nop 1
	v_cvt_pk_bf16_f32 v22, v42, v43
	v_cvt_pk_bf16_f32 v23, v44, v45
	v_lshl_add_u64 v[66:67], v[100:101], 1, v[108:109]
	s_nop 1
	v_cvt_pk_bf16_f32 v24, v46, v47
	v_cvt_pk_bf16_f32 v25, v48, v49
	ds_write_b64 v142, v[54:55]
	ds_write_b64 v143, v[56:57]
	ds_write_b64 v144, v[58:59]
	ds_write_b64 v128, v[50:51]
	ds_write_b64 v142, v[2:3] offset:4096
	ds_write_b64 v143, v[4:5] offset:4096
	ds_write_b64 v144, v[6:7] offset:4096
	ds_write_b64 v128, v[8:9] offset:4096
	ds_write_b64 v142, v[10:11] offset:8192
	ds_write_b64 v143, v[12:13] offset:8192
	ds_write_b64 v144, v[14:15] offset:8192
	ds_write_b64 v128, v[16:17] offset:8192
	ds_write_b64 v142, v[18:19] offset:12288
	ds_write_b64 v143, v[20:21] offset:12288
	ds_write_b64 v144, v[22:23] offset:12288
	ds_write_b64 v128, v[24:25] offset:12288
	s_waitcnt lgkmcnt(0)
	s_barrier
	ds_read_b128 v[2:5], v97
	ds_read_b128 v[6:9], v129
	ds_read_b128 v[10:13], v134
	ds_read_b128 v[14:17], v136
	ds_read_b128 v[18:21], v135
	ds_read_b128 v[22:25], v137
	ds_read_b128 v[26:29], v138
	ds_read_b128 v[30:33], v126
	v_lshl_add_u64 v[68:69], v[102:103], 1, v[110:111]
	v_lshl_add_u64 v[100:101], v[118:119], 1, v[112:113]
	v_lshl_add_u64 v[74:75], v[120:121], 1, v[114:115]
	v_lshl_add_u64 v[76:77], v[122:123], 1, v[116:117]
	s_waitcnt lgkmcnt(7)
	global_store_dwordx4 v[92:93], v[2:5], off sc1
	s_waitcnt lgkmcnt(6)
	global_store_dwordx4 v[98:99], v[6:9], off sc1
	s_waitcnt lgkmcnt(5)
	global_store_dwordx4 v[66:67], v[10:13], off sc1
	s_waitcnt lgkmcnt(4)
	global_store_dwordx4 v[68:69], v[14:17], off sc1
	s_waitcnt lgkmcnt(3)
	global_store_dwordx4 v[100:101], v[18:21], off sc1
	s_waitcnt lgkmcnt(2)
	global_store_dwordx4 v[74:75], v[22:25], off sc1
	s_waitcnt lgkmcnt(1)
	global_store_dwordx4 v[76:77], v[26:29], off sc1
	s_waitcnt lgkmcnt(0)
	global_store_dwordx4 v[90:91], v[30:33], off sc1
	s_waitcnt vmcnt(63) expcnt(7) lgkmcnt(15)
	s_barrier
	s_cbranch_scc1 .LBB0_1409

; DEV float bflo(unsigned u) { return __uint_as_float(u << 16); }
; DEV float bfhi(unsigned u) { return __uint_as_float(u & 0xffff0000u); }
; template <class Epi>
; DEV void gemm256_tile(const bf16_t* __restrict__ A, int lda, const bf16_t* __restrict__ Bt, int ldb, int K, unsigned char* lds, const Epi& epi) {
;     ...
; #pragma unroll 4
;         for (int i = 0; i < 16; ++i) {
;             const int idx = tid + 512 * i, row = idx >> 5, cp = idx & 31, c = cp ^ (row & 31);
;             const uint4 d = *(const uint4*)(lds + row * 512 + (cp << 4));
;             *(uint4*)(epi.obase + (size_t)row * epi.old + c * 8) = epi.finish(row, c * 8, d);
;         }
;     DEV uint4 finish(int r, int c, uint4 d) const {
;         const uint4 u = *(const uint4*)(res + (size_t)r * LDB + c);
;         const float r8[8] = {bflo(u.x), bfhi(u.x), bflo(u.y), bfhi(u.y), bflo(u.z), bfhi(u.z), bflo(u.w), bfhi(u.w)};
;         return add8_bf16(d, r8);
;     }
.LBB0_1468:
	v_add_u32_e32 v3, s12, v146
	v_ashrrev_i32_e32 v8, 5, v3
	v_xor_b32_e32 v6, v8, v146
	v_lshlrev_b32_e32 v6, 4, v6
	v_mad_i64_i32 v[4:5], s[20:21], v8, s17, v[26:27]
	v_and_b32_e32 v140, 0x1f0, v6
	v_lshl_add_u64 v[4:5], v[4:5], 0, v[140:141]
	global_load_dwordx4 v[4:7], v[4:5], off
	v_add_u32_e32 v9, 0x200, v3
	v_lshl_or_b32 v10, v8, 9, v2
	v_mad_i64_i32 v[12:13], s[20:21], v8, s17, v[28:29]
	v_ashrrev_i32_e32 v24, 5, v9
	ds_read_b128 v[8:11], v10
	v_xor_b32_e32 v16, v24, v146
	v_lshlrev_b32_e32 v16, 4, v16
	v_lshl_add_u64 v[12:13], v[12:13], 0, v[140:141]
	v_and_b32_e32 v140, 0x1f0, v16
	s_waitcnt lgkmcnt(0)
	v_lshlrev_b32_e32 v16, 16, v8
	v_and_b32_e32 v17, 0xffff0000, v8
	v_lshlrev_b32_e32 v8, 16, v9
	v_and_b32_e32 v9, 0xffff0000, v9
	v_lshlrev_b32_e32 v18, 16, v10
	v_and_b32_e32 v19, 0xffff0000, v10
	v_lshlrev_b32_e32 v10, 16, v11
	v_and_b32_e32 v11, 0xffff0000, v11
	v_mad_i64_i32 v[14:15], s[20:21], v24, s17, v[26:27]
	v_lshl_add_u64 v[14:15], v[14:15], 0, v[140:141]
	s_addk_i32 s12, 0x800
	s_cmpk_lg_i32 s12, 0x2000
	s_waitcnt vmcnt(0)
	v_lshlrev_b32_e32 v20, 16, v4
	v_and_b32_e32 v21, 0xffff0000, v4
	v_lshlrev_b32_e32 v4, 16, v5
	v_and_b32_e32 v5, 0xffff0000, v5
	v_lshlrev_b32_e32 v22, 16, v6
	v_and_b32_e32 v23, 0xffff0000, v6
	v_lshlrev_b32_e32 v6, 16, v7
	v_and_b32_e32 v7, 0xffff0000, v7
	v_pk_add_f32 v[16:17], v[16:17], v[20:21]
	v_pk_add_f32 v[8:9], v[8:9], v[4:5]
	v_pk_add_f32 v[18:19], v[18:19], v[22:23]
	v_pk_add_f32 v[10:11], v[10:11], v[6:7]
	v_cvt_pk_bf16_f32 v4, v16, v17
	v_cvt_pk_bf16_f32 v5, v8, v9
	v_cvt_pk_bf16_f32 v6, v18, v19
	v_cvt_pk_bf16_f32 v7, v10, v11
	global_store_dwordx4 v[12:13], v[4:7], off sc1
	global_load_dwordx4 v[4:7], v[14:15], off
	v_add_u32_e32 v8, 0x400, v3
	v_ashrrev_i32_e32 v25, 5, v8
	v_lshl_or_b32 v8, v24, 9, v2
	ds_read_b128 v[8:11], v8
	v_xor_b32_e32 v16, v25, v146
	v_mad_i64_i32 v[12:13], s[20:21], v24, s17, v[28:29]
	v_lshlrev_b32_e32 v16, 4, v16
	v_lshl_add_u64 v[12:13], v[12:13], 0, v[140:141]
	v_and_b32_e32 v140, 0x1f0, v16
	s_waitcnt lgkmcnt(0)
	v_lshlrev_b32_e32 v16, 16, v8
	v_and_b32_e32 v17, 0xffff0000, v8
	v_lshlrev_b32_e32 v8, 16, v9
	v_and_b32_e32 v9, 0xffff0000, v9
	v_lshlrev_b32_e32 v18, 16, v10
	v_and_b32_e32 v19, 0xffff0000, v10
	v_lshlrev_b32_e32 v10, 16, v11
	v_and_b32_e32 v11, 0xffff0000, v11
	v_mad_i64_i32 v[14:15], s[20:21], v25, s17, v[26:27]
	v_lshl_add_u64 v[14:15], v[14:15], 0, v[140:141]
	v_add_u32_e32 v3, 0x600, v3
	v_ashrrev_i32_e32 v3, 5, v3
	s_waitcnt vmcnt(0)
	v_lshlrev_b32_e32 v20, 16, v4
	v_and_b32_e32 v21, 0xffff0000, v4
	v_lshlrev_b32_e32 v4, 16, v5
	v_and_b32_e32 v5, 0xffff0000, v5
	v_lshlrev_b32_e32 v22, 16, v6
	v_and_b32_e32 v23, 0xffff0000, v6
	v_lshlrev_b32_e32 v6, 16, v7
	v_and_b32_e32 v7, 0xffff0000, v7
	v_pk_add_f32 v[16:17], v[16:17], v[20:21]
	v_pk_add_f32 v[8:9], v[8:9], v[4:5]
	v_pk_add_f32 v[18:19], v[18:19], v[22:23]
	v_pk_add_f32 v[10:11], v[10:11], v[6:7]
	v_cvt_pk_bf16_f32 v4, v16, v17
	v_cvt_pk_bf16_f32 v5, v8, v9
	v_cvt_pk_bf16_f32 v6, v18, v19
	v_cvt_pk_bf16_f32 v7, v10, v11
	global_store_dwordx4 v[12:13], v[4:7], off sc1
	global_load_dwordx4 v[4:7], v[14:15], off
	v_lshl_or_b32 v8, v25, 9, v2
	ds_read_b128 v[8:11], v8
	v_xor_b32_e32 v16, v3, v146
	v_mad_i64_i32 v[12:13], s[20:21], v25, s17, v[28:29]
	v_lshlrev_b32_e32 v16, 4, v16
	v_lshl_add_u64 v[12:13], v[12:13], 0, v[140:141]
	v_and_b32_e32 v140, 0x1f0, v16
	s_waitcnt lgkmcnt(0)
	v_lshlrev_b32_e32 v16, 16, v8
	v_and_b32_e32 v17, 0xffff0000, v8
	v_lshlrev_b32_e32 v8, 16, v9
	v_and_b32_e32 v9, 0xffff0000, v9
	v_lshlrev_b32_e32 v18, 16, v10
	v_and_b32_e32 v19, 0xffff0000, v10
	v_lshlrev_b32_e32 v10, 16, v11
	v_and_b32_e32 v11, 0xffff0000, v11
	v_mad_i64_i32 v[14:15], s[20:21], v3, s17, v[26:27]
	v_lshl_add_u64 v[14:15], v[14:15], 0, v[140:141]
	s_waitcnt vmcnt(0)
	v_lshlrev_b32_e32 v20, 16, v4
	v_and_b32_e32 v21, 0xffff0000, v4
	v_lshlrev_b32_e32 v4, 16, v5
	v_and_b32_e32 v5, 0xffff0000, v5
	v_lshlrev_b32_e32 v22, 16, v6
	v_and_b32_e32 v23, 0xffff0000, v6
	v_lshlrev_b32_e32 v6, 16, v7
	v_and_b32_e32 v7, 0xffff0000, v7
	v_pk_add_f32 v[16:17], v[16:17], v[20:21]
	v_pk_add_f32 v[8:9], v[8:9], v[4:5]
	v_pk_add_f32 v[18:19], v[18:19], v[22:23]
	v_pk_add_f32 v[10:11], v[10:11], v[6:7]
	v_cvt_pk_bf16_f32 v4, v16, v17
	v_cvt_pk_bf16_f32 v5, v8, v9
	v_cvt_pk_bf16_f32 v6, v18, v19
	v_cvt_pk_bf16_f32 v7, v10, v11
	global_store_dwordx4 v[12:13], v[4:7], off sc1
	global_load_dwordx4 v[4:7], v[14:15], off
	v_lshl_or_b32 v8, v3, 9, v2
	ds_read_b128 v[8:11], v8
	v_mad_i64_i32 v[12:13], s[20:21], v3, s17, v[28:29]
	v_lshl_add_u64 v[12:13], v[12:13], 0, v[140:141]
	s_waitcnt lgkmcnt(0)
	v_lshlrev_b32_e32 v14, 16, v8
	v_and_b32_e32 v15, 0xffff0000, v8
	v_lshlrev_b32_e32 v8, 16, v9
	v_and_b32_e32 v9, 0xffff0000, v9
	v_lshlrev_b32_e32 v16, 16, v10
	v_and_b32_e32 v17, 0xffff0000, v10
	v_lshlrev_b32_e32 v10, 16, v11
	v_and_b32_e32 v11, 0xffff0000, v11
	s_waitcnt vmcnt(0)
	v_lshlrev_b32_e32 v18, 16, v4
	v_and_b32_e32 v19, 0xffff0000, v4
	v_lshlrev_b32_e32 v4, 16, v5
	v_and_b32_e32 v5, 0xffff0000, v5
	v_lshlrev_b32_e32 v20, 16, v6
	v_and_b32_e32 v21, 0xffff0000, v6
	v_lshlrev_b32_e32 v6, 16, v7
	v_and_b32_e32 v7, 0xffff0000, v7
	v_pk_add_f32 v[14:15], v[14:15], v[18:19]
	v_pk_add_f32 v[8:9], v[8:9], v[4:5]
	v_pk_add_f32 v[16:17], v[16:17], v[20:21]
	v_pk_add_f32 v[10:11], v[10:11], v[6:7]
	v_cvt_pk_bf16_f32 v4, v14, v15
	v_cvt_pk_bf16_f32 v5, v8, v9
	v_cvt_pk_bf16_f32 v6, v16, v17
	v_cvt_pk_bf16_f32 v7, v10, v11
	global_store_dwordx4 v[12:13], v[4:7], off sc1
	s_cbranch_scc1 .LBB0_1468
	s_add_i32 s19, s19, s33
	s_cmpk_gt_i32 s19, 0xff
	s_barrier
	s_cbranch_scc0 .LBB0_1465

; DEV unsigned cvt_pk_bf16(float lo, float hi) { const f32x2_t v = {lo, hi}; const bf16x2_t b = __builtin_convertvector(v, bf16x2_t); return __builtin_bit_cast(unsigned, b); }
; DEV float bflo(unsigned u) { return __uint_as_float(u << 16); }
; DEV float bfhi(unsigned u) { return __uint_as_float(u & 0xffff0000u); }
; template <int WT, class Epi>
; DEV void gemm_tile(const bf16_t* __restrict__ A, int lda, const bf16_t* __restrict__ Bt, int ldb, int K, unsigned char* lds, const Epi& epi) {
;     ...
;     if constexpr (Epi::STAGE) {
;         constexpr int RB = 4 * WT, CPR = RB / 16;
; #pragma unroll
;         for (int mi = 0; mi < FI; ++mi)
; #pragma unroll
;             for (int ni = 0; ni < FI; ++ni) {
;                 const int row = wr * WT + mi * 16 + fr, col = wc * WT + ni * 16 + fq * 4;
;                 const f32x4 v = epi.xform(row, col, acc[mi][ni]);
;                 uint2 w; w.x = cvt_pk_bf16(v[0], v[1]); w.y = cvt_pk_bf16(v[2], v[3]);
;                 *(uint2*)(lds + row * RB + ((((col >> 3) ^ (row & (CPR - 1))) << 4) | (((col >> 2) & 1) << 3))) = w;
;             }
;         __syncthreads();
; #pragma unroll
;         for (int i = 0; i < (2 * WT * CPR) / 256; ++i) {
;             const int idx = tid + 256 * i, row = idx / CPR, cp = idx % CPR, c = cp ^ (row & (CPR - 1));
;             const uint4 d = *(const uint4*)(lds + row * RB + (cp << 4));
;             *(uint4*)(epi.obase + (size_t)row * epi.old + c * 8) = epi.finish(row, c * 8, d);
;         }
;         __syncthreads();
;     DEV uint4 finish(int r, int c, uint4 d) const {
;         const uint4 u = *(const uint4*)(res + (size_t)r * LDB + c);
;         const float r8[8] = {bflo(u.x), bfhi(u.x), bflo(u.y), bfhi(u.y), bflo(u.z), bfhi(u.z), bflo(u.w), bfhi(u.w)};
;         return add8_bf16(d, r8);
;     }
.Lsk11_nox:
	v_lshl_or_b32 v18, v30, 2, v32
	v_lshlrev_b32_e32 v22, 3, v26
	s_nop 0
	v_cvt_pk_bf16_f32 v14, v14, v15
	v_cvt_pk_bf16_f32 v15, v16, v17
	v_lshrrev_b32_e32 v16, 3, v18
	v_and_b32_e32 v22, 8, v22
	v_xor_b32_e32 v17, v16, v29
	v_cvt_pk_bf16_f32 v10, v10, v11
	v_cvt_pk_bf16_f32 v11, v12, v13
	v_bitop3_b32 v12, v16, v29, 2 bitop3:0x36
	v_add_u32_e32 v23, s43, v31
	v_lshl_or_b32 v17, v17, 4, v22
	v_lshl_or_b32 v12, v12, 4, v22
	v_add_u32_e32 v17, v23, v17
	v_add_u32_e32 v12, v23, v12
	v_cvt_pk_bf16_f32 v2, v2, v3
	v_cvt_pk_bf16_f32 v3, v4, v5
	s_barrier
	ds_write_b64 v17, v[14:15]
	ds_write_b64 v12, v[10:11]
	ds_write_b64 v17, v[2:3] offset:2048
	v_cvt_pk_bf16_f32 v2, v6, v7
	v_cvt_pk_bf16_f32 v3, v8, v9
	ds_write_b64 v12, v[2:3] offset:2048
	v_ashrrev_i32_e32 v2, 31, v25
	v_lshrrev_b32_e32 v2, 29, v2
	v_add_u32_e32 v2, v25, v2
	v_ashrrev_i32_e32 v8, 3, v2
	v_and_b32_e32 v2, -8, v2
	s_lshl_b32 s38, s49, 6
	v_sub_u32_e32 v9, v25, v2
	s_ashr_i32 s39, s38, 31
	s_lshl_b32 s4, s50, 1
	v_bitop3_b32 v2, v8, v9, 7 bitop3:0x6c
	v_lshl_add_u64 v[20:21], v[130:131], 0, s[4:5]
	s_lshl_b64 s[38:39], s[38:39], 1
	v_lshlrev_b32_e32 v2, 3, v2
	v_lshl_add_u64 v[20:21], v[20:21], 0, s[38:39]
	v_ashrrev_i32_e32 v3, 31, v2
	v_mad_i64_i32 v[4:5], s[40:41], v8, s47, v[20:21]
	v_lshlrev_b64 v[10:11], 1, v[2:3]
	v_lshl_add_u64 v[2:3], v[4:5], 0, v[10:11]
	s_waitcnt lgkmcnt(0)
	s_barrier
	global_load_dwordx4 v[2:5], v[2:3], off
	v_add_u32_e32 v16, 0x100, v25
	v_ashrrev_i32_e32 v12, 31, v16
	v_lshl_add_u64 v[6:7], v[134:135], 0, s[4:5]
	v_lshrrev_b32_e32 v14, 29, v12
	v_lshl_add_u64 v[12:13], v[6:7], 0, s[38:39]
	v_add_u32_e32 v6, v16, v14
	v_lshlrev_b32_e32 v7, 7, v8
	v_mad_i64_i32 v[14:15], s[38:39], v8, s47, v[12:13]
	v_ashrrev_i32_e32 v18, 3, v6
	v_and_b32_e32 v6, -8, v6
	v_lshlrev_b32_e32 v8, 4, v9
	v_sub_u32_e32 v25, v16, v6
	v_add3_u32 v6, s43, v7, v8
	ds_read_b128 v[6:9], v6
	v_mad_i64_i32 v[16:17], s[38:39], v18, s47, v[20:21]
	v_bitop3_b32 v20, v18, v25, 7 bitop3:0x6c
	v_lshl_add_u64 v[10:11], v[14:15], 0, v[10:11]
	s_waitcnt lgkmcnt(0)
	v_lshlrev_b32_e32 v14, 16, v6
	v_and_b32_e32 v15, 0xffff0000, v6
	v_lshlrev_b32_e32 v6, 16, v7
	v_and_b32_e32 v7, 0xffff0000, v7
	v_lshlrev_b32_e32 v22, 16, v8
	v_and_b32_e32 v23, 0xffff0000, v8
	v_lshlrev_b32_e32 v8, 16, v9
	v_and_b32_e32 v9, 0xffff0000, v9
	v_lshlrev_b32_e32 v20, 3, v20
	v_ashrrev_i32_e32 v21, 31, v20
	s_add_i32 s44, s44, s75
	v_mad_i64_i32 v[12:13], s[40:41], v18, s47, v[12:13]
	s_add_i32 s4, s44, s42
	s_min_i32 s38, s4, 0xff
	s_cmpk_lt_i32 s44, 0x100
	s_waitcnt vmcnt(0)
	v_lshlrev_b32_e32 v26, 16, v2
	v_and_b32_e32 v27, 0xffff0000, v2
	v_lshlrev_b32_e32 v2, 16, v3
	v_and_b32_e32 v3, 0xffff0000, v3
	v_lshlrev_b32_e32 v28, 16, v4
	v_and_b32_e32 v29, 0xffff0000, v4
	v_lshlrev_b32_e32 v4, 16, v5
	v_and_b32_e32 v5, 0xffff0000, v5
	v_pk_add_f32 v[14:15], v[14:15], v[26:27]
	v_pk_add_f32 v[6:7], v[6:7], v[2:3]
	v_pk_add_f32 v[22:23], v[22:23], v[28:29]
	v_pk_add_f32 v[8:9], v[8:9], v[4:5]
	v_cvt_pk_bf16_f32 v2, v14, v15
	v_cvt_pk_bf16_f32 v3, v6, v7
	v_cvt_pk_bf16_f32 v4, v22, v23
	v_cvt_pk_bf16_f32 v5, v8, v9
	global_store_dwordx4 v[10:11], v[2:5], off sc1
	v_lshlrev_b64 v[10:11], 1, v[20:21]
	v_lshlrev_b32_e32 v6, 7, v18
	v_lshl_add_u64 v[2:3], v[16:17], 0, v[10:11]
	global_load_dwordx4 v[2:5], v[2:3], off
	v_lshlrev_b32_e32 v7, 4, v25
	v_add3_u32 v6, s43, v6, v7
	ds_read_b128 v[6:9], v6
	v_lshl_add_u64 v[10:11], v[12:13], 0, v[10:11]
	s_waitcnt lgkmcnt(0)
	v_lshlrev_b32_e32 v12, 16, v6
	v_and_b32_e32 v13, 0xffff0000, v6
	v_lshlrev_b32_e32 v6, 16, v7
	v_and_b32_e32 v7, 0xffff0000, v7
	v_lshlrev_b32_e32 v14, 16, v8
	v_and_b32_e32 v15, 0xffff0000, v8
	v_lshlrev_b32_e32 v8, 16, v9
	v_and_b32_e32 v9, 0xffff0000, v9
	s_waitcnt vmcnt(0)
	v_lshlrev_b32_e32 v16, 16, v2
	v_and_b32_e32 v17, 0xffff0000, v2
	v_lshlrev_b32_e32 v2, 16, v3
	v_and_b32_e32 v3, 0xffff0000, v3
	v_lshlrev_b32_e32 v20, 16, v4
	v_and_b32_e32 v21, 0xffff0000, v4
	v_lshlrev_b32_e32 v4, 16, v5
	v_and_b32_e32 v5, 0xffff0000, v5
	v_pk_add_f32 v[12:13], v[12:13], v[16:17]
	v_pk_add_f32 v[6:7], v[6:7], v[2:3]
	v_pk_add_f32 v[14:15], v[14:15], v[20:21]
	v_pk_add_f32 v[8:9], v[8:9], v[4:5]
	v_cvt_pk_bf16_f32 v2, v12, v13
	v_cvt_pk_bf16_f32 v3, v6, v7
	v_cvt_pk_bf16_f32 v4, v14, v15
	v_cvt_pk_bf16_f32 v5, v8, v9
	global_store_dwordx4 v[10:11], v[2:5], off sc1
	s_barrier
	s_cbranch_scc0 .LBB0_1487

; DEV unsigned cvt_pk_bf16(float lo, float hi) { const f32x2_t v = {lo, hi}; const bf16x2_t b = __builtin_convertvector(v, bf16x2_t); return __builtin_bit_cast(unsigned, b); }
; DEV float bflo(unsigned u) { return __uint_as_float(u << 16); }
; DEV float bfhi(unsigned u) { return __uint_as_float(u & 0xffff0000u); }
; template <bool OUT_F32>
; DEV void rmsnorm_row_from_bf16(const bf16_t* __restrict__ x, const float* __restrict__ g, void* __restrict__ y, int lane) {
;     float v[4][8]; float ss = 0.f;
; #pragma unroll
;     for (int i = 0; i < 4; ++i) { uint4 u; if (OUT_F32) { const u32x4 t_ = __builtin_nontemporal_load((const u32x4*)x + i * 64 + lane); u = make_uint4(t_[0], t_[1], t_[2], t_[3]); } else u = ((const uint4*)x)[i * 64 + lane];
;         v[i][0] = bflo(u.x); v[i][1] = bfhi(u.x); v[i][2] = bflo(u.y); v[i][3] = bfhi(u.y); v[i][4] = bflo(u.z); v[i][5] = bfhi(u.z); v[i][6] = bflo(u.w); v[i][7] = bfhi(u.w);
; #pragma unroll
;         for (int e = 0; e < 8; ++e) ss += v[i][e] * v[i][e]; }
;     ss = wave_sum(ss);
;     const float rs = rsqrtf(ss * (1.f / 2048.f) + EPS);
; #pragma unroll
;     for (int i = 0; i < 4; ++i) {
;         const f32x4 g0 = ((const f32x4*)g)[(i * 64 + lane) * 2], g1 = ((const f32x4*)g)[(i * 64 + lane) * 2 + 1];
;         const f32x4 o0 = (f32x4){v[i][0], v[i][1], v[i][2], v[i][3]} * rs * g0, o1 = (f32x4){v[i][4], v[i][5], v[i][6], v[i][7]} * rs * g1;
;         if (OUT_F32) { __builtin_nontemporal_store(o0, (f32x4*)y + (i * 64 + lane) * 2); __builtin_nontemporal_store(o1, (f32x4*)y + (i * 64 + lane) * 2 + 1); }
;         else { uint4 w; w.x = cvt_pk_bf16(o0[0], o0[1]); w.y = cvt_pk_bf16(o0[2], o0[3]); w.z = cvt_pk_bf16(o1[0], o1[1]); w.w = cvt_pk_bf16(o1[2], o1[3]); ((uint4*)y)[i * 64 + lane] = w; }
;     }
; }
.LBB0_1542:
	s_or_b64 exec, exec, s[12:13]
	global_load_dwordx4 v[54:57], v[36:37], off offset:-2048 nt
	global_load_dwordx4 v[58:61], v[36:37], off offset:-1024 nt
	global_load_dwordx4 v[62:65], v[36:37], off nt
	global_load_dwordx4 v[66:69], v[36:37], off offset:1024 nt
	v_add_u32_e32 v46, s0, v46
	v_cmp_lt_i32_e32 vcc, s15, v46
	s_or_b64 s[8:9], vcc, s[8:9]
	v_lshl_add_u64 v[44:45], v[44:45], 2, s[6:7]
	v_lshl_add_u64 v[34:35], v[34:35], 0, s[2:3]
	v_lshl_add_u64 v[36:37], v[36:37], 0, s[4:5]
	s_waitcnt vmcnt(3)
	v_and_b32_e32 v71, 0xffff0000, v54
	v_lshlrev_b32_e32 v70, 16, v54
	v_lshlrev_b32_e32 v54, 16, v55
	s_waitcnt vmcnt(0)
	v_and_b32_e32 v84, 0xffff0000, v68
	v_lshlrev_b32_e32 v87, 16, v68
	v_mul_f32_e32 v68, v71, v71
	v_fmac_f32_e32 v68, v70, v70
	v_and_b32_e32 v55, 0xffff0000, v55
	v_fmac_f32_e32 v68, v54, v54
	v_lshlrev_b32_e32 v72, 16, v56
	v_fmac_f32_e32 v68, v55, v55
	v_and_b32_e32 v73, 0xffff0000, v56
	v_fmac_f32_e32 v68, v72, v72
	v_lshlrev_b32_e32 v56, 16, v57
	v_fmac_f32_e32 v68, v73, v73
	v_and_b32_e32 v57, 0xffff0000, v57
	v_fmac_f32_e32 v68, v56, v56
	v_lshlrev_b32_e32 v74, 16, v58
	v_fmac_f32_e32 v68, v57, v57
	v_and_b32_e32 v75, 0xffff0000, v58
	v_fmac_f32_e32 v68, v74, v74
	v_lshlrev_b32_e32 v58, 16, v59
	v_fmac_f32_e32 v68, v75, v75
	v_and_b32_e32 v59, 0xffff0000, v59
	v_fmac_f32_e32 v68, v58, v58
	v_lshlrev_b32_e32 v76, 16, v60
	v_fmac_f32_e32 v68, v59, v59
	v_and_b32_e32 v77, 0xffff0000, v60
	v_fmac_f32_e32 v68, v76, v76
	v_lshlrev_b32_e32 v60, 16, v61
	v_fmac_f32_e32 v68, v77, v77
	v_and_b32_e32 v61, 0xffff0000, v61
	v_fmac_f32_e32 v68, v60, v60
	v_lshlrev_b32_e32 v78, 16, v62
	v_fmac_f32_e32 v68, v61, v61
	v_and_b32_e32 v79, 0xffff0000, v62
	v_fmac_f32_e32 v68, v78, v78
	v_lshlrev_b32_e32 v62, 16, v63
	v_fmac_f32_e32 v68, v79, v79
	v_and_b32_e32 v63, 0xffff0000, v63
	v_fmac_f32_e32 v68, v62, v62
	v_lshlrev_b32_e32 v80, 16, v64
	v_fmac_f32_e32 v68, v63, v63
	v_and_b32_e32 v81, 0xffff0000, v64
	v_fmac_f32_e32 v68, v80, v80
	v_lshlrev_b32_e32 v64, 16, v65
	v_fmac_f32_e32 v68, v81, v81
	v_and_b32_e32 v65, 0xffff0000, v65
	v_fmac_f32_e32 v68, v64, v64
	v_lshlrev_b32_e32 v82, 16, v66
	v_fmac_f32_e32 v68, v65, v65
	v_and_b32_e32 v83, 0xffff0000, v66
	v_fmac_f32_e32 v68, v82, v82
	v_lshlrev_b32_e32 v66, 16, v67
	v_fmac_f32_e32 v68, v83, v83
	v_and_b32_e32 v67, 0xffff0000, v67
	v_mov_b32_e32 v86, v84
	v_fmac_f32_e32 v68, v66, v66
	v_and_b32_e32 v32, 0xffff0000, v69
	v_pk_mul_f32 v[90:91], v[86:87], v[86:87]
	v_fmac_f32_e32 v68, v67, v67
	v_lshlrev_b32_e32 v89, 16, v69
	v_mov_b32_e32 v88, v32
	v_add_f32_e32 v68, v91, v68
	v_pk_mul_f32 v[92:93], v[88:89], v[88:89]
	v_add_f32_e32 v68, v90, v68
	v_add_f32_e32 v68, v93, v68
	v_add_f32_e32 v68, v92, v68
	ds_bpermute_b32 v85, v47, v68
	v_lshl_add_u64 v[90:91], v[44:45], 0, v[38:39]
	v_lshl_add_u64 v[92:93], v[44:45], 0, v[40:41]
	v_lshl_add_u64 v[44:45], v[44:45], 0, v[42:43]
	s_waitcnt lgkmcnt(0)
	v_add_f32_e32 v68, v68, v85
	ds_bpermute_b32 v85, v48, v68
	s_waitcnt lgkmcnt(0)
	v_add_f32_e32 v68, v68, v85
	ds_bpermute_b32 v85, v49, v68
	s_waitcnt lgkmcnt(0)
	v_add_f32_e32 v68, v68, v85
	ds_bpermute_b32 v85, v50, v68
	s_waitcnt lgkmcnt(0)
	v_add_f32_e32 v68, v68, v85
	ds_bpermute_b32 v85, v51, v68
	s_waitcnt lgkmcnt(0)
	v_add_f32_e32 v68, v68, v85
	ds_bpermute_b32 v85, v52, v68
	s_waitcnt lgkmcnt(0)
	v_add_f32_e32 v68, v68, v85
	v_fmamk_f32 v68, v68, 0x3a000000, v53
	v_mul_f32_e32 v85, 0x4b800000, v68
	v_cmp_gt_f32_e32 vcc, s14, v68
	s_nop 1
	v_cndmask_b32_e32 v68, v68, v85, vcc
	v_rsq_f32_e32 v94, v68
	v_and_b32_e32 v85, s0, v69
	v_pk_mov_b32 v[68:69], v[86:87], v[84:85] op_sel:[1,0]
	v_pk_mov_b32 v[84:85], v[88:89], v[32:33] op_sel:[1,0]
	v_mul_f32_e32 v32, 0x45800000, v94
	v_cndmask_b32_e32 v32, v94, v32, vcc
	v_pk_mul_f32 v[70:71], v[70:71], v[32:33] op_sel_hi:[1,0]
	v_pk_mul_f32 v[54:55], v[54:55], v[32:33] op_sel_hi:[1,0]
	v_pk_mul_f32 v[72:73], v[72:73], v[32:33] op_sel_hi:[1,0]
	v_pk_mul_f32 v[86:87], v[56:57], v[32:33] op_sel_hi:[1,0]
	v_pk_mul_f32 v[74:75], v[74:75], v[32:33] op_sel_hi:[1,0]
	v_pk_mul_f32 v[88:89], v[58:59], v[32:33] op_sel_hi:[1,0]
	v_pk_mul_f32 v[76:77], v[76:77], v[32:33] op_sel_hi:[1,0]
	v_pk_mul_f32 v[94:95], v[60:61], v[32:33] op_sel_hi:[1,0]
	v_pk_mul_f32 v[78:79], v[78:79], v[32:33] op_sel_hi:[1,0]
	v_pk_mul_f32 v[96:97], v[62:63], v[32:33] op_sel_hi:[1,0]
	v_pk_mul_f32 v[80:81], v[80:81], v[32:33] op_sel_hi:[1,0]
	v_pk_mul_f32 v[98:99], v[64:65], v[32:33] op_sel_hi:[1,0]
	v_pk_mul_f32 v[82:83], v[82:83], v[32:33] op_sel_hi:[1,0]
	v_pk_mul_f32 v[100:101], v[66:67], v[32:33] op_sel_hi:[1,0]
	v_pk_mul_f32 v[102:103], v[32:33], v[68:69] op_sel_hi:[0,1]
	v_pk_mul_f32 v[84:85], v[32:33], v[84:85] op_sel_hi:[0,1]
	v_pk_mul_f32 v[56:57], v[6:7], v[54:55]
	v_pk_mul_f32 v[54:55], v[4:5], v[70:71]
	v_pk_mul_f32 v[60:61], v[2:3], v[86:87]
	v_pk_mul_f32 v[58:59], v[0:1], v[72:73]
	v_pk_mul_f32 v[64:65], v[14:15], v[88:89]
	v_pk_mul_f32 v[62:63], v[12:13], v[74:75]
	v_pk_mul_f32 v[68:69], v[10:11], v[94:95]
	v_pk_mul_f32 v[66:67], v[8:9], v[76:77]
	v_pk_mul_f32 v[72:73], v[22:23], v[96:97]
	v_pk_mul_f32 v[70:71], v[20:21], v[78:79]
	v_pk_mul_f32 v[76:77], v[18:19], v[98:99]
	v_pk_mul_f32 v[74:75], v[16:17], v[80:81]
	v_pk_mul_f32 v[80:81], v[30:31], v[100:101]
	v_pk_mul_f32 v[78:79], v[28:29], v[82:83]
	v_pk_mul_f32 v[84:85], v[26:27], v[84:85]
	v_pk_mul_f32 v[82:83], v[24:25], v[102:103]
	global_store_dwordx4 v[90:91], v[54:57], off nt sc1
	global_store_dwordx4 v[90:91], v[58:61], off offset:16 nt sc1
	global_store_dwordx4 v[90:91], v[62:65], off offset:2048 nt sc1
	global_store_dwordx4 v[90:91], v[66:69], off offset:2064 nt sc1
	global_store_dwordx4 v[92:93], v[70:73], off nt sc1
	global_store_dwordx4 v[92:93], v[74:77], off offset:16 nt sc1
	global_store_dwordx4 v[44:45], v[78:81], off nt sc1
	global_store_dwordx4 v[44:45], v[82:85], off offset:16 nt sc1
	s_andn2_b64 exec, exec, s[8:9]
	s_cbranch_execz .LBB0_1545
